# speedup vs baseline: 1.0597x; 1.0394x over previous
; template <int EPI, bool AF32>
; DEV void gemm_tile(const void* Ap, int lda, const u16* Bt, int ldb, int K, int m0, int n0, const Epi& ea, char* smem) {
;     ...
;   auto gload = [&](int kt) {
;     const int k0 = kt << 6;
; #pragma unroll
;     for (int i = 0; i < 4; i++) {
;       const int c = tid + i * 256, row = c >> 3, kc = c & 7;
;       if (AF32) {
;         const float* pa = (const float*)Ap + (size_t)(m0 + row) * lda + k0 + kc * 8;
;         rfa[2 * i] = *(const f32x4*)pa;
;         rfa[2 * i + 1] = *(const f32x4*)(pa + 4);
;       } else {
;         ra[i] = *(const u32x4*)((const u16*)Ap + (size_t)(m0 + row) * lda + k0 + kc * 8);
;       }
;       rb[i] = *(const u32x4*)(Bt + (size_t)(n0 + row) * ldb + k0 + kc * 8);
;     }
;   };
;   auto swrite = [&](int buf) {
; #pragma unroll
;     for (int i = 0; i < 4; i++) {
;       const int c = tid + i * 256, row = c >> 3, kc = c & 7;
;       u32x4 va;
;       if (AF32) {
;         va = (u32x4){pack2(rfa[2 * i][0], rfa[2 * i][1]), pack2(rfa[2 * i][2], rfa[2 * i][3]),
;                      pack2(rfa[2 * i + 1][0], rfa[2 * i + 1][1]), pack2(rfa[2 * i + 1][2], rfa[2 * i + 1][3])};
;       } else {
;         va = ra[i];
;       }
;       *(u32x4*)(sA + buf * 9216 + row * 72 + kc * 8) = va;
;       *(u32x4*)(sB + buf * 9216 + row * 72 + kc * 8) = rb[i];
;     }
;   };
;   gload(0);
;   swrite(0);
;   if (nk > 1) gload(1);
;   __syncthreads();
.LBB0_164:
	s_mul_hi_i32 s6, s8, 0x2aaaaaab
	s_lshr_b32 s7, s6, 31
	s_ashr_i32 s6, s6, 5
	s_add_i32 s6, s6, s7
	s_lshl_b32 s10, s6, 5
	s_mul_i32 s7, s6, 0xc0
	s_sub_i32 s6, 0x104, s10
	s_min_u32 s11, s6, 32
	s_sub_i32 s9, s8, s7
	v_cvt_f32_ubyte0_e32 v2, s11
	v_cvt_f32_i32_e32 v0, s9
	v_rcp_iflag_f32_e32 v3, v2
	s_ashr_i32 s6, s9, 30
	s_or_b32 s12, s6, 1
	s_waitcnt vmcnt(12)
	v_mov_b32_e32 v114, v157
	v_mul_f32_e32 v3, v0, v3
	v_trunc_f32_e32 v3, v3
	v_fma_f32 v0, -v3, v2, v0
	v_cvt_i32_f32_e32 v3, v3
	v_cmp_ge_f32_e64 s[6:7], |v0|, v2
	s_and_b64 s[6:7], s[6:7], exec
	s_cselect_b32 s6, s12, 0
	v_readfirstlane_b32 s7, v3
	s_add_i32 s6, s7, s6
	s_sext_i32_i16 s7, s6
	s_mul_i32 s6, s6, s11
	s_sub_i32 s6, s9, s6
	s_sext_i32_i16 s6, s6
	s_add_i32 s10, s10, s6
	s_lshl_b32 s9, s10, 7
	s_lshl_b32 s10, s7, 7
	v_ashrrev_i32_e32 v8, 3, v114
	v_add_u32_e32 v2, s9, v8
	v_ashrrev_i32_e32 v3, 31, v2
	v_lshlrev_b32_e32 v0, 3, v114
	v_add_u32_e32 v4, 0x100, v114
	v_lshlrev_b64 v[58:59], 11, v[2:3]
	v_and_b32_e32 v0, 56, v0
	v_ashrrev_i32_e32 v9, 3, v4
	v_lshl_add_u64 v[2:3], s[60:61], 0, v[58:59]
	v_lshlrev_b32_e32 v0, 1, v0
	v_add_u32_e32 v4, s9, v9
	v_add_u32_e32 v6, 0x200, v114
	v_lshl_add_u64 v[14:15], v[2:3], 0, v[0:1]
	v_add_u32_e32 v2, s10, v8
	v_ashrrev_i32_e32 v5, 31, v4
	v_ashrrev_i32_e32 v10, 3, v6
	v_ashrrev_i32_e32 v3, 31, v2
	v_lshlrev_b64 v[62:63], 11, v[4:5]
	v_add_u32_e32 v6, s9, v10
	v_lshlrev_b64 v[60:61], 11, v[2:3]
	v_lshl_add_u64 v[4:5], s[60:61], 0, v[62:63]
	v_ashrrev_i32_e32 v7, 31, v6
	v_lshl_add_u64 v[2:3], s[2:3], 0, v[60:61]
	v_lshl_add_u64 v[16:17], v[4:5], 0, v[0:1]
	v_add_u32_e32 v4, s10, v9
	v_lshlrev_b64 v[66:67], 11, v[6:7]
	v_lshl_add_u64 v[2:3], v[2:3], 0, v[0:1]
	v_ashrrev_i32_e32 v5, 31, v4
	v_lshl_add_u64 v[6:7], s[60:61], 0, v[66:67]
	global_load_dwordx4 v[30:33], v[2:3], off
	v_lshlrev_b64 v[64:65], 11, v[4:5]
	v_lshl_add_u64 v[68:69], v[6:7], 0, v[0:1]
	v_add_u32_e32 v6, s10, v10
	global_load_dwordx4 v[26:29], v[14:15], off
	global_load_dwordx4 v[34:37], v[16:17], off
	v_lshl_add_u64 v[4:5], s[2:3], 0, v[64:65]
	v_ashrrev_i32_e32 v7, 31, v6
	v_lshl_add_u64 v[4:5], v[4:5], 0, v[0:1]
	v_lshlrev_b64 v[70:71], 11, v[6:7]
	global_load_dwordx4 v[38:41], v[4:5], off
	v_lshl_add_u64 v[6:7], s[2:3], 0, v[70:71]
	global_load_dwordx4 v[42:45], v[68:69], off
	v_lshl_add_u64 v[18:19], v[6:7], 0, v[0:1]
	global_load_dwordx4 v[46:49], v[18:19], off
	v_add_u32_e32 v6, 0x300, v114
	v_ashrrev_i32_e32 v80, 3, v6
	v_add_u32_e32 v6, s9, v80
	v_ashrrev_i32_e32 v7, 31, v6
	v_lshlrev_b64 v[72:73], 11, v[6:7]
	v_lshl_add_u64 v[6:7], s[60:61], 0, v[72:73]
	v_lshl_add_u64 v[74:75], v[6:7], 0, v[0:1]
	v_add_u32_e32 v6, s10, v80
	v_ashrrev_i32_e32 v7, 31, v6
	v_lshlrev_b64 v[76:77], 11, v[6:7]
	v_lshl_add_u64 v[6:7], s[2:3], 0, v[76:77]
	v_lshl_add_u64 v[78:79], v[6:7], 0, v[0:1]
	global_load_dwordx4 v[50:53], v[74:75], off
	global_load_dwordx4 v[54:57], v[78:79], off
	s_waitcnt vmcnt(19)
	v_mul_lo_u32 v118, v8, s71
	v_mul_lo_u32 v119, v9, s71
	s_waitcnt vmcnt(18)
	v_mul_lo_u32 v123, v10, s71
	global_load_dwordx4 v[6:9], v[2:3], off offset:128
	global_load_dwordx4 v[10:13], v[4:5], off offset:128
	s_nop 0
	global_load_dwordx4 v[2:5], v[18:19], off offset:128
	global_load_dwordx4 v[22:25], v[14:15], off offset:128
	s_nop 0
	global_load_dwordx4 v[18:21], v[16:17], off offset:128
	s_nop 0
	global_load_dwordx4 v[14:17], v[68:69], off offset:128
	v_bfe_u32 v161, v157, 3, 4
	v_add_u32_e32 v161, 4, v161
	v_lshlrev_b32_e32 v161, 1, v161
	v_and_b32_e32 v161, 16, v161
	v_xor_b32_e32 v129, v0, v161
	v_lshl_add_u32 v122, v118, 1, v129
	v_lshl_add_u32 v121, v119, 1, v129
	v_lshl_add_u32 v120, v123, 1, v129
	v_and_b32_e32 v115, 15, v114
	s_waitcnt vmcnt(23)
	v_mul_lo_u32 v126, v80, s71
	v_bfe_u32 v116, v114, 4, 2
	v_lshl_add_u32 v124, v126, 1, v129
	s_mov_b32 s11, 0
	v_lshlrev_b32_e32 v125, 4, v116
	v_and_b32_e32 v161, 15, v157
	v_add_u32_e32 v161, 4, v161
	v_lshlrev_b32_e32 v161, 1, v161
	v_and_b32_e32 v161, 16, v161
	v_xor_b32_e32 v125, v125, v161
	s_mov_b64 s[6:7], 0
	s_waitcnt vmcnt(13)
	ds_write_b128 v122, v[30:33] offset:36864
	s_waitcnt vmcnt(12)
	ds_write_b128 v122, v[26:29]
	s_waitcnt vmcnt(11)
	ds_write_b128 v121, v[34:37]
	s_waitcnt vmcnt(10)
	ds_write_b128 v121, v[38:41] offset:36864
	s_waitcnt vmcnt(9)
	ds_write_b128 v120, v[42:45]
	s_waitcnt vmcnt(8)
	ds_write_b128 v120, v[46:49] offset:36864
	global_load_dwordx4 v[26:29], v[74:75], off offset:128
	global_load_dwordx4 v[30:33], v[78:79], off offset:128
	v_ashrrev_i32_e32 v34, 1, v114
	v_and_b32_e32 v117, 0xffffffc0, v34
	v_or_b32_e32 v34, v117, v115
	v_mul_lo_u32 v128, v34, s71
	v_lshlrev_b32_e32 v34, 4, v114
	v_and_b32_e32 v34, 0x70, v34
	v_and_b32_e32 v35, 0x4f, v114
	v_or_b32_e32 v76, v76, v34
	v_or_b32_e32 v72, v72, v34
	v_or_b32_e32 v70, v70, v34
	v_or_b32_e32 v66, v66, v34
	v_or_b32_e32 v64, v64, v34
	v_or_b32_e32 v62, v62, v34
	v_or_b32_e32 v60, v60, v34
	v_or_b32_e32 v58, v58, v34
	v_mov_b32_e32 v34, 0
	s_waitcnt vmcnt(9)
	ds_write_b128 v124, v[50:53]
	s_waitcnt vmcnt(8)
	ds_write_b128 v124, v[54:57] offset:36864
	v_mul_u32_u24_e32 v127, 0x48, v35
	v_lshl_add_u64 v[98:99], s[4:5], 0, v[76:77]
	v_lshl_add_u64 v[100:101], s[66:67], 0, v[72:73]
	v_lshl_add_u64 v[102:103], s[4:5], 0, v[70:71]
	v_lshl_add_u64 v[104:105], s[66:67], 0, v[66:67]
	v_lshl_add_u64 v[106:107], s[4:5], 0, v[64:65]
	v_lshl_add_u64 v[108:109], s[66:67], 0, v[62:63]
	v_lshl_add_u64 v[110:111], s[4:5], 0, v[60:61]
	v_lshl_add_u64 v[112:113], s[66:67], 0, v[58:59]
	v_mov_b32_e32 v35, v34
	v_mov_b32_e32 v36, v34
	v_mov_b32_e32 v37, v34
	v_mov_b32_e32 v38, v34
	v_mov_b32_e32 v39, v34
	v_mov_b32_e32 v40, v34
	v_mov_b32_e32 v41, v34
	v_mov_b32_e32 v42, v34
	v_mov_b32_e32 v43, v34
	v_mov_b32_e32 v44, v34
	v_mov_b32_e32 v45, v34
	v_mov_b32_e32 v46, v34
	v_mov_b32_e32 v47, v34
	v_mov_b32_e32 v48, v34
	v_mov_b32_e32 v49, v34
	v_mov_b32_e32 v50, v34
	v_mov_b32_e32 v51, v34
	v_mov_b32_e32 v52, v34
	v_mov_b32_e32 v53, v34
	v_mov_b32_e32 v54, v34
	v_mov_b32_e32 v55, v34
	v_mov_b32_e32 v56, v34
	v_mov_b32_e32 v57, v34
	v_mov_b32_e32 v58, v34
	v_mov_b32_e32 v59, v34
	v_mov_b32_e32 v60, v34
	v_mov_b32_e32 v61, v34
	v_mov_b32_e32 v62, v34
	v_mov_b32_e32 v63, v34
	v_mov_b32_e32 v64, v34
	v_mov_b32_e32 v65, v34
	v_mov_b32_e32 v66, v34
	v_mov_b32_e32 v67, v34
	v_mov_b32_e32 v68, v34
	v_mov_b32_e32 v69, v34
	v_mov_b32_e32 v70, v34
	v_mov_b32_e32 v71, v34
	v_mov_b32_e32 v72, v34
	v_mov_b32_e32 v73, v34
	v_mov_b32_e32 v74, v34
	v_mov_b32_e32 v75, v34
	v_mov_b32_e32 v76, v34
	v_mov_b32_e32 v77, v34
	v_mov_b32_e32 v78, v34
	v_mov_b32_e32 v79, v34
	v_mov_b32_e32 v80, v34
	v_mov_b32_e32 v81, v34
	v_mov_b32_e32 v82, v34
	v_mov_b32_e32 v83, v34
	v_mov_b32_e32 v84, v34
	v_mov_b32_e32 v85, v34
	v_mov_b32_e32 v86, v34
	v_mov_b32_e32 v87, v34
	v_mov_b32_e32 v88, v34
	v_mov_b32_e32 v89, v34
	v_mov_b32_e32 v90, v34
	v_mov_b32_e32 v91, v34
	v_mov_b32_e32 v92, v34
	v_mov_b32_e32 v93, v34
	v_mov_b32_e32 v94, v34
	v_mov_b32_e32 v95, v34
	v_mov_b32_e32 v96, v34
	v_mov_b32_e32 v97, v34
	s_waitcnt lgkmcnt(0)
	s_barrier
; DEV f32x4 mfma16(bf16x8 a, bf16x8 b, f32x4 c) { return __builtin_amdgcn_mfma_f32_16x16x32_bf16(a, b, c, 0, 0, 0); }
; template <int EPI, bool AF32>
; DEV void gemm_tile(const void* Ap, int lda, const u16* Bt, int ldb, int K, int m0, int n0, const Epi& ea, char* smem) {
;     ...
;   for (int kt = 0; kt < nk; kt++) {
;     const int buf = kt & 1;
;     if (kt + 1 < nk) swrite(buf ^ 1);
;     if (kt + 2 < nk) gload(kt + 2);
; #pragma unroll
;     for (int ks = 0; ks < 2; ks++) {
;       bf16x8 a[4], b[4];
; #pragma unroll
;       for (int m = 0; m < 4; m++) a[m] = *(const bf16x8*)(sA + buf * 9216 + (wr * 64 + m * 16 + fr) * 72 + ks * 32 + fq * 8);
; #pragma unroll
;       for (int n = 0; n < 4; n++) b[n] = *(const bf16x8*)(sB + buf * 9216 + (wc * 64 + n * 16 + fr) * 72 + ks * 32 + fq * 8);
;       __builtin_amdgcn_s_setprio(1);
; #pragma unroll
;       for (int m = 0; m < 4; m++)
; #pragma unroll
;         for (int n = 0; n < 4; n++) acc[m][n] = mfma16(a[m], b[n], acc[m][n]);
;       __builtin_amdgcn_s_setprio(0);
;     }
;     __syncthreads();
	v_lshl_add_u32 v161, v128, 1, v125
	v_lshl_add_u32 v129, v127, 1, v125
	s_mov_b32 s11, 0
	s_mov_b64 s[6:7], 0x100
	ds_read_b128 v[130:133], v161
	ds_read_b128 v[134:137], v161 offset:2304
	ds_read_b128 v[138:141], v161 offset:4608
	ds_read_b128 v[142:145], v161 offset:6912
	ds_read_b128 v[146:149], v129 offset:36864
	ds_read_b128 v[150:153], v129 offset:39168
	ds_read_b128 v[162:165], v129 offset:41472
	ds_read_b128 v[166:169], v129 offset:43776
.Lgk0_loop:
	s_waitcnt lgkmcnt(0)
	ds_read_b128 v[222:225], v161 offset:64
	ds_read_b128 v[226:229], v161 offset:2368
	ds_read_b128 v[230:233], v161 offset:4672
	ds_read_b128 v[234:237], v161 offset:6976
	ds_read_b128 v[238:241], v129 offset:36928
	ds_read_b128 v[242:245], v129 offset:39232
	ds_read_b128 v[246:249], v129 offset:41536
	ds_read_b128 v[250:253], v129 offset:43840
	v_mfma_f32_16x16x32_bf16 v[94:97], v[130:133], v[146:149], v[94:97]
	v_mfma_f32_16x16x32_bf16 v[90:93], v[130:133], v[150:153], v[90:93]
	v_mfma_f32_16x16x32_bf16 v[86:89], v[130:133], v[162:165], v[86:89]
	v_mfma_f32_16x16x32_bf16 v[82:85], v[130:133], v[166:169], v[82:85]
	s_waitcnt vmcnt(0)
	ds_write_b128 v122, v[22:25] offset:18432
	ds_write_b128 v122, v[6:9] offset:55296
	v_mfma_f32_16x16x32_bf16 v[78:81], v[134:137], v[146:149], v[78:81]
	ds_write_b128 v121, v[18:21] offset:18432
	ds_write_b128 v121, v[10:13] offset:55296
	v_mfma_f32_16x16x32_bf16 v[74:77], v[134:137], v[150:153], v[74:77]
	ds_write_b128 v120, v[14:17] offset:18432
	ds_write_b128 v120, v[2:5] offset:55296
	v_mfma_f32_16x16x32_bf16 v[70:73], v[134:137], v[162:165], v[70:73]
	ds_write_b128 v124, v[26:29] offset:18432
	ds_write_b128 v124, v[30:33] offset:55296
	v_mfma_f32_16x16x32_bf16 v[66:69], v[134:137], v[166:169], v[66:69]
	global_load_dwordx4 v[22:25], v[112:113], off
	v_mfma_f32_16x16x32_bf16 v[62:65], v[138:141], v[146:149], v[62:65]
	global_load_dwordx4 v[6:9], v[110:111], off
	v_mfma_f32_16x16x32_bf16 v[58:61], v[138:141], v[150:153], v[58:61]
	global_load_dwordx4 v[18:21], v[108:109], off
	v_mfma_f32_16x16x32_bf16 v[54:57], v[138:141], v[162:165], v[54:57]
	global_load_dwordx4 v[10:13], v[106:107], off
	v_mfma_f32_16x16x32_bf16 v[50:53], v[138:141], v[166:169], v[50:53]
	global_load_dwordx4 v[14:17], v[104:105], off
	v_mfma_f32_16x16x32_bf16 v[46:49], v[142:145], v[146:149], v[46:49]
	global_load_dwordx4 v[2:5], v[102:103], off
	v_mfma_f32_16x16x32_bf16 v[42:45], v[142:145], v[150:153], v[42:45]
	global_load_dwordx4 v[26:29], v[100:101], off
	v_mfma_f32_16x16x32_bf16 v[38:41], v[142:145], v[162:165], v[38:41]
	global_load_dwordx4 v[30:33], v[98:99], off
	v_mfma_f32_16x16x32_bf16 v[34:37], v[142:145], v[166:169], v[34:37]
	s_waitcnt lgkmcnt(0)
	s_barrier
	ds_read_b128 v[130:133], v161 offset:18432
	v_mfma_f32_16x16x32_bf16 v[94:97], v[222:225], v[238:241], v[94:97]
	ds_read_b128 v[134:137], v161 offset:20736
	v_mfma_f32_16x16x32_bf16 v[90:93], v[222:225], v[242:245], v[90:93]
	ds_read_b128 v[138:141], v161 offset:23040
	v_mfma_f32_16x16x32_bf16 v[86:89], v[222:225], v[246:249], v[86:89]
	ds_read_b128 v[142:145], v161 offset:25344
	v_mfma_f32_16x16x32_bf16 v[82:85], v[222:225], v[250:253], v[82:85]
	ds_read_b128 v[146:149], v129 offset:55296
	v_mfma_f32_16x16x32_bf16 v[78:81], v[226:229], v[238:241], v[78:81]
	ds_read_b128 v[150:153], v129 offset:57600
	v_mfma_f32_16x16x32_bf16 v[74:77], v[226:229], v[242:245], v[74:77]
	ds_read_b128 v[162:165], v129 offset:59904
	v_mfma_f32_16x16x32_bf16 v[70:73], v[226:229], v[246:249], v[70:73]
	ds_read_b128 v[166:169], v129 offset:62208
	v_mfma_f32_16x16x32_bf16 v[66:69], v[226:229], v[250:253], v[66:69]
	v_mfma_f32_16x16x32_bf16 v[62:65], v[230:233], v[238:241], v[62:65]
	v_mfma_f32_16x16x32_bf16 v[58:61], v[230:233], v[242:245], v[58:61]
	v_mfma_f32_16x16x32_bf16 v[54:57], v[230:233], v[246:249], v[54:57]
	v_mfma_f32_16x16x32_bf16 v[50:53], v[230:233], v[250:253], v[50:53]
	v_mfma_f32_16x16x32_bf16 v[46:49], v[234:237], v[238:241], v[46:49]
	v_mfma_f32_16x16x32_bf16 v[42:45], v[234:237], v[242:245], v[42:45]
	v_mfma_f32_16x16x32_bf16 v[38:41], v[234:237], v[246:249], v[38:41]
	v_mfma_f32_16x16x32_bf16 v[34:37], v[234:237], v[250:253], v[34:37]
	s_waitcnt lgkmcnt(0)
	ds_read_b128 v[222:225], v161 offset:18496
	ds_read_b128 v[226:229], v161 offset:20800
	ds_read_b128 v[230:233], v161 offset:23104
	ds_read_b128 v[234:237], v161 offset:25408
	ds_read_b128 v[238:241], v129 offset:55360
	ds_read_b128 v[242:245], v129 offset:57664
	ds_read_b128 v[246:249], v129 offset:59968
	ds_read_b128 v[250:253], v129 offset:62272
	v_mfma_f32_16x16x32_bf16 v[94:97], v[130:133], v[146:149], v[94:97]
	v_mfma_f32_16x16x32_bf16 v[90:93], v[130:133], v[150:153], v[90:93]
	v_mfma_f32_16x16x32_bf16 v[86:89], v[130:133], v[162:165], v[86:89]
	v_mfma_f32_16x16x32_bf16 v[82:85], v[130:133], v[166:169], v[82:85]
	s_waitcnt vmcnt(0)
	ds_write_b128 v122, v[22:25]
	ds_write_b128 v122, v[6:9] offset:36864
	v_mfma_f32_16x16x32_bf16 v[78:81], v[134:137], v[146:149], v[78:81]
	ds_write_b128 v121, v[18:21]
	ds_write_b128 v121, v[10:13] offset:36864
	v_mfma_f32_16x16x32_bf16 v[74:77], v[134:137], v[150:153], v[74:77]
	ds_write_b128 v120, v[14:17]
	ds_write_b128 v120, v[2:5] offset:36864
	v_mfma_f32_16x16x32_bf16 v[70:73], v[134:137], v[162:165], v[70:73]
	ds_write_b128 v124, v[26:29]
	ds_write_b128 v124, v[30:33] offset:36864
	v_mfma_f32_16x16x32_bf16 v[66:69], v[134:137], v[166:169], v[66:69]
	global_load_dwordx4 v[22:25], v[112:113], off offset:128
	v_mfma_f32_16x16x32_bf16 v[62:65], v[138:141], v[146:149], v[62:65]
	global_load_dwordx4 v[6:9], v[110:111], off offset:128
	v_mfma_f32_16x16x32_bf16 v[58:61], v[138:141], v[150:153], v[58:61]
	global_load_dwordx4 v[18:21], v[108:109], off offset:128
	v_mfma_f32_16x16x32_bf16 v[54:57], v[138:141], v[162:165], v[54:57]
	global_load_dwordx4 v[10:13], v[106:107], off offset:128
	v_mfma_f32_16x16x32_bf16 v[50:53], v[138:141], v[166:169], v[50:53]
	global_load_dwordx4 v[14:17], v[104:105], off offset:128
	v_mfma_f32_16x16x32_bf16 v[46:49], v[142:145], v[146:149], v[46:49]
	global_load_dwordx4 v[2:5], v[102:103], off offset:128
	v_mfma_f32_16x16x32_bf16 v[42:45], v[142:145], v[150:153], v[42:45]
	global_load_dwordx4 v[26:29], v[100:101], off offset:128
	v_mfma_f32_16x16x32_bf16 v[38:41], v[142:145], v[162:165], v[38:41]
	global_load_dwordx4 v[30:33], v[98:99], off offset:128
	v_mfma_f32_16x16x32_bf16 v[34:37], v[142:145], v[166:169], v[34:37]
	s_waitcnt lgkmcnt(0)
	s_barrier
; DEV f32x4 mfma16(bf16x8 a, bf16x8 b, f32x4 c) { return __builtin_amdgcn_mfma_f32_16x16x32_bf16(a, b, c, 0, 0, 0); }
; template <int EPI, bool AF32>
; DEV void gemm_tile(const void* Ap, int lda, const u16* Bt, int ldb, int K, int m0, int n0, const Epi& ea, char* smem) {
;     ...
;   for (int kt = 0; kt < nk; kt++) {
;     const int buf = kt & 1;
;     if (kt + 1 < nk) swrite(buf ^ 1);
;     if (kt + 2 < nk) gload(kt + 2);
; #pragma unroll
;     for (int ks = 0; ks < 2; ks++) {
;       bf16x8 a[4], b[4];
; #pragma unroll
;       for (int m = 0; m < 4; m++) a[m] = *(const bf16x8*)(sA + buf * 9216 + (wr * 64 + m * 16 + fr) * 72 + ks * 32 + fq * 8);
; #pragma unroll
;       for (int n = 0; n < 4; n++) b[n] = *(const bf16x8*)(sB + buf * 9216 + (wc * 64 + n * 16 + fr) * 72 + ks * 32 + fq * 8);
;       __builtin_amdgcn_s_setprio(1);
; #pragma unroll
;       for (int m = 0; m < 4; m++)
; #pragma unroll
;         for (int n = 0; n < 4; n++) acc[m][n] = mfma16(a[m], b[n], acc[m][n]);
;       __builtin_amdgcn_s_setprio(0);
;     }
;     __syncthreads();
	ds_read_b128 v[130:133], v161
	v_mfma_f32_16x16x32_bf16 v[94:97], v[222:225], v[238:241], v[94:97]
	ds_read_b128 v[134:137], v161 offset:2304
	v_mfma_f32_16x16x32_bf16 v[90:93], v[222:225], v[242:245], v[90:93]
	ds_read_b128 v[138:141], v161 offset:4608
	v_mfma_f32_16x16x32_bf16 v[86:89], v[222:225], v[246:249], v[86:89]
	ds_read_b128 v[142:145], v161 offset:6912
	v_mfma_f32_16x16x32_bf16 v[82:85], v[222:225], v[250:253], v[82:85]
	ds_read_b128 v[146:149], v129 offset:36864
	v_mfma_f32_16x16x32_bf16 v[78:81], v[226:229], v[238:241], v[78:81]
	ds_read_b128 v[150:153], v129 offset:39168
	v_mfma_f32_16x16x32_bf16 v[74:77], v[226:229], v[242:245], v[74:77]
	ds_read_b128 v[162:165], v129 offset:41472
	v_mfma_f32_16x16x32_bf16 v[70:73], v[226:229], v[246:249], v[70:73]
	ds_read_b128 v[166:169], v129 offset:43776
	v_mfma_f32_16x16x32_bf16 v[66:69], v[226:229], v[250:253], v[66:69]
	v_mfma_f32_16x16x32_bf16 v[62:65], v[230:233], v[238:241], v[62:65]
	v_lshl_add_u64 v[112:113], v[112:113], 0, s[6:7]
	v_mfma_f32_16x16x32_bf16 v[58:61], v[230:233], v[242:245], v[58:61]
	v_lshl_add_u64 v[110:111], v[110:111], 0, s[6:7]
	v_mfma_f32_16x16x32_bf16 v[54:57], v[230:233], v[246:249], v[54:57]
	v_lshl_add_u64 v[108:109], v[108:109], 0, s[6:7]
	v_mfma_f32_16x16x32_bf16 v[50:53], v[230:233], v[250:253], v[50:53]
	v_lshl_add_u64 v[106:107], v[106:107], 0, s[6:7]
	v_mfma_f32_16x16x32_bf16 v[46:49], v[234:237], v[238:241], v[46:49]
	v_lshl_add_u64 v[104:105], v[104:105], 0, s[6:7]
	v_mfma_f32_16x16x32_bf16 v[42:45], v[234:237], v[242:245], v[42:45]
	v_lshl_add_u64 v[102:103], v[102:103], 0, s[6:7]
	v_mfma_f32_16x16x32_bf16 v[38:41], v[234:237], v[246:249], v[38:41]
	v_lshl_add_u64 v[100:101], v[100:101], 0, s[6:7]
	v_mfma_f32_16x16x32_bf16 v[34:37], v[234:237], v[250:253], v[34:37]
	v_lshl_add_u64 v[98:99], v[98:99], 0, s[6:7]
	s_add_i32 s11, s11, 1
	s_cmp_lg_u32 s11, 7
	s_cbranch_scc1 .Lgk0_loop
	s_waitcnt vmcnt(7)
	ds_write_b128 v122, v[22:25] offset:18432
	s_waitcnt vmcnt(6)
	ds_write_b128 v122, v[6:9] offset:55296
	s_waitcnt vmcnt(5)
	ds_write_b128 v121, v[18:21] offset:18432
	s_waitcnt vmcnt(4)
	ds_write_b128 v121, v[10:13] offset:55296
	s_waitcnt vmcnt(3)
	ds_write_b128 v120, v[14:17] offset:18432
	s_waitcnt vmcnt(2)
	ds_write_b128 v120, v[2:5] offset:55296
	s_waitcnt vmcnt(1)
	ds_write_b128 v124, v[26:29] offset:18432
	s_waitcnt vmcnt(0)
	ds_write_b128 v124, v[30:33] offset:55296
	v_lshl_add_u32 v0, v128, 1, v125
	v_lshl_add_u32 v98, v127, 1, v125
	ds_read_b128 v[2:5], v0
	ds_read_b128 v[6:9], v0 offset:2304
	ds_read_b128 v[10:13], v0 offset:4608
	ds_read_b128 v[14:17], v0 offset:6912
	ds_read_b128 v[18:21], v98 offset:36864
	ds_read_b128 v[22:25], v98 offset:39168
	ds_read_b128 v[26:29], v98 offset:41472
	ds_read_b128 v[30:33], v98 offset:43776
	s_setprio 1
	s_waitcnt lgkmcnt(3)
	v_mfma_f32_16x16x32_bf16 v[94:97], v[2:5], v[18:21], v[94:97]
	s_waitcnt lgkmcnt(2)
	v_mfma_f32_16x16x32_bf16 v[90:93], v[2:5], v[22:25], v[90:93]
	s_waitcnt lgkmcnt(1)
	v_mfma_f32_16x16x32_bf16 v[86:89], v[2:5], v[26:29], v[86:89]
	s_waitcnt lgkmcnt(0)
	v_mfma_f32_16x16x32_bf16 v[2:5], v[2:5], v[30:33], v[82:85]
	v_mfma_f32_16x16x32_bf16 v[78:81], v[6:9], v[18:21], v[78:81]
	v_mfma_f32_16x16x32_bf16 v[74:77], v[6:9], v[22:25], v[74:77]
	v_mfma_f32_16x16x32_bf16 v[70:73], v[6:9], v[26:29], v[70:73]
	v_mfma_f32_16x16x32_bf16 v[6:9], v[6:9], v[30:33], v[66:69]
	v_mfma_f32_16x16x32_bf16 v[62:65], v[10:13], v[18:21], v[62:65]
	v_mfma_f32_16x16x32_bf16 v[58:61], v[10:13], v[22:25], v[58:61]
	v_mfma_f32_16x16x32_bf16 v[54:57], v[10:13], v[26:29], v[54:57]
	v_mfma_f32_16x16x32_bf16 v[10:13], v[10:13], v[30:33], v[50:53]
	v_mfma_f32_16x16x32_bf16 v[18:21], v[14:17], v[18:21], v[46:49]
	v_mfma_f32_16x16x32_bf16 v[22:25], v[14:17], v[22:25], v[42:45]
	v_mfma_f32_16x16x32_bf16 v[26:29], v[14:17], v[26:29], v[38:41]
	v_mfma_f32_16x16x32_bf16 v[14:17], v[14:17], v[30:33], v[34:37]
	s_setprio 0
	ds_read_b128 v[30:33], v0 offset:64
	s_nop 0
	ds_read_b128 v[34:37], v0 offset:2368
	ds_read_b128 v[38:41], v0 offset:4672
	ds_read_b128 v[42:45], v0 offset:6976
	ds_read_b128 v[46:49], v98 offset:36928
	ds_read_b128 v[50:53], v98 offset:39232
	ds_read_b128 v[66:69], v98 offset:41536
	ds_read_b128 v[82:85], v98 offset:43840
	s_setprio 1
	s_waitcnt lgkmcnt(3)
	v_mfma_f32_16x16x32_bf16 v[94:97], v[30:33], v[46:49], v[94:97]
	s_waitcnt lgkmcnt(2)
	v_mfma_f32_16x16x32_bf16 v[90:93], v[30:33], v[50:53], v[90:93]
	s_waitcnt lgkmcnt(1)
	v_mfma_f32_16x16x32_bf16 v[86:89], v[30:33], v[66:69], v[86:89]
	s_waitcnt lgkmcnt(0)
	v_mfma_f32_16x16x32_bf16 v[2:5], v[30:33], v[82:85], v[2:5]
	v_mfma_f32_16x16x32_bf16 v[30:33], v[34:37], v[46:49], v[78:81]
	v_mfma_f32_16x16x32_bf16 v[74:77], v[34:37], v[50:53], v[74:77]
	v_mfma_f32_16x16x32_bf16 v[70:73], v[34:37], v[66:69], v[70:73]
	v_mfma_f32_16x16x32_bf16 v[6:9], v[34:37], v[82:85], v[6:9]
	v_mfma_f32_16x16x32_bf16 v[34:37], v[38:41], v[46:49], v[62:65]
	v_mfma_f32_16x16x32_bf16 v[58:61], v[38:41], v[50:53], v[58:61]
	v_mfma_f32_16x16x32_bf16 v[54:57], v[38:41], v[66:69], v[54:57]
	v_mfma_f32_16x16x32_bf16 v[10:13], v[38:41], v[82:85], v[10:13]
	v_mfma_f32_16x16x32_bf16 v[18:21], v[42:45], v[46:49], v[18:21]
	v_mfma_f32_16x16x32_bf16 v[22:25], v[42:45], v[50:53], v[22:25]
	v_mfma_f32_16x16x32_bf16 v[26:29], v[42:45], v[66:69], v[26:29]
	v_mfma_f32_16x16x32_bf16 v[14:17], v[42:45], v[82:85], v[14:17]
	s_setprio 0
	s_barrier
; DEV f32x4 mfma16(bf16x8 a, bf16x8 b, f32x4 c) { return __builtin_amdgcn_mfma_f32_16x16x32_bf16(a, b, c, 0, 0, 0); }
; template <int EPI, bool AF32>
; DEV void gemm_tile(const void* Ap, int lda, const u16* Bt, int ldb, int K, int m0, int n0, const Epi& ea, char* smem) {
;     ...
;   for (int kt = 0; kt < nk; kt++) {
;     const int buf = kt & 1;
;     if (kt + 1 < nk) swrite(buf ^ 1);
;     if (kt + 2 < nk) gload(kt + 2);
; #pragma unroll
;     for (int ks = 0; ks < 2; ks++) {
;       bf16x8 a[4], b[4];
; #pragma unroll
;       for (int m = 0; m < 4; m++) a[m] = *(const bf16x8*)(sA + buf * 9216 + (wr * 64 + m * 16 + fr) * 72 + ks * 32 + fq * 8);
; #pragma unroll
;       for (int n = 0; n < 4; n++) b[n] = *(const bf16x8*)(sB + buf * 9216 + (wc * 64 + n * 16 + fr) * 72 + ks * 32 + fq * 8);
;       __builtin_amdgcn_s_setprio(1);
; #pragma unroll
;       for (int m = 0; m < 4; m++)
; #pragma unroll
;         for (int n = 0; n < 4; n++) acc[m][n] = mfma16(a[m], b[n], acc[m][n]);
;       __builtin_amdgcn_s_setprio(0);
;     }
;     __syncthreads();
;     ...
; #pragma unroll
;   for (int m = 0; m < 4; m++) {
; #pragma unroll
;     for (int j = 0; j < 4; j++) {
;       const int row = m0 + wr * 64 + m * 16 + fq * 4 + j;
;       if (EPI == EP_F32) {
;         float* C = (float*)ea.p0;
; #pragma unroll
;         for (int n = 0; n < 4; n++) C[(size_t)row * ea.ld + cb + n * 16 + fr] = acc[m][n][j];
	ds_read_b128 v[38:41], v0 offset:18432
	ds_read_b128 v[42:45], v0 offset:20736
	ds_read_b128 v[46:49], v0 offset:23040
	ds_read_b128 v[50:53], v0 offset:25344
	ds_read_b128 v[62:65], v98 offset:55296
	ds_read_b128 v[66:69], v98 offset:57600
	ds_read_b128 v[78:81], v98 offset:59904
	ds_read_b128 v[82:85], v98 offset:62208
	s_setprio 1
	s_waitcnt lgkmcnt(3)
	v_mfma_f32_16x16x32_bf16 v[94:97], v[38:41], v[62:65], v[94:97]
	s_waitcnt lgkmcnt(2)
	v_mfma_f32_16x16x32_bf16 v[90:93], v[38:41], v[66:69], v[90:93]
	s_waitcnt lgkmcnt(1)
	v_mfma_f32_16x16x32_bf16 v[86:89], v[38:41], v[78:81], v[86:89]
	s_waitcnt lgkmcnt(0)
	v_mfma_f32_16x16x32_bf16 v[2:5], v[38:41], v[82:85], v[2:5]
	v_mfma_f32_16x16x32_bf16 v[30:33], v[42:45], v[62:65], v[30:33]
	v_mfma_f32_16x16x32_bf16 v[38:41], v[42:45], v[66:69], v[74:77]
	v_mfma_f32_16x16x32_bf16 v[70:73], v[42:45], v[78:81], v[70:73]
	v_mfma_f32_16x16x32_bf16 v[6:9], v[42:45], v[82:85], v[6:9]
	v_mfma_f32_16x16x32_bf16 v[34:37], v[46:49], v[62:65], v[34:37]
	v_mfma_f32_16x16x32_bf16 v[42:45], v[46:49], v[66:69], v[58:61]
	v_mfma_f32_16x16x32_bf16 v[54:57], v[46:49], v[78:81], v[54:57]
	v_mfma_f32_16x16x32_bf16 v[10:13], v[46:49], v[82:85], v[10:13]
	v_mfma_f32_16x16x32_bf16 v[18:21], v[50:53], v[62:65], v[18:21]
	v_mfma_f32_16x16x32_bf16 v[22:25], v[50:53], v[66:69], v[22:25]
	v_mfma_f32_16x16x32_bf16 v[26:29], v[50:53], v[78:81], v[26:29]
	v_mfma_f32_16x16x32_bf16 v[14:17], v[50:53], v[82:85], v[14:17]
	s_setprio 0
	ds_read_b128 v[46:49], v0 offset:18496
	ds_read_b128 v[50:53], v0 offset:20800
	ds_read_b128 v[58:61], v0 offset:23104
	ds_read_b128 v[62:65], v0 offset:25408
	ds_read_b128 v[66:69], v98 offset:55360
	ds_read_b128 v[74:77], v98 offset:57664
	ds_read_b128 v[78:81], v98 offset:59968
	ds_read_b128 v[82:85], v98 offset:62272
	s_setprio 1
	s_waitcnt lgkmcnt(3)
	v_mfma_f32_16x16x32_bf16 v[94:97], v[46:49], v[66:69], v[94:97]
	s_waitcnt lgkmcnt(2)
	v_mfma_f32_16x16x32_bf16 v[90:93], v[46:49], v[74:77], v[90:93]
	s_waitcnt lgkmcnt(1)
	v_mfma_f32_16x16x32_bf16 v[86:89], v[46:49], v[78:81], v[86:89]
	s_waitcnt lgkmcnt(0)
	v_mfma_f32_16x16x32_bf16 v[2:5], v[46:49], v[82:85], v[2:5]
	v_mfma_f32_16x16x32_bf16 v[30:33], v[50:53], v[66:69], v[30:33]
	v_mfma_f32_16x16x32_bf16 v[38:41], v[50:53], v[74:77], v[38:41]
	v_mfma_f32_16x16x32_bf16 v[46:49], v[50:53], v[78:81], v[70:73]
	v_mfma_f32_16x16x32_bf16 v[6:9], v[50:53], v[82:85], v[6:9]
	v_mfma_f32_16x16x32_bf16 v[34:37], v[58:61], v[66:69], v[34:37]
	v_mfma_f32_16x16x32_bf16 v[42:45], v[58:61], v[74:77], v[42:45]
	v_mfma_f32_16x16x32_bf16 v[50:53], v[58:61], v[78:81], v[54:57]
	v_mfma_f32_16x16x32_bf16 v[10:13], v[58:61], v[82:85], v[10:13]
	v_mfma_f32_16x16x32_bf16 v[18:21], v[62:65], v[66:69], v[18:21]
	v_mfma_f32_16x16x32_bf16 v[22:25], v[62:65], v[74:77], v[22:25]
	v_mfma_f32_16x16x32_bf16 v[26:29], v[62:65], v[78:81], v[26:29]
	v_mfma_f32_16x16x32_bf16 v[14:17], v[62:65], v[82:85], v[14:17]
	s_setprio 0
	v_and_or_b32 v54, v114, 64, s10
	v_add_u32_e32 v0, s9, v117
	v_ashrrev_i32_e32 v55, 31, v54
	v_lshl_or_b32 v58, v116, 2, v0
	v_lshl_add_u64 v[54:55], v[54:55], 2, s[0:1]
	v_lshlrev_b32_e32 v0, 2, v115
	v_lshl_add_u64 v[54:55], v[54:55], 0, v[0:1]
	v_mad_i64_i32 v[56:57], s[6:7], v58, s68, v[54:55]
	v_or_b32_e32 v0, 1, v58
	s_barrier
; template <int EPI, bool AF32>
; DEV void gemm_tile(const void* Ap, int lda, const u16* Bt, int ldb, int K, int m0, int n0, const Epi& ea, char* smem) {
;     ...
; #pragma unroll
;   for (int m = 0; m < 4; m++) {
; #pragma unroll
;     for (int j = 0; j < 4; j++) {
;       const int row = m0 + wr * 64 + m * 16 + fq * 4 + j;
;       if (EPI == EP_F32) {
;         float* C = (float*)ea.p0;
; #pragma unroll
;         for (int n = 0; n < 4; n++) C[(size_t)row * ea.ld + cb + n * 16 + fr] = acc[m][n][j];
	global_store_dword v[56:57], v94, off
	global_store_dword v[56:57], v90, off offset:64
	global_store_dword v[56:57], v86, off offset:128
	global_store_dword v[56:57], v2, off offset:192
	v_mad_i64_i32 v[56:57], s[6:7], v0, s68, v[54:55]
	v_or_b32_e32 v0, 2, v58
	global_store_dword v[56:57], v95, off
	global_store_dword v[56:57], v91, off offset:64
	global_store_dword v[56:57], v87, off offset:128
	global_store_dword v[56:57], v3, off offset:192
	v_mad_i64_i32 v[2:3], s[6:7], v0, s68, v[54:55]
	v_or_b32_e32 v0, 3, v58
	global_store_dword v[2:3], v96, off
	global_store_dword v[2:3], v92, off offset:64
	global_store_dword v[2:3], v88, off offset:128
	global_store_dword v[2:3], v4, off offset:192
	v_mad_i64_i32 v[2:3], s[6:7], v0, s68, v[54:55]
	v_or_b32_e32 v0, 16, v58
	global_store_dword v[2:3], v97, off
	global_store_dword v[2:3], v93, off offset:64
	global_store_dword v[2:3], v89, off offset:128
	global_store_dword v[2:3], v5, off offset:192
	v_mad_i64_i32 v[2:3], s[6:7], v0, s68, v[54:55]
	v_or_b32_e32 v0, 17, v58
	global_store_dword v[2:3], v30, off
	global_store_dword v[2:3], v38, off offset:64
	global_store_dword v[2:3], v46, off offset:128
	global_store_dword v[2:3], v6, off offset:192
	v_mad_i64_i32 v[2:3], s[6:7], v0, s68, v[54:55]
	v_or_b32_e32 v0, 18, v58
	global_store_dword v[2:3], v31, off
	global_store_dword v[2:3], v39, off offset:64
	global_store_dword v[2:3], v47, off offset:128
	global_store_dword v[2:3], v7, off offset:192
	v_mad_i64_i32 v[2:3], s[6:7], v0, s68, v[54:55]
	v_or_b32_e32 v0, 19, v58
	global_store_dword v[2:3], v32, off
	global_store_dword v[2:3], v40, off offset:64
	global_store_dword v[2:3], v48, off offset:128
	global_store_dword v[2:3], v8, off offset:192
	v_mad_i64_i32 v[2:3], s[6:7], v0, s68, v[54:55]
	v_or_b32_e32 v0, 32, v58
	global_store_dword v[2:3], v33, off
	global_store_dword v[2:3], v41, off offset:64
	global_store_dword v[2:3], v49, off offset:128
	global_store_dword v[2:3], v9, off offset:192
	v_mad_i64_i32 v[2:3], s[6:7], v0, s68, v[54:55]
	v_or_b32_e32 v0, 33, v58
	global_store_dword v[2:3], v34, off
	global_store_dword v[2:3], v42, off offset:64
	global_store_dword v[2:3], v50, off offset:128
	global_store_dword v[2:3], v10, off offset:192
	v_mad_i64_i32 v[2:3], s[6:7], v0, s68, v[54:55]
	v_or_b32_e32 v0, 34, v58
	global_store_dword v[2:3], v35, off
	global_store_dword v[2:3], v43, off offset:64
	global_store_dword v[2:3], v51, off offset:128
	global_store_dword v[2:3], v11, off offset:192
	v_mad_i64_i32 v[2:3], s[6:7], v0, s68, v[54:55]
	v_or_b32_e32 v0, 35, v58
	global_store_dword v[2:3], v36, off
	global_store_dword v[2:3], v44, off offset:64
	global_store_dword v[2:3], v52, off offset:128
	global_store_dword v[2:3], v12, off offset:192
	v_mad_i64_i32 v[2:3], s[6:7], v0, s68, v[54:55]
	v_or_b32_e32 v0, 48, v58
	global_store_dword v[2:3], v37, off
	global_store_dword v[2:3], v45, off offset:64
	global_store_dword v[2:3], v53, off offset:128
	global_store_dword v[2:3], v13, off offset:192
	v_mad_i64_i32 v[2:3], s[6:7], v0, s68, v[54:55]
	v_or_b32_e32 v0, 49, v58
	global_store_dword v[2:3], v18, off
	global_store_dword v[2:3], v22, off offset:64
	global_store_dword v[2:3], v26, off offset:128
	global_store_dword v[2:3], v14, off offset:192
	v_mad_i64_i32 v[2:3], s[6:7], v0, s68, v[54:55]
	v_or_b32_e32 v0, 50, v58
	global_store_dword v[2:3], v19, off
	global_store_dword v[2:3], v23, off offset:64
	global_store_dword v[2:3], v27, off offset:128
	global_store_dword v[2:3], v15, off offset:192
	v_mad_i64_i32 v[2:3], s[6:7], v0, s68, v[54:55]
	v_or_b32_e32 v0, 51, v58
	global_store_dword v[2:3], v20, off
	global_store_dword v[2:3], v24, off offset:64
	global_store_dword v[2:3], v28, off offset:128
	global_store_dword v[2:3], v16, off offset:192
	v_mad_i64_i32 v[2:3], s[6:7], v0, s68, v[54:55]
	v_readfirstlane_b32 s6, v198
	global_store_dword v[2:3], v21, off
	global_store_dword v[2:3], v25, off offset:64
	global_store_dword v[2:3], v29, off offset:128
	global_store_dword v[2:3], v17, off offset:192
	s_add_i32 s8, s6, s8
	s_cmpk_lt_i32 s8, 0x618
	s_cbranch_scc1 .LBB0_164

; DEV f32x4 mfma16(bf16x8 a, bf16x8 b, f32x4 c) { return __builtin_amdgcn_mfma_f32_16x16x32_bf16(a, b, c, 0, 0, 0); }
; template <int DQ, int DV, int NQT, bool SAMPLE>
; DEV void attn_item(const Params& p, int item, char* smem) {
;     ...
;         float ps = 0.f;
; #pragma unroll
;         for (int a = 0; a < 2; a++)
; #pragma unroll
;           for (int j = 0; j < 4; j++) {
;             const float pv = __builtin_amdgcn_exp2f(s[a][qt][j] * sc - mnew);
;             s[a][qt][j] = pv;
;             ps += pv;
;           }
;         lrun[qt] += ps;
;         pb[qt] = mk8(pack2(s[0][qt][0], s[0][qt][1]), pack2(s[0][qt][2], s[0][qt][3]),
;                      pack2(s[1][qt][0], s[1][qt][1]), pack2(s[1][qt][2], s[1][qt][3]));
;       }
;       __builtin_amdgcn_s_setprio(1);
; #pragma unroll
;       for (int d = 0; d < DV / 16; d++) {
;         const uint2 vlo = *(const uint2*)(sV + (d * 16 + fr) * VS + fq * 4);
;         const uint2 vhi = *(const uint2*)(sV + (d * 16 + fr) * VS + 16 + fq * 4);
;         const bf16x8 vf = mk8(vlo.x, vlo.y, vhi.x, vhi.y);
; #pragma unroll
;         for (int qt = 0; qt < NQT; qt++) o[d][qt] = mfma16(vf, pb[qt], o[d][qt]);
;       }
;       __builtin_amdgcn_s_setprio(0);
.LBB0_462:
	v_fma_f32 v140, v140, s33, -v3
	v_exp_f32_e32 v140, v140
	v_fma_f32 v141, v141, s33, -v3
	v_exp_f32_e32 v141, v141
	v_fma_f32 v142, v142, s33, -v3
	v_exp_f32_e32 v142, v142
	v_fma_f32 v143, v143, s33, -v3
	v_exp_f32_e32 v143, v143
	v_fma_f32 v148, v148, s33, -v3
	v_add_f32_e32 v193, 0, v140
	v_exp_f32_e32 v148, v148
	v_fma_f32 v149, v149, s33, -v3
	v_add_f32_e32 v193, v141, v193
	v_exp_f32_e32 v149, v149
	v_fma_f32 v150, v150, s33, -v3
	v_add_f32_e32 v193, v142, v193
	v_exp_f32_e32 v150, v150
	v_fma_f32 v3, v151, s33, -v3
	v_add_f32_e32 v193, v143, v193
	v_exp_f32_e32 v3, v3
	v_add_f32_e32 v151, v148, v193
	v_add_f32_e32 v151, v149, v151
	v_add_f32_e32 v151, v150, v151
	v_add_f32_e32 v151, v3, v151
	v_cvt_pk_bf16_f32 v140, v140, v141
	v_cvt_pk_bf16_f32 v141, v142, v143
	v_cvt_pk_bf16_f32 v143, v150, v3
	v_fma_f32 v3, v136, s33, -v192
	v_exp_f32_e32 v3, v3
	v_fma_f32 v136, v137, s33, -v192
	v_exp_f32_e32 v136, v136
	v_fma_f32 v137, v138, s33, -v192
	v_exp_f32_e32 v137, v137
	v_fma_f32 v138, v139, s33, -v192
	v_exp_f32_e32 v138, v138
	v_fma_f32 v144, v144, s33, -v192
	v_add_f32_e32 v139, 0, v3
	v_exp_f32_e32 v144, v144
	v_fma_f32 v145, v145, s33, -v192
	v_add_f32_e32 v139, v136, v139
	v_exp_f32_e32 v145, v145
	v_fma_f32 v146, v146, s33, -v192
	v_add_f32_e32 v139, v137, v139
	v_exp_f32_e32 v146, v146
	v_fma_f32 v147, v147, s33, -v192
	v_add_f32_e32 v139, v138, v139
	v_exp_f32_e32 v147, v147
	v_add_f32_e32 v139, v144, v139
	v_add_f32_e32 v139, v145, v139
	v_add_f32_e32 v139, v146, v139
	v_add_f32_e32 v139, v147, v139
	v_add_f32_e32 v0, v151, v0
	v_add_f32_e32 v161, v139, v161
	v_cvt_pk_bf16_f32 v142, v148, v149
	v_cvt_pk_bf16_f32 v136, v3, v136
	v_cvt_pk_bf16_f32 v137, v137, v138
	v_cvt_pk_bf16_f32 v138, v144, v145
	v_cvt_pk_bf16_f32 v139, v146, v147
	s_setprio 1
	s_waitcnt lgkmcnt(0)
	s_nop 1
	v_mfma_f32_16x16x32_bf16 v[64:67], v[222:225], v[140:143], v[64:67]
	v_mfma_f32_16x16x32_bf16 v[32:35], v[222:225], v[136:139], v[32:35]
	v_mfma_f32_16x16x32_bf16 v[60:63], v[226:229], v[140:143], v[60:63]
	v_mfma_f32_16x16x32_bf16 v[28:31], v[226:229], v[136:139], v[28:31]
	v_mfma_f32_16x16x32_bf16 v[56:59], v[230:233], v[140:143], v[56:59]
	v_mfma_f32_16x16x32_bf16 v[24:27], v[230:233], v[136:139], v[24:27]
	v_mfma_f32_16x16x32_bf16 v[52:55], v[234:237], v[140:143], v[52:55]
	v_mfma_f32_16x16x32_bf16 v[20:23], v[234:237], v[136:139], v[20:23]
	v_mfma_f32_16x16x32_bf16 v[48:51], v[238:241], v[140:143], v[48:51]
	v_mfma_f32_16x16x32_bf16 v[16:19], v[238:241], v[136:139], v[16:19]
	v_mfma_f32_16x16x32_bf16 v[44:47], v[242:245], v[140:143], v[44:47]
	v_mfma_f32_16x16x32_bf16 v[12:15], v[242:245], v[136:139], v[12:15]
	v_mfma_f32_16x16x32_bf16 v[40:43], v[246:249], v[140:143], v[40:43]
	v_mfma_f32_16x16x32_bf16 v[8:11], v[246:249], v[136:139], v[8:11]
	v_mfma_f32_16x16x32_bf16 v[36:39], v[250:253], v[140:143], v[36:39]
	v_mfma_f32_16x16x32_bf16 v[4:7], v[250:253], v[136:139], v[4:7]
	s_setprio 0

; DEV f32x4 mfma16(bf16x8 a, bf16x8 b, f32x4 c) { return __builtin_amdgcn_mfma_f32_16x16x32_bf16(a, b, c, 0, 0, 0); }
; template <int DQ, int DV, int NQT, bool SAMPLE>
; DEV void attn_item(const Params& p, int item, char* smem) {
;     ...
;   auto swrite = [&]() {
; #pragma unroll
;     for (int i = 0; i < NKC; i++) {
;       const int c = tid + i * 256, row = c / CPR, col = (c % CPR) * 8;
;       *(u32x4*)(sK + row * KS + col) = rk[i];
;     }
; #pragma unroll
;     for (int i = 0; i < NVC; i++) {
;       const int c = tid + i * 256, row = c >> 2, kc = c & 3;
;       *(u32x4*)(sV + row * VS + kc * 8) = rv[i];
;     }
;   };
;   const float sc = 0.07216878364870322f * 1.4426950408889634f;
;   gload(0);
;   for (int kt = 0; kt < nkt; kt++) {
;     swrite();
;     __syncthreads();
;     if (kt + 1 < nkt) gload(kt + 1);
;     if (kt <= wlim) {
;       f32x4 s[2][NQT];
; #pragma unroll
;       for (int a = 0; a < 2; a++)
; #pragma unroll
;         for (int qt = 0; qt < NQT; qt++) s[a][qt] = (f32x4){0.f, 0.f, 0.f, 0.f};
;       __builtin_amdgcn_s_setprio(1);
; #pragma unroll
;       for (int a = 0; a < 2; a++)
; #pragma unroll
;         for (int ks = 0; ks < NKS; ks++) {
;           const bf16x8 kf = *(const bf16x8*)(sK + (a * 16 + fr) * KS + ks * 32 + fq * 8);
; #pragma unroll
;           for (int qt = 0; qt < NQT; qt++) s[a][qt] = mfma16(kf, qf[qt][ks], s[a][qt]);
;         }
;       __builtin_amdgcn_s_setprio(0);
;       bf16x8 pb[NQT];
; #pragma unroll
;       for (int qt = 0; qt < NQT; qt++) {
;         float mx = -INFINITY;
; #pragma unroll
;         for (int a = 0; a < 2; a++)
; #pragma unroll
;           for (int j = 0; j < 4; j++) mx = fmaxf(mx, s[a][qt][j]);
;         mx = xor16_max(mx);
;         mx = xor32_max(mx);
;         const float mnew = fmaxf(mrun[qt], mx * sc);
;         if (__builtin_amdgcn_ballot_w64(mnew > mrun[qt]) != 0ull) {
;           const float alpha = __builtin_amdgcn_exp2f(mrun[qt] - mnew);
;           lrun[qt] *= alpha;
; #pragma unroll
;           for (int d = 0; d < DV / 16; d++) o[d][qt] *= alpha;
;           mrun[qt] = mnew;
;         }
.LBB0_464:
	s_waitcnt vmcnt(4)
	ds_write_b128 v189, v[116:119]
	s_waitcnt vmcnt(3)
	ds_write_b128 v190, v[120:123]
	s_waitcnt vmcnt(2)
	ds_write_b128 v191, v[124:127]
	s_waitcnt vmcnt(1)
	ds_write_b128 v164, v[132:135] offset:12800
	s_waitcnt vmcnt(0)
	ds_write_b128 v166, v[128:131] offset:12800
	v_lshl_add_u64 v[116:117], s[8:9], 0, v[182:183]
	v_lshl_add_u64 v[118:119], s[8:9], 0, v[180:181]
	v_lshl_add_u64 v[120:121], s[8:9], 0, v[178:179]
	v_lshl_add_u64 v[122:123], s[8:9], 0, v[176:177]
	v_lshl_add_u64 v[124:125], s[8:9], 0, v[174:175]
	v_lshl_add_u64 v[126:127], s[8:9], 0, v[172:173]
	v_cndmask_b32_e64 v117, v119, v117, s[2:3]
	v_cndmask_b32_e64 v116, v118, v116, s[2:3]
	v_cndmask_b32_e64 v121, v123, v121, s[4:5]
	v_cndmask_b32_e64 v120, v122, v120, s[4:5]
	v_cndmask_b32_e64 v125, v127, v125, s[6:7]
	v_cndmask_b32_e64 v124, v126, v124, s[6:7]
	v_lshl_add_u64 v[128:129], s[8:9], 0, v[170:171]
	v_lshl_add_u64 v[130:131], s[8:9], 0, v[168:169]
	s_waitcnt lgkmcnt(0)
	s_barrier
	global_load_dwordx4 v[116:119], v[116:117], off
	v_cmp_le_i32_e32 vcc, s1, v188
	global_load_dwordx4 v[120:123], v[120:121], off
	s_nop 0
	global_load_dwordx4 v[124:127], v[124:125], off
	s_nop 0
	global_load_dwordx4 v[132:135], v[128:129], off
	s_nop 0
	global_load_dwordx4 v[128:131], v[130:131], off
	s_and_saveexec_b64 s[10:11], vcc
	s_cbranch_execz .LBB0_463
	s_setprio 1
	v_add_u32_e32 v3, v186, v187
	ds_read_b128 v[222:225], v3
	ds_read_b128 v[226:229], v3 offset:6400
	ds_read_b128 v[230:233], v3 offset:64
	ds_read_b128 v[234:237], v3 offset:6464
	ds_read_b128 v[238:241], v3 offset:128
	ds_read_b128 v[242:245], v3 offset:6528
	ds_read_b128 v[246:249], v3 offset:192
	ds_read_b128 v[250:253], v3 offset:6592
	ds_read_b128 v[192:195], v3 offset:256
	s_waitcnt lgkmcnt(8)
	v_mfma_f32_16x16x32_bf16 v[140:143], v[222:225], v[108:111], 0
	v_mfma_f32_16x16x32_bf16 v[136:139], v[222:225], v[112:115], 0
	s_waitcnt lgkmcnt(7)
	v_mfma_f32_16x16x32_bf16 v[148:151], v[226:229], v[108:111], 0
	v_mfma_f32_16x16x32_bf16 v[144:147], v[226:229], v[112:115], 0
	ds_read_b128 v[222:225], v3 offset:6656
	s_waitcnt lgkmcnt(7)
	v_mfma_f32_16x16x32_bf16 v[140:143], v[230:233], v[96:99], v[140:143]
	v_mfma_f32_16x16x32_bf16 v[136:139], v[230:233], v[104:107], v[136:139]
	ds_read_b128 v[226:229], v3 offset:320
	s_waitcnt lgkmcnt(7)
	v_mfma_f32_16x16x32_bf16 v[148:151], v[234:237], v[96:99], v[148:151]
	v_mfma_f32_16x16x32_bf16 v[144:147], v[234:237], v[104:107], v[144:147]
	ds_read_b128 v[230:233], v3 offset:6720
	s_waitcnt lgkmcnt(7)
	v_mfma_f32_16x16x32_bf16 v[140:143], v[238:241], v[92:95], v[140:143]
	v_mfma_f32_16x16x32_bf16 v[136:139], v[238:241], v[100:103], v[136:139]
	s_waitcnt lgkmcnt(6)
	v_mfma_f32_16x16x32_bf16 v[148:151], v[242:245], v[92:95], v[148:151]
	v_mfma_f32_16x16x32_bf16 v[144:147], v[242:245], v[100:103], v[144:147]
	s_waitcnt lgkmcnt(5)
	v_mfma_f32_16x16x32_bf16 v[140:143], v[246:249], v[80:83], v[140:143]
	v_mfma_f32_16x16x32_bf16 v[136:139], v[246:249], v[88:91], v[136:139]
	s_waitcnt lgkmcnt(4)
	v_mfma_f32_16x16x32_bf16 v[148:151], v[250:253], v[80:83], v[148:151]
	v_mfma_f32_16x16x32_bf16 v[144:147], v[250:253], v[88:91], v[144:147]
	s_waitcnt lgkmcnt(3)
	v_mfma_f32_16x16x32_bf16 v[140:143], v[192:195], v[76:79], v[140:143]
	v_mfma_f32_16x16x32_bf16 v[136:139], v[192:195], v[84:87], v[136:139]
	s_waitcnt lgkmcnt(2)
	v_mfma_f32_16x16x32_bf16 v[148:151], v[222:225], v[76:79], v[148:151]
	v_mfma_f32_16x16x32_bf16 v[144:147], v[222:225], v[84:87], v[144:147]
	s_waitcnt lgkmcnt(1)
	v_mfma_f32_16x16x32_bf16 v[140:143], v[226:229], v[68:71], v[140:143]
	v_mfma_f32_16x16x32_bf16 v[136:139], v[226:229], v[72:75], v[136:139]
	s_waitcnt lgkmcnt(0)
	v_mfma_f32_16x16x32_bf16 v[148:151], v[230:233], v[68:71], v[148:151]
	v_mfma_f32_16x16x32_bf16 v[144:147], v[230:233], v[72:75], v[144:147]
	v_add_u32_e32 v3, 0x3000, v167
	ds_read2_b64 v[222:225], v3 offset0:64 offset1:68
	v_add_u32_e32 v3, 0x3000, v184
	ds_read2_b64 v[226:229], v3 offset0:64 offset1:68
	v_add_u32_e32 v3, 0x3800, v167
	ds_read2_b64 v[230:233], v3 offset0:128 offset1:132
	v_add_u32_e32 v3, 0x4000, v167
	ds_read2_b64 v[234:237], v3 offset0:32 offset1:36
	ds_read2_b64 v[238:241], v3 offset0:192 offset1:196
	v_add_u32_e32 v3, 0x4800, v167
	ds_read2_b64 v[242:245], v3 offset0:96 offset1:100
	v_add_u32_e32 v3, 0x5000, v167
	ds_read2_b64 v[246:249], v3 offset1:4
	ds_read2_b64 v[250:253], v3 offset0:160 offset1:164
	s_setprio 0
	v_max3_f32 v3, v140, s29, v141
	v_max3_f32 v3, v3, v142, v143
	s_nop 3
	v_max3_f32 v3, v3, v148, v149
	v_max3_f32 v3, v3, v150, v151
	v_mov_b32_e32 v192, v3
	s_nop 1
	v_permlane16_swap_b32_e32 v3, v192
	v_max_f32_e32 v192, v192, v192
	v_max_f32_e32 v3, v3, v3
	v_max_f32_e32 v3, v3, v192
	v_mov_b32_e32 v192, v3
	s_nop 1
	v_permlane32_swap_b32_e32 v3, v192
	v_max_f32_e32 v192, v192, v192
	v_max_f32_e32 v3, v3, v3
	v_max_f32_e32 v3, v3, v192
	v_mul_f32_e32 v3, 0x3dd53b94, v3
	v_max_f32_e32 v192, v2, v2
	v_max_f32_e32 v3, v192, v3
	v_cmp_gt_f32_e32 vcc, v3, v2
	s_cbranch_vccz .LBB0_467
	v_sub_f32_e32 v2, v2, v3
	v_exp_f32_e32 v2, v2
	s_nop 0
	v_mul_f32_e32 v0, v0, v2
	v_pk_mul_f32 v[66:67], v[66:67], v[2:3] op_sel_hi:[1,0]
	v_pk_mul_f32 v[64:65], v[64:65], v[2:3] op_sel_hi:[1,0]
	v_pk_mul_f32 v[62:63], v[62:63], v[2:3] op_sel_hi:[1,0]
	v_pk_mul_f32 v[60:61], v[60:61], v[2:3] op_sel_hi:[1,0]
	v_pk_mul_f32 v[58:59], v[58:59], v[2:3] op_sel_hi:[1,0]
	v_pk_mul_f32 v[56:57], v[56:57], v[2:3] op_sel_hi:[1,0]
	v_pk_mul_f32 v[54:55], v[54:55], v[2:3] op_sel_hi:[1,0]
	v_pk_mul_f32 v[52:53], v[52:53], v[2:3] op_sel_hi:[1,0]
	v_pk_mul_f32 v[50:51], v[50:51], v[2:3] op_sel_hi:[1,0]
	v_pk_mul_f32 v[48:49], v[48:49], v[2:3] op_sel_hi:[1,0]
	v_pk_mul_f32 v[46:47], v[46:47], v[2:3] op_sel_hi:[1,0]
	v_pk_mul_f32 v[44:45], v[44:45], v[2:3] op_sel_hi:[1,0]
	v_pk_mul_f32 v[42:43], v[42:43], v[2:3] op_sel_hi:[1,0]
	v_pk_mul_f32 v[40:41], v[40:41], v[2:3] op_sel_hi:[1,0]
	v_pk_mul_f32 v[38:39], v[38:39], v[2:3] op_sel_hi:[1,0]
	v_pk_mul_f32 v[36:37], v[36:37], v[2:3] op_sel_hi:[1,0]
	v_mov_b32_e32 v2, v3

; template <int EPI, bool AF32>
; DEV void gemm_tile(const void* Ap, int lda, const u16* Bt, int ldb, int K, int m0, int n0, const Epi& ea, char* smem) {
;     ...
;   auto gload = [&](int kt) {
;     const int k0 = kt << 6;
; #pragma unroll
;     for (int i = 0; i < 4; i++) {
;       const int c = tid + i * 256, row = c >> 3, kc = c & 7;
;       if (AF32) {
;         const float* pa = (const float*)Ap + (size_t)(m0 + row) * lda + k0 + kc * 8;
;         rfa[2 * i] = *(const f32x4*)pa;
;         rfa[2 * i + 1] = *(const f32x4*)(pa + 4);
;       } else {
;         ra[i] = *(const u32x4*)((const u16*)Ap + (size_t)(m0 + row) * lda + k0 + kc * 8);
;       }
;       rb[i] = *(const u32x4*)(Bt + (size_t)(n0 + row) * ldb + k0 + kc * 8);
;     }
;   };
;   auto swrite = [&](int buf) {
; #pragma unroll
;     for (int i = 0; i < 4; i++) {
;       const int c = tid + i * 256, row = c >> 3, kc = c & 7;
;       u32x4 va;
;       if (AF32) {
;         va = (u32x4){pack2(rfa[2 * i][0], rfa[2 * i][1]), pack2(rfa[2 * i][2], rfa[2 * i][3]),
;                      pack2(rfa[2 * i + 1][0], rfa[2 * i + 1][1]), pack2(rfa[2 * i + 1][2], rfa[2 * i + 1][3])};
;       } else {
;         va = ra[i];
;       }
;       *(u32x4*)(sA + buf * 9216 + row * 72 + kc * 8) = va;
;       *(u32x4*)(sB + buf * 9216 + row * 72 + kc * 8) = rb[i];
;     }
;   };
;   gload(0);
;   swrite(0);
;   if (nk > 1) gload(1);
;   __syncthreads();
.LBB0_547:
	s_ashr_i32 s0, s26, 31
	s_lshr_b32 s0, s0, 22
	s_add_i32 s0, s26, s0
	s_ashr_i32 s1, s0, 10
	s_and_b32 s0, s0, 0xfffffc00
	s_lshl_b32 s3, s1, 5
	s_sub_i32 s2, s26, s0
	s_sub_i32 s0, 0x104, s3
	s_min_u32 s4, s0, 32
	v_cvt_f32_ubyte0_e32 v2, s4
	v_cvt_f32_i32_e32 v0, s2
	v_rcp_iflag_f32_e32 v3, v2
	s_ashr_i32 s0, s2, 30
	s_or_b32 s5, s0, 1
	s_waitcnt vmcnt(12)
	v_mov_b32_e32 v114, v157
	v_mul_f32_e32 v3, v0, v3
	v_trunc_f32_e32 v3, v3
	v_fma_f32 v0, -v3, v2, v0
	v_cvt_i32_f32_e32 v3, v3
	v_cmp_ge_f32_e64 s[0:1], |v0|, v2
	s_and_b64 s[0:1], s[0:1], exec
	s_cselect_b32 s0, s5, 0
	v_readfirstlane_b32 s1, v3
	s_add_i32 s0, s1, s0
	s_sext_i32_i16 s29, s0
	s_mul_i32 s0, s0, s4
	s_sub_i32 s0, s2, s0
	s_sext_i32_i16 s0, s0
	s_add_i32 s3, s3, s0
	s_lshl_b32 s2, s3, 7
	s_lshl_b32 s3, s29, 7
	v_ashrrev_i32_e32 v8, 3, v114
	v_add_u32_e32 v2, s2, v8
	v_ashrrev_i32_e32 v3, 31, v2
	v_lshlrev_b32_e32 v0, 3, v114
	v_add_u32_e32 v4, 0x100, v114
	v_lshlrev_b64 v[58:59], 11, v[2:3]
	v_and_b32_e32 v0, 56, v0
	v_ashrrev_i32_e32 v9, 3, v4
	v_lshl_add_u64 v[2:3], s[60:61], 0, v[58:59]
	v_lshlrev_b32_e32 v0, 1, v0
	v_add_u32_e32 v4, s2, v9
	v_add_u32_e32 v6, 0x200, v114
	v_lshl_add_u64 v[14:15], v[2:3], 0, v[0:1]
	v_add_u32_e32 v2, s3, v8
	v_ashrrev_i32_e32 v5, 31, v4
	v_ashrrev_i32_e32 v10, 3, v6
	v_ashrrev_i32_e32 v3, 31, v2
	v_lshlrev_b64 v[62:63], 11, v[4:5]
	v_add_u32_e32 v6, s2, v10
	v_lshlrev_b64 v[60:61], 11, v[2:3]
	v_lshl_add_u64 v[4:5], s[60:61], 0, v[62:63]
	v_ashrrev_i32_e32 v7, 31, v6
	v_lshl_add_u64 v[2:3], s[12:13], 0, v[60:61]
	v_lshl_add_u64 v[16:17], v[4:5], 0, v[0:1]
	v_add_u32_e32 v4, s3, v9
	v_lshlrev_b64 v[66:67], 11, v[6:7]
	v_lshl_add_u64 v[2:3], v[2:3], 0, v[0:1]
	v_ashrrev_i32_e32 v5, 31, v4
	v_lshl_add_u64 v[6:7], s[60:61], 0, v[66:67]
	global_load_dwordx4 v[30:33], v[2:3], off
	v_lshlrev_b64 v[64:65], 11, v[4:5]
	v_lshl_add_u64 v[68:69], v[6:7], 0, v[0:1]
	v_add_u32_e32 v6, s3, v10
	global_load_dwordx4 v[26:29], v[14:15], off
	global_load_dwordx4 v[34:37], v[16:17], off
	v_lshl_add_u64 v[4:5], s[12:13], 0, v[64:65]
	v_ashrrev_i32_e32 v7, 31, v6
	v_lshl_add_u64 v[4:5], v[4:5], 0, v[0:1]
	v_lshlrev_b64 v[70:71], 11, v[6:7]
	global_load_dwordx4 v[38:41], v[4:5], off
	v_lshl_add_u64 v[6:7], s[12:13], 0, v[70:71]
	global_load_dwordx4 v[42:45], v[68:69], off
	v_lshl_add_u64 v[18:19], v[6:7], 0, v[0:1]
	global_load_dwordx4 v[46:49], v[18:19], off
	v_add_u32_e32 v6, 0x300, v114
	v_ashrrev_i32_e32 v80, 3, v6
	v_add_u32_e32 v6, s2, v80
	v_ashrrev_i32_e32 v7, 31, v6
	v_lshlrev_b64 v[72:73], 11, v[6:7]
	v_lshl_add_u64 v[6:7], s[60:61], 0, v[72:73]
	v_lshl_add_u64 v[74:75], v[6:7], 0, v[0:1]
	v_add_u32_e32 v6, s3, v80
	v_ashrrev_i32_e32 v7, 31, v6
	v_lshlrev_b64 v[76:77], 11, v[6:7]
	v_lshl_add_u64 v[6:7], s[12:13], 0, v[76:77]
	v_lshl_add_u64 v[78:79], v[6:7], 0, v[0:1]
	global_load_dwordx4 v[50:53], v[74:75], off
	global_load_dwordx4 v[54:57], v[78:79], off
	s_waitcnt vmcnt(19)
	v_mul_lo_u32 v118, v8, s71
	v_mul_lo_u32 v119, v9, s71
	s_waitcnt vmcnt(18)
	v_mul_lo_u32 v123, v10, s71
	global_load_dwordx4 v[6:9], v[2:3], off offset:128
	global_load_dwordx4 v[10:13], v[4:5], off offset:128
	s_nop 0
	global_load_dwordx4 v[2:5], v[18:19], off offset:128
	global_load_dwordx4 v[22:25], v[14:15], off offset:128
	s_nop 0
	global_load_dwordx4 v[18:21], v[16:17], off offset:128
	s_nop 0
	global_load_dwordx4 v[14:17], v[68:69], off offset:128
	v_bfe_u32 v161, v157, 3, 4
	v_add_u32_e32 v161, 4, v161
	v_lshlrev_b32_e32 v161, 1, v161
	v_and_b32_e32 v161, 16, v161
	v_xor_b32_e32 v129, v0, v161
	v_lshl_add_u32 v122, v118, 1, v129
	v_lshl_add_u32 v121, v119, 1, v129
	v_lshl_add_u32 v120, v123, 1, v129
	v_and_b32_e32 v116, 15, v114
	s_waitcnt vmcnt(23)
	v_mul_lo_u32 v126, v80, s71
	v_bfe_u32 v115, v114, 4, 2
	v_lshl_add_u32 v124, v126, 1, v129
	s_mov_b32 s4, 0
	v_lshlrev_b32_e32 v125, 4, v115
	v_and_b32_e32 v161, 15, v157
	v_add_u32_e32 v161, 4, v161
	v_lshlrev_b32_e32 v161, 1, v161
	v_and_b32_e32 v161, 16, v161
	v_xor_b32_e32 v125, v125, v161
	s_mov_b64 s[0:1], 0
	s_waitcnt vmcnt(13)
	ds_write_b128 v122, v[30:33] offset:36864
	s_waitcnt vmcnt(12)
	ds_write_b128 v122, v[26:29]
	s_waitcnt vmcnt(11)
	ds_write_b128 v121, v[34:37]
	s_waitcnt vmcnt(10)
	ds_write_b128 v121, v[38:41] offset:36864
	s_waitcnt vmcnt(9)
	ds_write_b128 v120, v[42:45]
	s_waitcnt vmcnt(8)
	ds_write_b128 v120, v[46:49] offset:36864
	global_load_dwordx4 v[26:29], v[74:75], off offset:128
	global_load_dwordx4 v[30:33], v[78:79], off offset:128
	v_ashrrev_i32_e32 v34, 1, v114
	v_and_b32_e32 v117, 0xffffffc0, v34
	v_or_b32_e32 v34, v117, v116
	v_mul_lo_u32 v128, v34, s71
	v_lshlrev_b32_e32 v34, 4, v114
	v_and_b32_e32 v34, 0x70, v34
	v_and_b32_e32 v35, 0x4f, v114
	v_or_b32_e32 v76, v76, v34
	v_or_b32_e32 v72, v72, v34
	v_or_b32_e32 v70, v70, v34
	v_or_b32_e32 v66, v66, v34
	v_or_b32_e32 v64, v64, v34
	v_or_b32_e32 v62, v62, v34
	v_or_b32_e32 v60, v60, v34
	v_or_b32_e32 v58, v58, v34
	v_mov_b32_e32 v34, 0
	s_waitcnt vmcnt(9)
	ds_write_b128 v124, v[50:53]
	s_waitcnt vmcnt(8)
	ds_write_b128 v124, v[54:57] offset:36864
	v_mul_u32_u24_e32 v127, 0x48, v35
	v_lshl_add_u64 v[98:99], s[20:21], 0, v[76:77]
	v_lshl_add_u64 v[100:101], s[66:67], 0, v[72:73]
	v_lshl_add_u64 v[102:103], s[20:21], 0, v[70:71]
	v_lshl_add_u64 v[104:105], s[66:67], 0, v[66:67]
	v_lshl_add_u64 v[106:107], s[20:21], 0, v[64:65]
	v_lshl_add_u64 v[108:109], s[66:67], 0, v[62:63]
	v_lshl_add_u64 v[110:111], s[20:21], 0, v[60:61]
	v_lshl_add_u64 v[112:113], s[66:67], 0, v[58:59]
	v_mov_b32_e32 v35, v34
	v_mov_b32_e32 v36, v34
	v_mov_b32_e32 v37, v34
	v_mov_b32_e32 v38, v34
	v_mov_b32_e32 v39, v34
	v_mov_b32_e32 v40, v34
	v_mov_b32_e32 v41, v34
	v_mov_b32_e32 v42, v34
	v_mov_b32_e32 v43, v34
	v_mov_b32_e32 v44, v34
	v_mov_b32_e32 v45, v34
	v_mov_b32_e32 v46, v34
	v_mov_b32_e32 v47, v34
	v_mov_b32_e32 v48, v34
	v_mov_b32_e32 v49, v34
	v_mov_b32_e32 v50, v34
	v_mov_b32_e32 v51, v34
	v_mov_b32_e32 v52, v34
	v_mov_b32_e32 v53, v34
	v_mov_b32_e32 v54, v34
	v_mov_b32_e32 v55, v34
	v_mov_b32_e32 v56, v34
	v_mov_b32_e32 v57, v34
	v_mov_b32_e32 v58, v34
	v_mov_b32_e32 v59, v34
	v_mov_b32_e32 v60, v34
	v_mov_b32_e32 v61, v34
	v_mov_b32_e32 v62, v34
	v_mov_b32_e32 v63, v34
	v_mov_b32_e32 v64, v34
	v_mov_b32_e32 v65, v34
	v_mov_b32_e32 v66, v34
	v_mov_b32_e32 v67, v34
	v_mov_b32_e32 v68, v34
	v_mov_b32_e32 v69, v34
	v_mov_b32_e32 v70, v34
	v_mov_b32_e32 v71, v34
	v_mov_b32_e32 v72, v34
	v_mov_b32_e32 v73, v34
	v_mov_b32_e32 v74, v34
	v_mov_b32_e32 v75, v34
	v_mov_b32_e32 v76, v34
	v_mov_b32_e32 v77, v34
	v_mov_b32_e32 v78, v34
	v_mov_b32_e32 v79, v34
	v_mov_b32_e32 v80, v34
	v_mov_b32_e32 v81, v34
	v_mov_b32_e32 v82, v34
	v_mov_b32_e32 v83, v34
	v_mov_b32_e32 v84, v34
	v_mov_b32_e32 v85, v34
	v_mov_b32_e32 v86, v34
	v_mov_b32_e32 v87, v34
	v_mov_b32_e32 v88, v34
	v_mov_b32_e32 v89, v34
	v_mov_b32_e32 v90, v34
	v_mov_b32_e32 v91, v34
	v_mov_b32_e32 v92, v34
	v_mov_b32_e32 v93, v34
	v_mov_b32_e32 v94, v34
	v_mov_b32_e32 v95, v34
	v_mov_b32_e32 v96, v34
	v_mov_b32_e32 v97, v34
	s_waitcnt lgkmcnt(0)
	s_barrier
; DEV f32x4 mfma16(bf16x8 a, bf16x8 b, f32x4 c) { return __builtin_amdgcn_mfma_f32_16x16x32_bf16(a, b, c, 0, 0, 0); }
; template <int EPI, bool AF32>
; DEV void gemm_tile(const void* Ap, int lda, const u16* Bt, int ldb, int K, int m0, int n0, const Epi& ea, char* smem) {
;     ...
;   for (int kt = 0; kt < nk; kt++) {
;     const int buf = kt & 1;
;     if (kt + 1 < nk) swrite(buf ^ 1);
;     if (kt + 2 < nk) gload(kt + 2);
; #pragma unroll
;     for (int ks = 0; ks < 2; ks++) {
;       bf16x8 a[4], b[4];
; #pragma unroll
;       for (int m = 0; m < 4; m++) a[m] = *(const bf16x8*)(sA + buf * 9216 + (wr * 64 + m * 16 + fr) * 72 + ks * 32 + fq * 8);
; #pragma unroll
;       for (int n = 0; n < 4; n++) b[n] = *(const bf16x8*)(sB + buf * 9216 + (wc * 64 + n * 16 + fr) * 72 + ks * 32 + fq * 8);
;       __builtin_amdgcn_s_setprio(1);
; #pragma unroll
;       for (int m = 0; m < 4; m++)
; #pragma unroll
;         for (int n = 0; n < 4; n++) acc[m][n] = mfma16(a[m], b[n], acc[m][n]);
;       __builtin_amdgcn_s_setprio(0);
;     }
;     __syncthreads();
	v_lshl_add_u32 v161, v128, 1, v125
	v_lshl_add_u32 v129, v127, 1, v125
	s_mov_b32 s4, 0
	s_mov_b64 s[0:1], 0x100
	ds_read_b128 v[130:133], v161
	ds_read_b128 v[134:137], v161 offset:2304
	ds_read_b128 v[138:141], v161 offset:4608
	ds_read_b128 v[142:145], v161 offset:6912
	ds_read_b128 v[146:149], v129 offset:36864
	ds_read_b128 v[150:153], v129 offset:39168
	ds_read_b128 v[162:165], v129 offset:41472
	ds_read_b128 v[166:169], v129 offset:43776
.Lgk1_loop:
	s_waitcnt lgkmcnt(0)
	ds_read_b128 v[222:225], v161 offset:64
	ds_read_b128 v[226:229], v161 offset:2368
	ds_read_b128 v[230:233], v161 offset:4672
	ds_read_b128 v[234:237], v161 offset:6976
	ds_read_b128 v[238:241], v129 offset:36928
	ds_read_b128 v[242:245], v129 offset:39232
	ds_read_b128 v[246:249], v129 offset:41536
	ds_read_b128 v[250:253], v129 offset:43840
	v_mfma_f32_16x16x32_bf16 v[94:97], v[130:133], v[146:149], v[94:97]
	v_mfma_f32_16x16x32_bf16 v[90:93], v[130:133], v[150:153], v[90:93]
	v_mfma_f32_16x16x32_bf16 v[86:89], v[130:133], v[162:165], v[86:89]
	v_mfma_f32_16x16x32_bf16 v[82:85], v[130:133], v[166:169], v[82:85]
	s_waitcnt vmcnt(0)
	ds_write_b128 v122, v[22:25] offset:18432
	ds_write_b128 v122, v[6:9] offset:55296
	v_mfma_f32_16x16x32_bf16 v[78:81], v[134:137], v[146:149], v[78:81]
	ds_write_b128 v121, v[18:21] offset:18432
	ds_write_b128 v121, v[10:13] offset:55296
	v_mfma_f32_16x16x32_bf16 v[74:77], v[134:137], v[150:153], v[74:77]
	ds_write_b128 v120, v[14:17] offset:18432
	ds_write_b128 v120, v[2:5] offset:55296
	v_mfma_f32_16x16x32_bf16 v[70:73], v[134:137], v[162:165], v[70:73]
	ds_write_b128 v124, v[26:29] offset:18432
	ds_write_b128 v124, v[30:33] offset:55296
	v_mfma_f32_16x16x32_bf16 v[66:69], v[134:137], v[166:169], v[66:69]
	global_load_dwordx4 v[22:25], v[112:113], off
	v_mfma_f32_16x16x32_bf16 v[62:65], v[138:141], v[146:149], v[62:65]
	global_load_dwordx4 v[6:9], v[110:111], off
	v_mfma_f32_16x16x32_bf16 v[58:61], v[138:141], v[150:153], v[58:61]
	global_load_dwordx4 v[18:21], v[108:109], off
	v_mfma_f32_16x16x32_bf16 v[54:57], v[138:141], v[162:165], v[54:57]
	global_load_dwordx4 v[10:13], v[106:107], off
	v_mfma_f32_16x16x32_bf16 v[50:53], v[138:141], v[166:169], v[50:53]
	global_load_dwordx4 v[14:17], v[104:105], off
	v_mfma_f32_16x16x32_bf16 v[46:49], v[142:145], v[146:149], v[46:49]
	global_load_dwordx4 v[2:5], v[102:103], off
	v_mfma_f32_16x16x32_bf16 v[42:45], v[142:145], v[150:153], v[42:45]
	global_load_dwordx4 v[26:29], v[100:101], off
	v_mfma_f32_16x16x32_bf16 v[38:41], v[142:145], v[162:165], v[38:41]
	global_load_dwordx4 v[30:33], v[98:99], off
	v_mfma_f32_16x16x32_bf16 v[34:37], v[142:145], v[166:169], v[34:37]
	s_waitcnt lgkmcnt(0)
	s_barrier
	ds_read_b128 v[130:133], v161 offset:18432
	v_mfma_f32_16x16x32_bf16 v[94:97], v[222:225], v[238:241], v[94:97]
	ds_read_b128 v[134:137], v161 offset:20736
	v_mfma_f32_16x16x32_bf16 v[90:93], v[222:225], v[242:245], v[90:93]
	ds_read_b128 v[138:141], v161 offset:23040
	v_mfma_f32_16x16x32_bf16 v[86:89], v[222:225], v[246:249], v[86:89]
	ds_read_b128 v[142:145], v161 offset:25344
	v_mfma_f32_16x16x32_bf16 v[82:85], v[222:225], v[250:253], v[82:85]
	ds_read_b128 v[146:149], v129 offset:55296
	v_mfma_f32_16x16x32_bf16 v[78:81], v[226:229], v[238:241], v[78:81]
	ds_read_b128 v[150:153], v129 offset:57600
	v_mfma_f32_16x16x32_bf16 v[74:77], v[226:229], v[242:245], v[74:77]
	ds_read_b128 v[162:165], v129 offset:59904
	v_mfma_f32_16x16x32_bf16 v[70:73], v[226:229], v[246:249], v[70:73]
	ds_read_b128 v[166:169], v129 offset:62208
	v_mfma_f32_16x16x32_bf16 v[66:69], v[226:229], v[250:253], v[66:69]
	v_mfma_f32_16x16x32_bf16 v[62:65], v[230:233], v[238:241], v[62:65]
	v_mfma_f32_16x16x32_bf16 v[58:61], v[230:233], v[242:245], v[58:61]
	v_mfma_f32_16x16x32_bf16 v[54:57], v[230:233], v[246:249], v[54:57]
	v_mfma_f32_16x16x32_bf16 v[50:53], v[230:233], v[250:253], v[50:53]
	v_mfma_f32_16x16x32_bf16 v[46:49], v[234:237], v[238:241], v[46:49]
	v_mfma_f32_16x16x32_bf16 v[42:45], v[234:237], v[242:245], v[42:45]
	v_mfma_f32_16x16x32_bf16 v[38:41], v[234:237], v[246:249], v[38:41]
	v_mfma_f32_16x16x32_bf16 v[34:37], v[234:237], v[250:253], v[34:37]
	s_waitcnt lgkmcnt(0)
	ds_read_b128 v[222:225], v161 offset:18496
	ds_read_b128 v[226:229], v161 offset:20800
	ds_read_b128 v[230:233], v161 offset:23104
	ds_read_b128 v[234:237], v161 offset:25408
	ds_read_b128 v[238:241], v129 offset:55360
	ds_read_b128 v[242:245], v129 offset:57664
	ds_read_b128 v[246:249], v129 offset:59968
	ds_read_b128 v[250:253], v129 offset:62272
	v_mfma_f32_16x16x32_bf16 v[94:97], v[130:133], v[146:149], v[94:97]
	v_mfma_f32_16x16x32_bf16 v[90:93], v[130:133], v[150:153], v[90:93]
	v_mfma_f32_16x16x32_bf16 v[86:89], v[130:133], v[162:165], v[86:89]
	v_mfma_f32_16x16x32_bf16 v[82:85], v[130:133], v[166:169], v[82:85]
	s_waitcnt vmcnt(0)
	ds_write_b128 v122, v[22:25]
	ds_write_b128 v122, v[6:9] offset:36864
	v_mfma_f32_16x16x32_bf16 v[78:81], v[134:137], v[146:149], v[78:81]
	ds_write_b128 v121, v[18:21]
	ds_write_b128 v121, v[10:13] offset:36864
	v_mfma_f32_16x16x32_bf16 v[74:77], v[134:137], v[150:153], v[74:77]
	ds_write_b128 v120, v[14:17]
	ds_write_b128 v120, v[2:5] offset:36864
	v_mfma_f32_16x16x32_bf16 v[70:73], v[134:137], v[162:165], v[70:73]
	ds_write_b128 v124, v[26:29]
	ds_write_b128 v124, v[30:33] offset:36864
	v_mfma_f32_16x16x32_bf16 v[66:69], v[134:137], v[166:169], v[66:69]
	global_load_dwordx4 v[22:25], v[112:113], off offset:128
	v_mfma_f32_16x16x32_bf16 v[62:65], v[138:141], v[146:149], v[62:65]
	global_load_dwordx4 v[6:9], v[110:111], off offset:128
	v_mfma_f32_16x16x32_bf16 v[58:61], v[138:141], v[150:153], v[58:61]
	global_load_dwordx4 v[18:21], v[108:109], off offset:128
	v_mfma_f32_16x16x32_bf16 v[54:57], v[138:141], v[162:165], v[54:57]
	global_load_dwordx4 v[10:13], v[106:107], off offset:128
	v_mfma_f32_16x16x32_bf16 v[50:53], v[138:141], v[166:169], v[50:53]
	global_load_dwordx4 v[14:17], v[104:105], off offset:128
	v_mfma_f32_16x16x32_bf16 v[46:49], v[142:145], v[146:149], v[46:49]
	global_load_dwordx4 v[2:5], v[102:103], off offset:128
	v_mfma_f32_16x16x32_bf16 v[42:45], v[142:145], v[150:153], v[42:45]
	global_load_dwordx4 v[26:29], v[100:101], off offset:128
	v_mfma_f32_16x16x32_bf16 v[38:41], v[142:145], v[162:165], v[38:41]
	global_load_dwordx4 v[30:33], v[98:99], off offset:128
	v_mfma_f32_16x16x32_bf16 v[34:37], v[142:145], v[166:169], v[34:37]
	s_waitcnt lgkmcnt(0)
	s_barrier
; DEV f32x4 mfma16(bf16x8 a, bf16x8 b, f32x4 c) { return __builtin_amdgcn_mfma_f32_16x16x32_bf16(a, b, c, 0, 0, 0); }
; template <int EPI, bool AF32>
; DEV void gemm_tile(const void* Ap, int lda, const u16* Bt, int ldb, int K, int m0, int n0, const Epi& ea, char* smem) {
;     ...
;   for (int kt = 0; kt < nk; kt++) {
;     const int buf = kt & 1;
;     if (kt + 1 < nk) swrite(buf ^ 1);
;     if (kt + 2 < nk) gload(kt + 2);
; #pragma unroll
;     for (int ks = 0; ks < 2; ks++) {
;       bf16x8 a[4], b[4];
; #pragma unroll
;       for (int m = 0; m < 4; m++) a[m] = *(const bf16x8*)(sA + buf * 9216 + (wr * 64 + m * 16 + fr) * 72 + ks * 32 + fq * 8);
; #pragma unroll
;       for (int n = 0; n < 4; n++) b[n] = *(const bf16x8*)(sB + buf * 9216 + (wc * 64 + n * 16 + fr) * 72 + ks * 32 + fq * 8);
;       __builtin_amdgcn_s_setprio(1);
; #pragma unroll
;       for (int m = 0; m < 4; m++)
; #pragma unroll
;         for (int n = 0; n < 4; n++) acc[m][n] = mfma16(a[m], b[n], acc[m][n]);
;       __builtin_amdgcn_s_setprio(0);
;     }
;     __syncthreads();
	ds_read_b128 v[130:133], v161
	v_mfma_f32_16x16x32_bf16 v[94:97], v[222:225], v[238:241], v[94:97]
	ds_read_b128 v[134:137], v161 offset:2304
	v_mfma_f32_16x16x32_bf16 v[90:93], v[222:225], v[242:245], v[90:93]
	ds_read_b128 v[138:141], v161 offset:4608
	v_mfma_f32_16x16x32_bf16 v[86:89], v[222:225], v[246:249], v[86:89]
	ds_read_b128 v[142:145], v161 offset:6912
	v_mfma_f32_16x16x32_bf16 v[82:85], v[222:225], v[250:253], v[82:85]
	ds_read_b128 v[146:149], v129 offset:36864
	v_mfma_f32_16x16x32_bf16 v[78:81], v[226:229], v[238:241], v[78:81]
	ds_read_b128 v[150:153], v129 offset:39168
	v_mfma_f32_16x16x32_bf16 v[74:77], v[226:229], v[242:245], v[74:77]
	ds_read_b128 v[162:165], v129 offset:41472
	v_mfma_f32_16x16x32_bf16 v[70:73], v[226:229], v[246:249], v[70:73]
	ds_read_b128 v[166:169], v129 offset:43776
	v_mfma_f32_16x16x32_bf16 v[66:69], v[226:229], v[250:253], v[66:69]
	v_mfma_f32_16x16x32_bf16 v[62:65], v[230:233], v[238:241], v[62:65]
	v_lshl_add_u64 v[112:113], v[112:113], 0, s[0:1]
	v_mfma_f32_16x16x32_bf16 v[58:61], v[230:233], v[242:245], v[58:61]
	v_lshl_add_u64 v[110:111], v[110:111], 0, s[0:1]
	v_mfma_f32_16x16x32_bf16 v[54:57], v[230:233], v[246:249], v[54:57]
	v_lshl_add_u64 v[108:109], v[108:109], 0, s[0:1]
	v_mfma_f32_16x16x32_bf16 v[50:53], v[230:233], v[250:253], v[50:53]
	v_lshl_add_u64 v[106:107], v[106:107], 0, s[0:1]
	v_mfma_f32_16x16x32_bf16 v[46:49], v[234:237], v[238:241], v[46:49]
	v_lshl_add_u64 v[104:105], v[104:105], 0, s[0:1]
	v_mfma_f32_16x16x32_bf16 v[42:45], v[234:237], v[242:245], v[42:45]
	v_lshl_add_u64 v[102:103], v[102:103], 0, s[0:1]
	v_mfma_f32_16x16x32_bf16 v[38:41], v[234:237], v[246:249], v[38:41]
	v_lshl_add_u64 v[100:101], v[100:101], 0, s[0:1]
	v_mfma_f32_16x16x32_bf16 v[34:37], v[234:237], v[250:253], v[34:37]
	v_lshl_add_u64 v[98:99], v[98:99], 0, s[0:1]
	s_add_i32 s4, s4, 1
	s_cmp_lg_u32 s4, 7
	s_cbranch_scc1 .Lgk1_loop
	s_waitcnt vmcnt(7)
	ds_write_b128 v122, v[22:25] offset:18432
	s_waitcnt vmcnt(6)
	ds_write_b128 v122, v[6:9] offset:55296
	s_waitcnt vmcnt(5)
	ds_write_b128 v121, v[18:21] offset:18432
	s_waitcnt vmcnt(4)
	ds_write_b128 v121, v[10:13] offset:55296
	s_waitcnt vmcnt(3)
	ds_write_b128 v120, v[14:17] offset:18432
	s_waitcnt vmcnt(2)
	ds_write_b128 v120, v[2:5] offset:55296
	s_waitcnt vmcnt(1)
	ds_write_b128 v124, v[26:29] offset:18432
	s_waitcnt vmcnt(0)
	ds_write_b128 v124, v[30:33] offset:55296
	v_lshl_add_u32 v0, v128, 1, v125
	v_lshl_add_u32 v134, v127, 1, v125
	ds_read_b128 v[2:5], v0
	ds_read_b128 v[6:9], v0 offset:2304
	ds_read_b128 v[10:13], v0 offset:4608
	ds_read_b128 v[14:17], v0 offset:6912
	ds_read_b128 v[18:21], v134 offset:36864
	ds_read_b128 v[22:25], v134 offset:39168
	ds_read_b128 v[26:29], v134 offset:41472
	ds_read_b128 v[30:33], v134 offset:43776
	s_setprio 1
	s_waitcnt lgkmcnt(3)
	v_mfma_f32_16x16x32_bf16 v[94:97], v[2:5], v[18:21], v[94:97]
	s_waitcnt lgkmcnt(2)
	v_mfma_f32_16x16x32_bf16 v[90:93], v[2:5], v[22:25], v[90:93]
	s_waitcnt lgkmcnt(1)
	v_mfma_f32_16x16x32_bf16 v[86:89], v[2:5], v[26:29], v[86:89]
	s_waitcnt lgkmcnt(0)
	v_mfma_f32_16x16x32_bf16 v[2:5], v[2:5], v[30:33], v[82:85]
	v_mfma_f32_16x16x32_bf16 v[78:81], v[6:9], v[18:21], v[78:81]
	v_mfma_f32_16x16x32_bf16 v[74:77], v[6:9], v[22:25], v[74:77]
	v_mfma_f32_16x16x32_bf16 v[70:73], v[6:9], v[26:29], v[70:73]
	v_mfma_f32_16x16x32_bf16 v[6:9], v[6:9], v[30:33], v[66:69]
	v_mfma_f32_16x16x32_bf16 v[62:65], v[10:13], v[18:21], v[62:65]
	v_mfma_f32_16x16x32_bf16 v[58:61], v[10:13], v[22:25], v[58:61]
	v_mfma_f32_16x16x32_bf16 v[54:57], v[10:13], v[26:29], v[54:57]
	v_mfma_f32_16x16x32_bf16 v[10:13], v[10:13], v[30:33], v[50:53]
	v_mfma_f32_16x16x32_bf16 v[18:21], v[14:17], v[18:21], v[46:49]
	v_mfma_f32_16x16x32_bf16 v[22:25], v[14:17], v[22:25], v[42:45]
	v_mfma_f32_16x16x32_bf16 v[26:29], v[14:17], v[26:29], v[38:41]
	v_mfma_f32_16x16x32_bf16 v[14:17], v[14:17], v[30:33], v[34:37]
	s_setprio 0
	ds_read_b128 v[30:33], v0 offset:64
	s_nop 0
	ds_read_b128 v[34:37], v0 offset:2368
	ds_read_b128 v[38:41], v0 offset:4672
	ds_read_b128 v[42:45], v0 offset:6976
	ds_read_b128 v[46:49], v134 offset:36928
	ds_read_b128 v[50:53], v134 offset:39232
	ds_read_b128 v[66:69], v134 offset:41536
	ds_read_b128 v[82:85], v134 offset:43840
	s_setprio 1
	s_waitcnt lgkmcnt(3)
	v_mfma_f32_16x16x32_bf16 v[94:97], v[30:33], v[46:49], v[94:97]
	s_waitcnt lgkmcnt(2)
	v_mfma_f32_16x16x32_bf16 v[90:93], v[30:33], v[50:53], v[90:93]
	s_waitcnt lgkmcnt(1)
	v_mfma_f32_16x16x32_bf16 v[86:89], v[30:33], v[66:69], v[86:89]
	s_waitcnt lgkmcnt(0)
	v_mfma_f32_16x16x32_bf16 v[2:5], v[30:33], v[82:85], v[2:5]
	v_mfma_f32_16x16x32_bf16 v[30:33], v[34:37], v[46:49], v[78:81]
	v_mfma_f32_16x16x32_bf16 v[74:77], v[34:37], v[50:53], v[74:77]
	v_mfma_f32_16x16x32_bf16 v[70:73], v[34:37], v[66:69], v[70:73]
	v_mfma_f32_16x16x32_bf16 v[6:9], v[34:37], v[82:85], v[6:9]
	v_mfma_f32_16x16x32_bf16 v[34:37], v[38:41], v[46:49], v[62:65]
	v_mfma_f32_16x16x32_bf16 v[58:61], v[38:41], v[50:53], v[58:61]
	v_mfma_f32_16x16x32_bf16 v[54:57], v[38:41], v[66:69], v[54:57]
	v_mfma_f32_16x16x32_bf16 v[10:13], v[38:41], v[82:85], v[10:13]
	v_mfma_f32_16x16x32_bf16 v[18:21], v[42:45], v[46:49], v[18:21]
	v_mfma_f32_16x16x32_bf16 v[22:25], v[42:45], v[50:53], v[22:25]
	v_mfma_f32_16x16x32_bf16 v[26:29], v[42:45], v[66:69], v[26:29]
	v_mfma_f32_16x16x32_bf16 v[14:17], v[42:45], v[82:85], v[14:17]
	s_setprio 0
	s_barrier
; DEV f32x4 mfma16(bf16x8 a, bf16x8 b, f32x4 c) { return __builtin_amdgcn_mfma_f32_16x16x32_bf16(a, b, c, 0, 0, 0); }
; template <int EPI, bool AF32>
; DEV void gemm_tile(const void* Ap, int lda, const u16* Bt, int ldb, int K, int m0, int n0, const Epi& ea, char* smem) {
;     ...
;   for (int kt = 0; kt < nk; kt++) {
;     const int buf = kt & 1;
;     if (kt + 1 < nk) swrite(buf ^ 1);
;     if (kt + 2 < nk) gload(kt + 2);
; #pragma unroll
;     for (int ks = 0; ks < 2; ks++) {
;       bf16x8 a[4], b[4];
; #pragma unroll
;       for (int m = 0; m < 4; m++) a[m] = *(const bf16x8*)(sA + buf * 9216 + (wr * 64 + m * 16 + fr) * 72 + ks * 32 + fq * 8);
; #pragma unroll
;       for (int n = 0; n < 4; n++) b[n] = *(const bf16x8*)(sB + buf * 9216 + (wc * 64 + n * 16 + fr) * 72 + ks * 32 + fq * 8);
;       __builtin_amdgcn_s_setprio(1);
; #pragma unroll
;       for (int m = 0; m < 4; m++)
; #pragma unroll
;         for (int n = 0; n < 4; n++) acc[m][n] = mfma16(a[m], b[n], acc[m][n]);
;       __builtin_amdgcn_s_setprio(0);
;     }
;     __syncthreads();
;     ...
;         } else {
;           u16* Z = (u16*)ea.p1;
; #pragma unroll
;           for (int n = 0; n < 4; n++) Z[(size_t)row * 1024 + cb - 3072 + n * 16 + fr] = f2bf(acc[m][n][j]);
;         }
	ds_read_b128 v[38:41], v0 offset:18432
	ds_read_b128 v[42:45], v0 offset:20736
	ds_read_b128 v[46:49], v0 offset:23040
	ds_read_b128 v[50:53], v0 offset:25344
	ds_read_b128 v[62:65], v134 offset:55296
	ds_read_b128 v[66:69], v134 offset:57600
	ds_read_b128 v[78:81], v134 offset:59904
	ds_read_b128 v[82:85], v134 offset:62208
	s_setprio 1
	s_waitcnt lgkmcnt(3)
	v_mfma_f32_16x16x32_bf16 v[94:97], v[38:41], v[62:65], v[94:97]
	s_waitcnt lgkmcnt(2)
	v_mfma_f32_16x16x32_bf16 v[90:93], v[38:41], v[66:69], v[90:93]
	s_waitcnt lgkmcnt(1)
	v_mfma_f32_16x16x32_bf16 v[86:89], v[38:41], v[78:81], v[86:89]
	s_waitcnt lgkmcnt(0)
	v_mfma_f32_16x16x32_bf16 v[2:5], v[38:41], v[82:85], v[2:5]
	v_mfma_f32_16x16x32_bf16 v[30:33], v[42:45], v[62:65], v[30:33]
	v_mfma_f32_16x16x32_bf16 v[38:41], v[42:45], v[66:69], v[74:77]
	v_mfma_f32_16x16x32_bf16 v[70:73], v[42:45], v[78:81], v[70:73]
	v_mfma_f32_16x16x32_bf16 v[6:9], v[42:45], v[82:85], v[6:9]
	v_mfma_f32_16x16x32_bf16 v[98:101], v[46:49], v[66:69], v[58:61]
	v_mfma_f32_16x16x32_bf16 v[102:105], v[46:49], v[78:81], v[54:57]
	v_mfma_f32_16x16x32_bf16 v[10:13], v[46:49], v[82:85], v[10:13]
	v_mfma_f32_16x16x32_bf16 v[66:69], v[50:53], v[66:69], v[22:25]
	v_mfma_f32_16x16x32_bf16 v[78:81], v[50:53], v[78:81], v[26:29]
	v_mfma_f32_16x16x32_bf16 v[74:77], v[46:49], v[62:65], v[34:37]
	v_mfma_f32_16x16x32_bf16 v[106:109], v[50:53], v[62:65], v[18:21]
	v_mfma_f32_16x16x32_bf16 v[82:85], v[50:53], v[82:85], v[14:17]
	s_setprio 0
	s_nop 1
	ds_read_b128 v[14:17], v0 offset:18496
	ds_read_b128 v[18:21], v0 offset:20800
	ds_read_b128 v[110:113], v0 offset:23104
	ds_read_b128 v[118:121], v0 offset:25408
	ds_read_b128 v[122:125], v134 offset:55360
	ds_read_b128 v[126:129], v134 offset:57664
	ds_read_b128 v[130:133], v134 offset:59968
	ds_read_b128 v[134:137], v134 offset:62272
	s_setprio 1
	s_waitcnt lgkmcnt(3)
	v_mfma_f32_16x16x32_bf16 v[62:65], v[14:17], v[122:125], v[94:97]
	s_waitcnt lgkmcnt(2)
	v_mfma_f32_16x16x32_bf16 v[58:61], v[14:17], v[126:129], v[90:93]
	s_waitcnt lgkmcnt(1)
	v_mfma_f32_16x16x32_bf16 v[54:57], v[14:17], v[130:133], v[86:89]
	s_waitcnt lgkmcnt(0)
	v_mfma_f32_16x16x32_bf16 v[50:53], v[14:17], v[134:137], v[2:5]
	v_mfma_f32_16x16x32_bf16 v[46:49], v[18:21], v[122:125], v[30:33]
	v_mfma_f32_16x16x32_bf16 v[42:45], v[18:21], v[126:129], v[38:41]
	v_mfma_f32_16x16x32_bf16 v[38:41], v[18:21], v[130:133], v[70:73]
	v_mfma_f32_16x16x32_bf16 v[34:37], v[18:21], v[134:137], v[6:9]
	v_mfma_f32_16x16x32_bf16 v[30:33], v[110:113], v[122:125], v[74:77]
	v_mfma_f32_16x16x32_bf16 v[26:29], v[110:113], v[126:129], v[98:101]
	v_mfma_f32_16x16x32_bf16 v[22:25], v[110:113], v[130:133], v[102:105]
	v_mfma_f32_16x16x32_bf16 v[18:21], v[110:113], v[134:137], v[10:13]
	v_mfma_f32_16x16x32_bf16 v[14:17], v[118:121], v[122:125], v[106:109]
	v_mfma_f32_16x16x32_bf16 v[10:13], v[118:121], v[126:129], v[66:69]
	v_mfma_f32_16x16x32_bf16 v[6:9], v[118:121], v[130:133], v[78:81]
	v_mfma_f32_16x16x32_bf16 v[2:5], v[118:121], v[134:137], v[82:85]
	s_setprio 0
	v_and_or_b32 v0, v114, 64, s3
	v_add_u32_e32 v80, s2, v117
	s_movk_i32 s0, 0xbff
	v_lshl_or_b32 v68, v115, 2, v80
	v_cmp_lt_i32_e64 s[2:3], s0, v0
	v_lshl_add_u64 v[72:73], v[0:1], 1, s[16:17]
	v_lshlrev_b32_e32 v70, 1, v116
	s_barrier
	s_and_saveexec_b64 s[0:1], s[2:3]
	s_xor_b64 s[0:1], exec, s[0:1]
	s_cbranch_execz .LBB0_551
	v_ashrrev_i32_e32 v69, 31, v68
	v_lshlrev_b64 v[66:67], 11, v[68:69]
	v_lshl_add_u64 v[66:67], v[72:73], 0, v[66:67]
	v_mov_b32_e32 v71, v1
	v_lshl_add_u64 v[66:67], v[66:67], 0, v[70:71]
	v_lshl_add_u64 v[74:75], v[66:67], 0, s[36:37]
	v_add_co_u32_e32 v66, vcc, 0xfffff000, v66
	v_cvt_pk_bf16_f32 v69, v62, s0
	s_nop 0
	v_addc_co_u32_e32 v67, vcc, -1, v67, vcc
	global_store_short v[66:67], v69, off offset:-2048
	v_cvt_pk_bf16_f32 v66, v58, s0
	global_store_short v[74:75], v66, off offset:32
	v_cvt_pk_bf16_f32 v66, v54, s0
	global_store_short v[74:75], v66, off offset:64
	v_cvt_pk_bf16_f32 v66, v50, s0
	global_store_short v[74:75], v66, off offset:96

; DEV int tidx() { int t = threadIdx.x; asm volatile("" : "+v"(t)); return t; }
; template <int EPI, bool AF32>
; DEV void gemm_tile(const void* Ap, int lda, const u16* Bt, int ldb, int K, int m0, int n0, const Epi& ea, char* smem) {
;   u16* sA = (u16*)smem;
;   u16* sB = sA + 2 * 128 * 72;
;   const int tid = tidx(), lane = tid & 63, wv = tid >> 6;
;   const int wr = wv >> 1, wc = wv & 1, fr = lane & 15, fq = lane >> 4;
;   f32x4 acc[4][4];
; #pragma unroll
;   for (int m = 0; m < 4; m++)
; #pragma unroll
;     for (int n = 0; n < 4; n++) acc[m][n] = (f32x4){0.f, 0.f, 0.f, 0.f};
;   u32x4 ra[4], rb[4];
;   f32x4 rfa[8];
;   const int nk = K >> 6;
;   auto gload = [&](int kt) {
;     const int k0 = kt << 6;
; #pragma unroll
;     for (int i = 0; i < 4; i++) {
;       const int c = tid + i * 256, row = c >> 3, kc = c & 7;
;       if (AF32) {
;         const float* pa = (const float*)Ap + (size_t)(m0 + row) * lda + k0 + kc * 8;
;         rfa[2 * i] = *(const f32x4*)pa;
;         rfa[2 * i + 1] = *(const f32x4*)(pa + 4);
;       } else {
;         ra[i] = *(const u32x4*)((const u16*)Ap + (size_t)(m0 + row) * lda + k0 + kc * 8);
;       }
;       rb[i] = *(const u32x4*)(Bt + (size_t)(n0 + row) * ldb + k0 + kc * 8);
;     }
;   };
;   auto swrite = [&](int buf) {
; #pragma unroll
;     for (int i = 0; i < 4; i++) {
;       const int c = tid + i * 256, row = c >> 3, kc = c & 7;
;       u32x4 va;
;       if (AF32) {
;         va = (u32x4){pack2(rfa[2 * i][0], rfa[2 * i][1]), pack2(rfa[2 * i][2], rfa[2 * i][3]),
;                      pack2(rfa[2 * i + 1][0], rfa[2 * i + 1][1]), pack2(rfa[2 * i + 1][2], rfa[2 * i + 1][3])};
;       } else {
;         va = ra[i];
;       }
;       *(u32x4*)(sA + buf * 9216 + row * 72 + kc * 8) = va;
;       *(u32x4*)(sB + buf * 9216 + row * 72 + kc * 8) = rb[i];
;     }
;   };
;   gload(0);
;   swrite(0);
;   if (nk > 1) gload(1);
;   __syncthreads();
.LBB0_1262:
	s_ashr_i32 s0, s8, 31
	s_lshr_b32 s0, s0, 23
	s_add_i32 s0, s8, s0
	s_ashr_i32 s1, s0, 9
	s_and_b32 s0, s0, 0xfffffe00
	s_lshl_b32 s10, s1, 5
	s_sub_i32 s9, s8, s0
	s_sub_i32 s0, 0x104, s10
	s_min_u32 s11, s0, 32
	v_cvt_f32_ubyte0_e32 v2, s11
	v_cvt_f32_i32_e32 v0, s9
	v_rcp_iflag_f32_e32 v3, v2
	s_ashr_i32 s0, s9, 30
	s_or_b32 s12, s0, 1
	s_waitcnt vmcnt(12)
	v_mov_b32_e32 v114, v157
	v_mul_f32_e32 v3, v0, v3
	v_trunc_f32_e32 v3, v3
	v_fma_f32 v0, -v3, v2, v0
	v_cvt_i32_f32_e32 v3, v3
	v_cmp_ge_f32_e64 s[0:1], |v0|, v2
	s_and_b64 s[0:1], s[0:1], exec
	s_cselect_b32 s0, s12, 0
	v_readfirstlane_b32 s1, v3
	s_add_i32 s0, s1, s0
	s_sext_i32_i16 s1, s0
	s_mul_i32 s0, s0, s11
	s_sub_i32 s0, s9, s0
	s_sext_i32_i16 s0, s0
	s_add_i32 s10, s10, s0
	s_lshl_b32 s9, s10, 7
	s_lshl_b32 s10, s1, 7
	v_ashrrev_i32_e32 v8, 3, v114
	v_add_u32_e32 v2, s9, v8
	v_ashrrev_i32_e32 v3, 31, v2
	v_lshlrev_b32_e32 v0, 3, v114
	v_add_u32_e32 v4, 0x100, v114
	v_lshlrev_b64 v[58:59], 11, v[2:3]
	v_and_b32_e32 v0, 56, v0
	v_ashrrev_i32_e32 v9, 3, v4
	v_lshl_add_u64 v[2:3], s[60:61], 0, v[58:59]
	v_lshlrev_b32_e32 v0, 1, v0
	v_add_u32_e32 v4, s9, v9
	v_add_u32_e32 v6, 0x200, v114
	v_lshl_add_u64 v[14:15], v[2:3], 0, v[0:1]
	v_add_u32_e32 v2, s10, v8
	v_ashrrev_i32_e32 v5, 31, v4
	v_ashrrev_i32_e32 v10, 3, v6
	v_ashrrev_i32_e32 v3, 31, v2
	v_lshlrev_b64 v[62:63], 11, v[4:5]
	v_add_u32_e32 v6, s9, v10
	v_lshlrev_b64 v[60:61], 11, v[2:3]
	v_lshl_add_u64 v[4:5], s[60:61], 0, v[62:63]
	v_ashrrev_i32_e32 v7, 31, v6
	v_lshl_add_u64 v[2:3], s[4:5], 0, v[60:61]
	v_lshl_add_u64 v[16:17], v[4:5], 0, v[0:1]
	v_add_u32_e32 v4, s10, v9
	v_lshlrev_b64 v[66:67], 11, v[6:7]
	v_lshl_add_u64 v[2:3], v[2:3], 0, v[0:1]
	v_ashrrev_i32_e32 v5, 31, v4
	v_lshl_add_u64 v[6:7], s[60:61], 0, v[66:67]
	global_load_dwordx4 v[30:33], v[2:3], off
	v_lshlrev_b64 v[64:65], 11, v[4:5]
	v_lshl_add_u64 v[68:69], v[6:7], 0, v[0:1]
	v_add_u32_e32 v6, s10, v10
	global_load_dwordx4 v[26:29], v[14:15], off
	global_load_dwordx4 v[34:37], v[16:17], off
	v_lshl_add_u64 v[4:5], s[4:5], 0, v[64:65]
	v_ashrrev_i32_e32 v7, 31, v6
	v_lshl_add_u64 v[4:5], v[4:5], 0, v[0:1]
	v_lshlrev_b64 v[70:71], 11, v[6:7]
	global_load_dwordx4 v[38:41], v[4:5], off
	v_lshl_add_u64 v[6:7], s[4:5], 0, v[70:71]
	global_load_dwordx4 v[42:45], v[68:69], off
	v_lshl_add_u64 v[18:19], v[6:7], 0, v[0:1]
	global_load_dwordx4 v[46:49], v[18:19], off
	v_add_u32_e32 v6, 0x300, v114
	v_ashrrev_i32_e32 v80, 3, v6
	v_add_u32_e32 v6, s9, v80
	v_ashrrev_i32_e32 v7, 31, v6
	v_lshlrev_b64 v[72:73], 11, v[6:7]
	v_lshl_add_u64 v[6:7], s[60:61], 0, v[72:73]
	v_lshl_add_u64 v[74:75], v[6:7], 0, v[0:1]
	v_add_u32_e32 v6, s10, v80
	v_ashrrev_i32_e32 v7, 31, v6
	v_lshlrev_b64 v[76:77], 11, v[6:7]
	v_lshl_add_u64 v[6:7], s[4:5], 0, v[76:77]
	v_lshl_add_u64 v[78:79], v[6:7], 0, v[0:1]
	global_load_dwordx4 v[50:53], v[74:75], off
	global_load_dwordx4 v[54:57], v[78:79], off
	s_waitcnt vmcnt(19)
	v_mul_lo_u32 v118, v8, s71
	v_mul_lo_u32 v119, v9, s71
	s_waitcnt vmcnt(18)
	v_mul_lo_u32 v123, v10, s71
	global_load_dwordx4 v[6:9], v[2:3], off offset:128
	global_load_dwordx4 v[10:13], v[4:5], off offset:128
	s_nop 0
	global_load_dwordx4 v[2:5], v[18:19], off offset:128
	global_load_dwordx4 v[22:25], v[14:15], off offset:128
	s_nop 0
	global_load_dwordx4 v[18:21], v[16:17], off offset:128
	s_nop 0
	global_load_dwordx4 v[14:17], v[68:69], off offset:128
	v_bfe_u32 v161, v157, 3, 4
	v_add_u32_e32 v161, 4, v161
	v_lshlrev_b32_e32 v161, 1, v161
	v_and_b32_e32 v161, 16, v161
	v_xor_b32_e32 v129, v0, v161
	v_lshl_add_u32 v122, v118, 1, v129
	v_lshl_add_u32 v121, v119, 1, v129
	v_lshl_add_u32 v120, v123, 1, v129
	v_and_b32_e32 v115, 15, v114
	s_waitcnt vmcnt(23)
	v_mul_lo_u32 v126, v80, s71
	v_bfe_u32 v116, v114, 4, 2
	v_lshl_add_u32 v124, v126, 1, v129
	s_mov_b32 s11, 0
	v_lshlrev_b32_e32 v125, 4, v116
	v_and_b32_e32 v161, 15, v157
	v_add_u32_e32 v161, 4, v161
	v_lshlrev_b32_e32 v161, 1, v161
	v_and_b32_e32 v161, 16, v161
	v_xor_b32_e32 v125, v125, v161
	s_mov_b64 s[0:1], 0
	s_waitcnt vmcnt(13)
	ds_write_b128 v122, v[30:33] offset:36864
	s_waitcnt vmcnt(12)
	ds_write_b128 v122, v[26:29]
	s_waitcnt vmcnt(11)
	ds_write_b128 v121, v[34:37]
	s_waitcnt vmcnt(10)
	ds_write_b128 v121, v[38:41] offset:36864
	s_waitcnt vmcnt(9)
	ds_write_b128 v120, v[42:45]
	s_waitcnt vmcnt(8)
	ds_write_b128 v120, v[46:49] offset:36864
	global_load_dwordx4 v[26:29], v[74:75], off offset:128
	global_load_dwordx4 v[30:33], v[78:79], off offset:128
	v_ashrrev_i32_e32 v34, 1, v114
	v_and_b32_e32 v117, 0xffffffc0, v34
	v_or_b32_e32 v34, v117, v115
	v_mul_lo_u32 v128, v34, s71
	v_lshlrev_b32_e32 v34, 4, v114
	v_and_b32_e32 v34, 0x70, v34
	v_and_b32_e32 v35, 0x4f, v114
	v_or_b32_e32 v76, v76, v34
	v_or_b32_e32 v72, v72, v34
	v_or_b32_e32 v70, v70, v34
	v_or_b32_e32 v66, v66, v34
	v_or_b32_e32 v64, v64, v34
	v_or_b32_e32 v62, v62, v34
	v_or_b32_e32 v60, v60, v34
	v_or_b32_e32 v58, v58, v34
	v_mov_b32_e32 v34, 0
	s_waitcnt vmcnt(9)
	ds_write_b128 v124, v[50:53]
	s_waitcnt vmcnt(8)
	ds_write_b128 v124, v[54:57] offset:36864
	v_mul_u32_u24_e32 v127, 0x48, v35
	v_lshl_add_u64 v[98:99], s[6:7], 0, v[76:77]
	v_lshl_add_u64 v[100:101], s[66:67], 0, v[72:73]
	v_lshl_add_u64 v[102:103], s[6:7], 0, v[70:71]
	v_lshl_add_u64 v[104:105], s[66:67], 0, v[66:67]
	v_lshl_add_u64 v[106:107], s[6:7], 0, v[64:65]
	v_lshl_add_u64 v[108:109], s[66:67], 0, v[62:63]
	v_lshl_add_u64 v[110:111], s[6:7], 0, v[60:61]
	v_lshl_add_u64 v[112:113], s[66:67], 0, v[58:59]
	v_mov_b32_e32 v35, v34
	v_mov_b32_e32 v36, v34
	v_mov_b32_e32 v37, v34
	v_mov_b32_e32 v38, v34
	v_mov_b32_e32 v39, v34
	v_mov_b32_e32 v40, v34
	v_mov_b32_e32 v41, v34
	v_mov_b32_e32 v42, v34
	v_mov_b32_e32 v43, v34
	v_mov_b32_e32 v44, v34
	v_mov_b32_e32 v45, v34
	v_mov_b32_e32 v46, v34
	v_mov_b32_e32 v47, v34
	v_mov_b32_e32 v48, v34
	v_mov_b32_e32 v49, v34
	v_mov_b32_e32 v50, v34
	v_mov_b32_e32 v51, v34
	v_mov_b32_e32 v52, v34
	v_mov_b32_e32 v53, v34
	v_mov_b32_e32 v54, v34
	v_mov_b32_e32 v55, v34
	v_mov_b32_e32 v56, v34
	v_mov_b32_e32 v57, v34
	v_mov_b32_e32 v58, v34
	v_mov_b32_e32 v59, v34
	v_mov_b32_e32 v60, v34
	v_mov_b32_e32 v61, v34
	v_mov_b32_e32 v62, v34
	v_mov_b32_e32 v63, v34
	v_mov_b32_e32 v64, v34
	v_mov_b32_e32 v65, v34
	v_mov_b32_e32 v66, v34
	v_mov_b32_e32 v67, v34
	v_mov_b32_e32 v68, v34
	v_mov_b32_e32 v69, v34
	v_mov_b32_e32 v70, v34
	v_mov_b32_e32 v71, v34
	v_mov_b32_e32 v72, v34
	v_mov_b32_e32 v73, v34
	v_mov_b32_e32 v74, v34
	v_mov_b32_e32 v75, v34
	v_mov_b32_e32 v76, v34
	v_mov_b32_e32 v77, v34
	v_mov_b32_e32 v78, v34
	v_mov_b32_e32 v79, v34
	v_mov_b32_e32 v80, v34
	v_mov_b32_e32 v81, v34
	v_mov_b32_e32 v82, v34
	v_mov_b32_e32 v83, v34
	v_mov_b32_e32 v84, v34
	v_mov_b32_e32 v85, v34
	v_mov_b32_e32 v86, v34
	v_mov_b32_e32 v87, v34
	v_mov_b32_e32 v88, v34
	v_mov_b32_e32 v89, v34
	v_mov_b32_e32 v90, v34
	v_mov_b32_e32 v91, v34
	v_mov_b32_e32 v92, v34
	v_mov_b32_e32 v93, v34
	v_mov_b32_e32 v94, v34
	v_mov_b32_e32 v95, v34
	v_mov_b32_e32 v96, v34
	v_mov_b32_e32 v97, v34
	s_waitcnt lgkmcnt(0)
	s_barrier
; DEV f32x4 mfma16(bf16x8 a, bf16x8 b, f32x4 c) { return __builtin_amdgcn_mfma_f32_16x16x32_bf16(a, b, c, 0, 0, 0); }
; template <int EPI, bool AF32>
; DEV void gemm_tile(const void* Ap, int lda, const u16* Bt, int ldb, int K, int m0, int n0, const Epi& ea, char* smem) {
;     ...
;   for (int kt = 0; kt < nk; kt++) {
;     const int buf = kt & 1;
;     if (kt + 1 < nk) swrite(buf ^ 1);
;     if (kt + 2 < nk) gload(kt + 2);
; #pragma unroll
;     for (int ks = 0; ks < 2; ks++) {
;       bf16x8 a[4], b[4];
; #pragma unroll
;       for (int m = 0; m < 4; m++) a[m] = *(const bf16x8*)(sA + buf * 9216 + (wr * 64 + m * 16 + fr) * 72 + ks * 32 + fq * 8);
; #pragma unroll
;       for (int n = 0; n < 4; n++) b[n] = *(const bf16x8*)(sB + buf * 9216 + (wc * 64 + n * 16 + fr) * 72 + ks * 32 + fq * 8);
;       __builtin_amdgcn_s_setprio(1);
; #pragma unroll
;       for (int m = 0; m < 4; m++)
; #pragma unroll
;         for (int n = 0; n < 4; n++) acc[m][n] = mfma16(a[m], b[n], acc[m][n]);
;       __builtin_amdgcn_s_setprio(0);
;     }
;     __syncthreads();
;   }
	v_lshl_add_u32 v161, v128, 1, v125
	v_lshl_add_u32 v129, v127, 1, v125
	s_mov_b32 s11, 0
	s_mov_b64 s[0:1], 0x100
	ds_read_b128 v[130:133], v161
	ds_read_b128 v[134:137], v161 offset:2304
	ds_read_b128 v[138:141], v161 offset:4608
	ds_read_b128 v[142:145], v161 offset:6912
	ds_read_b128 v[146:149], v129 offset:36864
	ds_read_b128 v[150:153], v129 offset:39168
	ds_read_b128 v[162:165], v129 offset:41472
	ds_read_b128 v[166:169], v129 offset:43776
.Lgk2_loop:
	s_waitcnt lgkmcnt(0)
	ds_read_b128 v[222:225], v161 offset:64
	ds_read_b128 v[226:229], v161 offset:2368
	ds_read_b128 v[230:233], v161 offset:4672
	ds_read_b128 v[234:237], v161 offset:6976
	ds_read_b128 v[238:241], v129 offset:36928
	ds_read_b128 v[242:245], v129 offset:39232
	ds_read_b128 v[246:249], v129 offset:41536
	ds_read_b128 v[250:253], v129 offset:43840
	v_mfma_f32_16x16x32_bf16 v[94:97], v[130:133], v[146:149], v[94:97]
	v_mfma_f32_16x16x32_bf16 v[90:93], v[130:133], v[150:153], v[90:93]
	v_mfma_f32_16x16x32_bf16 v[86:89], v[130:133], v[162:165], v[86:89]
	v_mfma_f32_16x16x32_bf16 v[82:85], v[130:133], v[166:169], v[82:85]
	s_waitcnt vmcnt(0)
	ds_write_b128 v122, v[22:25] offset:18432
	ds_write_b128 v122, v[6:9] offset:55296
	v_mfma_f32_16x16x32_bf16 v[78:81], v[134:137], v[146:149], v[78:81]
	ds_write_b128 v121, v[18:21] offset:18432
	ds_write_b128 v121, v[10:13] offset:55296
	v_mfma_f32_16x16x32_bf16 v[74:77], v[134:137], v[150:153], v[74:77]
	ds_write_b128 v120, v[14:17] offset:18432
	ds_write_b128 v120, v[2:5] offset:55296
	v_mfma_f32_16x16x32_bf16 v[70:73], v[134:137], v[162:165], v[70:73]
	ds_write_b128 v124, v[26:29] offset:18432
	ds_write_b128 v124, v[30:33] offset:55296
	v_mfma_f32_16x16x32_bf16 v[66:69], v[134:137], v[166:169], v[66:69]
	global_load_dwordx4 v[22:25], v[112:113], off
	v_mfma_f32_16x16x32_bf16 v[62:65], v[138:141], v[146:149], v[62:65]
	global_load_dwordx4 v[6:9], v[110:111], off
	v_mfma_f32_16x16x32_bf16 v[58:61], v[138:141], v[150:153], v[58:61]
	global_load_dwordx4 v[18:21], v[108:109], off
	v_mfma_f32_16x16x32_bf16 v[54:57], v[138:141], v[162:165], v[54:57]
	global_load_dwordx4 v[10:13], v[106:107], off
	v_mfma_f32_16x16x32_bf16 v[50:53], v[138:141], v[166:169], v[50:53]
	global_load_dwordx4 v[14:17], v[104:105], off
	v_mfma_f32_16x16x32_bf16 v[46:49], v[142:145], v[146:149], v[46:49]
	global_load_dwordx4 v[2:5], v[102:103], off
	v_mfma_f32_16x16x32_bf16 v[42:45], v[142:145], v[150:153], v[42:45]
	global_load_dwordx4 v[26:29], v[100:101], off
	v_mfma_f32_16x16x32_bf16 v[38:41], v[142:145], v[162:165], v[38:41]
	global_load_dwordx4 v[30:33], v[98:99], off
	v_mfma_f32_16x16x32_bf16 v[34:37], v[142:145], v[166:169], v[34:37]
	s_waitcnt lgkmcnt(0)
	s_barrier
	ds_read_b128 v[130:133], v161 offset:18432
	v_mfma_f32_16x16x32_bf16 v[94:97], v[222:225], v[238:241], v[94:97]
	ds_read_b128 v[134:137], v161 offset:20736
	v_mfma_f32_16x16x32_bf16 v[90:93], v[222:225], v[242:245], v[90:93]
	ds_read_b128 v[138:141], v161 offset:23040
	v_mfma_f32_16x16x32_bf16 v[86:89], v[222:225], v[246:249], v[86:89]
	ds_read_b128 v[142:145], v161 offset:25344
	v_mfma_f32_16x16x32_bf16 v[82:85], v[222:225], v[250:253], v[82:85]
	ds_read_b128 v[146:149], v129 offset:55296
	v_mfma_f32_16x16x32_bf16 v[78:81], v[226:229], v[238:241], v[78:81]
	ds_read_b128 v[150:153], v129 offset:57600
	v_mfma_f32_16x16x32_bf16 v[74:77], v[226:229], v[242:245], v[74:77]
	ds_read_b128 v[162:165], v129 offset:59904
	v_mfma_f32_16x16x32_bf16 v[70:73], v[226:229], v[246:249], v[70:73]
	ds_read_b128 v[166:169], v129 offset:62208
	v_mfma_f32_16x16x32_bf16 v[66:69], v[226:229], v[250:253], v[66:69]
	v_mfma_f32_16x16x32_bf16 v[62:65], v[230:233], v[238:241], v[62:65]
	v_mfma_f32_16x16x32_bf16 v[58:61], v[230:233], v[242:245], v[58:61]
	v_mfma_f32_16x16x32_bf16 v[54:57], v[230:233], v[246:249], v[54:57]
	v_mfma_f32_16x16x32_bf16 v[50:53], v[230:233], v[250:253], v[50:53]
	v_mfma_f32_16x16x32_bf16 v[46:49], v[234:237], v[238:241], v[46:49]
	v_mfma_f32_16x16x32_bf16 v[42:45], v[234:237], v[242:245], v[42:45]
	v_mfma_f32_16x16x32_bf16 v[38:41], v[234:237], v[246:249], v[38:41]
	v_mfma_f32_16x16x32_bf16 v[34:37], v[234:237], v[250:253], v[34:37]
	s_waitcnt lgkmcnt(0)
	ds_read_b128 v[222:225], v161 offset:18496
	ds_read_b128 v[226:229], v161 offset:20800
	ds_read_b128 v[230:233], v161 offset:23104
	ds_read_b128 v[234:237], v161 offset:25408
	ds_read_b128 v[238:241], v129 offset:55360
	ds_read_b128 v[242:245], v129 offset:57664
	ds_read_b128 v[246:249], v129 offset:59968
	ds_read_b128 v[250:253], v129 offset:62272
	v_mfma_f32_16x16x32_bf16 v[94:97], v[130:133], v[146:149], v[94:97]
	v_mfma_f32_16x16x32_bf16 v[90:93], v[130:133], v[150:153], v[90:93]
	v_mfma_f32_16x16x32_bf16 v[86:89], v[130:133], v[162:165], v[86:89]
	v_mfma_f32_16x16x32_bf16 v[82:85], v[130:133], v[166:169], v[82:85]
	s_waitcnt vmcnt(0)
	ds_write_b128 v122, v[22:25]
	ds_write_b128 v122, v[6:9] offset:36864
	v_mfma_f32_16x16x32_bf16 v[78:81], v[134:137], v[146:149], v[78:81]
	ds_write_b128 v121, v[18:21]
	ds_write_b128 v121, v[10:13] offset:36864
	v_mfma_f32_16x16x32_bf16 v[74:77], v[134:137], v[150:153], v[74:77]
	ds_write_b128 v120, v[14:17]
	ds_write_b128 v120, v[2:5] offset:36864
	v_mfma_f32_16x16x32_bf16 v[70:73], v[134:137], v[162:165], v[70:73]
	ds_write_b128 v124, v[26:29]
	ds_write_b128 v124, v[30:33] offset:36864
	v_mfma_f32_16x16x32_bf16 v[66:69], v[134:137], v[166:169], v[66:69]
	global_load_dwordx4 v[22:25], v[112:113], off offset:128
	v_mfma_f32_16x16x32_bf16 v[62:65], v[138:141], v[146:149], v[62:65]
	global_load_dwordx4 v[6:9], v[110:111], off offset:128
	v_mfma_f32_16x16x32_bf16 v[58:61], v[138:141], v[150:153], v[58:61]
	global_load_dwordx4 v[18:21], v[108:109], off offset:128
	v_mfma_f32_16x16x32_bf16 v[54:57], v[138:141], v[162:165], v[54:57]
	global_load_dwordx4 v[10:13], v[106:107], off offset:128
	v_mfma_f32_16x16x32_bf16 v[50:53], v[138:141], v[166:169], v[50:53]
	global_load_dwordx4 v[14:17], v[104:105], off offset:128
	v_mfma_f32_16x16x32_bf16 v[46:49], v[142:145], v[146:149], v[46:49]
	global_load_dwordx4 v[2:5], v[102:103], off offset:128
	v_mfma_f32_16x16x32_bf16 v[42:45], v[142:145], v[150:153], v[42:45]
	global_load_dwordx4 v[26:29], v[100:101], off offset:128
	v_mfma_f32_16x16x32_bf16 v[38:41], v[142:145], v[162:165], v[38:41]
	global_load_dwordx4 v[30:33], v[98:99], off offset:128
	v_mfma_f32_16x16x32_bf16 v[34:37], v[142:145], v[166:169], v[34:37]
	s_waitcnt lgkmcnt(0)
	s_barrier
; DEV f32x4 mfma16(bf16x8 a, bf16x8 b, f32x4 c) { return __builtin_amdgcn_mfma_f32_16x16x32_bf16(a, b, c, 0, 0, 0); }
; template <int EPI, bool AF32>
; DEV void gemm_tile(const void* Ap, int lda, const u16* Bt, int ldb, int K, int m0, int n0, const Epi& ea, char* smem) {
;     ...
;   for (int kt = 0; kt < nk; kt++) {
;     const int buf = kt & 1;
;     if (kt + 1 < nk) swrite(buf ^ 1);
;     if (kt + 2 < nk) gload(kt + 2);
; #pragma unroll
;     for (int ks = 0; ks < 2; ks++) {
;       bf16x8 a[4], b[4];
; #pragma unroll
;       for (int m = 0; m < 4; m++) a[m] = *(const bf16x8*)(sA + buf * 9216 + (wr * 64 + m * 16 + fr) * 72 + ks * 32 + fq * 8);
; #pragma unroll
;       for (int n = 0; n < 4; n++) b[n] = *(const bf16x8*)(sB + buf * 9216 + (wc * 64 + n * 16 + fr) * 72 + ks * 32 + fq * 8);
;       __builtin_amdgcn_s_setprio(1);
; #pragma unroll
;       for (int m = 0; m < 4; m++)
; #pragma unroll
;         for (int n = 0; n < 4; n++) acc[m][n] = mfma16(a[m], b[n], acc[m][n]);
;       __builtin_amdgcn_s_setprio(0);
;     }
;     __syncthreads();
;   }
	ds_read_b128 v[130:133], v161
	v_mfma_f32_16x16x32_bf16 v[94:97], v[222:225], v[238:241], v[94:97]
	ds_read_b128 v[134:137], v161 offset:2304
	v_mfma_f32_16x16x32_bf16 v[90:93], v[222:225], v[242:245], v[90:93]
	ds_read_b128 v[138:141], v161 offset:4608
	v_mfma_f32_16x16x32_bf16 v[86:89], v[222:225], v[246:249], v[86:89]
	ds_read_b128 v[142:145], v161 offset:6912
	v_mfma_f32_16x16x32_bf16 v[82:85], v[222:225], v[250:253], v[82:85]
	ds_read_b128 v[146:149], v129 offset:36864
	v_mfma_f32_16x16x32_bf16 v[78:81], v[226:229], v[238:241], v[78:81]
	ds_read_b128 v[150:153], v129 offset:39168
	v_mfma_f32_16x16x32_bf16 v[74:77], v[226:229], v[242:245], v[74:77]
	ds_read_b128 v[162:165], v129 offset:41472
	v_mfma_f32_16x16x32_bf16 v[70:73], v[226:229], v[246:249], v[70:73]
	ds_read_b128 v[166:169], v129 offset:43776
	v_mfma_f32_16x16x32_bf16 v[66:69], v[226:229], v[250:253], v[66:69]
	v_mfma_f32_16x16x32_bf16 v[62:65], v[230:233], v[238:241], v[62:65]
	v_lshl_add_u64 v[112:113], v[112:113], 0, s[0:1]
	v_mfma_f32_16x16x32_bf16 v[58:61], v[230:233], v[242:245], v[58:61]
	v_lshl_add_u64 v[110:111], v[110:111], 0, s[0:1]
	v_mfma_f32_16x16x32_bf16 v[54:57], v[230:233], v[246:249], v[54:57]
	v_lshl_add_u64 v[108:109], v[108:109], 0, s[0:1]
	v_mfma_f32_16x16x32_bf16 v[50:53], v[230:233], v[250:253], v[50:53]
	v_lshl_add_u64 v[106:107], v[106:107], 0, s[0:1]
	v_mfma_f32_16x16x32_bf16 v[46:49], v[234:237], v[238:241], v[46:49]
	v_lshl_add_u64 v[104:105], v[104:105], 0, s[0:1]
	v_mfma_f32_16x16x32_bf16 v[42:45], v[234:237], v[242:245], v[42:45]
	v_lshl_add_u64 v[102:103], v[102:103], 0, s[0:1]
	v_mfma_f32_16x16x32_bf16 v[38:41], v[234:237], v[246:249], v[38:41]
	v_lshl_add_u64 v[100:101], v[100:101], 0, s[0:1]
	v_mfma_f32_16x16x32_bf16 v[34:37], v[234:237], v[250:253], v[34:37]
	v_lshl_add_u64 v[98:99], v[98:99], 0, s[0:1]
	s_add_i32 s11, s11, 1
	s_cmp_lg_u32 s11, 7
	s_cbranch_scc1 .Lgk2_loop
	s_waitcnt vmcnt(7)
	ds_write_b128 v122, v[22:25] offset:18432
	s_waitcnt vmcnt(6)
	ds_write_b128 v122, v[6:9] offset:55296
	s_waitcnt vmcnt(5)
	ds_write_b128 v121, v[18:21] offset:18432
	s_waitcnt vmcnt(4)
	ds_write_b128 v121, v[10:13] offset:55296
	s_waitcnt vmcnt(3)
	ds_write_b128 v120, v[14:17] offset:18432
	s_waitcnt vmcnt(2)
	ds_write_b128 v120, v[2:5] offset:55296
	s_waitcnt vmcnt(1)
	ds_write_b128 v124, v[26:29] offset:18432
	s_waitcnt vmcnt(0)
	ds_write_b128 v124, v[30:33] offset:55296
	v_lshl_add_u32 v0, v128, 1, v125
	v_lshl_add_u32 v118, v127, 1, v125
	ds_read_b128 v[2:5], v0
	ds_read_b128 v[6:9], v0 offset:2304
	ds_read_b128 v[10:13], v0 offset:4608
	ds_read_b128 v[14:17], v0 offset:6912
	ds_read_b128 v[18:21], v118 offset:36864
	ds_read_b128 v[22:25], v118 offset:39168
	ds_read_b128 v[26:29], v118 offset:41472
	ds_read_b128 v[30:33], v118 offset:43776
	s_setprio 1
	s_waitcnt lgkmcnt(3)
	v_mfma_f32_16x16x32_bf16 v[94:97], v[2:5], v[18:21], v[94:97]
	s_waitcnt lgkmcnt(2)
	v_mfma_f32_16x16x32_bf16 v[90:93], v[2:5], v[22:25], v[90:93]
	s_waitcnt lgkmcnt(1)
	v_mfma_f32_16x16x32_bf16 v[86:89], v[2:5], v[26:29], v[86:89]
	s_waitcnt lgkmcnt(0)
	v_mfma_f32_16x16x32_bf16 v[2:5], v[2:5], v[30:33], v[82:85]
	v_mfma_f32_16x16x32_bf16 v[78:81], v[6:9], v[18:21], v[78:81]
	v_mfma_f32_16x16x32_bf16 v[74:77], v[6:9], v[22:25], v[74:77]
	v_mfma_f32_16x16x32_bf16 v[70:73], v[6:9], v[26:29], v[70:73]
	v_mfma_f32_16x16x32_bf16 v[6:9], v[6:9], v[30:33], v[66:69]
	v_mfma_f32_16x16x32_bf16 v[62:65], v[10:13], v[18:21], v[62:65]
	v_mfma_f32_16x16x32_bf16 v[58:61], v[10:13], v[22:25], v[58:61]
	v_mfma_f32_16x16x32_bf16 v[54:57], v[10:13], v[26:29], v[54:57]
	v_mfma_f32_16x16x32_bf16 v[10:13], v[10:13], v[30:33], v[50:53]
	v_mfma_f32_16x16x32_bf16 v[18:21], v[14:17], v[18:21], v[46:49]
	v_mfma_f32_16x16x32_bf16 v[22:25], v[14:17], v[22:25], v[42:45]
	v_mfma_f32_16x16x32_bf16 v[26:29], v[14:17], v[26:29], v[38:41]
	v_mfma_f32_16x16x32_bf16 v[14:17], v[14:17], v[30:33], v[34:37]
	s_setprio 0
	ds_read_b128 v[30:33], v0 offset:64
	s_nop 0
	ds_read_b128 v[34:37], v0 offset:2368
	ds_read_b128 v[38:41], v0 offset:4672
	ds_read_b128 v[42:45], v0 offset:6976
	ds_read_b128 v[46:49], v118 offset:36928
	ds_read_b128 v[50:53], v118 offset:39232
	ds_read_b128 v[66:69], v118 offset:41536
	ds_read_b128 v[82:85], v118 offset:43840
	s_setprio 1
	s_waitcnt lgkmcnt(3)
	v_mfma_f32_16x16x32_bf16 v[94:97], v[30:33], v[46:49], v[94:97]
	s_waitcnt lgkmcnt(2)
	v_mfma_f32_16x16x32_bf16 v[90:93], v[30:33], v[50:53], v[90:93]
	s_waitcnt lgkmcnt(1)
	v_mfma_f32_16x16x32_bf16 v[86:89], v[30:33], v[66:69], v[86:89]
	s_waitcnt lgkmcnt(0)
	v_mfma_f32_16x16x32_bf16 v[2:5], v[30:33], v[82:85], v[2:5]
	v_mfma_f32_16x16x32_bf16 v[30:33], v[34:37], v[46:49], v[78:81]
	v_mfma_f32_16x16x32_bf16 v[74:77], v[34:37], v[50:53], v[74:77]
	v_mfma_f32_16x16x32_bf16 v[70:73], v[34:37], v[66:69], v[70:73]
	v_mfma_f32_16x16x32_bf16 v[6:9], v[34:37], v[82:85], v[6:9]
	v_mfma_f32_16x16x32_bf16 v[34:37], v[38:41], v[46:49], v[62:65]
	v_mfma_f32_16x16x32_bf16 v[58:61], v[38:41], v[50:53], v[58:61]
	v_mfma_f32_16x16x32_bf16 v[54:57], v[38:41], v[66:69], v[54:57]
	v_mfma_f32_16x16x32_bf16 v[10:13], v[38:41], v[82:85], v[10:13]
	v_mfma_f32_16x16x32_bf16 v[18:21], v[42:45], v[46:49], v[18:21]
	v_mfma_f32_16x16x32_bf16 v[22:25], v[42:45], v[50:53], v[22:25]
	v_mfma_f32_16x16x32_bf16 v[26:29], v[42:45], v[66:69], v[26:29]
	v_mfma_f32_16x16x32_bf16 v[14:17], v[42:45], v[82:85], v[14:17]
	s_setprio 0
	s_barrier
; DEV float sigmf(float x) { return __builtin_amdgcn_rcpf(1.f + __expf(-x)); }
; DEV f32x4 mfma16(bf16x8 a, bf16x8 b, f32x4 c) { return __builtin_amdgcn_mfma_f32_16x16x32_bf16(a, b, c, 0, 0, 0); }
; template <int EPI, bool AF32>
; DEV void gemm_tile(const void* Ap, int lda, const u16* Bt, int ldb, int K, int m0, int n0, const Epi& ea, char* smem) {
;     ...
;     for (int ks = 0; ks < 2; ks++) {
;       bf16x8 a[4], b[4];
; #pragma unroll
;       for (int m = 0; m < 4; m++) a[m] = *(const bf16x8*)(sA + buf * 9216 + (wr * 64 + m * 16 + fr) * 72 + ks * 32 + fq * 8);
; #pragma unroll
;       for (int n = 0; n < 4; n++) b[n] = *(const bf16x8*)(sB + buf * 9216 + (wc * 64 + n * 16 + fr) * 72 + ks * 32 + fq * 8);
;       __builtin_amdgcn_s_setprio(1);
; #pragma unroll
;       for (int m = 0; m < 4; m++)
; #pragma unroll
;         for (int n = 0; n < 4; n++) acc[m][n] = mfma16(a[m], b[n], acc[m][n]);
;       __builtin_amdgcn_s_setprio(0);
;     }
;     __syncthreads();
;   }
;     ...
; #pragma unroll
;   for (int m = 0; m < 4; m++) {
; #pragma unroll
;     for (int j = 0; j < 4; j++) {
;       const int row = m0 + wr * 64 + m * 16 + fq * 4 + j;
;       if (EPI == EP_F32) {
;         float* C = (float*)ea.p0;
; #pragma unroll
;         for (int n = 0; n < 4; n++) C[(size_t)row * ea.ld + cb + n * 16 + fr] = acc[m][n][j];
;       } else if (EPI == EP_BF16) {
;         u16* C = (u16*)ea.p0;
; #pragma unroll
;         for (int n = 0; n < 4; n++) C[(size_t)row * ea.ld + cb + n * 16 + fr] = f2bf(acc[m][n][j]);
;       } else if (EPI == EP_SIG) {
;         u16* C = (u16*)ea.p0;
; #pragma unroll
;         for (int n = 0; n < 4; n++) C[(size_t)row * ea.ld + cb + n * 16 + fr] = f2bf(sigmf(acc[m][n][j]));
	ds_read_b128 v[38:41], v0 offset:18432
	ds_read_b128 v[42:45], v0 offset:20736
	ds_read_b128 v[46:49], v0 offset:23040
	ds_read_b128 v[50:53], v0 offset:25344
	ds_read_b128 v[62:65], v118 offset:55296
	ds_read_b128 v[66:69], v118 offset:57600
	ds_read_b128 v[78:81], v118 offset:59904
	ds_read_b128 v[82:85], v118 offset:62208
	s_setprio 1
	s_waitcnt lgkmcnt(3)
	v_mfma_f32_16x16x32_bf16 v[94:97], v[38:41], v[62:65], v[94:97]
	s_waitcnt lgkmcnt(2)
	v_mfma_f32_16x16x32_bf16 v[90:93], v[38:41], v[66:69], v[90:93]
	s_waitcnt lgkmcnt(1)
	v_mfma_f32_16x16x32_bf16 v[86:89], v[38:41], v[78:81], v[86:89]
	s_waitcnt lgkmcnt(0)
	v_mfma_f32_16x16x32_bf16 v[2:5], v[38:41], v[82:85], v[2:5]
	v_mfma_f32_16x16x32_bf16 v[30:33], v[42:45], v[62:65], v[30:33]
	v_mfma_f32_16x16x32_bf16 v[38:41], v[42:45], v[66:69], v[74:77]
	v_mfma_f32_16x16x32_bf16 v[70:73], v[42:45], v[78:81], v[70:73]
	v_mfma_f32_16x16x32_bf16 v[6:9], v[42:45], v[82:85], v[6:9]
	v_mfma_f32_16x16x32_bf16 v[74:77], v[46:49], v[62:65], v[34:37]
	v_mfma_f32_16x16x32_bf16 v[58:61], v[46:49], v[66:69], v[58:61]
	v_mfma_f32_16x16x32_bf16 v[54:57], v[46:49], v[78:81], v[54:57]
	v_mfma_f32_16x16x32_bf16 v[10:13], v[46:49], v[82:85], v[10:13]
	v_mfma_f32_16x16x32_bf16 v[62:65], v[50:53], v[62:65], v[18:21]
	v_mfma_f32_16x16x32_bf16 v[66:69], v[50:53], v[66:69], v[22:25]
	v_mfma_f32_16x16x32_bf16 v[78:81], v[50:53], v[78:81], v[26:29]
	v_mfma_f32_16x16x32_bf16 v[50:53], v[50:53], v[82:85], v[14:17]
	s_setprio 0
	s_nop 1
	ds_read_b128 v[14:17], v0 offset:18496
	ds_read_b128 v[18:21], v0 offset:20800
	ds_read_b128 v[82:85], v0 offset:23104
	ds_read_b128 v[98:101], v0 offset:25408
	ds_read_b128 v[102:105], v118 offset:55360
	ds_read_b128 v[106:109], v118 offset:57664
	ds_read_b128 v[110:113], v118 offset:59968
	ds_read_b128 v[118:121], v118 offset:62272
	s_setprio 1
	s_waitcnt lgkmcnt(3)
	v_mfma_f32_16x16x32_bf16 v[94:97], v[14:17], v[102:105], v[94:97]
	s_waitcnt lgkmcnt(2)
	v_mfma_f32_16x16x32_bf16 v[90:93], v[14:17], v[106:109], v[90:93]
	s_waitcnt lgkmcnt(1)
	v_mfma_f32_16x16x32_bf16 v[86:89], v[14:17], v[110:113], v[86:89]
	s_waitcnt lgkmcnt(0)
	v_mfma_f32_16x16x32_bf16 v[122:125], v[14:17], v[118:121], v[2:5]
	v_mfma_f32_16x16x32_bf16 v[46:49], v[18:21], v[102:105], v[30:33]
	v_mfma_f32_16x16x32_bf16 v[42:45], v[18:21], v[106:109], v[38:41]
	v_mfma_f32_16x16x32_bf16 v[38:41], v[18:21], v[110:113], v[70:73]
	v_mfma_f32_16x16x32_bf16 v[34:37], v[18:21], v[118:121], v[6:9]
	v_mfma_f32_16x16x32_bf16 v[30:33], v[82:85], v[102:105], v[74:77]
	v_mfma_f32_16x16x32_bf16 v[26:29], v[82:85], v[106:109], v[58:61]
	v_mfma_f32_16x16x32_bf16 v[22:25], v[82:85], v[110:113], v[54:57]
	v_mfma_f32_16x16x32_bf16 v[18:21], v[82:85], v[118:121], v[10:13]
	v_mfma_f32_16x16x32_bf16 v[14:17], v[98:101], v[102:105], v[62:65]
	v_mfma_f32_16x16x32_bf16 v[10:13], v[98:101], v[106:109], v[66:69]
	v_mfma_f32_16x16x32_bf16 v[6:9], v[98:101], v[110:113], v[78:81]
	v_mfma_f32_16x16x32_bf16 v[2:5], v[98:101], v[118:121], v[50:53]
	s_setprio 0
	s_nop 1
	v_mul_f32_e32 v51, 0xbfb8aa3b, v94
	v_exp_f32_e32 v56, v51
	v_and_or_b32 v52, v114, 64, s10
	v_add_u32_e32 v0, s9, v117
	v_ashrrev_i32_e32 v53, 31, v52
	v_lshl_or_b32 v50, v116, 2, v0
	v_lshl_add_u64 v[52:53], v[52:53], 1, s[2:3]
	v_lshlrev_b32_e32 v0, 1, v115
	v_lshl_add_u64 v[52:53], v[52:53], 0, v[0:1]
	v_ashrrev_i32_e32 v51, 31, v50
	v_add_f32_e32 v0, 1.0, v56
	v_lshlrev_b64 v[54:55], 12, v[50:51]
	v_rcp_f32_e32 v0, v0
	v_mul_f32_e32 v51, 0xbfb8aa3b, v90
	v_exp_f32_e32 v51, v51
	v_lshl_add_u64 v[54:55], v[52:53], 0, v[54:55]
	v_cvt_pk_bf16_f32 v0, v0, s0
	s_barrier
	global_store_short v[54:55], v0, off
	v_add_f32_e32 v0, 1.0, v51
	v_mul_f32_e32 v51, 0xbfb8aa3b, v86
	v_exp_f32_e32 v51, v51
	v_mul_f32_e32 v56, 0xbfb8aa3b, v122
	v_exp_f32_e32 v56, v56
	v_rcp_f32_e32 v0, v0
	v_add_f32_e32 v51, 1.0, v51
	v_rcp_f32_e32 v51, v51
	v_add_f32_e32 v56, 1.0, v56
	v_rcp_f32_e32 v56, v56
	v_cvt_pk_bf16_f32 v0, v0, s0
	global_store_short v[54:55], v0, off offset:32
	v_cvt_pk_bf16_f32 v0, v51, s0
	global_store_short v[54:55], v0, off offset:64
	v_cvt_pk_bf16_f32 v0, v56, s0
	global_store_short v[54:55], v0, off offset:96
	v_mul_f32_e32 v0, 0xbfb8aa3b, v95
	v_exp_f32_e32 v0, v0
	v_mul_f32_e32 v51, 0xbfb8aa3b, v91
	v_or_b32_e32 v54, 1, v50
	v_exp_f32_e32 v51, v51
	v_add_f32_e32 v0, 1.0, v0
	v_rcp_f32_e32 v0, v0
	v_ashrrev_i32_e32 v55, 31, v54
	v_lshlrev_b64 v[54:55], 12, v[54:55]
	v_lshl_add_u64 v[54:55], v[52:53], 0, v[54:55]
	v_cvt_pk_bf16_f32 v0, v0, s0
	global_store_short v[54:55], v0, off
	v_add_f32_e32 v0, 1.0, v51
	v_mul_f32_e32 v51, 0xbfb8aa3b, v87
	v_exp_f32_e32 v51, v51
	v_mul_f32_e32 v56, 0xbfb8aa3b, v123
	v_exp_f32_e32 v56, v56
	v_rcp_f32_e32 v0, v0
	v_add_f32_e32 v51, 1.0, v51
	v_rcp_f32_e32 v51, v51
	v_add_f32_e32 v56, 1.0, v56
	v_rcp_f32_e32 v56, v56
	v_cvt_pk_bf16_f32 v0, v0, s0
	global_store_short v[54:55], v0, off offset:32
	v_cvt_pk_bf16_f32 v0, v51, s0
	global_store_short v[54:55], v0, off offset:64
	v_cvt_pk_bf16_f32 v0, v56, s0
	global_store_short v[54:55], v0, off offset:96
	v_mul_f32_e32 v0, 0xbfb8aa3b, v96
	v_exp_f32_e32 v0, v0
	v_mul_f32_e32 v51, 0xbfb8aa3b, v92
	v_or_b32_e32 v54, 2, v50
	v_exp_f32_e32 v51, v51
	v_add_f32_e32 v0, 1.0, v0
	v_rcp_f32_e32 v0, v0
	v_ashrrev_i32_e32 v55, 31, v54
	v_lshlrev_b64 v[54:55], 12, v[54:55]
	v_lshl_add_u64 v[54:55], v[52:53], 0, v[54:55]
	v_cvt_pk_bf16_f32 v0, v0, s0
	global_store_short v[54:55], v0, off
	v_add_f32_e32 v0, 1.0, v51
	v_mul_f32_e32 v51, 0xbfb8aa3b, v88
	v_exp_f32_e32 v51, v51
	v_mul_f32_e32 v56, 0xbfb8aa3b, v124
	v_exp_f32_e32 v56, v56
	v_rcp_f32_e32 v0, v0
	v_add_f32_e32 v51, 1.0, v51
	v_rcp_f32_e32 v51, v51
; DEV float sigmf(float x) { return __builtin_amdgcn_rcpf(1.f + __expf(-x)); }
; template <int EPI, bool AF32>
; DEV void gemm_tile(const void* Ap, int lda, const u16* Bt, int ldb, int K, int m0, int n0, const Epi& ea, char* smem) {
;     ...
; #pragma unroll
;   for (int m = 0; m < 4; m++) {
; #pragma unroll
;     for (int j = 0; j < 4; j++) {
;       const int row = m0 + wr * 64 + m * 16 + fq * 4 + j;
;       if (EPI == EP_F32) {
;         float* C = (float*)ea.p0;
; #pragma unroll
;         for (int n = 0; n < 4; n++) C[(size_t)row * ea.ld + cb + n * 16 + fr] = acc[m][n][j];
;       } else if (EPI == EP_BF16) {
;         u16* C = (u16*)ea.p0;
; #pragma unroll
;         for (int n = 0; n < 4; n++) C[(size_t)row * ea.ld + cb + n * 16 + fr] = f2bf(acc[m][n][j]);
;       } else if (EPI == EP_SIG) {
;         u16* C = (u16*)ea.p0;
; #pragma unroll
;         for (int n = 0; n < 4; n++) C[(size_t)row * ea.ld + cb + n * 16 + fr] = f2bf(sigmf(acc[m][n][j]));
	v_add_f32_e32 v56, 1.0, v56
	v_rcp_f32_e32 v56, v56
	v_cvt_pk_bf16_f32 v0, v0, s0
	global_store_short v[54:55], v0, off offset:32
	v_cvt_pk_bf16_f32 v0, v51, s0
	global_store_short v[54:55], v0, off offset:64
	v_cvt_pk_bf16_f32 v0, v56, s0
	global_store_short v[54:55], v0, off offset:96
	v_mul_f32_e32 v0, 0xbfb8aa3b, v97
	v_exp_f32_e32 v0, v0
	v_mul_f32_e32 v51, 0xbfb8aa3b, v93
	v_or_b32_e32 v54, 3, v50
	v_exp_f32_e32 v51, v51
	v_add_f32_e32 v0, 1.0, v0
	v_rcp_f32_e32 v0, v0
	v_ashrrev_i32_e32 v55, 31, v54
	v_lshlrev_b64 v[54:55], 12, v[54:55]
	v_lshl_add_u64 v[54:55], v[52:53], 0, v[54:55]
	v_cvt_pk_bf16_f32 v0, v0, s0
	global_store_short v[54:55], v0, off
	v_add_f32_e32 v0, 1.0, v51
	v_mul_f32_e32 v51, 0xbfb8aa3b, v89
	v_exp_f32_e32 v51, v51
	v_mul_f32_e32 v56, 0xbfb8aa3b, v125
	v_exp_f32_e32 v56, v56
	v_rcp_f32_e32 v0, v0
	v_add_f32_e32 v51, 1.0, v51
	v_rcp_f32_e32 v51, v51
	v_add_f32_e32 v56, 1.0, v56
	v_rcp_f32_e32 v56, v56
	v_cvt_pk_bf16_f32 v0, v0, s0
	global_store_short v[54:55], v0, off offset:32
	v_cvt_pk_bf16_f32 v0, v51, s0
	global_store_short v[54:55], v0, off offset:64
	v_cvt_pk_bf16_f32 v0, v56, s0
	global_store_short v[54:55], v0, off offset:96
	v_mul_f32_e32 v0, 0xbfb8aa3b, v46
	v_exp_f32_e32 v0, v0
	v_mul_f32_e32 v42, 0xbfb8aa3b, v42
	v_or_b32_e32 v54, 16, v50
	v_exp_f32_e32 v42, v42
	v_add_f32_e32 v0, 1.0, v0
	v_rcp_f32_e32 v0, v0
	v_mul_f32_e32 v38, 0xbfb8aa3b, v38
	v_ashrrev_i32_e32 v55, 31, v54
	v_exp_f32_e32 v38, v38
	v_mul_f32_e32 v34, 0xbfb8aa3b, v34
	v_lshlrev_b64 v[54:55], 12, v[54:55]
	v_exp_f32_e32 v34, v34
	v_lshl_add_u64 v[54:55], v[52:53], 0, v[54:55]
	v_cvt_pk_bf16_f32 v0, v0, s0
	global_store_short v[54:55], v0, off
	v_add_f32_e32 v0, 1.0, v42
	v_rcp_f32_e32 v0, v0
	v_add_f32_e32 v38, 1.0, v38
	v_rcp_f32_e32 v38, v38
	v_add_f32_e32 v34, 1.0, v34
	v_rcp_f32_e32 v34, v34
	v_cvt_pk_bf16_f32 v0, v0, s0
	global_store_short v[54:55], v0, off offset:32
	v_cvt_pk_bf16_f32 v0, v38, s0
	global_store_short v[54:55], v0, off offset:64
	v_cvt_pk_bf16_f32 v0, v34, s0
	global_store_short v[54:55], v0, off offset:96
	v_mul_f32_e32 v0, 0xbfb8aa3b, v47
	v_exp_f32_e32 v0, v0
	v_mul_f32_e32 v34, 0xbfb8aa3b, v43
	v_or_b32_e32 v46, 17, v50
	v_exp_f32_e32 v34, v34
	v_add_f32_e32 v0, 1.0, v0
	v_rcp_f32_e32 v0, v0
	v_ashrrev_i32_e32 v47, 31, v46
	v_lshlrev_b64 v[46:47], 12, v[46:47]
	v_lshl_add_u64 v[42:43], v[52:53], 0, v[46:47]
	v_cvt_pk_bf16_f32 v0, v0, s0
	global_store_short v[42:43], v0, off
	v_add_f32_e32 v0, 1.0, v34
	v_mul_f32_e32 v34, 0xbfb8aa3b, v39
	v_exp_f32_e32 v34, v34
	v_mul_f32_e32 v35, 0xbfb8aa3b, v35
	v_exp_f32_e32 v35, v35
	v_rcp_f32_e32 v0, v0
	v_add_f32_e32 v34, 1.0, v34
	v_rcp_f32_e32 v34, v34
	v_add_f32_e32 v35, 1.0, v35
	v_rcp_f32_e32 v35, v35
	v_cvt_pk_bf16_f32 v0, v0, s0
	global_store_short v[42:43], v0, off offset:32
	v_cvt_pk_bf16_f32 v0, v34, s0
	global_store_short v[42:43], v0, off offset:64
	v_cvt_pk_bf16_f32 v0, v35, s0
	global_store_short v[42:43], v0, off offset:96
	v_mul_f32_e32 v0, 0xbfb8aa3b, v48
	v_exp_f32_e32 v0, v0
	v_mul_f32_e32 v38, 0xbfb8aa3b, v44
	v_or_b32_e32 v34, 18, v50
	v_exp_f32_e32 v38, v38
	v_add_f32_e32 v0, 1.0, v0
	v_rcp_f32_e32 v0, v0
	v_ashrrev_i32_e32 v35, 31, v34
	v_lshlrev_b64 v[34:35], 12, v[34:35]
	v_lshl_add_u64 v[34:35], v[52:53], 0, v[34:35]
	v_cvt_pk_bf16_f32 v0, v0, s0
	global_store_short v[34:35], v0, off
	v_add_f32_e32 v0, 1.0, v38
	v_mul_f32_e32 v38, 0xbfb8aa3b, v40
	v_exp_f32_e32 v38, v38
	v_mul_f32_e32 v36, 0xbfb8aa3b, v36
	v_exp_f32_e32 v36, v36
	v_rcp_f32_e32 v0, v0
	v_add_f32_e32 v38, 1.0, v38
	v_rcp_f32_e32 v38, v38
	v_add_f32_e32 v36, 1.0, v36
	v_rcp_f32_e32 v36, v36
	v_cvt_pk_bf16_f32 v0, v0, s0
	global_store_short v[34:35], v0, off offset:32
	v_cvt_pk_bf16_f32 v0, v38, s0
	global_store_short v[34:35], v0, off offset:64
	v_cvt_pk_bf16_f32 v0, v36, s0
	global_store_short v[34:35], v0, off offset:96
	v_mul_f32_e32 v0, 0xbfb8aa3b, v49
	v_exp_f32_e32 v0, v0
	v_mul_f32_e32 v36, 0xbfb8aa3b, v45
	v_or_b32_e32 v34, 19, v50
	v_exp_f32_e32 v36, v36
	v_add_f32_e32 v0, 1.0, v0
	v_rcp_f32_e32 v0, v0
	v_ashrrev_i32_e32 v35, 31, v34
	v_lshlrev_b64 v[34:35], 12, v[34:35]
	v_lshl_add_u64 v[34:35], v[52:53], 0, v[34:35]
	v_cvt_pk_bf16_f32 v0, v0, s0
	global_store_short v[34:35], v0, off
	v_add_f32_e32 v0, 1.0, v36
	v_mul_f32_e32 v36, 0xbfb8aa3b, v41
	v_exp_f32_e32 v36, v36
	v_mul_f32_e32 v37, 0xbfb8aa3b, v37
	v_exp_f32_e32 v37, v37
	v_rcp_f32_e32 v0, v0
	v_add_f32_e32 v36, 1.0, v36
	v_rcp_f32_e32 v36, v36
	v_add_f32_e32 v37, 1.0, v37
	v_rcp_f32_e32 v37, v37
	v_cvt_pk_bf16_f32 v0, v0, s0
	global_store_short v[34:35], v0, off offset:32
	v_cvt_pk_bf16_f32 v0, v36, s0
	global_store_short v[34:35], v0, off offset:64
	v_cvt_pk_bf16_f32 v0, v37, s0
	global_store_short v[34:35], v0, off offset:96
	v_mul_f32_e32 v0, 0xbfb8aa3b, v30
	v_exp_f32_e32 v0, v0
	v_mul_f32_e32 v26, 0xbfb8aa3b, v26
	v_or_b32_e32 v34, 32, v50
	v_exp_f32_e32 v26, v26
	v_add_f32_e32 v0, 1.0, v0
	v_rcp_f32_e32 v0, v0
	v_mul_f32_e32 v22, 0xbfb8aa3b, v22
	v_ashrrev_i32_e32 v35, 31, v34
	v_exp_f32_e32 v22, v22
	v_mul_f32_e32 v18, 0xbfb8aa3b, v18
	v_lshlrev_b64 v[34:35], 12, v[34:35]
	v_exp_f32_e32 v18, v18
	v_lshl_add_u64 v[34:35], v[52:53], 0, v[34:35]
	v_cvt_pk_bf16_f32 v0, v0, s0
	global_store_short v[34:35], v0, off
	v_add_f32_e32 v0, 1.0, v26
	v_rcp_f32_e32 v0, v0
	v_add_f32_e32 v22, 1.0, v22
	v_rcp_f32_e32 v22, v22
	v_add_f32_e32 v18, 1.0, v18
	v_rcp_f32_e32 v18, v18
	v_cvt_pk_bf16_f32 v0, v0, s0
	global_store_short v[34:35], v0, off offset:32
	v_cvt_pk_bf16_f32 v0, v22, s0
	global_store_short v[34:35], v0, off offset:64
	v_cvt_pk_bf16_f32 v0, v18, s0
	global_store_short v[34:35], v0, off offset:96
; DEV int bidx() { int b = __builtin_amdgcn_readfirstlane(blockIdx.x); asm volatile("" : "+s"(b)); return b; }
; DEV int gdim() { int g = __builtin_amdgcn_readfirstlane(gridDim.x); asm volatile("" : "+s"(g)); return g; }
; DEV float sigmf(float x) { return __builtin_amdgcn_rcpf(1.f + __expf(-x)); }
; template <int EPI, bool AF32>
; DEV void gemm_tile(const void* Ap, int lda, const u16* Bt, int ldb, int K, int m0, int n0, const Epi& ea, char* smem) {
;     ...
; #pragma unroll
;   for (int m = 0; m < 4; m++) {
; #pragma unroll
;     for (int j = 0; j < 4; j++) {
;       const int row = m0 + wr * 64 + m * 16 + fq * 4 + j;
;       if (EPI == EP_F32) {
;         float* C = (float*)ea.p0;
; #pragma unroll
;         for (int n = 0; n < 4; n++) C[(size_t)row * ea.ld + cb + n * 16 + fr] = acc[m][n][j];
;       } else if (EPI == EP_BF16) {
;         u16* C = (u16*)ea.p0;
; #pragma unroll
;         for (int n = 0; n < 4; n++) C[(size_t)row * ea.ld + cb + n * 16 + fr] = f2bf(acc[m][n][j]);
;       } else if (EPI == EP_SIG) {
;         u16* C = (u16*)ea.p0;
; #pragma unroll
;         for (int n = 0; n < 4; n++) C[(size_t)row * ea.ld + cb + n * 16 + fr] = f2bf(sigmf(acc[m][n][j]));
; template <int EPI, bool AF32>
; DEV void gemm_phase(const void* A, int lda, const u16* Bt, int ldb, int M, int N, int K, const Epi& ea, char* smem) {
;     ...
;   for (int tile = bidx(); tile < ntm * ntn; tile += gdim()) {
;     int m, n;
;     tile_mn(tile, ntm, ntn, m, n);
;     gemm_tile<EPI, AF32>(A, lda, Bt, ldb, K, m << 7, n << 7, ea, smem);
;   }
	v_mul_f32_e32 v0, 0xbfb8aa3b, v31
	v_exp_f32_e32 v0, v0
	v_mul_f32_e32 v18, 0xbfb8aa3b, v27
	v_or_b32_e32 v30, 33, v50
	v_exp_f32_e32 v18, v18
	v_add_f32_e32 v0, 1.0, v0
	v_rcp_f32_e32 v0, v0
	v_ashrrev_i32_e32 v31, 31, v30
	v_lshlrev_b64 v[30:31], 12, v[30:31]
	v_lshl_add_u64 v[26:27], v[52:53], 0, v[30:31]
	v_cvt_pk_bf16_f32 v0, v0, s0
	global_store_short v[26:27], v0, off
	v_add_f32_e32 v0, 1.0, v18
	v_mul_f32_e32 v18, 0xbfb8aa3b, v23
	v_exp_f32_e32 v18, v18
	v_mul_f32_e32 v19, 0xbfb8aa3b, v19
	v_exp_f32_e32 v19, v19
	v_rcp_f32_e32 v0, v0
	v_add_f32_e32 v18, 1.0, v18
	v_rcp_f32_e32 v18, v18
	v_add_f32_e32 v19, 1.0, v19
	v_rcp_f32_e32 v19, v19
	v_cvt_pk_bf16_f32 v0, v0, s0
	global_store_short v[26:27], v0, off offset:32
	v_cvt_pk_bf16_f32 v0, v18, s0
	global_store_short v[26:27], v0, off offset:64
	v_cvt_pk_bf16_f32 v0, v19, s0
	global_store_short v[26:27], v0, off offset:96
	v_mul_f32_e32 v0, 0xbfb8aa3b, v32
	v_exp_f32_e32 v0, v0
	v_mul_f32_e32 v22, 0xbfb8aa3b, v28
	v_or_b32_e32 v18, 34, v50
	v_exp_f32_e32 v22, v22
	v_add_f32_e32 v0, 1.0, v0
	v_rcp_f32_e32 v0, v0
	v_ashrrev_i32_e32 v19, 31, v18
	v_lshlrev_b64 v[18:19], 12, v[18:19]
	v_lshl_add_u64 v[18:19], v[52:53], 0, v[18:19]
	v_cvt_pk_bf16_f32 v0, v0, s0
	global_store_short v[18:19], v0, off
	v_add_f32_e32 v0, 1.0, v22
	v_mul_f32_e32 v22, 0xbfb8aa3b, v24
	v_exp_f32_e32 v22, v22
	v_mul_f32_e32 v20, 0xbfb8aa3b, v20
	v_exp_f32_e32 v20, v20
	v_rcp_f32_e32 v0, v0
	v_add_f32_e32 v22, 1.0, v22
	v_rcp_f32_e32 v22, v22
	v_add_f32_e32 v20, 1.0, v20
	v_rcp_f32_e32 v20, v20
	v_cvt_pk_bf16_f32 v0, v0, s0
	global_store_short v[18:19], v0, off offset:32
	v_cvt_pk_bf16_f32 v0, v22, s0
	global_store_short v[18:19], v0, off offset:64
	v_cvt_pk_bf16_f32 v0, v20, s0
	global_store_short v[18:19], v0, off offset:96
	v_mul_f32_e32 v0, 0xbfb8aa3b, v33
	v_exp_f32_e32 v0, v0
	v_mul_f32_e32 v20, 0xbfb8aa3b, v29
	v_or_b32_e32 v18, 35, v50
	v_exp_f32_e32 v20, v20
	v_add_f32_e32 v0, 1.0, v0
	v_rcp_f32_e32 v0, v0
	v_ashrrev_i32_e32 v19, 31, v18
	v_lshlrev_b64 v[18:19], 12, v[18:19]
	v_lshl_add_u64 v[18:19], v[52:53], 0, v[18:19]
	v_cvt_pk_bf16_f32 v0, v0, s0
	global_store_short v[18:19], v0, off
	v_add_f32_e32 v0, 1.0, v20
	v_mul_f32_e32 v20, 0xbfb8aa3b, v25
	v_exp_f32_e32 v20, v20
	v_mul_f32_e32 v21, 0xbfb8aa3b, v21
	v_exp_f32_e32 v21, v21
	v_rcp_f32_e32 v0, v0
	v_add_f32_e32 v20, 1.0, v20
	v_rcp_f32_e32 v20, v20
	v_add_f32_e32 v21, 1.0, v21
	v_rcp_f32_e32 v21, v21
	v_cvt_pk_bf16_f32 v0, v0, s0
	global_store_short v[18:19], v0, off offset:32
	v_cvt_pk_bf16_f32 v0, v20, s0
	global_store_short v[18:19], v0, off offset:64
	v_cvt_pk_bf16_f32 v0, v21, s0
	global_store_short v[18:19], v0, off offset:96
	v_mul_f32_e32 v0, 0xbfb8aa3b, v14
	v_exp_f32_e32 v0, v0
	v_mul_f32_e32 v10, 0xbfb8aa3b, v10
	v_or_b32_e32 v18, 48, v50
	v_exp_f32_e32 v10, v10
	v_add_f32_e32 v0, 1.0, v0
	v_rcp_f32_e32 v0, v0
	v_mul_f32_e32 v6, 0xbfb8aa3b, v6
	v_ashrrev_i32_e32 v19, 31, v18
	v_exp_f32_e32 v6, v6
	v_mul_f32_e32 v2, 0xbfb8aa3b, v2
	v_lshlrev_b64 v[18:19], 12, v[18:19]
	v_exp_f32_e32 v2, v2
	v_lshl_add_u64 v[18:19], v[52:53], 0, v[18:19]
	v_cvt_pk_bf16_f32 v0, v0, s0
	global_store_short v[18:19], v0, off
	v_add_f32_e32 v0, 1.0, v10
	v_rcp_f32_e32 v0, v0
	v_add_f32_e32 v6, 1.0, v6
	v_rcp_f32_e32 v6, v6
	v_add_f32_e32 v2, 1.0, v2
	v_rcp_f32_e32 v2, v2
	v_cvt_pk_bf16_f32 v0, v0, s0
	global_store_short v[18:19], v0, off offset:32
	v_cvt_pk_bf16_f32 v0, v6, s0
	global_store_short v[18:19], v0, off offset:64
	v_cvt_pk_bf16_f32 v0, v2, s0
	global_store_short v[18:19], v0, off offset:96
	v_mul_f32_e32 v0, 0xbfb8aa3b, v15
	v_exp_f32_e32 v0, v0
	v_mul_f32_e32 v2, 0xbfb8aa3b, v11
	v_or_b32_e32 v14, 49, v50
	v_exp_f32_e32 v2, v2
	v_add_f32_e32 v0, 1.0, v0
	v_rcp_f32_e32 v0, v0
	v_ashrrev_i32_e32 v15, 31, v14
	v_lshlrev_b64 v[14:15], 12, v[14:15]
	v_lshl_add_u64 v[10:11], v[52:53], 0, v[14:15]
	v_cvt_pk_bf16_f32 v0, v0, s0
	global_store_short v[10:11], v0, off
	v_add_f32_e32 v0, 1.0, v2
	v_mul_f32_e32 v2, 0xbfb8aa3b, v7
	v_exp_f32_e32 v2, v2
	v_mul_f32_e32 v3, 0xbfb8aa3b, v3
	v_exp_f32_e32 v3, v3
	v_rcp_f32_e32 v0, v0
	v_add_f32_e32 v2, 1.0, v2
	v_rcp_f32_e32 v2, v2
	v_add_f32_e32 v3, 1.0, v3
	v_rcp_f32_e32 v3, v3
	v_cvt_pk_bf16_f32 v0, v0, s0
	global_store_short v[10:11], v0, off offset:32
	v_cvt_pk_bf16_f32 v0, v2, s0
	global_store_short v[10:11], v0, off offset:64
	v_cvt_pk_bf16_f32 v0, v3, s0
	global_store_short v[10:11], v0, off offset:96
	v_mul_f32_e32 v0, 0xbfb8aa3b, v16
	v_exp_f32_e32 v0, v0
	v_mul_f32_e32 v6, 0xbfb8aa3b, v12
	v_or_b32_e32 v2, 50, v50
	v_exp_f32_e32 v6, v6
	v_add_f32_e32 v0, 1.0, v0
	v_rcp_f32_e32 v0, v0
	v_ashrrev_i32_e32 v3, 31, v2
	v_lshlrev_b64 v[2:3], 12, v[2:3]
	v_lshl_add_u64 v[2:3], v[52:53], 0, v[2:3]
	v_cvt_pk_bf16_f32 v0, v0, s0
	global_store_short v[2:3], v0, off
	v_add_f32_e32 v0, 1.0, v6
	v_mul_f32_e32 v6, 0xbfb8aa3b, v8
	v_exp_f32_e32 v6, v6
	v_mul_f32_e32 v4, 0xbfb8aa3b, v4
	v_exp_f32_e32 v4, v4
	v_rcp_f32_e32 v0, v0
	v_add_f32_e32 v6, 1.0, v6
	v_rcp_f32_e32 v6, v6
	v_add_f32_e32 v4, 1.0, v4
	v_rcp_f32_e32 v4, v4
	v_cvt_pk_bf16_f32 v0, v0, s0
	global_store_short v[2:3], v0, off offset:32
	v_cvt_pk_bf16_f32 v0, v6, s0
	global_store_short v[2:3], v0, off offset:64
	v_cvt_pk_bf16_f32 v0, v4, s0
	global_store_short v[2:3], v0, off offset:96
	v_mul_f32_e32 v0, 0xbfb8aa3b, v17
	v_exp_f32_e32 v0, v0
	v_mul_f32_e32 v4, 0xbfb8aa3b, v13
	v_or_b32_e32 v2, 51, v50
	v_exp_f32_e32 v4, v4
	v_add_f32_e32 v0, 1.0, v0
	v_rcp_f32_e32 v0, v0
	v_ashrrev_i32_e32 v3, 31, v2
	v_lshlrev_b64 v[2:3], 12, v[2:3]
	v_lshl_add_u64 v[2:3], v[52:53], 0, v[2:3]
	v_cvt_pk_bf16_f32 v0, v0, s0
	global_store_short v[2:3], v0, off
	v_add_f32_e32 v0, 1.0, v4
	v_mul_f32_e32 v4, 0xbfb8aa3b, v9
	v_exp_f32_e32 v4, v4
	v_mul_f32_e32 v5, 0xbfb8aa3b, v5
	v_exp_f32_e32 v5, v5
	v_rcp_f32_e32 v0, v0
	v_add_f32_e32 v4, 1.0, v4
	v_rcp_f32_e32 v4, v4
	v_add_f32_e32 v5, 1.0, v5
	v_rcp_f32_e32 v5, v5
	v_cvt_pk_bf16_f32 v0, v0, s0
	global_store_short v[2:3], v0, off offset:32
	v_cvt_pk_bf16_f32 v0, v4, s0
	global_store_short v[2:3], v0, off offset:64
	v_cvt_pk_bf16_f32 v0, v5, s0
	v_readfirstlane_b32 s0, v198
	global_store_short v[2:3], v0, off offset:96
	s_add_i32 s8, s0, s8
	s_cmpk_lt_i32 s8, 0x1040
	s_cbranch_scc1 .LBB0_1262

; DEV int tidx() { int t = threadIdx.x; asm volatile("" : "+v"(t)); return t; }
; template <int EPI, bool AF32>
; DEV void gemm_tile(const void* Ap, int lda, const u16* Bt, int ldb, int K, int m0, int n0, const Epi& ea, char* smem) {
;   u16* sA = (u16*)smem;
;   u16* sB = sA + 2 * 128 * 72;
;   const int tid = tidx(), lane = tid & 63, wv = tid >> 6;
;   const int wr = wv >> 1, wc = wv & 1, fr = lane & 15, fq = lane >> 4;
;   f32x4 acc[4][4];
; #pragma unroll
;   for (int m = 0; m < 4; m++)
; #pragma unroll
;     for (int n = 0; n < 4; n++) acc[m][n] = (f32x4){0.f, 0.f, 0.f, 0.f};
;   u32x4 ra[4], rb[4];
;   f32x4 rfa[8];
;   const int nk = K >> 6;
;   auto gload = [&](int kt) {
;     const int k0 = kt << 6;
; #pragma unroll
;     for (int i = 0; i < 4; i++) {
;       const int c = tid + i * 256, row = c >> 3, kc = c & 7;
;       if (AF32) {
;         const float* pa = (const float*)Ap + (size_t)(m0 + row) * lda + k0 + kc * 8;
;         rfa[2 * i] = *(const f32x4*)pa;
;         rfa[2 * i + 1] = *(const f32x4*)(pa + 4);
;       } else {
;         ra[i] = *(const u32x4*)((const u16*)Ap + (size_t)(m0 + row) * lda + k0 + kc * 8);
;       }
;       rb[i] = *(const u32x4*)(Bt + (size_t)(n0 + row) * ldb + k0 + kc * 8);
;     }
;   };
;   auto swrite = [&](int buf) {
; #pragma unroll
;     for (int i = 0; i < 4; i++) {
;       const int c = tid + i * 256, row = c >> 3, kc = c & 7;
;       u32x4 va;
;       if (AF32) {
;         va = (u32x4){pack2(rfa[2 * i][0], rfa[2 * i][1]), pack2(rfa[2 * i][2], rfa[2 * i][3]),
;                      pack2(rfa[2 * i + 1][0], rfa[2 * i + 1][1]), pack2(rfa[2 * i + 1][2], rfa[2 * i + 1][3])};
;       } else {
;         va = ra[i];
;       }
;       *(u32x4*)(sA + buf * 9216 + row * 72 + kc * 8) = va;
;       *(u32x4*)(sB + buf * 9216 + row * 72 + kc * 8) = rb[i];
;     }
;   };
;   gload(0);
;   swrite(0);
;   if (nk > 1) gload(1);
;   __syncthreads();
.LBB0_1304:
	s_ashr_i32 s0, s16, 31
	s_lshr_b32 s0, s0, 24
	s_add_i32 s0, s16, s0
	s_ashr_i32 s1, s0, 8
	s_and_b32 s0, s0, 0xffffff00
	s_lshl_b32 s18, s1, 5
	s_sub_i32 s17, s16, s0
	s_sub_i32 s0, 0x104, s18
	s_min_u32 s19, s0, 32
	v_cvt_f32_ubyte0_e32 v2, s19
	v_cvt_f32_i32_e32 v0, s17
	v_rcp_iflag_f32_e32 v3, v2
	s_ashr_i32 s0, s17, 30
	s_or_b32 s20, s0, 1
	s_waitcnt vmcnt(12)
	v_mov_b32_e32 v114, v157
	v_mul_f32_e32 v3, v0, v3
	v_trunc_f32_e32 v3, v3
	v_fma_f32 v0, -v3, v2, v0
	v_cvt_i32_f32_e32 v3, v3
	v_cmp_ge_f32_e64 s[0:1], |v0|, v2
	s_and_b64 s[0:1], s[0:1], exec
	s_cselect_b32 s0, s20, 0
	v_readfirstlane_b32 s1, v3
	s_add_i32 s0, s1, s0
	s_sext_i32_i16 s1, s0
	s_mul_i32 s0, s0, s19
	s_sub_i32 s0, s17, s0
	s_sext_i32_i16 s0, s0
	s_add_i32 s18, s18, s0
	s_lshl_b32 s18, s18, 7
	s_lshl_b32 s17, s1, 7
	v_ashrrev_i32_e32 v8, 3, v114
	v_add_u32_e32 v2, s18, v8
	v_ashrrev_i32_e32 v3, 31, v2
	v_lshlrev_b32_e32 v0, 3, v114
	v_add_u32_e32 v4, 0x100, v114
	v_lshlrev_b64 v[58:59], 11, v[2:3]
	v_and_b32_e32 v0, 56, v0
	v_ashrrev_i32_e32 v9, 3, v4
	v_lshl_add_u64 v[2:3], s[6:7], 0, v[58:59]
	v_lshlrev_b32_e32 v0, 1, v0
	v_add_u32_e32 v4, s18, v9
	v_add_u32_e32 v6, 0x200, v114
	v_lshl_add_u64 v[14:15], v[2:3], 0, v[0:1]
	v_add_u32_e32 v2, s17, v8
	v_ashrrev_i32_e32 v5, 31, v4
	v_ashrrev_i32_e32 v10, 3, v6
	v_ashrrev_i32_e32 v3, 31, v2
	v_lshlrev_b64 v[62:63], 11, v[4:5]
	v_add_u32_e32 v6, s18, v10
	v_lshlrev_b64 v[60:61], 11, v[2:3]
	v_lshl_add_u64 v[4:5], s[6:7], 0, v[62:63]
	v_ashrrev_i32_e32 v7, 31, v6
	v_lshl_add_u64 v[2:3], s[10:11], 0, v[60:61]
	v_lshl_add_u64 v[16:17], v[4:5], 0, v[0:1]
	v_add_u32_e32 v4, s17, v9
	v_lshlrev_b64 v[66:67], 11, v[6:7]
	v_lshl_add_u64 v[2:3], v[2:3], 0, v[0:1]
	v_ashrrev_i32_e32 v5, 31, v4
	v_lshl_add_u64 v[6:7], s[6:7], 0, v[66:67]
	global_load_dwordx4 v[30:33], v[2:3], off
	v_lshlrev_b64 v[64:65], 11, v[4:5]
	v_lshl_add_u64 v[68:69], v[6:7], 0, v[0:1]
	v_add_u32_e32 v6, s17, v10
	global_load_dwordx4 v[26:29], v[14:15], off
	global_load_dwordx4 v[34:37], v[16:17], off
	v_lshl_add_u64 v[4:5], s[10:11], 0, v[64:65]
	v_ashrrev_i32_e32 v7, 31, v6
	v_lshl_add_u64 v[4:5], v[4:5], 0, v[0:1]
	v_lshlrev_b64 v[70:71], 11, v[6:7]
	global_load_dwordx4 v[38:41], v[4:5], off
	v_lshl_add_u64 v[6:7], s[10:11], 0, v[70:71]
	global_load_dwordx4 v[42:45], v[68:69], off
	v_lshl_add_u64 v[18:19], v[6:7], 0, v[0:1]
	global_load_dwordx4 v[46:49], v[18:19], off
	v_add_u32_e32 v6, 0x300, v114
	v_ashrrev_i32_e32 v80, 3, v6
	v_add_u32_e32 v6, s18, v80
	v_ashrrev_i32_e32 v7, 31, v6
	v_lshlrev_b64 v[72:73], 11, v[6:7]
	v_lshl_add_u64 v[6:7], s[6:7], 0, v[72:73]
	v_lshl_add_u64 v[74:75], v[6:7], 0, v[0:1]
	v_add_u32_e32 v6, s17, v80
	v_ashrrev_i32_e32 v7, 31, v6
	v_lshlrev_b64 v[76:77], 11, v[6:7]
	v_lshl_add_u64 v[6:7], s[10:11], 0, v[76:77]
	v_lshl_add_u64 v[78:79], v[6:7], 0, v[0:1]
	global_load_dwordx4 v[50:53], v[74:75], off
	global_load_dwordx4 v[54:57], v[78:79], off
	s_waitcnt vmcnt(19)
	v_mul_lo_u32 v118, v8, s71
	v_mul_lo_u32 v119, v9, s71
	s_waitcnt vmcnt(18)
	v_mul_lo_u32 v123, v10, s71
	global_load_dwordx4 v[6:9], v[2:3], off offset:128
	global_load_dwordx4 v[10:13], v[4:5], off offset:128
	s_nop 0
	global_load_dwordx4 v[2:5], v[18:19], off offset:128
	global_load_dwordx4 v[22:25], v[14:15], off offset:128
	s_nop 0
	global_load_dwordx4 v[18:21], v[16:17], off offset:128
	s_nop 0
	global_load_dwordx4 v[14:17], v[68:69], off offset:128
	v_bfe_u32 v161, v157, 3, 4
	v_add_u32_e32 v161, 4, v161
	v_lshlrev_b32_e32 v161, 1, v161
	v_and_b32_e32 v161, 16, v161
	v_xor_b32_e32 v129, v0, v161
	v_lshl_add_u32 v122, v118, 1, v129
	v_lshl_add_u32 v121, v119, 1, v129
	v_lshl_add_u32 v120, v123, 1, v129
	v_and_b32_e32 v115, 15, v114
	s_waitcnt vmcnt(23)
	v_mul_lo_u32 v126, v80, s71
	v_bfe_u32 v116, v114, 4, 2
	v_lshl_add_u32 v124, v126, 1, v129
	s_mov_b32 s19, 0
	v_lshlrev_b32_e32 v125, 4, v116
	v_and_b32_e32 v161, 15, v157
	v_add_u32_e32 v161, 4, v161
	v_lshlrev_b32_e32 v161, 1, v161
	v_and_b32_e32 v161, 16, v161
	v_xor_b32_e32 v125, v125, v161
	s_mov_b64 s[0:1], 0
	s_waitcnt vmcnt(13)
	ds_write_b128 v122, v[30:33] offset:36864
	s_waitcnt vmcnt(12)
	ds_write_b128 v122, v[26:29]
	s_waitcnt vmcnt(11)
	ds_write_b128 v121, v[34:37]
	s_waitcnt vmcnt(10)
	ds_write_b128 v121, v[38:41] offset:36864
	s_waitcnt vmcnt(9)
	ds_write_b128 v120, v[42:45]
	s_waitcnt vmcnt(8)
	ds_write_b128 v120, v[46:49] offset:36864
	global_load_dwordx4 v[26:29], v[74:75], off offset:128
	global_load_dwordx4 v[30:33], v[78:79], off offset:128
	v_ashrrev_i32_e32 v34, 1, v114
	v_and_b32_e32 v117, 0xffffffc0, v34
	v_or_b32_e32 v34, v117, v115
	v_mul_lo_u32 v128, v34, s71
	v_lshlrev_b32_e32 v34, 4, v114
	v_and_b32_e32 v34, 0x70, v34
	v_and_b32_e32 v35, 0x4f, v114
	v_or_b32_e32 v76, v76, v34
	v_or_b32_e32 v72, v72, v34
	v_or_b32_e32 v70, v70, v34
	v_or_b32_e32 v66, v66, v34
	v_or_b32_e32 v64, v64, v34
	v_or_b32_e32 v62, v62, v34
	v_or_b32_e32 v60, v60, v34
	v_or_b32_e32 v58, v58, v34
	v_mov_b32_e32 v34, 0
	s_waitcnt vmcnt(9)
	ds_write_b128 v124, v[50:53]
	s_waitcnt vmcnt(8)
	ds_write_b128 v124, v[54:57] offset:36864
	v_mul_u32_u24_e32 v127, 0x48, v35
	v_lshl_add_u64 v[98:99], s[12:13], 0, v[76:77]
	v_lshl_add_u64 v[100:101], s[14:15], 0, v[72:73]
	v_lshl_add_u64 v[102:103], s[12:13], 0, v[70:71]
	v_lshl_add_u64 v[104:105], s[14:15], 0, v[66:67]
	v_lshl_add_u64 v[106:107], s[12:13], 0, v[64:65]
	v_lshl_add_u64 v[108:109], s[14:15], 0, v[62:63]
	v_lshl_add_u64 v[110:111], s[12:13], 0, v[60:61]
	v_lshl_add_u64 v[112:113], s[14:15], 0, v[58:59]
	v_mov_b32_e32 v35, v34
	v_mov_b32_e32 v36, v34
	v_mov_b32_e32 v37, v34
	v_mov_b32_e32 v38, v34
	v_mov_b32_e32 v39, v34
	v_mov_b32_e32 v40, v34
	v_mov_b32_e32 v41, v34
	v_mov_b32_e32 v42, v34
	v_mov_b32_e32 v43, v34
	v_mov_b32_e32 v44, v34
	v_mov_b32_e32 v45, v34
	v_mov_b32_e32 v46, v34
	v_mov_b32_e32 v47, v34
	v_mov_b32_e32 v48, v34
	v_mov_b32_e32 v49, v34
	v_mov_b32_e32 v50, v34
	v_mov_b32_e32 v51, v34
	v_mov_b32_e32 v52, v34
	v_mov_b32_e32 v53, v34
	v_mov_b32_e32 v54, v34
	v_mov_b32_e32 v55, v34
	v_mov_b32_e32 v56, v34
	v_mov_b32_e32 v57, v34
	v_mov_b32_e32 v58, v34
	v_mov_b32_e32 v59, v34
	v_mov_b32_e32 v60, v34
	v_mov_b32_e32 v61, v34
	v_mov_b32_e32 v62, v34
	v_mov_b32_e32 v63, v34
	v_mov_b32_e32 v64, v34
	v_mov_b32_e32 v65, v34
	v_mov_b32_e32 v66, v34
	v_mov_b32_e32 v67, v34
	v_mov_b32_e32 v68, v34
	v_mov_b32_e32 v69, v34
	v_mov_b32_e32 v70, v34
	v_mov_b32_e32 v71, v34
	v_mov_b32_e32 v72, v34
	v_mov_b32_e32 v73, v34
	v_mov_b32_e32 v74, v34
	v_mov_b32_e32 v75, v34
	v_mov_b32_e32 v76, v34
	v_mov_b32_e32 v77, v34
	v_mov_b32_e32 v78, v34
	v_mov_b32_e32 v79, v34
	v_mov_b32_e32 v80, v34
	v_mov_b32_e32 v81, v34
	v_mov_b32_e32 v82, v34
	v_mov_b32_e32 v83, v34
	v_mov_b32_e32 v84, v34
	v_mov_b32_e32 v85, v34
	v_mov_b32_e32 v86, v34
	v_mov_b32_e32 v87, v34
	v_mov_b32_e32 v88, v34
	v_mov_b32_e32 v89, v34
	v_mov_b32_e32 v90, v34
	v_mov_b32_e32 v91, v34
	v_mov_b32_e32 v92, v34
	v_mov_b32_e32 v93, v34
	v_mov_b32_e32 v94, v34
	v_mov_b32_e32 v95, v34
	v_mov_b32_e32 v96, v34
	v_mov_b32_e32 v97, v34
	s_waitcnt lgkmcnt(0)
	s_barrier
; DEV f32x4 mfma16(bf16x8 a, bf16x8 b, f32x4 c) { return __builtin_amdgcn_mfma_f32_16x16x32_bf16(a, b, c, 0, 0, 0); }
; template <int EPI, bool AF32>
; DEV void gemm_tile(const void* Ap, int lda, const u16* Bt, int ldb, int K, int m0, int n0, const Epi& ea, char* smem) {
;     ...
;   for (int kt = 0; kt < nk; kt++) {
;     const int buf = kt & 1;
;     if (kt + 1 < nk) swrite(buf ^ 1);
;     if (kt + 2 < nk) gload(kt + 2);
; #pragma unroll
;     for (int ks = 0; ks < 2; ks++) {
;       bf16x8 a[4], b[4];
; #pragma unroll
;       for (int m = 0; m < 4; m++) a[m] = *(const bf16x8*)(sA + buf * 9216 + (wr * 64 + m * 16 + fr) * 72 + ks * 32 + fq * 8);
; #pragma unroll
;       for (int n = 0; n < 4; n++) b[n] = *(const bf16x8*)(sB + buf * 9216 + (wc * 64 + n * 16 + fr) * 72 + ks * 32 + fq * 8);
;       __builtin_amdgcn_s_setprio(1);
; #pragma unroll
;       for (int m = 0; m < 4; m++)
; #pragma unroll
;         for (int n = 0; n < 4; n++) acc[m][n] = mfma16(a[m], b[n], acc[m][n]);
;       __builtin_amdgcn_s_setprio(0);
;     }
;     __syncthreads();
;   }
	v_lshl_add_u32 v161, v128, 1, v125
	v_lshl_add_u32 v129, v127, 1, v125
	s_mov_b32 s19, 0
	s_mov_b64 s[0:1], 0x100
	ds_read_b128 v[130:133], v161
	ds_read_b128 v[134:137], v161 offset:2304
	ds_read_b128 v[138:141], v161 offset:4608
	ds_read_b128 v[142:145], v161 offset:6912
	ds_read_b128 v[146:149], v129 offset:36864
	ds_read_b128 v[150:153], v129 offset:39168
	ds_read_b128 v[162:165], v129 offset:41472
	ds_read_b128 v[166:169], v129 offset:43776
.Lgk3_loop:
	s_waitcnt lgkmcnt(0)
	ds_read_b128 v[222:225], v161 offset:64
	ds_read_b128 v[226:229], v161 offset:2368
	ds_read_b128 v[230:233], v161 offset:4672
	ds_read_b128 v[234:237], v161 offset:6976
	ds_read_b128 v[238:241], v129 offset:36928
	ds_read_b128 v[242:245], v129 offset:39232
	ds_read_b128 v[246:249], v129 offset:41536
	ds_read_b128 v[250:253], v129 offset:43840
	v_mfma_f32_16x16x32_bf16 v[34:37], v[130:133], v[146:149], v[34:37]
	v_mfma_f32_16x16x32_bf16 v[38:41], v[130:133], v[150:153], v[38:41]
	v_mfma_f32_16x16x32_bf16 v[42:45], v[130:133], v[162:165], v[42:45]
	v_mfma_f32_16x16x32_bf16 v[46:49], v[130:133], v[166:169], v[46:49]
	s_waitcnt vmcnt(0)
	ds_write_b128 v122, v[22:25] offset:18432
	ds_write_b128 v122, v[6:9] offset:55296
	v_mfma_f32_16x16x32_bf16 v[50:53], v[134:137], v[146:149], v[50:53]
	ds_write_b128 v121, v[18:21] offset:18432
	ds_write_b128 v121, v[10:13] offset:55296
	v_mfma_f32_16x16x32_bf16 v[54:57], v[134:137], v[150:153], v[54:57]
	ds_write_b128 v120, v[14:17] offset:18432
	ds_write_b128 v120, v[2:5] offset:55296
	v_mfma_f32_16x16x32_bf16 v[58:61], v[134:137], v[162:165], v[58:61]
	ds_write_b128 v124, v[26:29] offset:18432
	ds_write_b128 v124, v[30:33] offset:55296
	v_mfma_f32_16x16x32_bf16 v[62:65], v[134:137], v[166:169], v[62:65]
	global_load_dwordx4 v[22:25], v[112:113], off
	v_mfma_f32_16x16x32_bf16 v[66:69], v[138:141], v[146:149], v[66:69]
	global_load_dwordx4 v[6:9], v[110:111], off
	v_mfma_f32_16x16x32_bf16 v[70:73], v[138:141], v[150:153], v[70:73]
	global_load_dwordx4 v[18:21], v[108:109], off
	v_mfma_f32_16x16x32_bf16 v[74:77], v[138:141], v[162:165], v[74:77]
	global_load_dwordx4 v[10:13], v[106:107], off
	v_mfma_f32_16x16x32_bf16 v[78:81], v[138:141], v[166:169], v[78:81]
	global_load_dwordx4 v[14:17], v[104:105], off
	v_mfma_f32_16x16x32_bf16 v[82:85], v[142:145], v[146:149], v[82:85]
	global_load_dwordx4 v[2:5], v[102:103], off
	v_mfma_f32_16x16x32_bf16 v[86:89], v[142:145], v[150:153], v[86:89]
	global_load_dwordx4 v[26:29], v[100:101], off
	v_mfma_f32_16x16x32_bf16 v[90:93], v[142:145], v[162:165], v[90:93]
	global_load_dwordx4 v[30:33], v[98:99], off
	v_mfma_f32_16x16x32_bf16 v[94:97], v[142:145], v[166:169], v[94:97]
	s_waitcnt lgkmcnt(0)
	s_barrier
	ds_read_b128 v[130:133], v161 offset:18432
	v_mfma_f32_16x16x32_bf16 v[34:37], v[222:225], v[238:241], v[34:37]
	ds_read_b128 v[134:137], v161 offset:20736
	v_mfma_f32_16x16x32_bf16 v[38:41], v[222:225], v[242:245], v[38:41]
	ds_read_b128 v[138:141], v161 offset:23040
	v_mfma_f32_16x16x32_bf16 v[42:45], v[222:225], v[246:249], v[42:45]
	ds_read_b128 v[142:145], v161 offset:25344
	v_mfma_f32_16x16x32_bf16 v[46:49], v[222:225], v[250:253], v[46:49]
	ds_read_b128 v[146:149], v129 offset:55296
	v_mfma_f32_16x16x32_bf16 v[50:53], v[226:229], v[238:241], v[50:53]
	ds_read_b128 v[150:153], v129 offset:57600
	v_mfma_f32_16x16x32_bf16 v[54:57], v[226:229], v[242:245], v[54:57]
	ds_read_b128 v[162:165], v129 offset:59904
	v_mfma_f32_16x16x32_bf16 v[58:61], v[226:229], v[246:249], v[58:61]
	ds_read_b128 v[166:169], v129 offset:62208
	v_mfma_f32_16x16x32_bf16 v[62:65], v[226:229], v[250:253], v[62:65]
	v_mfma_f32_16x16x32_bf16 v[66:69], v[230:233], v[238:241], v[66:69]
	v_mfma_f32_16x16x32_bf16 v[70:73], v[230:233], v[242:245], v[70:73]
	v_mfma_f32_16x16x32_bf16 v[74:77], v[230:233], v[246:249], v[74:77]
	v_mfma_f32_16x16x32_bf16 v[78:81], v[230:233], v[250:253], v[78:81]
	v_mfma_f32_16x16x32_bf16 v[82:85], v[234:237], v[238:241], v[82:85]
	v_mfma_f32_16x16x32_bf16 v[86:89], v[234:237], v[242:245], v[86:89]
	v_mfma_f32_16x16x32_bf16 v[90:93], v[234:237], v[246:249], v[90:93]
	v_mfma_f32_16x16x32_bf16 v[94:97], v[234:237], v[250:253], v[94:97]
	s_waitcnt lgkmcnt(0)
	ds_read_b128 v[222:225], v161 offset:18496
	ds_read_b128 v[226:229], v161 offset:20800
	ds_read_b128 v[230:233], v161 offset:23104
	ds_read_b128 v[234:237], v161 offset:25408
	ds_read_b128 v[238:241], v129 offset:55360
	ds_read_b128 v[242:245], v129 offset:57664
	ds_read_b128 v[246:249], v129 offset:59968
	ds_read_b128 v[250:253], v129 offset:62272
	v_mfma_f32_16x16x32_bf16 v[34:37], v[130:133], v[146:149], v[34:37]
	v_mfma_f32_16x16x32_bf16 v[38:41], v[130:133], v[150:153], v[38:41]
	v_mfma_f32_16x16x32_bf16 v[42:45], v[130:133], v[162:165], v[42:45]
	v_mfma_f32_16x16x32_bf16 v[46:49], v[130:133], v[166:169], v[46:49]
	s_waitcnt vmcnt(0)
	ds_write_b128 v122, v[22:25]
	ds_write_b128 v122, v[6:9] offset:36864
	v_mfma_f32_16x16x32_bf16 v[50:53], v[134:137], v[146:149], v[50:53]
	ds_write_b128 v121, v[18:21]
	ds_write_b128 v121, v[10:13] offset:36864
	v_mfma_f32_16x16x32_bf16 v[54:57], v[134:137], v[150:153], v[54:57]
	ds_write_b128 v120, v[14:17]
	ds_write_b128 v120, v[2:5] offset:36864
	v_mfma_f32_16x16x32_bf16 v[58:61], v[134:137], v[162:165], v[58:61]
	ds_write_b128 v124, v[26:29]
	ds_write_b128 v124, v[30:33] offset:36864
	v_mfma_f32_16x16x32_bf16 v[62:65], v[134:137], v[166:169], v[62:65]
	global_load_dwordx4 v[22:25], v[112:113], off offset:128
	v_mfma_f32_16x16x32_bf16 v[66:69], v[138:141], v[146:149], v[66:69]
	global_load_dwordx4 v[6:9], v[110:111], off offset:128
	v_mfma_f32_16x16x32_bf16 v[70:73], v[138:141], v[150:153], v[70:73]
	global_load_dwordx4 v[18:21], v[108:109], off offset:128
	v_mfma_f32_16x16x32_bf16 v[74:77], v[138:141], v[162:165], v[74:77]
	global_load_dwordx4 v[10:13], v[106:107], off offset:128
	v_mfma_f32_16x16x32_bf16 v[78:81], v[138:141], v[166:169], v[78:81]
	global_load_dwordx4 v[14:17], v[104:105], off offset:128
	v_mfma_f32_16x16x32_bf16 v[82:85], v[142:145], v[146:149], v[82:85]
	global_load_dwordx4 v[2:5], v[102:103], off offset:128
	v_mfma_f32_16x16x32_bf16 v[86:89], v[142:145], v[150:153], v[86:89]
	global_load_dwordx4 v[26:29], v[100:101], off offset:128
	v_mfma_f32_16x16x32_bf16 v[90:93], v[142:145], v[162:165], v[90:93]
	global_load_dwordx4 v[30:33], v[98:99], off offset:128
	v_mfma_f32_16x16x32_bf16 v[94:97], v[142:145], v[166:169], v[94:97]
	s_waitcnt lgkmcnt(0)
	s_barrier
; DEV f32x4 mfma16(bf16x8 a, bf16x8 b, f32x4 c) { return __builtin_amdgcn_mfma_f32_16x16x32_bf16(a, b, c, 0, 0, 0); }
; template <int EPI, bool AF32>
; DEV void gemm_tile(const void* Ap, int lda, const u16* Bt, int ldb, int K, int m0, int n0, const Epi& ea, char* smem) {
;     ...
;   for (int kt = 0; kt < nk; kt++) {
;     const int buf = kt & 1;
;     if (kt + 1 < nk) swrite(buf ^ 1);
;     if (kt + 2 < nk) gload(kt + 2);
; #pragma unroll
;     for (int ks = 0; ks < 2; ks++) {
;       bf16x8 a[4], b[4];
; #pragma unroll
;       for (int m = 0; m < 4; m++) a[m] = *(const bf16x8*)(sA + buf * 9216 + (wr * 64 + m * 16 + fr) * 72 + ks * 32 + fq * 8);
; #pragma unroll
;       for (int n = 0; n < 4; n++) b[n] = *(const bf16x8*)(sB + buf * 9216 + (wc * 64 + n * 16 + fr) * 72 + ks * 32 + fq * 8);
;       __builtin_amdgcn_s_setprio(1);
; #pragma unroll
;       for (int m = 0; m < 4; m++)
; #pragma unroll
;         for (int n = 0; n < 4; n++) acc[m][n] = mfma16(a[m], b[n], acc[m][n]);
;       __builtin_amdgcn_s_setprio(0);
;     }
;     __syncthreads();
;   }
	ds_read_b128 v[130:133], v161
	v_mfma_f32_16x16x32_bf16 v[34:37], v[222:225], v[238:241], v[34:37]
	ds_read_b128 v[134:137], v161 offset:2304
	v_mfma_f32_16x16x32_bf16 v[38:41], v[222:225], v[242:245], v[38:41]
	ds_read_b128 v[138:141], v161 offset:4608
	v_mfma_f32_16x16x32_bf16 v[42:45], v[222:225], v[246:249], v[42:45]
	ds_read_b128 v[142:145], v161 offset:6912
	v_mfma_f32_16x16x32_bf16 v[46:49], v[222:225], v[250:253], v[46:49]
	ds_read_b128 v[146:149], v129 offset:36864
	v_mfma_f32_16x16x32_bf16 v[50:53], v[226:229], v[238:241], v[50:53]
	ds_read_b128 v[150:153], v129 offset:39168
	v_mfma_f32_16x16x32_bf16 v[54:57], v[226:229], v[242:245], v[54:57]
	ds_read_b128 v[162:165], v129 offset:41472
	v_mfma_f32_16x16x32_bf16 v[58:61], v[226:229], v[246:249], v[58:61]
	ds_read_b128 v[166:169], v129 offset:43776
	v_mfma_f32_16x16x32_bf16 v[62:65], v[226:229], v[250:253], v[62:65]
	v_mfma_f32_16x16x32_bf16 v[66:69], v[230:233], v[238:241], v[66:69]
	v_lshl_add_u64 v[112:113], v[112:113], 0, s[0:1]
	v_mfma_f32_16x16x32_bf16 v[70:73], v[230:233], v[242:245], v[70:73]
	v_lshl_add_u64 v[110:111], v[110:111], 0, s[0:1]
	v_mfma_f32_16x16x32_bf16 v[74:77], v[230:233], v[246:249], v[74:77]
	v_lshl_add_u64 v[108:109], v[108:109], 0, s[0:1]
	v_mfma_f32_16x16x32_bf16 v[78:81], v[230:233], v[250:253], v[78:81]
	v_lshl_add_u64 v[106:107], v[106:107], 0, s[0:1]
	v_mfma_f32_16x16x32_bf16 v[82:85], v[234:237], v[238:241], v[82:85]
	v_lshl_add_u64 v[104:105], v[104:105], 0, s[0:1]
	v_mfma_f32_16x16x32_bf16 v[86:89], v[234:237], v[242:245], v[86:89]
	v_lshl_add_u64 v[102:103], v[102:103], 0, s[0:1]
	v_mfma_f32_16x16x32_bf16 v[90:93], v[234:237], v[246:249], v[90:93]
	v_lshl_add_u64 v[100:101], v[100:101], 0, s[0:1]
	v_mfma_f32_16x16x32_bf16 v[94:97], v[234:237], v[250:253], v[94:97]
	v_lshl_add_u64 v[98:99], v[98:99], 0, s[0:1]
	s_add_i32 s19, s19, 1
	s_cmp_lg_u32 s19, 7
	s_cbranch_scc1 .Lgk3_loop
	s_waitcnt vmcnt(7)
	ds_write_b128 v122, v[22:25] offset:18432
	s_waitcnt vmcnt(6)
	ds_write_b128 v122, v[6:9] offset:55296
	s_waitcnt vmcnt(5)
	ds_write_b128 v121, v[18:21] offset:18432
	s_waitcnt vmcnt(4)
	ds_write_b128 v121, v[10:13] offset:55296
	s_waitcnt vmcnt(3)
	ds_write_b128 v120, v[14:17] offset:18432
	s_waitcnt vmcnt(2)
	ds_write_b128 v120, v[2:5] offset:55296
	s_waitcnt vmcnt(1)
	ds_write_b128 v124, v[26:29] offset:18432
	s_waitcnt vmcnt(0)
	ds_write_b128 v124, v[30:33] offset:55296
	v_lshl_add_u32 v0, v128, 1, v125
	v_lshl_add_u32 v110, v127, 1, v125
	ds_read_b128 v[2:5], v0
	ds_read_b128 v[6:9], v0 offset:2304
	ds_read_b128 v[10:13], v0 offset:4608
	ds_read_b128 v[14:17], v0 offset:6912
	ds_read_b128 v[18:21], v110 offset:36864
	ds_read_b128 v[22:25], v110 offset:39168
	ds_read_b128 v[26:29], v110 offset:41472
	ds_read_b128 v[30:33], v110 offset:43776
	s_setprio 1
	s_waitcnt lgkmcnt(3)
	v_mfma_f32_16x16x32_bf16 v[34:37], v[2:5], v[18:21], v[34:37]
	s_waitcnt lgkmcnt(2)
	v_mfma_f32_16x16x32_bf16 v[38:41], v[2:5], v[22:25], v[38:41]
	s_waitcnt lgkmcnt(1)
	v_mfma_f32_16x16x32_bf16 v[42:45], v[2:5], v[26:29], v[42:45]
	s_waitcnt lgkmcnt(0)
	v_mfma_f32_16x16x32_bf16 v[2:5], v[2:5], v[30:33], v[46:49]
	v_mfma_f32_16x16x32_bf16 v[46:49], v[6:9], v[18:21], v[50:53]
	v_mfma_f32_16x16x32_bf16 v[50:53], v[6:9], v[22:25], v[54:57]
	v_mfma_f32_16x16x32_bf16 v[54:57], v[6:9], v[26:29], v[58:61]
	v_mfma_f32_16x16x32_bf16 v[6:9], v[6:9], v[30:33], v[62:65]
	v_mfma_f32_16x16x32_bf16 v[58:61], v[10:13], v[18:21], v[66:69]
	v_mfma_f32_16x16x32_bf16 v[62:65], v[10:13], v[22:25], v[70:73]
	v_mfma_f32_16x16x32_bf16 v[66:69], v[10:13], v[26:29], v[74:77]
	v_mfma_f32_16x16x32_bf16 v[10:13], v[10:13], v[30:33], v[78:81]
	v_mfma_f32_16x16x32_bf16 v[18:21], v[14:17], v[18:21], v[82:85]
	v_mfma_f32_16x16x32_bf16 v[22:25], v[14:17], v[22:25], v[86:89]
	v_mfma_f32_16x16x32_bf16 v[26:29], v[14:17], v[26:29], v[90:93]
	v_mfma_f32_16x16x32_bf16 v[14:17], v[14:17], v[30:33], v[94:97]
	s_setprio 0
	ds_read_b128 v[30:33], v0 offset:64
	ds_read_b128 v[70:73], v0 offset:2368
	ds_read_b128 v[74:77], v0 offset:4672
	ds_read_b128 v[78:81], v0 offset:6976
	ds_read_b128 v[82:85], v110 offset:36928
	ds_read_b128 v[86:89], v110 offset:39232
	ds_read_b128 v[90:93], v110 offset:41536
	ds_read_b128 v[94:97], v110 offset:43840
	s_setprio 1
	s_waitcnt lgkmcnt(3)
	v_mfma_f32_16x16x32_bf16 v[34:37], v[30:33], v[82:85], v[34:37]
	s_waitcnt lgkmcnt(2)
	v_mfma_f32_16x16x32_bf16 v[38:41], v[30:33], v[86:89], v[38:41]
	s_waitcnt lgkmcnt(1)
	v_mfma_f32_16x16x32_bf16 v[42:45], v[30:33], v[90:93], v[42:45]
	s_waitcnt lgkmcnt(0)
	v_mfma_f32_16x16x32_bf16 v[2:5], v[30:33], v[94:97], v[2:5]
	v_mfma_f32_16x16x32_bf16 v[30:33], v[70:73], v[82:85], v[46:49]
	v_mfma_f32_16x16x32_bf16 v[46:49], v[70:73], v[86:89], v[50:53]
	v_mfma_f32_16x16x32_bf16 v[50:53], v[70:73], v[90:93], v[54:57]
	v_mfma_f32_16x16x32_bf16 v[6:9], v[70:73], v[94:97], v[6:9]
	v_mfma_f32_16x16x32_bf16 v[54:57], v[74:77], v[82:85], v[58:61]
	v_mfma_f32_16x16x32_bf16 v[58:61], v[74:77], v[86:89], v[62:65]
	v_mfma_f32_16x16x32_bf16 v[62:65], v[74:77], v[90:93], v[66:69]
	v_mfma_f32_16x16x32_bf16 v[10:13], v[74:77], v[94:97], v[10:13]
	v_mfma_f32_16x16x32_bf16 v[18:21], v[78:81], v[82:85], v[18:21]
	v_mfma_f32_16x16x32_bf16 v[22:25], v[78:81], v[86:89], v[22:25]
	v_mfma_f32_16x16x32_bf16 v[26:29], v[78:81], v[90:93], v[26:29]
	v_mfma_f32_16x16x32_bf16 v[14:17], v[78:81], v[94:97], v[14:17]
	s_setprio 0
	s_barrier
; DEV f32x4 mfma16(bf16x8 a, bf16x8 b, f32x4 c) { return __builtin_amdgcn_mfma_f32_16x16x32_bf16(a, b, c, 0, 0, 0); }
; template <int EPI, bool AF32>
; DEV void gemm_tile(const void* Ap, int lda, const u16* Bt, int ldb, int K, int m0, int n0, const Epi& ea, char* smem) {
;     ...
;     for (int ks = 0; ks < 2; ks++) {
;       bf16x8 a[4], b[4];
; #pragma unroll
;       for (int m = 0; m < 4; m++) a[m] = *(const bf16x8*)(sA + buf * 9216 + (wr * 64 + m * 16 + fr) * 72 + ks * 32 + fq * 8);
; #pragma unroll
;       for (int n = 0; n < 4; n++) b[n] = *(const bf16x8*)(sB + buf * 9216 + (wc * 64 + n * 16 + fr) * 72 + ks * 32 + fq * 8);
;       __builtin_amdgcn_s_setprio(1);
; #pragma unroll
;       for (int m = 0; m < 4; m++)
; #pragma unroll
;         for (int n = 0; n < 4; n++) acc[m][n] = mfma16(a[m], b[n], acc[m][n]);
;       __builtin_amdgcn_s_setprio(0);
;     }
;     __syncthreads();
;   }
;     ...
;       u16* C = (u16*)ea.p0;
;       const u16* G = (const u16*)ea.p1 + (EPI == EP_MERGE2 ? 1024 : 0);
;       u16 gv[4][4][4], cv[4][4][4];
; #pragma unroll
;       for (int m = 0; m < 4; m++)
; #pragma unroll
;         for (int j = 0; j < 4; j++)
; #pragma unroll
;           for (int n = 0; n < 4; n++) {
;             gv[m][j][n] = G[(size_t)(rbase + m * 16 + j) * 2048 + cbase + n * 16];
;             if (EPI == EP_MERGE2) cv[m][j][n] = C[(size_t)(rbase + m * 16 + j) * 1024 + cbase + n * 16];
;           }
	ds_read_b128 v[66:69], v0 offset:18432
	ds_read_b128 v[70:73], v0 offset:20736
	ds_read_b128 v[74:77], v0 offset:23040
	ds_read_b128 v[78:81], v0 offset:25344
	ds_read_b128 v[82:85], v110 offset:55296
	ds_read_b128 v[86:89], v110 offset:57600
	ds_read_b128 v[90:93], v110 offset:59904
	ds_read_b128 v[94:97], v110 offset:62208
	v_and_b32_e32 v114, 64, v114
	s_setprio 1
	s_waitcnt lgkmcnt(3)
	v_mfma_f32_16x16x32_bf16 v[34:37], v[66:69], v[82:85], v[34:37]
	s_waitcnt lgkmcnt(2)
	v_mfma_f32_16x16x32_bf16 v[38:41], v[66:69], v[86:89], v[38:41]
	s_waitcnt lgkmcnt(1)
	v_mfma_f32_16x16x32_bf16 v[42:45], v[66:69], v[90:93], v[42:45]
	s_waitcnt lgkmcnt(0)
	v_mfma_f32_16x16x32_bf16 v[2:5], v[66:69], v[94:97], v[2:5]
	v_mfma_f32_16x16x32_bf16 v[30:33], v[70:73], v[82:85], v[30:33]
	v_mfma_f32_16x16x32_bf16 v[66:69], v[70:73], v[86:89], v[46:49]
	v_mfma_f32_16x16x32_bf16 v[98:101], v[70:73], v[90:93], v[50:53]
	v_mfma_f32_16x16x32_bf16 v[6:9], v[70:73], v[94:97], v[6:9]
	v_mfma_f32_16x16x32_bf16 v[54:57], v[74:77], v[82:85], v[54:57]
	v_mfma_f32_16x16x32_bf16 v[58:61], v[74:77], v[86:89], v[58:61]
	v_mfma_f32_16x16x32_bf16 v[62:65], v[74:77], v[90:93], v[62:65]
	v_mfma_f32_16x16x32_bf16 v[10:13], v[74:77], v[94:97], v[10:13]
	v_mfma_f32_16x16x32_bf16 v[70:73], v[78:81], v[82:85], v[18:21]
	v_mfma_f32_16x16x32_bf16 v[74:77], v[78:81], v[86:89], v[22:25]
	v_mfma_f32_16x16x32_bf16 v[82:85], v[78:81], v[90:93], v[26:29]
	v_mfma_f32_16x16x32_bf16 v[78:81], v[78:81], v[94:97], v[14:17]
	s_setprio 0
	s_nop 1
	ds_read_b128 v[14:17], v0 offset:18496
	ds_read_b128 v[18:21], v0 offset:20800
	ds_read_b128 v[86:89], v0 offset:23104
	ds_read_b128 v[90:93], v0 offset:25408
	ds_read_b128 v[94:97], v110 offset:55360
	ds_read_b128 v[102:105], v110 offset:57664
	ds_read_b128 v[106:109], v110 offset:59968
	ds_read_b128 v[110:113], v110 offset:62272
	s_setprio 1
	s_waitcnt lgkmcnt(3)
	v_mfma_f32_16x16x32_bf16 v[118:121], v[14:17], v[94:97], v[34:37]
	s_waitcnt lgkmcnt(2)
	v_mfma_f32_16x16x32_bf16 v[122:125], v[14:17], v[102:105], v[38:41]
	s_waitcnt lgkmcnt(1)
	v_mfma_f32_16x16x32_bf16 v[126:129], v[14:17], v[106:109], v[42:45]
	s_waitcnt lgkmcnt(0)
	v_mfma_f32_16x16x32_bf16 v[50:53], v[14:17], v[110:113], v[2:5]
	v_mfma_f32_16x16x32_bf16 v[46:49], v[18:21], v[94:97], v[30:33]
	v_mfma_f32_16x16x32_bf16 v[42:45], v[18:21], v[102:105], v[66:69]
	v_mfma_f32_16x16x32_bf16 v[38:41], v[18:21], v[106:109], v[98:101]
	v_mfma_f32_16x16x32_bf16 v[34:37], v[18:21], v[110:113], v[6:9]
	v_mfma_f32_16x16x32_bf16 v[30:33], v[86:89], v[94:97], v[54:57]
	v_mfma_f32_16x16x32_bf16 v[26:29], v[86:89], v[102:105], v[58:61]
	v_mfma_f32_16x16x32_bf16 v[22:25], v[86:89], v[106:109], v[62:65]
	v_mfma_f32_16x16x32_bf16 v[18:21], v[86:89], v[110:113], v[10:13]
	v_mfma_f32_16x16x32_bf16 v[14:17], v[90:93], v[94:97], v[70:73]
	v_mfma_f32_16x16x32_bf16 v[10:13], v[90:93], v[102:105], v[74:77]
	v_mfma_f32_16x16x32_bf16 v[6:9], v[90:93], v[106:109], v[82:85]
	v_mfma_f32_16x16x32_bf16 v[2:5], v[90:93], v[110:113], v[78:81]
	s_setprio 0
	v_add_u32_e32 v0, s18, v117
	v_or3_b32 v54, v114, s17, v115
	v_lshl_or_b32 v72, v116, 2, v0
	v_ashrrev_i32_e32 v55, 31, v54
	v_lshlrev_b64 v[66:67], 1, v[54:55]
	v_ashrrev_i32_e32 v73, 31, v72
	v_or_b32_e32 v78, 1, v72
	v_lshl_add_u64 v[74:75], s[4:5], 0, v[66:67]
	v_lshlrev_b64 v[54:55], 12, v[72:73]
	v_ashrrev_i32_e32 v79, 31, v78
	v_or_b32_e32 v82, 2, v72
	v_lshl_add_u64 v[76:77], v[74:75], 0, v[54:55]
	v_lshlrev_b64 v[54:55], 12, v[78:79]
	v_ashrrev_i32_e32 v83, 31, v82
	v_or_b32_e32 v86, 3, v72
	v_lshl_add_u64 v[80:81], v[74:75], 0, v[54:55]
	v_lshlrev_b64 v[54:55], 12, v[82:83]
	v_ashrrev_i32_e32 v87, 31, v86
	v_or_b32_e32 v90, 16, v72
	v_lshl_add_u64 v[84:85], v[74:75], 0, v[54:55]
	v_lshlrev_b64 v[54:55], 12, v[86:87]
	v_ashrrev_i32_e32 v91, 31, v90
	v_or_b32_e32 v94, 17, v72
	v_lshl_add_u64 v[88:89], v[74:75], 0, v[54:55]
	v_lshlrev_b64 v[54:55], 12, v[90:91]
	v_ashrrev_i32_e32 v95, 31, v94
	v_or_b32_e32 v98, 18, v72
	v_lshl_add_u64 v[92:93], v[74:75], 0, v[54:55]
	v_lshlrev_b64 v[54:55], 12, v[94:95]
	v_ashrrev_i32_e32 v99, 31, v98
	v_or_b32_e32 v102, 19, v72
	v_lshl_add_u64 v[96:97], v[74:75], 0, v[54:55]
	v_lshlrev_b64 v[54:55], 12, v[98:99]
	v_ashrrev_i32_e32 v103, 31, v102
	v_or_b32_e32 v70, 32, v72
	v_lshl_add_u64 v[100:101], v[74:75], 0, v[54:55]
	v_lshlrev_b64 v[54:55], 12, v[102:103]
	v_ashrrev_i32_e32 v71, 31, v70
	v_or_b32_e32 v68, 33, v72
	v_lshl_add_u64 v[104:105], v[74:75], 0, v[54:55]
	v_lshlrev_b64 v[54:55], 12, v[70:71]
	v_ashrrev_i32_e32 v69, 31, v68
	v_or_b32_e32 v64, 34, v72
	v_lshl_add_u64 v[106:107], v[74:75], 0, v[54:55]
	v_lshlrev_b64 v[54:55], 12, v[68:69]
	v_ashrrev_i32_e32 v65, 31, v64
	v_or_b32_e32 v62, 35, v72
	v_lshl_add_u64 v[108:109], v[74:75], 0, v[54:55]
	v_lshlrev_b64 v[54:55], 12, v[64:65]
	v_ashrrev_i32_e32 v63, 31, v62
	v_or_b32_e32 v60, 48, v72
	v_lshl_add_u64 v[110:111], v[74:75], 0, v[54:55]
	v_lshlrev_b64 v[54:55], 12, v[62:63]
	v_ashrrev_i32_e32 v61, 31, v60
	v_or_b32_e32 v58, 49, v72
	v_lshl_add_u64 v[112:113], v[74:75], 0, v[54:55]
	v_lshlrev_b64 v[54:55], 12, v[60:61]
	v_ashrrev_i32_e32 v59, 31, v58
	v_or_b32_e32 v56, 50, v72
	v_lshl_add_u64 v[114:115], v[74:75], 0, v[54:55]
	v_lshlrev_b64 v[54:55], 12, v[58:59]
	v_ashrrev_i32_e32 v57, 31, v56
	v_lshl_add_u64 v[116:117], v[74:75], 0, v[54:55]
	v_lshlrev_b64 v[54:55], 12, v[56:57]
	v_lshl_add_u64 v[130:131], v[74:75], 0, v[54:55]
	v_or_b32_e32 v54, 51, v72
	v_ashrrev_i32_e32 v55, 31, v54
	v_lshlrev_b64 v[132:133], 12, v[54:55]
	v_lshl_add_u64 v[74:75], v[74:75], 0, v[132:133]
	s_barrier
; DEV float bf2f(u16 h) { return __uint_as_float(((unsigned)h) << 16); }
; template <int EPI, bool AF32>
; DEV void gemm_tile(const void* Ap, int lda, const u16* Bt, int ldb, int K, int m0, int n0, const Epi& ea, char* smem) {
;     ...
;       u16* C = (u16*)ea.p0;
;       const u16* G = (const u16*)ea.p1 + (EPI == EP_MERGE2 ? 1024 : 0);
;       u16 gv[4][4][4], cv[4][4][4];
; #pragma unroll
;       for (int m = 0; m < 4; m++)
; #pragma unroll
;         for (int j = 0; j < 4; j++)
; #pragma unroll
;           for (int n = 0; n < 4; n++) {
;             gv[m][j][n] = G[(size_t)(rbase + m * 16 + j) * 2048 + cbase + n * 16];
;             if (EPI == EP_MERGE2) cv[m][j][n] = C[(size_t)(rbase + m * 16 + j) * 1024 + cbase + n * 16];
;           }
;       __builtin_amdgcn_sched_barrier(0);
; #pragma unroll
;       for (int m = 0; m < 4; m++)
; #pragma unroll
;         for (int j = 0; j < 4; j++)
; #pragma unroll
;           for (int n = 0; n < 4; n++) {
;             float v = bf2f(gv[m][j][n]) * acc[m][n][j];
;             if (EPI == EP_MERGE2) v += bf2f(cv[m][j][n]);
;             C[(size_t)(rbase + m * 16 + j) * 1024 + cbase + n * 16] = f2bf(v);
	global_load_ushort v0, v[76:77], off
	global_load_ushort v132, v[76:77], off offset:32
	global_load_ushort v133, v[76:77], off offset:64
	s_nop 0
	global_load_ushort v76, v[76:77], off offset:96
	s_nop 0
	global_load_ushort v77, v[80:81], off
	global_load_ushort v134, v[80:81], off offset:32
	global_load_ushort v135, v[80:81], off offset:64
	s_nop 0
	global_load_ushort v80, v[80:81], off offset:96
	s_nop 0
	global_load_ushort v81, v[84:85], off
	global_load_ushort v136, v[84:85], off offset:32
	global_load_ushort v137, v[84:85], off offset:64
	s_nop 0
	global_load_ushort v84, v[84:85], off offset:96
	s_nop 0
	global_load_ushort v85, v[88:89], off
	global_load_ushort v138, v[88:89], off offset:32
	global_load_ushort v139, v[88:89], off offset:64
	s_nop 0
	global_load_ushort v88, v[88:89], off offset:96
	s_nop 0
	global_load_ushort v89, v[92:93], off
	global_load_ushort v140, v[92:93], off offset:32
	global_load_ushort v141, v[92:93], off offset:64
	s_nop 0
	global_load_ushort v92, v[92:93], off offset:96
	s_nop 0
	global_load_ushort v93, v[96:97], off
	global_load_ushort v142, v[96:97], off offset:32
	global_load_ushort v143, v[96:97], off offset:64
	s_nop 0
	global_load_ushort v96, v[96:97], off offset:96
	s_nop 0
	global_load_ushort v97, v[100:101], off
	global_load_ushort v144, v[100:101], off offset:32
	global_load_ushort v145, v[100:101], off offset:64
	s_nop 0
	global_load_ushort v100, v[100:101], off offset:96
	s_nop 0
	global_load_ushort v101, v[104:105], off
	global_load_ushort v146, v[104:105], off offset:32
	global_load_ushort v147, v[104:105], off offset:64
	s_nop 0
	global_load_ushort v104, v[104:105], off offset:96
	s_nop 0
	global_load_ushort v105, v[106:107], off
	global_load_ushort v148, v[106:107], off offset:32
	global_load_ushort v149, v[106:107], off offset:64
	s_nop 0
	global_load_ushort v106, v[106:107], off offset:96
	s_nop 0
	global_load_ushort v107, v[108:109], off
	global_load_ushort v150, v[108:109], off offset:32
	global_load_ushort v151, v[108:109], off offset:64
	s_nop 0
	global_load_ushort v108, v[108:109], off offset:96
	s_nop 0
	global_load_ushort v109, v[110:111], off
	global_load_ushort v152, v[110:111], off offset:32
	global_load_ushort v153, v[110:111], off offset:64
	s_nop 0
	global_load_ushort v110, v[110:111], off offset:96
	s_nop 0
	global_load_ushort v111, v[112:113], off
	global_load_ushort v161, v[112:113], off offset:32
	global_load_ushort v162, v[112:113], off offset:64
	s_nop 0
	global_load_ushort v112, v[112:113], off offset:96
	s_nop 0
	global_load_ushort v113, v[114:115], off
	global_load_ushort v163, v[114:115], off offset:32
	global_load_ushort v164, v[114:115], off offset:64
	s_nop 0
	global_load_ushort v114, v[114:115], off offset:96
	s_nop 0
	global_load_ushort v115, v[116:117], off
	global_load_ushort v165, v[116:117], off offset:32
	global_load_ushort v166, v[116:117], off offset:64
	s_nop 0
	global_load_ushort v116, v[116:117], off offset:96
	s_nop 0
	global_load_ushort v117, v[130:131], off
	global_load_ushort v167, v[130:131], off offset:32
	global_load_ushort v168, v[130:131], off offset:64
	s_nop 0
	global_load_ushort v130, v[130:131], off offset:96
	s_nop 0
	global_load_ushort v131, v[74:75], off
	global_load_ushort v169, v[74:75], off offset:32
	global_load_ushort v170, v[74:75], off offset:64
	s_nop 0
	global_load_ushort v74, v[74:75], off offset:96
	s_waitcnt vmcnt(62)
	v_lshlrev_b32_e32 v0, 16, v0
	v_lshl_add_u64 v[66:67], s[2:3], 0, v[66:67]
	v_lshlrev_b64 v[72:73], 11, v[72:73]
	v_mul_f32_e32 v0, v118, v0
	v_lshl_add_u64 v[72:73], v[66:67], 0, v[72:73]
	v_cvt_pk_bf16_f32 v0, v0, s0
	global_store_short v[72:73], v0, off
	v_lshlrev_b32_e32 v0, 16, v132
	v_mul_f32_e32 v0, v122, v0
	v_cvt_pk_bf16_f32 v0, v0, s0
	global_store_short v[72:73], v0, off offset:32
	s_waitcnt vmcnt(62)
	v_lshlrev_b32_e32 v0, 16, v133
	v_mul_f32_e32 v0, v126, v0
	v_cvt_pk_bf16_f32 v0, v0, s0
	global_store_short v[72:73], v0, off offset:64
	v_lshlrev_b32_e32 v0, 16, v76
	v_mul_f32_e32 v0, v50, v0
	v_cvt_pk_bf16_f32 v0, v0, s0
	global_store_short v[72:73], v0, off offset:96
	s_waitcnt vmcnt(62)
	v_lshlrev_b32_e32 v0, 16, v77
	v_lshlrev_b64 v[72:73], 11, v[78:79]
	v_mul_f32_e32 v0, v119, v0
	v_lshl_add_u64 v[72:73], v[66:67], 0, v[72:73]
	v_cvt_pk_bf16_f32 v0, v0, s0
	global_store_short v[72:73], v0, off
	v_lshlrev_b32_e32 v0, 16, v134
	v_mul_f32_e32 v0, v123, v0
	v_cvt_pk_bf16_f32 v0, v0, s0
	global_store_short v[72:73], v0, off offset:32
	s_waitcnt vmcnt(62)
	v_lshlrev_b32_e32 v0, 16, v135
	v_mul_f32_e32 v0, v127, v0
	v_cvt_pk_bf16_f32 v0, v0, s0
	global_store_short v[72:73], v0, off offset:64
	v_lshlrev_b32_e32 v0, 16, v80
	v_mul_f32_e32 v0, v51, v0
	v_cvt_pk_bf16_f32 v0, v0, s0
	global_store_short v[72:73], v0, off offset:96
	s_waitcnt vmcnt(62)
	v_lshlrev_b32_e32 v0, 16, v81
	v_lshlrev_b64 v[50:51], 11, v[82:83]
	v_mul_f32_e32 v0, v120, v0
	v_lshl_add_u64 v[50:51], v[66:67], 0, v[50:51]
	v_cvt_pk_bf16_f32 v0, v0, s0
	global_store_short v[50:51], v0, off
	v_lshlrev_b32_e32 v0, 16, v136
	v_mul_f32_e32 v0, v124, v0
	v_cvt_pk_bf16_f32 v0, v0, s0
	global_store_short v[50:51], v0, off offset:32
	s_waitcnt vmcnt(62)
	v_lshlrev_b32_e32 v0, 16, v137
	v_mul_f32_e32 v0, v128, v0
	v_cvt_pk_bf16_f32 v0, v0, s0
	global_store_short v[50:51], v0, off offset:64
	v_lshlrev_b32_e32 v0, 16, v84
	v_mul_f32_e32 v0, v52, v0
	v_cvt_pk_bf16_f32 v0, v0, s0
	global_store_short v[50:51], v0, off offset:96
	s_waitcnt vmcnt(62)
	v_lshlrev_b32_e32 v0, 16, v85
	v_lshlrev_b64 v[50:51], 11, v[86:87]
	v_mul_f32_e32 v0, v121, v0
	v_lshl_add_u64 v[50:51], v[66:67], 0, v[50:51]
	v_cvt_pk_bf16_f32 v0, v0, s0
	global_store_short v[50:51], v0, off
	v_lshlrev_b32_e32 v0, 16, v138
	v_mul_f32_e32 v0, v125, v0
	v_cvt_pk_bf16_f32 v0, v0, s0
	global_store_short v[50:51], v0, off offset:32
	s_waitcnt vmcnt(62)
; DEV float bf2f(u16 h) { return __uint_as_float(((unsigned)h) << 16); }
; template <int EPI, bool AF32>
; DEV void gemm_tile(const void* Ap, int lda, const u16* Bt, int ldb, int K, int m0, int n0, const Epi& ea, char* smem) {
;     ...
; #pragma unroll
;       for (int m = 0; m < 4; m++)
; #pragma unroll
;         for (int j = 0; j < 4; j++)
; #pragma unroll
;           for (int n = 0; n < 4; n++) {
;             float v = bf2f(gv[m][j][n]) * acc[m][n][j];
;             if (EPI == EP_MERGE2) v += bf2f(cv[m][j][n]);
;             C[(size_t)(rbase + m * 16 + j) * 1024 + cbase + n * 16] = f2bf(v);
	v_lshlrev_b32_e32 v0, 16, v139
	v_mul_f32_e32 v0, v129, v0
	v_cvt_pk_bf16_f32 v0, v0, s0
	global_store_short v[50:51], v0, off offset:64
	v_lshlrev_b32_e32 v0, 16, v88
	v_mul_f32_e32 v0, v53, v0
	v_cvt_pk_bf16_f32 v0, v0, s0
	global_store_short v[50:51], v0, off offset:96
	s_waitcnt vmcnt(62)
	v_lshlrev_b32_e32 v0, 16, v89
	v_lshlrev_b64 v[50:51], 11, v[90:91]
	v_mul_f32_e32 v0, v46, v0
	v_lshl_add_u64 v[50:51], v[66:67], 0, v[50:51]
	v_cvt_pk_bf16_f32 v0, v0, s0
	global_store_short v[50:51], v0, off
	v_lshlrev_b32_e32 v0, 16, v140
	v_mul_f32_e32 v0, v42, v0
	v_cvt_pk_bf16_f32 v0, v0, s0
	global_store_short v[50:51], v0, off offset:32
	s_waitcnt vmcnt(62)
	v_lshlrev_b32_e32 v0, 16, v141
	v_mul_f32_e32 v0, v38, v0
	v_cvt_pk_bf16_f32 v0, v0, s0
	global_store_short v[50:51], v0, off offset:64
	v_lshlrev_b32_e32 v0, 16, v92
	v_mul_f32_e32 v0, v34, v0
	v_cvt_pk_bf16_f32 v0, v0, s0
	global_store_short v[50:51], v0, off offset:96
	s_waitcnt vmcnt(62)
	v_lshlrev_b32_e32 v0, 16, v93
	v_lshlrev_b64 v[50:51], 11, v[94:95]
	v_mul_f32_e32 v0, v47, v0
	v_lshl_add_u64 v[50:51], v[66:67], 0, v[50:51]
	v_cvt_pk_bf16_f32 v0, v0, s0
	global_store_short v[50:51], v0, off
	v_lshlrev_b32_e32 v0, 16, v142
	v_mul_f32_e32 v0, v43, v0
	v_cvt_pk_bf16_f32 v0, v0, s0
	global_store_short v[50:51], v0, off offset:32
	s_waitcnt vmcnt(62)
	v_lshlrev_b32_e32 v0, 16, v143
	v_mul_f32_e32 v0, v39, v0
	v_cvt_pk_bf16_f32 v0, v0, s0
	global_store_short v[50:51], v0, off offset:64
	v_lshlrev_b32_e32 v0, 16, v96
	v_mul_f32_e32 v0, v35, v0
	v_cvt_pk_bf16_f32 v0, v0, s0
	global_store_short v[50:51], v0, off offset:96
	s_waitcnt vmcnt(62)
	v_lshlrev_b32_e32 v0, 16, v97
	v_lshlrev_b64 v[34:35], 11, v[98:99]
	v_mul_f32_e32 v0, v48, v0
	v_lshl_add_u64 v[34:35], v[66:67], 0, v[34:35]
	v_cvt_pk_bf16_f32 v0, v0, s0
	global_store_short v[34:35], v0, off
	v_lshlrev_b32_e32 v0, 16, v144
	v_mul_f32_e32 v0, v44, v0
	v_cvt_pk_bf16_f32 v0, v0, s0
	global_store_short v[34:35], v0, off offset:32
	s_waitcnt vmcnt(62)
	v_lshlrev_b32_e32 v0, 16, v145
	v_mul_f32_e32 v0, v40, v0
	v_cvt_pk_bf16_f32 v0, v0, s0
	global_store_short v[34:35], v0, off offset:64
	v_lshlrev_b32_e32 v0, 16, v100
	v_mul_f32_e32 v0, v36, v0
	v_cvt_pk_bf16_f32 v0, v0, s0
	global_store_short v[34:35], v0, off offset:96
	s_waitcnt vmcnt(62)
	v_lshlrev_b32_e32 v0, 16, v101
	v_lshlrev_b64 v[34:35], 11, v[102:103]
	v_mul_f32_e32 v0, v49, v0
	v_lshl_add_u64 v[34:35], v[66:67], 0, v[34:35]
	v_cvt_pk_bf16_f32 v0, v0, s0
	global_store_short v[34:35], v0, off
	v_lshlrev_b32_e32 v0, 16, v146
	v_mul_f32_e32 v0, v45, v0
	v_cvt_pk_bf16_f32 v0, v0, s0
	global_store_short v[34:35], v0, off offset:32
	s_waitcnt vmcnt(62)
	v_lshlrev_b32_e32 v0, 16, v147
	v_mul_f32_e32 v0, v41, v0
	v_cvt_pk_bf16_f32 v0, v0, s0
	global_store_short v[34:35], v0, off offset:64
	v_lshlrev_b32_e32 v0, 16, v104
	v_mul_f32_e32 v0, v37, v0
	v_cvt_pk_bf16_f32 v0, v0, s0
	global_store_short v[34:35], v0, off offset:96
	s_waitcnt vmcnt(62)
	v_lshlrev_b32_e32 v0, 16, v105
	v_lshlrev_b64 v[34:35], 11, v[70:71]
	v_mul_f32_e32 v0, v30, v0
	v_lshl_add_u64 v[34:35], v[66:67], 0, v[34:35]
	v_cvt_pk_bf16_f32 v0, v0, s0
	global_store_short v[34:35], v0, off
	v_lshlrev_b32_e32 v0, 16, v148
	v_mul_f32_e32 v0, v26, v0
	v_cvt_pk_bf16_f32 v0, v0, s0
	global_store_short v[34:35], v0, off offset:32
	s_waitcnt vmcnt(62)
	v_lshlrev_b32_e32 v0, 16, v149
	v_mul_f32_e32 v0, v22, v0
	v_cvt_pk_bf16_f32 v0, v0, s0
	global_store_short v[34:35], v0, off offset:64
	v_lshlrev_b32_e32 v0, 16, v106
	v_mul_f32_e32 v0, v18, v0
	v_cvt_pk_bf16_f32 v0, v0, s0
	global_store_short v[34:35], v0, off offset:96
	s_waitcnt vmcnt(62)
	v_lshlrev_b32_e32 v0, 16, v107
	v_lshlrev_b64 v[34:35], 11, v[68:69]
	v_mul_f32_e32 v0, v31, v0
	v_lshl_add_u64 v[34:35], v[66:67], 0, v[34:35]
	v_cvt_pk_bf16_f32 v0, v0, s0
	global_store_short v[34:35], v0, off
	v_lshlrev_b32_e32 v0, 16, v150
	v_mul_f32_e32 v0, v27, v0
	v_cvt_pk_bf16_f32 v0, v0, s0
	global_store_short v[34:35], v0, off offset:32
	s_waitcnt vmcnt(62)
	v_lshlrev_b32_e32 v0, 16, v151
	v_mul_f32_e32 v0, v23, v0
	v_cvt_pk_bf16_f32 v0, v0, s0
	global_store_short v[34:35], v0, off offset:64
	v_lshlrev_b32_e32 v0, 16, v108
	v_mul_f32_e32 v0, v19, v0
	v_cvt_pk_bf16_f32 v0, v0, s0
	global_store_short v[34:35], v0, off offset:96
	s_waitcnt vmcnt(62)
; DEV int bidx() { int b = __builtin_amdgcn_readfirstlane(blockIdx.x); asm volatile("" : "+s"(b)); return b; }
; DEV int gdim() { int g = __builtin_amdgcn_readfirstlane(gridDim.x); asm volatile("" : "+s"(g)); return g; }
; DEV float bf2f(u16 h) { return __uint_as_float(((unsigned)h) << 16); }
; template <int EPI, bool AF32>
; DEV void gemm_tile(const void* Ap, int lda, const u16* Bt, int ldb, int K, int m0, int n0, const Epi& ea, char* smem) {
;     ...
; #pragma unroll
;       for (int m = 0; m < 4; m++)
; #pragma unroll
;         for (int j = 0; j < 4; j++)
; #pragma unroll
;           for (int n = 0; n < 4; n++) {
;             float v = bf2f(gv[m][j][n]) * acc[m][n][j];
;             if (EPI == EP_MERGE2) v += bf2f(cv[m][j][n]);
;             C[(size_t)(rbase + m * 16 + j) * 1024 + cbase + n * 16] = f2bf(v);
; template <int EPI, bool AF32>
; DEV void gemm_phase(const void* A, int lda, const u16* Bt, int ldb, int M, int N, int K, const Epi& ea, char* smem) {
;     ...
;   for (int tile = bidx(); tile < ntm * ntn; tile += gdim()) {
;     int m, n;
;     tile_mn(tile, ntm, ntn, m, n);
;     gemm_tile<EPI, AF32>(A, lda, Bt, ldb, K, m << 7, n << 7, ea, smem);
;   }
	v_lshlrev_b32_e32 v0, 16, v109
	v_lshlrev_b64 v[18:19], 11, v[64:65]
	v_mul_f32_e32 v0, v32, v0
	v_lshl_add_u64 v[18:19], v[66:67], 0, v[18:19]
	v_cvt_pk_bf16_f32 v0, v0, s0
	global_store_short v[18:19], v0, off
	v_lshlrev_b32_e32 v0, 16, v152
	v_mul_f32_e32 v0, v28, v0
	v_cvt_pk_bf16_f32 v0, v0, s0
	global_store_short v[18:19], v0, off offset:32
	s_waitcnt vmcnt(62)
	v_lshlrev_b32_e32 v0, 16, v153
	v_mul_f32_e32 v0, v24, v0
	v_cvt_pk_bf16_f32 v0, v0, s0
	global_store_short v[18:19], v0, off offset:64
	v_lshlrev_b32_e32 v0, 16, v110
	v_mul_f32_e32 v0, v20, v0
	v_cvt_pk_bf16_f32 v0, v0, s0
	global_store_short v[18:19], v0, off offset:96
	s_waitcnt vmcnt(62)
	v_lshlrev_b32_e32 v0, 16, v111
	v_lshlrev_b64 v[18:19], 11, v[62:63]
	v_mul_f32_e32 v0, v33, v0
	v_lshl_add_u64 v[18:19], v[66:67], 0, v[18:19]
	v_cvt_pk_bf16_f32 v0, v0, s0
	global_store_short v[18:19], v0, off
	v_lshlrev_b32_e32 v0, 16, v161
	v_mul_f32_e32 v0, v29, v0
	v_cvt_pk_bf16_f32 v0, v0, s0
	global_store_short v[18:19], v0, off offset:32
	s_waitcnt vmcnt(62)
	v_lshlrev_b32_e32 v0, 16, v162
	v_mul_f32_e32 v0, v25, v0
	v_cvt_pk_bf16_f32 v0, v0, s0
	global_store_short v[18:19], v0, off offset:64
	v_lshlrev_b32_e32 v0, 16, v112
	v_mul_f32_e32 v0, v21, v0
	v_cvt_pk_bf16_f32 v0, v0, s0
	global_store_short v[18:19], v0, off offset:96
	s_waitcnt vmcnt(62)
	v_lshlrev_b32_e32 v0, 16, v113
	v_lshlrev_b64 v[18:19], 11, v[60:61]
	v_mul_f32_e32 v0, v14, v0
	v_lshl_add_u64 v[18:19], v[66:67], 0, v[18:19]
	v_cvt_pk_bf16_f32 v0, v0, s0
	global_store_short v[18:19], v0, off
	v_lshlrev_b32_e32 v0, 16, v163
	v_mul_f32_e32 v0, v10, v0
	v_cvt_pk_bf16_f32 v0, v0, s0
	global_store_short v[18:19], v0, off offset:32
	s_waitcnt vmcnt(62)
	v_lshlrev_b32_e32 v0, 16, v164
	v_mul_f32_e32 v0, v6, v0
	v_cvt_pk_bf16_f32 v0, v0, s0
	global_store_short v[18:19], v0, off offset:64
	v_lshlrev_b32_e32 v0, 16, v114
	v_mul_f32_e32 v0, v2, v0
	v_cvt_pk_bf16_f32 v0, v0, s0
	global_store_short v[18:19], v0, off offset:96
	s_waitcnt vmcnt(62)
	v_lshlrev_b32_e32 v0, 16, v115
	v_lshlrev_b64 v[18:19], 11, v[58:59]
	v_mul_f32_e32 v0, v15, v0
	v_lshl_add_u64 v[18:19], v[66:67], 0, v[18:19]
	v_cvt_pk_bf16_f32 v0, v0, s0
	global_store_short v[18:19], v0, off
	v_lshlrev_b32_e32 v0, 16, v165
	v_mul_f32_e32 v0, v11, v0
	v_cvt_pk_bf16_f32 v0, v0, s0
	global_store_short v[18:19], v0, off offset:32
	s_waitcnt vmcnt(62)
	v_lshlrev_b32_e32 v0, 16, v166
	v_mul_f32_e32 v0, v7, v0
	v_cvt_pk_bf16_f32 v0, v0, s0
	global_store_short v[18:19], v0, off offset:64
	v_lshlrev_b32_e32 v0, 16, v116
	v_mul_f32_e32 v0, v3, v0
	v_cvt_pk_bf16_f32 v0, v0, s0
	global_store_short v[18:19], v0, off offset:96
	s_waitcnt vmcnt(62)
	v_lshlrev_b32_e32 v0, 16, v117
	v_lshlrev_b64 v[2:3], 11, v[56:57]
	v_mul_f32_e32 v0, v16, v0
	v_lshl_add_u64 v[2:3], v[66:67], 0, v[2:3]
	v_cvt_pk_bf16_f32 v0, v0, s0
	global_store_short v[2:3], v0, off
	v_lshlrev_b32_e32 v0, 16, v167
	v_mul_f32_e32 v0, v12, v0
	v_cvt_pk_bf16_f32 v0, v0, s0
	global_store_short v[2:3], v0, off offset:32
	s_waitcnt vmcnt(62)
	v_lshlrev_b32_e32 v0, 16, v168
	v_mul_f32_e32 v0, v8, v0
	v_cvt_pk_bf16_f32 v0, v0, s0
	global_store_short v[2:3], v0, off offset:64
	v_lshlrev_b32_e32 v0, 16, v130
	v_mul_f32_e32 v0, v4, v0
	v_cvt_pk_bf16_f32 v0, v0, s0
	global_store_short v[2:3], v0, off offset:96
	s_waitcnt vmcnt(62)
	v_lshlrev_b32_e32 v0, 16, v131
	v_lshlrev_b64 v[2:3], 11, v[54:55]
	v_mul_f32_e32 v0, v17, v0
	v_lshl_add_u64 v[2:3], v[66:67], 0, v[2:3]
	v_cvt_pk_bf16_f32 v0, v0, s0
	global_store_short v[2:3], v0, off
	v_lshlrev_b32_e32 v0, 16, v169
	v_mul_f32_e32 v0, v13, v0
	v_cvt_pk_bf16_f32 v0, v0, s0
	global_store_short v[2:3], v0, off offset:32
	s_waitcnt vmcnt(62)
	v_lshlrev_b32_e32 v0, 16, v170
	v_mul_f32_e32 v0, v9, v0
	v_cvt_pk_bf16_f32 v0, v0, s0
	global_store_short v[2:3], v0, off offset:64
	v_lshlrev_b32_e32 v0, 16, v74
	v_mul_f32_e32 v0, v5, v0
	v_cvt_pk_bf16_f32 v0, v0, s0
	v_readfirstlane_b32 s0, v198
	global_store_short v[2:3], v0, off offset:96
	s_add_i32 s16, s0, s16
	s_cmpk_lt_i32 s16, 0x820
	s_cbranch_scc1 .LBB0_1304

; DEV int tidx() { int t = threadIdx.x; asm volatile("" : "+v"(t)); return t; }
; template <int EPI, bool AF32>
; DEV void gemm_tile(const void* Ap, int lda, const u16* Bt, int ldb, int K, int m0, int n0, const Epi& ea, char* smem) {
;   u16* sA = (u16*)smem;
;   u16* sB = sA + 2 * 128 * 72;
;   const int tid = tidx(), lane = tid & 63, wv = tid >> 6;
;   const int wr = wv >> 1, wc = wv & 1, fr = lane & 15, fq = lane >> 4;
;   f32x4 acc[4][4];
; #pragma unroll
;   for (int m = 0; m < 4; m++)
; #pragma unroll
;     for (int n = 0; n < 4; n++) acc[m][n] = (f32x4){0.f, 0.f, 0.f, 0.f};
;   u32x4 ra[4], rb[4];
;   f32x4 rfa[8];
;   const int nk = K >> 6;
;   auto gload = [&](int kt) {
;     const int k0 = kt << 6;
; #pragma unroll
;     for (int i = 0; i < 4; i++) {
;       const int c = tid + i * 256, row = c >> 3, kc = c & 7;
;       if (AF32) {
;         const float* pa = (const float*)Ap + (size_t)(m0 + row) * lda + k0 + kc * 8;
;         rfa[2 * i] = *(const f32x4*)pa;
;         rfa[2 * i + 1] = *(const f32x4*)(pa + 4);
;       } else {
;         ra[i] = *(const u32x4*)((const u16*)Ap + (size_t)(m0 + row) * lda + k0 + kc * 8);
;       }
;       rb[i] = *(const u32x4*)(Bt + (size_t)(n0 + row) * ldb + k0 + kc * 8);
;     }
;   };
;   auto swrite = [&](int buf) {
; #pragma unroll
;     for (int i = 0; i < 4; i++) {
;       const int c = tid + i * 256, row = c >> 3, kc = c & 7;
;       u32x4 va;
;       if (AF32) {
;         va = (u32x4){pack2(rfa[2 * i][0], rfa[2 * i][1]), pack2(rfa[2 * i][2], rfa[2 * i][3]),
;                      pack2(rfa[2 * i + 1][0], rfa[2 * i + 1][1]), pack2(rfa[2 * i + 1][2], rfa[2 * i + 1][3])};
;       } else {
;         va = ra[i];
;       }
;       *(u32x4*)(sA + buf * 9216 + row * 72 + kc * 8) = va;
;       *(u32x4*)(sB + buf * 9216 + row * 72 + kc * 8) = rb[i];
;     }
;   };
;   gload(0);
;   swrite(0);
;   if (nk > 1) gload(1);
;   __syncthreads();
.LBB0_1309:
	s_ashr_i32 s0, s14, 31
	s_lshr_b32 s0, s0, 24
	s_add_i32 s0, s14, s0
	s_ashr_i32 s1, s0, 8
	s_and_b32 s0, s0, 0xffffff00
	s_lshl_b32 s16, s1, 5
	s_sub_i32 s15, s14, s0
	s_sub_i32 s0, 0x104, s16
	s_min_u32 s17, s0, 32
	v_cvt_f32_ubyte0_e32 v2, s17
	v_cvt_f32_i32_e32 v0, s15
	v_rcp_iflag_f32_e32 v3, v2
	s_ashr_i32 s0, s15, 30
	s_or_b32 s18, s0, 1
	s_waitcnt vmcnt(12)
	v_mov_b32_e32 v114, v157
	v_mul_f32_e32 v3, v0, v3
	v_trunc_f32_e32 v3, v3
	v_fma_f32 v0, -v3, v2, v0
	v_cvt_i32_f32_e32 v3, v3
	v_cmp_ge_f32_e64 s[0:1], |v0|, v2
	s_and_b64 s[0:1], s[0:1], exec
	s_cselect_b32 s0, s18, 0
	v_readfirstlane_b32 s1, v3
	s_add_i32 s0, s1, s0
	s_sext_i32_i16 s1, s0
	s_mul_i32 s0, s0, s17
	s_sub_i32 s0, s15, s0
	s_sext_i32_i16 s0, s0
	s_add_i32 s16, s16, s0
	s_lshl_b32 s16, s16, 7
	s_lshl_b32 s15, s1, 7
	v_ashrrev_i32_e32 v8, 3, v114
	v_add_u32_e32 v2, s16, v8
	v_ashrrev_i32_e32 v3, 31, v2
	v_lshlrev_b32_e32 v0, 3, v114
	v_add_u32_e32 v4, 0x100, v114
	v_lshlrev_b64 v[58:59], 11, v[2:3]
	v_and_b32_e32 v0, 56, v0
	v_ashrrev_i32_e32 v9, 3, v4
	v_lshl_add_u64 v[2:3], s[4:5], 0, v[58:59]
	v_lshlrev_b32_e32 v0, 1, v0
	v_add_u32_e32 v4, s16, v9
	v_add_u32_e32 v6, 0x200, v114
	v_lshl_add_u64 v[14:15], v[2:3], 0, v[0:1]
	v_add_u32_e32 v2, s15, v8
	v_ashrrev_i32_e32 v5, 31, v4
	v_ashrrev_i32_e32 v10, 3, v6
	v_ashrrev_i32_e32 v3, 31, v2
	v_lshlrev_b64 v[62:63], 11, v[4:5]
	v_add_u32_e32 v6, s16, v10
	v_lshlrev_b64 v[60:61], 11, v[2:3]
	v_lshl_add_u64 v[4:5], s[4:5], 0, v[62:63]
	v_ashrrev_i32_e32 v7, 31, v6
	v_lshl_add_u64 v[2:3], s[6:7], 0, v[60:61]
	v_lshl_add_u64 v[16:17], v[4:5], 0, v[0:1]
	v_add_u32_e32 v4, s15, v9
	v_lshlrev_b64 v[66:67], 11, v[6:7]
	v_lshl_add_u64 v[2:3], v[2:3], 0, v[0:1]
	v_ashrrev_i32_e32 v5, 31, v4
	v_lshl_add_u64 v[6:7], s[4:5], 0, v[66:67]
	global_load_dwordx4 v[30:33], v[2:3], off
	v_lshlrev_b64 v[64:65], 11, v[4:5]
	v_lshl_add_u64 v[68:69], v[6:7], 0, v[0:1]
	v_add_u32_e32 v6, s15, v10
	global_load_dwordx4 v[26:29], v[14:15], off
	global_load_dwordx4 v[34:37], v[16:17], off
	v_lshl_add_u64 v[4:5], s[6:7], 0, v[64:65]
	v_ashrrev_i32_e32 v7, 31, v6
	v_lshl_add_u64 v[4:5], v[4:5], 0, v[0:1]
	v_lshlrev_b64 v[70:71], 11, v[6:7]
	global_load_dwordx4 v[38:41], v[4:5], off
	v_lshl_add_u64 v[6:7], s[6:7], 0, v[70:71]
	global_load_dwordx4 v[42:45], v[68:69], off
	v_lshl_add_u64 v[18:19], v[6:7], 0, v[0:1]
	global_load_dwordx4 v[46:49], v[18:19], off
	v_add_u32_e32 v6, 0x300, v114
	v_ashrrev_i32_e32 v80, 3, v6
	v_add_u32_e32 v6, s16, v80
	v_ashrrev_i32_e32 v7, 31, v6
	v_lshlrev_b64 v[72:73], 11, v[6:7]
	v_lshl_add_u64 v[6:7], s[4:5], 0, v[72:73]
	v_lshl_add_u64 v[74:75], v[6:7], 0, v[0:1]
	v_add_u32_e32 v6, s15, v80
	v_ashrrev_i32_e32 v7, 31, v6
	v_lshlrev_b64 v[76:77], 11, v[6:7]
	v_lshl_add_u64 v[6:7], s[6:7], 0, v[76:77]
	v_lshl_add_u64 v[78:79], v[6:7], 0, v[0:1]
	global_load_dwordx4 v[50:53], v[74:75], off
	global_load_dwordx4 v[54:57], v[78:79], off
	s_waitcnt vmcnt(19)
	v_mul_lo_u32 v118, v8, s71
	v_mul_lo_u32 v119, v9, s71
	s_waitcnt vmcnt(18)
	v_mul_lo_u32 v123, v10, s71
	global_load_dwordx4 v[6:9], v[2:3], off offset:128
	global_load_dwordx4 v[10:13], v[4:5], off offset:128
	s_nop 0
	global_load_dwordx4 v[2:5], v[18:19], off offset:128
	global_load_dwordx4 v[22:25], v[14:15], off offset:128
	s_nop 0
	global_load_dwordx4 v[18:21], v[16:17], off offset:128
	s_nop 0
	global_load_dwordx4 v[14:17], v[68:69], off offset:128
	v_bfe_u32 v161, v157, 3, 4
	v_add_u32_e32 v161, 4, v161
	v_lshlrev_b32_e32 v161, 1, v161
	v_and_b32_e32 v161, 16, v161
	v_xor_b32_e32 v129, v0, v161
	v_lshl_add_u32 v122, v118, 1, v129
	v_lshl_add_u32 v121, v119, 1, v129
	v_lshl_add_u32 v120, v123, 1, v129
	v_and_b32_e32 v115, 15, v114
	s_waitcnt vmcnt(23)
	v_mul_lo_u32 v126, v80, s71
	v_bfe_u32 v116, v114, 4, 2
	v_lshl_add_u32 v124, v126, 1, v129
	s_mov_b32 s17, 0
	v_lshlrev_b32_e32 v125, 4, v116
	v_and_b32_e32 v161, 15, v157
	v_add_u32_e32 v161, 4, v161
	v_lshlrev_b32_e32 v161, 1, v161
	v_and_b32_e32 v161, 16, v161
	v_xor_b32_e32 v125, v125, v161
	s_mov_b64 s[0:1], 0
	s_waitcnt vmcnt(13)
	ds_write_b128 v122, v[30:33] offset:36864
	s_waitcnt vmcnt(12)
	ds_write_b128 v122, v[26:29]
	s_waitcnt vmcnt(11)
	ds_write_b128 v121, v[34:37]
	s_waitcnt vmcnt(10)
	ds_write_b128 v121, v[38:41] offset:36864
	s_waitcnt vmcnt(9)
	ds_write_b128 v120, v[42:45]
	s_waitcnt vmcnt(8)
	ds_write_b128 v120, v[46:49] offset:36864
	global_load_dwordx4 v[26:29], v[74:75], off offset:128
	global_load_dwordx4 v[30:33], v[78:79], off offset:128
	v_ashrrev_i32_e32 v34, 1, v114
	v_and_b32_e32 v117, 0xffffffc0, v34
	v_or_b32_e32 v34, v117, v115
	v_mul_lo_u32 v128, v34, s71
	v_lshlrev_b32_e32 v34, 4, v114
	v_and_b32_e32 v34, 0x70, v34
	v_and_b32_e32 v35, 0x4f, v114
	v_or_b32_e32 v76, v76, v34
	v_or_b32_e32 v72, v72, v34
	v_or_b32_e32 v70, v70, v34
	v_or_b32_e32 v66, v66, v34
	v_or_b32_e32 v64, v64, v34
	v_or_b32_e32 v62, v62, v34
	v_or_b32_e32 v60, v60, v34
	v_or_b32_e32 v58, v58, v34
	v_mov_b32_e32 v34, 0
	s_waitcnt vmcnt(9)
	ds_write_b128 v124, v[50:53]
	s_waitcnt vmcnt(8)
	ds_write_b128 v124, v[54:57] offset:36864
	v_mul_u32_u24_e32 v127, 0x48, v35
	v_lshl_add_u64 v[98:99], s[10:11], 0, v[76:77]
	v_lshl_add_u64 v[100:101], s[12:13], 0, v[72:73]
	v_lshl_add_u64 v[102:103], s[10:11], 0, v[70:71]
	v_lshl_add_u64 v[104:105], s[12:13], 0, v[66:67]
	v_lshl_add_u64 v[106:107], s[10:11], 0, v[64:65]
	v_lshl_add_u64 v[108:109], s[12:13], 0, v[62:63]
	v_lshl_add_u64 v[110:111], s[10:11], 0, v[60:61]
	v_lshl_add_u64 v[112:113], s[12:13], 0, v[58:59]
	v_mov_b32_e32 v35, v34
	v_mov_b32_e32 v36, v34
	v_mov_b32_e32 v37, v34
	v_mov_b32_e32 v38, v34
	v_mov_b32_e32 v39, v34
	v_mov_b32_e32 v40, v34
	v_mov_b32_e32 v41, v34
	v_mov_b32_e32 v42, v34
	v_mov_b32_e32 v43, v34
	v_mov_b32_e32 v44, v34
	v_mov_b32_e32 v45, v34
	v_mov_b32_e32 v46, v34
	v_mov_b32_e32 v47, v34
	v_mov_b32_e32 v48, v34
	v_mov_b32_e32 v49, v34
	v_mov_b32_e32 v50, v34
	v_mov_b32_e32 v51, v34
	v_mov_b32_e32 v52, v34
	v_mov_b32_e32 v53, v34
	v_mov_b32_e32 v54, v34
	v_mov_b32_e32 v55, v34
	v_mov_b32_e32 v56, v34
	v_mov_b32_e32 v57, v34
	v_mov_b32_e32 v58, v34
	v_mov_b32_e32 v59, v34
	v_mov_b32_e32 v60, v34
	v_mov_b32_e32 v61, v34
	v_mov_b32_e32 v62, v34
	v_mov_b32_e32 v63, v34
	v_mov_b32_e32 v64, v34
	v_mov_b32_e32 v65, v34
	v_mov_b32_e32 v66, v34
	v_mov_b32_e32 v67, v34
	v_mov_b32_e32 v68, v34
	v_mov_b32_e32 v69, v34
	v_mov_b32_e32 v70, v34
	v_mov_b32_e32 v71, v34
	v_mov_b32_e32 v72, v34
	v_mov_b32_e32 v73, v34
	v_mov_b32_e32 v74, v34
	v_mov_b32_e32 v75, v34
	v_mov_b32_e32 v76, v34
	v_mov_b32_e32 v77, v34
	v_mov_b32_e32 v78, v34
	v_mov_b32_e32 v79, v34
	v_mov_b32_e32 v80, v34
	v_mov_b32_e32 v81, v34
	v_mov_b32_e32 v82, v34
	v_mov_b32_e32 v83, v34
	v_mov_b32_e32 v84, v34
	v_mov_b32_e32 v85, v34
	v_mov_b32_e32 v86, v34
	v_mov_b32_e32 v87, v34
	v_mov_b32_e32 v88, v34
	v_mov_b32_e32 v89, v34
	v_mov_b32_e32 v90, v34
	v_mov_b32_e32 v91, v34
	v_mov_b32_e32 v92, v34
	v_mov_b32_e32 v93, v34
	v_mov_b32_e32 v94, v34
	v_mov_b32_e32 v95, v34
	v_mov_b32_e32 v96, v34
	v_mov_b32_e32 v97, v34
	s_waitcnt lgkmcnt(0)
	s_barrier
; DEV f32x4 mfma16(bf16x8 a, bf16x8 b, f32x4 c) { return __builtin_amdgcn_mfma_f32_16x16x32_bf16(a, b, c, 0, 0, 0); }
; template <int EPI, bool AF32>
; DEV void gemm_tile(const void* Ap, int lda, const u16* Bt, int ldb, int K, int m0, int n0, const Epi& ea, char* smem) {
;     ...
;   for (int kt = 0; kt < nk; kt++) {
;     const int buf = kt & 1;
;     if (kt + 1 < nk) swrite(buf ^ 1);
;     if (kt + 2 < nk) gload(kt + 2);
; #pragma unroll
;     for (int ks = 0; ks < 2; ks++) {
;       bf16x8 a[4], b[4];
; #pragma unroll
;       for (int m = 0; m < 4; m++) a[m] = *(const bf16x8*)(sA + buf * 9216 + (wr * 64 + m * 16 + fr) * 72 + ks * 32 + fq * 8);
; #pragma unroll
;       for (int n = 0; n < 4; n++) b[n] = *(const bf16x8*)(sB + buf * 9216 + (wc * 64 + n * 16 + fr) * 72 + ks * 32 + fq * 8);
;       __builtin_amdgcn_s_setprio(1);
; #pragma unroll
;       for (int m = 0; m < 4; m++)
; #pragma unroll
;         for (int n = 0; n < 4; n++) acc[m][n] = mfma16(a[m], b[n], acc[m][n]);
;       __builtin_amdgcn_s_setprio(0);
;     }
;     __syncthreads();
;   }
	v_lshl_add_u32 v161, v128, 1, v125
	v_lshl_add_u32 v129, v127, 1, v125
	s_mov_b32 s17, 0
	s_mov_b64 s[0:1], 0x100
	ds_read_b128 v[130:133], v161
	ds_read_b128 v[134:137], v161 offset:2304
	ds_read_b128 v[138:141], v161 offset:4608
	ds_read_b128 v[142:145], v161 offset:6912
	ds_read_b128 v[146:149], v129 offset:36864
	ds_read_b128 v[150:153], v129 offset:39168
	ds_read_b128 v[162:165], v129 offset:41472
	ds_read_b128 v[166:169], v129 offset:43776
.Lgk4_loop:
	s_waitcnt lgkmcnt(0)
	ds_read_b128 v[222:225], v161 offset:64
	ds_read_b128 v[226:229], v161 offset:2368
	ds_read_b128 v[230:233], v161 offset:4672
	ds_read_b128 v[234:237], v161 offset:6976
	ds_read_b128 v[238:241], v129 offset:36928
	ds_read_b128 v[242:245], v129 offset:39232
	ds_read_b128 v[246:249], v129 offset:41536
	ds_read_b128 v[250:253], v129 offset:43840
	v_mfma_f32_16x16x32_bf16 v[34:37], v[130:133], v[146:149], v[34:37]
	v_mfma_f32_16x16x32_bf16 v[38:41], v[130:133], v[150:153], v[38:41]
	v_mfma_f32_16x16x32_bf16 v[42:45], v[130:133], v[162:165], v[42:45]
	v_mfma_f32_16x16x32_bf16 v[46:49], v[130:133], v[166:169], v[46:49]
	s_waitcnt vmcnt(0)
	ds_write_b128 v122, v[22:25] offset:18432
	ds_write_b128 v122, v[6:9] offset:55296
	v_mfma_f32_16x16x32_bf16 v[50:53], v[134:137], v[146:149], v[50:53]
	ds_write_b128 v121, v[18:21] offset:18432
	ds_write_b128 v121, v[10:13] offset:55296
	v_mfma_f32_16x16x32_bf16 v[54:57], v[134:137], v[150:153], v[54:57]
	ds_write_b128 v120, v[14:17] offset:18432
	ds_write_b128 v120, v[2:5] offset:55296
	v_mfma_f32_16x16x32_bf16 v[58:61], v[134:137], v[162:165], v[58:61]
	ds_write_b128 v124, v[26:29] offset:18432
	ds_write_b128 v124, v[30:33] offset:55296
	v_mfma_f32_16x16x32_bf16 v[62:65], v[134:137], v[166:169], v[62:65]
	global_load_dwordx4 v[22:25], v[112:113], off
	v_mfma_f32_16x16x32_bf16 v[66:69], v[138:141], v[146:149], v[66:69]
	global_load_dwordx4 v[6:9], v[110:111], off
	v_mfma_f32_16x16x32_bf16 v[70:73], v[138:141], v[150:153], v[70:73]
	global_load_dwordx4 v[18:21], v[108:109], off
	v_mfma_f32_16x16x32_bf16 v[74:77], v[138:141], v[162:165], v[74:77]
	global_load_dwordx4 v[10:13], v[106:107], off
	v_mfma_f32_16x16x32_bf16 v[78:81], v[138:141], v[166:169], v[78:81]
	global_load_dwordx4 v[14:17], v[104:105], off
	v_mfma_f32_16x16x32_bf16 v[82:85], v[142:145], v[146:149], v[82:85]
	global_load_dwordx4 v[2:5], v[102:103], off
	v_mfma_f32_16x16x32_bf16 v[86:89], v[142:145], v[150:153], v[86:89]
	global_load_dwordx4 v[26:29], v[100:101], off
	v_mfma_f32_16x16x32_bf16 v[90:93], v[142:145], v[162:165], v[90:93]
	global_load_dwordx4 v[30:33], v[98:99], off
	v_mfma_f32_16x16x32_bf16 v[94:97], v[142:145], v[166:169], v[94:97]
	s_waitcnt lgkmcnt(0)
	s_barrier
	ds_read_b128 v[130:133], v161 offset:18432
	v_mfma_f32_16x16x32_bf16 v[34:37], v[222:225], v[238:241], v[34:37]
	ds_read_b128 v[134:137], v161 offset:20736
	v_mfma_f32_16x16x32_bf16 v[38:41], v[222:225], v[242:245], v[38:41]
	ds_read_b128 v[138:141], v161 offset:23040
	v_mfma_f32_16x16x32_bf16 v[42:45], v[222:225], v[246:249], v[42:45]
	ds_read_b128 v[142:145], v161 offset:25344
	v_mfma_f32_16x16x32_bf16 v[46:49], v[222:225], v[250:253], v[46:49]
	ds_read_b128 v[146:149], v129 offset:55296
	v_mfma_f32_16x16x32_bf16 v[50:53], v[226:229], v[238:241], v[50:53]
	ds_read_b128 v[150:153], v129 offset:57600
	v_mfma_f32_16x16x32_bf16 v[54:57], v[226:229], v[242:245], v[54:57]
	ds_read_b128 v[162:165], v129 offset:59904
	v_mfma_f32_16x16x32_bf16 v[58:61], v[226:229], v[246:249], v[58:61]
	ds_read_b128 v[166:169], v129 offset:62208
	v_mfma_f32_16x16x32_bf16 v[62:65], v[226:229], v[250:253], v[62:65]
	v_mfma_f32_16x16x32_bf16 v[66:69], v[230:233], v[238:241], v[66:69]
	v_mfma_f32_16x16x32_bf16 v[70:73], v[230:233], v[242:245], v[70:73]
	v_mfma_f32_16x16x32_bf16 v[74:77], v[230:233], v[246:249], v[74:77]
	v_mfma_f32_16x16x32_bf16 v[78:81], v[230:233], v[250:253], v[78:81]
	v_mfma_f32_16x16x32_bf16 v[82:85], v[234:237], v[238:241], v[82:85]
	v_mfma_f32_16x16x32_bf16 v[86:89], v[234:237], v[242:245], v[86:89]
	v_mfma_f32_16x16x32_bf16 v[90:93], v[234:237], v[246:249], v[90:93]
	v_mfma_f32_16x16x32_bf16 v[94:97], v[234:237], v[250:253], v[94:97]
	s_waitcnt lgkmcnt(0)
	ds_read_b128 v[222:225], v161 offset:18496
	ds_read_b128 v[226:229], v161 offset:20800
	ds_read_b128 v[230:233], v161 offset:23104
	ds_read_b128 v[234:237], v161 offset:25408
	ds_read_b128 v[238:241], v129 offset:55360
	ds_read_b128 v[242:245], v129 offset:57664
	ds_read_b128 v[246:249], v129 offset:59968
	ds_read_b128 v[250:253], v129 offset:62272
	v_mfma_f32_16x16x32_bf16 v[34:37], v[130:133], v[146:149], v[34:37]
	v_mfma_f32_16x16x32_bf16 v[38:41], v[130:133], v[150:153], v[38:41]
	v_mfma_f32_16x16x32_bf16 v[42:45], v[130:133], v[162:165], v[42:45]
	v_mfma_f32_16x16x32_bf16 v[46:49], v[130:133], v[166:169], v[46:49]
	s_waitcnt vmcnt(0)
	ds_write_b128 v122, v[22:25]
	ds_write_b128 v122, v[6:9] offset:36864
	v_mfma_f32_16x16x32_bf16 v[50:53], v[134:137], v[146:149], v[50:53]
	ds_write_b128 v121, v[18:21]
	ds_write_b128 v121, v[10:13] offset:36864
	v_mfma_f32_16x16x32_bf16 v[54:57], v[134:137], v[150:153], v[54:57]
	ds_write_b128 v120, v[14:17]
	ds_write_b128 v120, v[2:5] offset:36864
	v_mfma_f32_16x16x32_bf16 v[58:61], v[134:137], v[162:165], v[58:61]
	ds_write_b128 v124, v[26:29]
	ds_write_b128 v124, v[30:33] offset:36864
	v_mfma_f32_16x16x32_bf16 v[62:65], v[134:137], v[166:169], v[62:65]
	global_load_dwordx4 v[22:25], v[112:113], off offset:128
	v_mfma_f32_16x16x32_bf16 v[66:69], v[138:141], v[146:149], v[66:69]
	global_load_dwordx4 v[6:9], v[110:111], off offset:128
	v_mfma_f32_16x16x32_bf16 v[70:73], v[138:141], v[150:153], v[70:73]
	global_load_dwordx4 v[18:21], v[108:109], off offset:128
	v_mfma_f32_16x16x32_bf16 v[74:77], v[138:141], v[162:165], v[74:77]
	global_load_dwordx4 v[10:13], v[106:107], off offset:128
	v_mfma_f32_16x16x32_bf16 v[78:81], v[138:141], v[166:169], v[78:81]
	global_load_dwordx4 v[14:17], v[104:105], off offset:128
	v_mfma_f32_16x16x32_bf16 v[82:85], v[142:145], v[146:149], v[82:85]
	global_load_dwordx4 v[2:5], v[102:103], off offset:128
	v_mfma_f32_16x16x32_bf16 v[86:89], v[142:145], v[150:153], v[86:89]
	global_load_dwordx4 v[26:29], v[100:101], off offset:128
	v_mfma_f32_16x16x32_bf16 v[90:93], v[142:145], v[162:165], v[90:93]
	global_load_dwordx4 v[30:33], v[98:99], off offset:128
	v_mfma_f32_16x16x32_bf16 v[94:97], v[142:145], v[166:169], v[94:97]
	s_waitcnt lgkmcnt(0)
	s_barrier
; DEV f32x4 mfma16(bf16x8 a, bf16x8 b, f32x4 c) { return __builtin_amdgcn_mfma_f32_16x16x32_bf16(a, b, c, 0, 0, 0); }
; template <int EPI, bool AF32>
; DEV void gemm_tile(const void* Ap, int lda, const u16* Bt, int ldb, int K, int m0, int n0, const Epi& ea, char* smem) {
;     ...
;   for (int kt = 0; kt < nk; kt++) {
;     const int buf = kt & 1;
;     if (kt + 1 < nk) swrite(buf ^ 1);
;     if (kt + 2 < nk) gload(kt + 2);
; #pragma unroll
;     for (int ks = 0; ks < 2; ks++) {
;       bf16x8 a[4], b[4];
; #pragma unroll
;       for (int m = 0; m < 4; m++) a[m] = *(const bf16x8*)(sA + buf * 9216 + (wr * 64 + m * 16 + fr) * 72 + ks * 32 + fq * 8);
; #pragma unroll
;       for (int n = 0; n < 4; n++) b[n] = *(const bf16x8*)(sB + buf * 9216 + (wc * 64 + n * 16 + fr) * 72 + ks * 32 + fq * 8);
;       __builtin_amdgcn_s_setprio(1);
; #pragma unroll
;       for (int m = 0; m < 4; m++)
; #pragma unroll
;         for (int n = 0; n < 4; n++) acc[m][n] = mfma16(a[m], b[n], acc[m][n]);
;       __builtin_amdgcn_s_setprio(0);
;     }
;     __syncthreads();
;   }
	ds_read_b128 v[130:133], v161
	v_mfma_f32_16x16x32_bf16 v[34:37], v[222:225], v[238:241], v[34:37]
	ds_read_b128 v[134:137], v161 offset:2304
	v_mfma_f32_16x16x32_bf16 v[38:41], v[222:225], v[242:245], v[38:41]
	ds_read_b128 v[138:141], v161 offset:4608
	v_mfma_f32_16x16x32_bf16 v[42:45], v[222:225], v[246:249], v[42:45]
	ds_read_b128 v[142:145], v161 offset:6912
	v_mfma_f32_16x16x32_bf16 v[46:49], v[222:225], v[250:253], v[46:49]
	ds_read_b128 v[146:149], v129 offset:36864
	v_mfma_f32_16x16x32_bf16 v[50:53], v[226:229], v[238:241], v[50:53]
	ds_read_b128 v[150:153], v129 offset:39168
	v_mfma_f32_16x16x32_bf16 v[54:57], v[226:229], v[242:245], v[54:57]
	ds_read_b128 v[162:165], v129 offset:41472
	v_mfma_f32_16x16x32_bf16 v[58:61], v[226:229], v[246:249], v[58:61]
	ds_read_b128 v[166:169], v129 offset:43776
	v_mfma_f32_16x16x32_bf16 v[62:65], v[226:229], v[250:253], v[62:65]
	v_mfma_f32_16x16x32_bf16 v[66:69], v[230:233], v[238:241], v[66:69]
	v_lshl_add_u64 v[112:113], v[112:113], 0, s[0:1]
	v_mfma_f32_16x16x32_bf16 v[70:73], v[230:233], v[242:245], v[70:73]
	v_lshl_add_u64 v[110:111], v[110:111], 0, s[0:1]
	v_mfma_f32_16x16x32_bf16 v[74:77], v[230:233], v[246:249], v[74:77]
	v_lshl_add_u64 v[108:109], v[108:109], 0, s[0:1]
	v_mfma_f32_16x16x32_bf16 v[78:81], v[230:233], v[250:253], v[78:81]
	v_lshl_add_u64 v[106:107], v[106:107], 0, s[0:1]
	v_mfma_f32_16x16x32_bf16 v[82:85], v[234:237], v[238:241], v[82:85]
	v_lshl_add_u64 v[104:105], v[104:105], 0, s[0:1]
	v_mfma_f32_16x16x32_bf16 v[86:89], v[234:237], v[242:245], v[86:89]
	v_lshl_add_u64 v[102:103], v[102:103], 0, s[0:1]
	v_mfma_f32_16x16x32_bf16 v[90:93], v[234:237], v[246:249], v[90:93]
	v_lshl_add_u64 v[100:101], v[100:101], 0, s[0:1]
	v_mfma_f32_16x16x32_bf16 v[94:97], v[234:237], v[250:253], v[94:97]
	v_lshl_add_u64 v[98:99], v[98:99], 0, s[0:1]
	s_add_i32 s17, s17, 1
	s_cmp_lg_u32 s17, 7
	s_cbranch_scc1 .Lgk4_loop
	s_waitcnt vmcnt(7)
	ds_write_b128 v122, v[22:25] offset:18432
	s_waitcnt vmcnt(6)
	ds_write_b128 v122, v[6:9] offset:55296
	s_waitcnt vmcnt(5)
	ds_write_b128 v121, v[18:21] offset:18432
	s_waitcnt vmcnt(4)
	ds_write_b128 v121, v[10:13] offset:55296
	s_waitcnt vmcnt(3)
	ds_write_b128 v120, v[14:17] offset:18432
	s_waitcnt vmcnt(2)
	ds_write_b128 v120, v[2:5] offset:55296
	s_waitcnt vmcnt(1)
	ds_write_b128 v124, v[26:29] offset:18432
	s_waitcnt vmcnt(0)
	ds_write_b128 v124, v[30:33] offset:55296
	v_lshl_add_u32 v0, v128, 1, v125
	v_lshl_add_u32 v126, v127, 1, v125
	ds_read_b128 v[2:5], v0
	ds_read_b128 v[6:9], v0 offset:2304
	ds_read_b128 v[10:13], v0 offset:4608
	ds_read_b128 v[14:17], v0 offset:6912
	ds_read_b128 v[18:21], v126 offset:36864
	ds_read_b128 v[22:25], v126 offset:39168
	ds_read_b128 v[26:29], v126 offset:41472
	ds_read_b128 v[30:33], v126 offset:43776
	s_setprio 1
	s_waitcnt lgkmcnt(3)
	v_mfma_f32_16x16x32_bf16 v[34:37], v[2:5], v[18:21], v[34:37]
	s_waitcnt lgkmcnt(2)
	v_mfma_f32_16x16x32_bf16 v[38:41], v[2:5], v[22:25], v[38:41]
	s_waitcnt lgkmcnt(1)
	v_mfma_f32_16x16x32_bf16 v[42:45], v[2:5], v[26:29], v[42:45]
	s_waitcnt lgkmcnt(0)
	v_mfma_f32_16x16x32_bf16 v[2:5], v[2:5], v[30:33], v[46:49]
	v_mfma_f32_16x16x32_bf16 v[46:49], v[6:9], v[18:21], v[50:53]
	v_mfma_f32_16x16x32_bf16 v[50:53], v[6:9], v[22:25], v[54:57]
	v_mfma_f32_16x16x32_bf16 v[54:57], v[6:9], v[26:29], v[58:61]
	v_mfma_f32_16x16x32_bf16 v[6:9], v[6:9], v[30:33], v[62:65]
	v_mfma_f32_16x16x32_bf16 v[58:61], v[10:13], v[18:21], v[66:69]
	v_mfma_f32_16x16x32_bf16 v[62:65], v[10:13], v[22:25], v[70:73]
	v_mfma_f32_16x16x32_bf16 v[66:69], v[10:13], v[26:29], v[74:77]
	v_mfma_f32_16x16x32_bf16 v[10:13], v[10:13], v[30:33], v[78:81]
	v_mfma_f32_16x16x32_bf16 v[18:21], v[14:17], v[18:21], v[82:85]
	v_mfma_f32_16x16x32_bf16 v[22:25], v[14:17], v[22:25], v[86:89]
	v_mfma_f32_16x16x32_bf16 v[26:29], v[14:17], v[26:29], v[90:93]
	v_mfma_f32_16x16x32_bf16 v[14:17], v[14:17], v[30:33], v[94:97]
	s_setprio 0
	ds_read_b128 v[30:33], v0 offset:64
	ds_read_b128 v[70:73], v0 offset:2368
	ds_read_b128 v[74:77], v0 offset:4672
	ds_read_b128 v[78:81], v0 offset:6976
	ds_read_b128 v[82:85], v126 offset:36928
	ds_read_b128 v[86:89], v126 offset:39232
	ds_read_b128 v[90:93], v126 offset:41536
	ds_read_b128 v[94:97], v126 offset:43840
	s_setprio 1
	s_waitcnt lgkmcnt(3)
	v_mfma_f32_16x16x32_bf16 v[34:37], v[30:33], v[82:85], v[34:37]
	s_waitcnt lgkmcnt(2)
	v_mfma_f32_16x16x32_bf16 v[38:41], v[30:33], v[86:89], v[38:41]
	s_waitcnt lgkmcnt(1)
	v_mfma_f32_16x16x32_bf16 v[42:45], v[30:33], v[90:93], v[42:45]
	s_waitcnt lgkmcnt(0)
	v_mfma_f32_16x16x32_bf16 v[2:5], v[30:33], v[94:97], v[2:5]
	v_mfma_f32_16x16x32_bf16 v[30:33], v[70:73], v[82:85], v[46:49]
	v_mfma_f32_16x16x32_bf16 v[46:49], v[70:73], v[86:89], v[50:53]
	v_mfma_f32_16x16x32_bf16 v[50:53], v[70:73], v[90:93], v[54:57]
	v_mfma_f32_16x16x32_bf16 v[6:9], v[70:73], v[94:97], v[6:9]
	v_mfma_f32_16x16x32_bf16 v[54:57], v[74:77], v[82:85], v[58:61]
	v_mfma_f32_16x16x32_bf16 v[58:61], v[74:77], v[86:89], v[62:65]
	v_mfma_f32_16x16x32_bf16 v[62:65], v[74:77], v[90:93], v[66:69]
	v_mfma_f32_16x16x32_bf16 v[10:13], v[74:77], v[94:97], v[10:13]
	v_mfma_f32_16x16x32_bf16 v[18:21], v[78:81], v[82:85], v[18:21]
	v_mfma_f32_16x16x32_bf16 v[22:25], v[78:81], v[86:89], v[22:25]
	v_mfma_f32_16x16x32_bf16 v[26:29], v[78:81], v[90:93], v[26:29]
	v_mfma_f32_16x16x32_bf16 v[14:17], v[78:81], v[94:97], v[14:17]
	s_setprio 0
	s_barrier
; DEV f32x4 mfma16(bf16x8 a, bf16x8 b, f32x4 c) { return __builtin_amdgcn_mfma_f32_16x16x32_bf16(a, b, c, 0, 0, 0); }
; template <int EPI, bool AF32>
; DEV void gemm_tile(const void* Ap, int lda, const u16* Bt, int ldb, int K, int m0, int n0, const Epi& ea, char* smem) {
;     ...
;     for (int ks = 0; ks < 2; ks++) {
;       bf16x8 a[4], b[4];
; #pragma unroll
;       for (int m = 0; m < 4; m++) a[m] = *(const bf16x8*)(sA + buf * 9216 + (wr * 64 + m * 16 + fr) * 72 + ks * 32 + fq * 8);
; #pragma unroll
;       for (int n = 0; n < 4; n++) b[n] = *(const bf16x8*)(sB + buf * 9216 + (wc * 64 + n * 16 + fr) * 72 + ks * 32 + fq * 8);
;       __builtin_amdgcn_s_setprio(1);
; #pragma unroll
;       for (int m = 0; m < 4; m++)
; #pragma unroll
;         for (int n = 0; n < 4; n++) acc[m][n] = mfma16(a[m], b[n], acc[m][n]);
;       __builtin_amdgcn_s_setprio(0);
;     }
;     __syncthreads();
;   }
;     ...
;       u16* C = (u16*)ea.p0;
;       const u16* G = (const u16*)ea.p1 + (EPI == EP_MERGE2 ? 1024 : 0);
;       u16 gv[4][4][4], cv[4][4][4];
; #pragma unroll
;       for (int m = 0; m < 4; m++)
; #pragma unroll
;         for (int j = 0; j < 4; j++)
; #pragma unroll
;           for (int n = 0; n < 4; n++) {
;             gv[m][j][n] = G[(size_t)(rbase + m * 16 + j) * 2048 + cbase + n * 16];
;             if (EPI == EP_MERGE2) cv[m][j][n] = C[(size_t)(rbase + m * 16 + j) * 1024 + cbase + n * 16];
;           }
	ds_read_b128 v[66:69], v0 offset:18432
	ds_read_b128 v[70:73], v0 offset:20736
	ds_read_b128 v[74:77], v0 offset:23040
	ds_read_b128 v[78:81], v0 offset:25344
	ds_read_b128 v[82:85], v126 offset:55296
	ds_read_b128 v[86:89], v126 offset:57600
	ds_read_b128 v[90:93], v126 offset:59904
	ds_read_b128 v[94:97], v126 offset:62208
	v_and_b32_e32 v114, 64, v114
	s_setprio 1
	s_waitcnt lgkmcnt(3)
	v_mfma_f32_16x16x32_bf16 v[34:37], v[66:69], v[82:85], v[34:37]
	s_waitcnt lgkmcnt(2)
	v_mfma_f32_16x16x32_bf16 v[38:41], v[66:69], v[86:89], v[38:41]
	s_waitcnt lgkmcnt(1)
	v_mfma_f32_16x16x32_bf16 v[42:45], v[66:69], v[90:93], v[42:45]
	s_waitcnt lgkmcnt(0)
	v_mfma_f32_16x16x32_bf16 v[2:5], v[66:69], v[94:97], v[2:5]
	v_mfma_f32_16x16x32_bf16 v[30:33], v[70:73], v[82:85], v[30:33]
	v_mfma_f32_16x16x32_bf16 v[66:69], v[70:73], v[86:89], v[46:49]
	v_mfma_f32_16x16x32_bf16 v[98:101], v[70:73], v[90:93], v[50:53]
	v_mfma_f32_16x16x32_bf16 v[6:9], v[70:73], v[94:97], v[6:9]
	v_mfma_f32_16x16x32_bf16 v[70:73], v[74:77], v[82:85], v[54:57]
	v_mfma_f32_16x16x32_bf16 v[102:105], v[74:77], v[86:89], v[58:61]
	v_mfma_f32_16x16x32_bf16 v[106:109], v[74:77], v[90:93], v[62:65]
	v_mfma_f32_16x16x32_bf16 v[10:13], v[74:77], v[94:97], v[10:13]
	v_mfma_f32_16x16x32_bf16 v[74:77], v[78:81], v[82:85], v[18:21]
	v_mfma_f32_16x16x32_bf16 v[82:85], v[78:81], v[86:89], v[22:25]
	v_mfma_f32_16x16x32_bf16 v[86:89], v[78:81], v[90:93], v[26:29]
	v_mfma_f32_16x16x32_bf16 v[78:81], v[78:81], v[94:97], v[14:17]
	s_setprio 0
	s_nop 1
	ds_read_b128 v[14:17], v0 offset:18496
	ds_read_b128 v[18:21], v0 offset:20800
	ds_read_b128 v[90:93], v0 offset:23104
	ds_read_b128 v[94:97], v0 offset:25408
	ds_read_b128 v[110:113], v126 offset:55360
	ds_read_b128 v[118:121], v126 offset:57664
	ds_read_b128 v[122:125], v126 offset:59968
	ds_read_b128 v[126:129], v126 offset:62272
	s_setprio 1
	s_waitcnt lgkmcnt(3)
	v_mfma_f32_16x16x32_bf16 v[62:65], v[14:17], v[110:113], v[34:37]
	s_waitcnt lgkmcnt(2)
	v_mfma_f32_16x16x32_bf16 v[58:61], v[14:17], v[118:121], v[38:41]
	s_waitcnt lgkmcnt(1)
	v_mfma_f32_16x16x32_bf16 v[54:57], v[14:17], v[122:125], v[42:45]
	s_waitcnt lgkmcnt(0)
	v_mfma_f32_16x16x32_bf16 v[50:53], v[14:17], v[126:129], v[2:5]
	v_mfma_f32_16x16x32_bf16 v[46:49], v[18:21], v[110:113], v[30:33]
	v_mfma_f32_16x16x32_bf16 v[42:45], v[18:21], v[118:121], v[66:69]
	v_mfma_f32_16x16x32_bf16 v[38:41], v[18:21], v[122:125], v[98:101]
	v_mfma_f32_16x16x32_bf16 v[34:37], v[18:21], v[126:129], v[6:9]
	v_mfma_f32_16x16x32_bf16 v[30:33], v[90:93], v[110:113], v[70:73]
	v_mfma_f32_16x16x32_bf16 v[26:29], v[90:93], v[118:121], v[102:105]
	v_mfma_f32_16x16x32_bf16 v[22:25], v[90:93], v[122:125], v[106:109]
	v_mfma_f32_16x16x32_bf16 v[18:21], v[90:93], v[126:129], v[10:13]
	v_mfma_f32_16x16x32_bf16 v[14:17], v[94:97], v[110:113], v[74:77]
	v_mfma_f32_16x16x32_bf16 v[10:13], v[94:97], v[118:121], v[82:85]
	v_mfma_f32_16x16x32_bf16 v[6:9], v[94:97], v[122:125], v[86:89]
	v_mfma_f32_16x16x32_bf16 v[2:5], v[94:97], v[126:129], v[78:81]
	s_setprio 0
	v_add_u32_e32 v0, s16, v117
	v_or3_b32 v68, v114, s15, v115
	v_lshl_or_b32 v66, v116, 2, v0
	v_ashrrev_i32_e32 v69, 31, v68
	v_lshlrev_b64 v[68:69], 1, v[68:69]
	v_ashrrev_i32_e32 v67, 31, v66
	v_lshl_add_u64 v[98:99], s[8:9], 0, v[68:69]
	v_lshl_add_u64 v[100:101], s[2:3], 0, v[68:69]
	v_lshlrev_b64 v[68:69], 12, v[66:67]
	v_lshl_add_u64 v[102:103], v[98:99], 0, v[68:69]
	v_lshlrev_b64 v[68:69], 11, v[66:67]
	v_lshl_add_u64 v[96:97], v[100:101], 0, v[68:69]
	v_or_b32_e32 v68, 1, v66
	v_ashrrev_i32_e32 v69, 31, v68
	v_lshlrev_b64 v[70:71], 12, v[68:69]
	v_lshlrev_b64 v[68:69], 11, v[68:69]
	v_lshl_add_u64 v[94:95], v[100:101], 0, v[68:69]
	v_or_b32_e32 v68, 2, v66
	v_ashrrev_i32_e32 v69, 31, v68
	v_lshl_add_u64 v[104:105], v[98:99], 0, v[70:71]
	v_lshlrev_b64 v[70:71], 12, v[68:69]
	v_lshlrev_b64 v[68:69], 11, v[68:69]
	v_lshl_add_u64 v[92:93], v[100:101], 0, v[68:69]
	v_or_b32_e32 v68, 3, v66
	v_ashrrev_i32_e32 v69, 31, v68
	v_lshl_add_u64 v[106:107], v[98:99], 0, v[70:71]
	v_lshlrev_b64 v[70:71], 12, v[68:69]
	v_lshlrev_b64 v[68:69], 11, v[68:69]
	v_lshl_add_u64 v[90:91], v[100:101], 0, v[68:69]
	v_or_b32_e32 v68, 16, v66
	v_ashrrev_i32_e32 v69, 31, v68
	v_lshl_add_u64 v[108:109], v[98:99], 0, v[70:71]
	v_lshlrev_b64 v[70:71], 12, v[68:69]
	v_lshlrev_b64 v[68:69], 11, v[68:69]
	v_lshl_add_u64 v[88:89], v[100:101], 0, v[68:69]
	v_or_b32_e32 v68, 17, v66
	v_ashrrev_i32_e32 v69, 31, v68
	v_lshl_add_u64 v[110:111], v[98:99], 0, v[70:71]
	v_lshlrev_b64 v[70:71], 12, v[68:69]
	v_lshlrev_b64 v[68:69], 11, v[68:69]
	v_lshl_add_u64 v[86:87], v[100:101], 0, v[68:69]
	v_or_b32_e32 v68, 18, v66
	v_ashrrev_i32_e32 v69, 31, v68
	v_lshl_add_u64 v[112:113], v[98:99], 0, v[70:71]
	v_lshlrev_b64 v[70:71], 12, v[68:69]
	v_lshlrev_b64 v[68:69], 11, v[68:69]
	v_lshl_add_u64 v[84:85], v[100:101], 0, v[68:69]
	v_or_b32_e32 v68, 19, v66
	v_ashrrev_i32_e32 v69, 31, v68
	v_lshl_add_u64 v[114:115], v[98:99], 0, v[70:71]
	v_lshlrev_b64 v[70:71], 12, v[68:69]
	v_lshlrev_b64 v[68:69], 11, v[68:69]
	v_lshl_add_u64 v[82:83], v[100:101], 0, v[68:69]
	v_or_b32_e32 v68, 32, v66
	v_ashrrev_i32_e32 v69, 31, v68
	v_lshl_add_u64 v[116:117], v[98:99], 0, v[70:71]
	v_lshlrev_b64 v[70:71], 12, v[68:69]
	v_lshlrev_b64 v[68:69], 11, v[68:69]
	v_lshl_add_u64 v[80:81], v[100:101], 0, v[68:69]
	v_or_b32_e32 v68, 33, v66
	v_ashrrev_i32_e32 v69, 31, v68
	v_lshl_add_u64 v[118:119], v[98:99], 0, v[70:71]
	v_lshlrev_b64 v[70:71], 12, v[68:69]
	v_lshlrev_b64 v[68:69], 11, v[68:69]
	v_lshl_add_u64 v[78:79], v[100:101], 0, v[68:69]
	v_or_b32_e32 v68, 34, v66
	v_ashrrev_i32_e32 v69, 31, v68
	v_lshl_add_u64 v[120:121], v[98:99], 0, v[70:71]
	v_lshlrev_b64 v[70:71], 12, v[68:69]
	v_lshlrev_b64 v[68:69], 11, v[68:69]
	v_lshl_add_u64 v[76:77], v[100:101], 0, v[68:69]
	v_or_b32_e32 v68, 35, v66
	v_ashrrev_i32_e32 v69, 31, v68
	v_lshl_add_u64 v[122:123], v[98:99], 0, v[70:71]
	v_lshlrev_b64 v[70:71], 12, v[68:69]
	v_lshlrev_b64 v[68:69], 11, v[68:69]
	v_lshl_add_u64 v[74:75], v[100:101], 0, v[68:69]
	v_or_b32_e32 v68, 48, v66
	v_ashrrev_i32_e32 v69, 31, v68
	v_lshl_add_u64 v[124:125], v[98:99], 0, v[70:71]
	v_lshlrev_b64 v[70:71], 12, v[68:69]
	v_lshlrev_b64 v[68:69], 11, v[68:69]
	v_lshl_add_u64 v[72:73], v[100:101], 0, v[68:69]
	v_or_b32_e32 v68, 49, v66
	v_ashrrev_i32_e32 v69, 31, v68
	v_lshl_add_u64 v[126:127], v[98:99], 0, v[70:71]
	v_lshlrev_b64 v[70:71], 12, v[68:69]
	v_lshlrev_b64 v[68:69], 11, v[68:69]
	v_lshl_add_u64 v[128:129], v[98:99], 0, v[70:71]
	v_lshl_add_u64 v[70:71], v[100:101], 0, v[68:69]
	v_or_b32_e32 v68, 50, v66
	v_or_b32_e32 v66, 51, v66
	v_ashrrev_i32_e32 v69, 31, v68
	v_ashrrev_i32_e32 v67, 31, v66
	v_lshlrev_b64 v[130:131], 12, v[68:69]
	v_lshlrev_b64 v[132:133], 12, v[66:67]
	v_lshl_add_u64 v[130:131], v[98:99], 0, v[130:131]
	v_lshlrev_b64 v[68:69], 11, v[68:69]
	v_lshl_add_u64 v[98:99], v[98:99], 0, v[132:133]
	v_lshlrev_b64 v[66:67], 11, v[66:67]
	s_barrier
; template <int EPI, bool AF32>
; DEV void gemm_tile(const void* Ap, int lda, const u16* Bt, int ldb, int K, int m0, int n0, const Epi& ea, char* smem) {
;     ...
;       u16* C = (u16*)ea.p0;
;       const u16* G = (const u16*)ea.p1 + (EPI == EP_MERGE2 ? 1024 : 0);
;       u16 gv[4][4][4], cv[4][4][4];
; #pragma unroll
;       for (int m = 0; m < 4; m++)
; #pragma unroll
;         for (int j = 0; j < 4; j++)
; #pragma unroll
;           for (int n = 0; n < 4; n++) {
;             gv[m][j][n] = G[(size_t)(rbase + m * 16 + j) * 2048 + cbase + n * 16];
;             if (EPI == EP_MERGE2) cv[m][j][n] = C[(size_t)(rbase + m * 16 + j) * 1024 + cbase + n * 16];
;           }
	v_lshl_add_u64 v[68:69], v[100:101], 0, v[68:69]
	v_lshl_add_u64 v[66:67], v[100:101], 0, v[66:67]
	global_load_ushort v0, v[102:103], off
	global_load_ushort v100, v[102:103], off offset:32
	global_load_ushort v101, v[102:103], off offset:64
	s_nop 0
	global_load_ushort v102, v[102:103], off offset:96
	s_nop 0
	global_load_ushort v103, v[96:97], off
	global_load_ushort v132, v[96:97], off offset:32
	global_load_ushort v133, v[96:97], off offset:64
	global_load_ushort v134, v[96:97], off offset:96
	global_load_ushort v135, v[104:105], off
	global_load_ushort v136, v[104:105], off offset:32
	global_load_ushort v137, v[104:105], off offset:64
	s_nop 0
	global_load_ushort v104, v[104:105], off offset:96
	s_nop 0
	global_load_ushort v105, v[94:95], off
	global_load_ushort v138, v[94:95], off offset:32
	global_load_ushort v139, v[94:95], off offset:64
	global_load_ushort v140, v[94:95], off offset:96
	global_load_ushort v141, v[106:107], off
	global_load_ushort v142, v[106:107], off offset:32
	global_load_ushort v143, v[106:107], off offset:64
	s_nop 0
	global_load_ushort v106, v[106:107], off offset:96
	s_nop 0
	global_load_ushort v107, v[92:93], off
	global_load_ushort v144, v[92:93], off offset:32
	global_load_ushort v145, v[92:93], off offset:64
	global_load_ushort v146, v[92:93], off offset:96
	global_load_ushort v147, v[108:109], off
	global_load_ushort v148, v[108:109], off offset:32
	global_load_ushort v149, v[108:109], off offset:64
	s_nop 0
	global_load_ushort v108, v[108:109], off offset:96
	s_nop 0
	global_load_ushort v109, v[90:91], off
	global_load_ushort v150, v[90:91], off offset:32
	global_load_ushort v151, v[90:91], off offset:64
	global_load_ushort v152, v[90:91], off offset:96
	global_load_ushort v153, v[110:111], off
	global_load_ushort v161, v[110:111], off offset:32
	global_load_ushort v162, v[110:111], off offset:64
	s_nop 0
	global_load_ushort v110, v[110:111], off offset:96
	s_nop 0
	global_load_ushort v111, v[88:89], off
	global_load_ushort v163, v[88:89], off offset:32
	global_load_ushort v164, v[88:89], off offset:64
	global_load_ushort v165, v[88:89], off offset:96
	global_load_ushort v166, v[112:113], off
	global_load_ushort v167, v[112:113], off offset:32
	global_load_ushort v168, v[112:113], off offset:64
	s_nop 0
	global_load_ushort v112, v[112:113], off offset:96
	s_nop 0
	global_load_ushort v113, v[86:87], off
	global_load_ushort v169, v[86:87], off offset:32
	global_load_ushort v170, v[86:87], off offset:64
	global_load_ushort v171, v[86:87], off offset:96
	global_load_ushort v172, v[114:115], off
	global_load_ushort v173, v[114:115], off offset:32
	global_load_ushort v174, v[114:115], off offset:64
	s_nop 0
	global_load_ushort v114, v[114:115], off offset:96
	s_nop 0
	global_load_ushort v115, v[84:85], off
	global_load_ushort v175, v[84:85], off offset:32
	global_load_ushort v176, v[84:85], off offset:64
	global_load_ushort v177, v[84:85], off offset:96
	global_load_ushort v178, v[116:117], off
	global_load_ushort v179, v[116:117], off offset:32
	global_load_ushort v180, v[116:117], off offset:64
	s_nop 0
	global_load_ushort v116, v[116:117], off offset:96
	s_nop 0
	global_load_ushort v117, v[82:83], off
	global_load_ushort v181, v[82:83], off offset:32
	global_load_ushort v182, v[82:83], off offset:64
	global_load_ushort v183, v[82:83], off offset:96
	global_load_ushort v184, v[118:119], off
	global_load_ushort v185, v[118:119], off offset:32
	global_load_ushort v186, v[118:119], off offset:64
	s_nop 0
	global_load_ushort v118, v[118:119], off offset:96
	s_nop 0
	global_load_ushort v119, v[80:81], off
	global_load_ushort v187, v[80:81], off offset:32
	global_load_ushort v188, v[80:81], off offset:64
	global_load_ushort v189, v[80:81], off offset:96
	global_load_ushort v190, v[120:121], off
	global_load_ushort v191, v[120:121], off offset:32
	global_load_ushort v192, v[120:121], off offset:64
	s_nop 0
	global_load_ushort v120, v[120:121], off offset:96
	s_nop 0
	global_load_ushort v121, v[78:79], off
	global_load_ushort v193, v[78:79], off offset:32
	global_load_ushort v194, v[78:79], off offset:64
	global_load_ushort v195, v[78:79], off offset:96
	global_load_ushort v196, v[122:123], off
	global_load_ushort v197, v[122:123], off offset:32
	global_load_ushort v221, v[122:123], off offset:64
	s_nop 0
	global_load_ushort v122, v[122:123], off offset:96
	s_nop 0
	global_load_ushort v123, v[76:77], off
	global_load_ushort v222, v[76:77], off offset:32
	global_load_ushort v223, v[76:77], off offset:64
	global_load_ushort v224, v[76:77], off offset:96
	global_load_ushort v225, v[124:125], off
	global_load_ushort v226, v[124:125], off offset:32
	global_load_ushort v227, v[124:125], off offset:64
	s_nop 0
	global_load_ushort v124, v[124:125], off offset:96
	s_nop 0
	global_load_ushort v125, v[74:75], off
	global_load_ushort v228, v[74:75], off offset:32
	global_load_ushort v229, v[74:75], off offset:64
	global_load_ushort v230, v[74:75], off offset:96
	global_load_ushort v231, v[126:127], off
	global_load_ushort v232, v[126:127], off offset:32
	global_load_ushort v233, v[126:127], off offset:64
	s_nop 0
	global_load_ushort v126, v[126:127], off offset:96
	s_nop 0
	global_load_ushort v127, v[72:73], off
	global_load_ushort v234, v[72:73], off offset:32
	global_load_ushort v235, v[72:73], off offset:64
	global_load_ushort v236, v[72:73], off offset:96
	global_load_ushort v237, v[128:129], off
	global_load_ushort v238, v[128:129], off offset:32
	global_load_ushort v239, v[128:129], off offset:64
	s_nop 0
	global_load_ushort v128, v[128:129], off offset:96
	s_nop 0
	global_load_ushort v129, v[70:71], off
	global_load_ushort v240, v[70:71], off offset:32
	global_load_ushort v241, v[70:71], off offset:64
	global_load_ushort v242, v[70:71], off offset:96
	global_load_ushort v243, v[130:131], off
	global_load_ushort v244, v[130:131], off offset:32
	global_load_ushort v245, v[130:131], off offset:64
	s_nop 0
	global_load_ushort v130, v[130:131], off offset:96
	s_nop 0
	global_load_ushort v131, v[68:69], off
	global_load_ushort v246, v[68:69], off offset:32
	global_load_ushort v247, v[68:69], off offset:64
	global_load_ushort v248, v[68:69], off offset:96
	global_load_ushort v249, v[98:99], off
	global_load_ushort v250, v[98:99], off offset:32
	global_load_ushort v251, v[98:99], off offset:64
	s_nop 0
	global_load_ushort v98, v[98:99], off offset:96
	s_nop 0
	global_load_ushort v99, v[66:67], off
	global_load_ushort v252, v[66:67], off offset:32
	global_load_ushort v253, v[66:67], off offset:64
	global_load_ushort v201, v[66:67], off offset:96
	s_waitcnt vmcnt(62)
; DEV float bf2f(u16 h) { return __uint_as_float(((unsigned)h) << 16); }
; template <int EPI, bool AF32>
; DEV void gemm_tile(const void* Ap, int lda, const u16* Bt, int ldb, int K, int m0, int n0, const Epi& ea, char* smem) {
;     ...
; #pragma unroll
;       for (int m = 0; m < 4; m++)
; #pragma unroll
;         for (int j = 0; j < 4; j++)
; #pragma unroll
;           for (int n = 0; n < 4; n++) {
;             float v = bf2f(gv[m][j][n]) * acc[m][n][j];
;             if (EPI == EP_MERGE2) v += bf2f(cv[m][j][n]);
;             C[(size_t)(rbase + m * 16 + j) * 1024 + cbase + n * 16] = f2bf(v);
;           }
	v_lshlrev_b32_e32 v0, 16, v0
	v_lshlrev_b32_e32 v103, 16, v103
	v_fmac_f32_e32 v103, v62, v0
	v_cvt_pk_bf16_f32 v0, v103, s0
	global_store_short v[96:97], v0, off
	v_lshlrev_b32_e32 v0, 16, v100
	v_lshlrev_b32_e32 v62, 16, v132
	v_fmac_f32_e32 v62, v58, v0
	v_cvt_pk_bf16_f32 v0, v62, s0
	global_store_short v[96:97], v0, off offset:32
	v_lshlrev_b32_e32 v0, 16, v101
	v_lshlrev_b32_e32 v58, 16, v133
	v_fmac_f32_e32 v58, v54, v0
	v_cvt_pk_bf16_f32 v0, v58, s0
	global_store_short v[96:97], v0, off offset:64
	v_lshlrev_b32_e32 v0, 16, v102
	v_lshlrev_b32_e32 v54, 16, v134
	v_fmac_f32_e32 v54, v50, v0
	v_cvt_pk_bf16_f32 v0, v54, s0
	global_store_short v[96:97], v0, off offset:96
	v_lshlrev_b32_e32 v0, 16, v135
	v_lshlrev_b32_e32 v50, 16, v105
	v_fmac_f32_e32 v50, v63, v0
	v_cvt_pk_bf16_f32 v0, v50, s0
	global_store_short v[94:95], v0, off
	v_lshlrev_b32_e32 v0, 16, v136
	v_lshlrev_b32_e32 v50, 16, v138
	v_fmac_f32_e32 v50, v59, v0
	v_cvt_pk_bf16_f32 v0, v50, s0
	global_store_short v[94:95], v0, off offset:32
	v_lshlrev_b32_e32 v0, 16, v137
	v_lshlrev_b32_e32 v50, 16, v139
	v_fmac_f32_e32 v50, v55, v0
	v_cvt_pk_bf16_f32 v0, v50, s0
	global_store_short v[94:95], v0, off offset:64
	v_lshlrev_b32_e32 v0, 16, v104
	v_lshlrev_b32_e32 v50, 16, v140
	v_fmac_f32_e32 v50, v51, v0
	v_cvt_pk_bf16_f32 v0, v50, s0
	global_store_short v[94:95], v0, off offset:96
	v_lshlrev_b32_e32 v0, 16, v141
	v_lshlrev_b32_e32 v50, 16, v107
	v_fmac_f32_e32 v50, v64, v0
	v_cvt_pk_bf16_f32 v0, v50, s0
	global_store_short v[92:93], v0, off
	v_lshlrev_b32_e32 v0, 16, v142
	v_lshlrev_b32_e32 v50, 16, v144
	v_fmac_f32_e32 v50, v60, v0
	v_cvt_pk_bf16_f32 v0, v50, s0
	global_store_short v[92:93], v0, off offset:32
	v_lshlrev_b32_e32 v0, 16, v143
	v_lshlrev_b32_e32 v50, 16, v145
	v_fmac_f32_e32 v50, v56, v0
	v_cvt_pk_bf16_f32 v0, v50, s0
	global_store_short v[92:93], v0, off offset:64
	v_lshlrev_b32_e32 v0, 16, v106
	v_lshlrev_b32_e32 v50, 16, v146
	v_fmac_f32_e32 v50, v52, v0
	v_cvt_pk_bf16_f32 v0, v50, s0
	global_store_short v[92:93], v0, off offset:96
	v_lshlrev_b32_e32 v0, 16, v147
	v_lshlrev_b32_e32 v50, 16, v109
	v_fmac_f32_e32 v50, v65, v0
	v_cvt_pk_bf16_f32 v0, v50, s0
	global_store_short v[90:91], v0, off
	v_lshlrev_b32_e32 v0, 16, v148
	v_lshlrev_b32_e32 v50, 16, v150
	v_fmac_f32_e32 v50, v61, v0
	v_cvt_pk_bf16_f32 v0, v50, s0
	global_store_short v[90:91], v0, off offset:32
	v_lshlrev_b32_e32 v0, 16, v149
	v_lshlrev_b32_e32 v50, 16, v151
	v_fmac_f32_e32 v50, v57, v0
	v_cvt_pk_bf16_f32 v0, v50, s0
	global_store_short v[90:91], v0, off offset:64
	v_lshlrev_b32_e32 v0, 16, v108
	v_lshlrev_b32_e32 v50, 16, v152
	v_fmac_f32_e32 v50, v53, v0
	v_cvt_pk_bf16_f32 v0, v50, s0
	global_store_short v[90:91], v0, off offset:96
	v_lshlrev_b32_e32 v0, 16, v153
	v_lshlrev_b32_e32 v50, 16, v111
	v_fmac_f32_e32 v50, v46, v0
	v_cvt_pk_bf16_f32 v0, v50, s0
	global_store_short v[88:89], v0, off
	v_lshlrev_b32_e32 v0, 16, v161
	v_lshlrev_b32_e32 v46, 16, v163
	v_fmac_f32_e32 v46, v42, v0
	v_cvt_pk_bf16_f32 v0, v46, s0
	global_store_short v[88:89], v0, off offset:32
	v_lshlrev_b32_e32 v0, 16, v162
	v_lshlrev_b32_e32 v42, 16, v164
	v_fmac_f32_e32 v42, v38, v0
	v_cvt_pk_bf16_f32 v0, v42, s0
	global_store_short v[88:89], v0, off offset:64
	v_lshlrev_b32_e32 v0, 16, v110
	v_lshlrev_b32_e32 v38, 16, v165
	v_fmac_f32_e32 v38, v34, v0
	v_cvt_pk_bf16_f32 v0, v38, s0
	global_store_short v[88:89], v0, off offset:96
	v_lshlrev_b32_e32 v0, 16, v166
	v_lshlrev_b32_e32 v34, 16, v113
	v_fmac_f32_e32 v34, v47, v0
	v_cvt_pk_bf16_f32 v0, v34, s0
	global_store_short v[86:87], v0, off
	v_lshlrev_b32_e32 v0, 16, v167
	v_lshlrev_b32_e32 v34, 16, v169
	v_fmac_f32_e32 v34, v43, v0
	v_cvt_pk_bf16_f32 v0, v34, s0
	global_store_short v[86:87], v0, off offset:32
	v_lshlrev_b32_e32 v0, 16, v168
	v_lshlrev_b32_e32 v34, 16, v170
	v_fmac_f32_e32 v34, v39, v0
	v_cvt_pk_bf16_f32 v0, v34, s0
	global_store_short v[86:87], v0, off offset:64
	v_lshlrev_b32_e32 v0, 16, v112
	v_lshlrev_b32_e32 v34, 16, v171
	v_fmac_f32_e32 v34, v35, v0
	v_cvt_pk_bf16_f32 v0, v34, s0
	global_store_short v[86:87], v0, off offset:96
	v_lshlrev_b32_e32 v0, 16, v172
	v_lshlrev_b32_e32 v34, 16, v115
	v_fmac_f32_e32 v34, v48, v0
	v_cvt_pk_bf16_f32 v0, v34, s0
	global_store_short v[84:85], v0, off
	v_lshlrev_b32_e32 v0, 16, v173
	v_lshlrev_b32_e32 v34, 16, v175
	v_fmac_f32_e32 v34, v44, v0
	v_cvt_pk_bf16_f32 v0, v34, s0
	global_store_short v[84:85], v0, off offset:32
	v_lshlrev_b32_e32 v0, 16, v174
	v_lshlrev_b32_e32 v34, 16, v176
	v_fmac_f32_e32 v34, v40, v0
	v_cvt_pk_bf16_f32 v0, v34, s0
	global_store_short v[84:85], v0, off offset:64
	v_lshlrev_b32_e32 v0, 16, v114
	v_lshlrev_b32_e32 v34, 16, v177
	v_fmac_f32_e32 v34, v36, v0
	v_cvt_pk_bf16_f32 v0, v34, s0
	global_store_short v[84:85], v0, off offset:96
	v_lshlrev_b32_e32 v0, 16, v178
	v_lshlrev_b32_e32 v34, 16, v117
	v_fmac_f32_e32 v34, v49, v0
	v_cvt_pk_bf16_f32 v0, v34, s0
	global_store_short v[82:83], v0, off
	v_lshlrev_b32_e32 v0, 16, v179
	v_lshlrev_b32_e32 v34, 16, v181
	v_fmac_f32_e32 v34, v45, v0
	v_cvt_pk_bf16_f32 v0, v34, s0
	global_store_short v[82:83], v0, off offset:32
	v_lshlrev_b32_e32 v0, 16, v180
	v_lshlrev_b32_e32 v34, 16, v182
	v_fmac_f32_e32 v34, v41, v0
	v_cvt_pk_bf16_f32 v0, v34, s0
	global_store_short v[82:83], v0, off offset:64
	v_lshlrev_b32_e32 v0, 16, v116
	v_lshlrev_b32_e32 v34, 16, v183
	v_fmac_f32_e32 v34, v37, v0
	v_cvt_pk_bf16_f32 v0, v34, s0
	global_store_short v[82:83], v0, off offset:96
	v_lshlrev_b32_e32 v0, 16, v184
	s_waitcnt vmcnt(62)
; DEV int bidx() { int b = __builtin_amdgcn_readfirstlane(blockIdx.x); asm volatile("" : "+s"(b)); return b; }
; DEV int gdim() { int g = __builtin_amdgcn_readfirstlane(gridDim.x); asm volatile("" : "+s"(g)); return g; }
; DEV float bf2f(u16 h) { return __uint_as_float(((unsigned)h) << 16); }
; template <int EPI, bool AF32>
; DEV void gemm_tile(const void* Ap, int lda, const u16* Bt, int ldb, int K, int m0, int n0, const Epi& ea, char* smem) {
;     ...
; #pragma unroll
;       for (int m = 0; m < 4; m++)
; #pragma unroll
;         for (int j = 0; j < 4; j++)
; #pragma unroll
;           for (int n = 0; n < 4; n++) {
;             float v = bf2f(gv[m][j][n]) * acc[m][n][j];
;             if (EPI == EP_MERGE2) v += bf2f(cv[m][j][n]);
;             C[(size_t)(rbase + m * 16 + j) * 1024 + cbase + n * 16] = f2bf(v);
;           }
; template <int EPI, bool AF32>
; DEV void gemm_phase(const void* A, int lda, const u16* Bt, int ldb, int M, int N, int K, const Epi& ea, char* smem) {
;     ...
;   for (int tile = bidx(); tile < ntm * ntn; tile += gdim()) {
;     int m, n;
;     tile_mn(tile, ntm, ntn, m, n);
;     gemm_tile<EPI, AF32>(A, lda, Bt, ldb, K, m << 7, n << 7, ea, smem);
;   }
	v_lshlrev_b32_e32 v34, 16, v119
	v_fmac_f32_e32 v34, v30, v0
	v_cvt_pk_bf16_f32 v0, v34, s0
	global_store_short v[80:81], v0, off
	v_lshlrev_b32_e32 v0, 16, v185
	v_lshlrev_b32_e32 v30, 16, v187
	v_fmac_f32_e32 v30, v26, v0
	v_cvt_pk_bf16_f32 v0, v30, s0
	global_store_short v[80:81], v0, off offset:32
	v_lshlrev_b32_e32 v0, 16, v186
	v_lshlrev_b32_e32 v26, 16, v188
	v_fmac_f32_e32 v26, v22, v0
	v_cvt_pk_bf16_f32 v0, v26, s0
	global_store_short v[80:81], v0, off offset:64
	v_lshlrev_b32_e32 v0, 16, v118
	v_lshlrev_b32_e32 v22, 16, v189
	v_fmac_f32_e32 v22, v18, v0
	v_cvt_pk_bf16_f32 v0, v22, s0
	global_store_short v[80:81], v0, off offset:96
	v_lshlrev_b32_e32 v0, 16, v190
	v_lshlrev_b32_e32 v18, 16, v121
	v_fmac_f32_e32 v18, v31, v0
	v_cvt_pk_bf16_f32 v0, v18, s0
	global_store_short v[78:79], v0, off
	v_lshlrev_b32_e32 v0, 16, v191
	v_lshlrev_b32_e32 v18, 16, v193
	v_fmac_f32_e32 v18, v27, v0
	v_cvt_pk_bf16_f32 v0, v18, s0
	global_store_short v[78:79], v0, off offset:32
	v_lshlrev_b32_e32 v0, 16, v192
	v_lshlrev_b32_e32 v18, 16, v194
	v_fmac_f32_e32 v18, v23, v0
	v_cvt_pk_bf16_f32 v0, v18, s0
	global_store_short v[78:79], v0, off offset:64
	v_lshlrev_b32_e32 v0, 16, v120
	v_lshlrev_b32_e32 v18, 16, v195
	v_fmac_f32_e32 v18, v19, v0
	v_cvt_pk_bf16_f32 v0, v18, s0
	global_store_short v[78:79], v0, off offset:96
	v_lshlrev_b32_e32 v0, 16, v196
	v_lshlrev_b32_e32 v18, 16, v123
	v_fmac_f32_e32 v18, v32, v0
	v_cvt_pk_bf16_f32 v0, v18, s0
	global_store_short v[76:77], v0, off
	v_lshlrev_b32_e32 v0, 16, v197
	v_lshlrev_b32_e32 v18, 16, v222
	v_fmac_f32_e32 v18, v28, v0
	v_cvt_pk_bf16_f32 v0, v18, s0
	global_store_short v[76:77], v0, off offset:32
	v_lshlrev_b32_e32 v0, 16, v221
	v_lshlrev_b32_e32 v18, 16, v223
	v_fmac_f32_e32 v18, v24, v0
	v_cvt_pk_bf16_f32 v0, v18, s0
	global_store_short v[76:77], v0, off offset:64
	v_lshlrev_b32_e32 v0, 16, v122
	v_lshlrev_b32_e32 v18, 16, v224
	v_fmac_f32_e32 v18, v20, v0
	v_cvt_pk_bf16_f32 v0, v18, s0
	global_store_short v[76:77], v0, off offset:96
	v_lshlrev_b32_e32 v0, 16, v225
	v_lshlrev_b32_e32 v18, 16, v125
	v_fmac_f32_e32 v18, v33, v0
	v_cvt_pk_bf16_f32 v0, v18, s0
	global_store_short v[74:75], v0, off
	v_lshlrev_b32_e32 v0, 16, v226
	v_lshlrev_b32_e32 v18, 16, v228
	v_fmac_f32_e32 v18, v29, v0
	v_cvt_pk_bf16_f32 v0, v18, s0
	global_store_short v[74:75], v0, off offset:32
	v_lshlrev_b32_e32 v0, 16, v227
	v_lshlrev_b32_e32 v18, 16, v229
	v_fmac_f32_e32 v18, v25, v0
	v_cvt_pk_bf16_f32 v0, v18, s0
	global_store_short v[74:75], v0, off offset:64
	v_lshlrev_b32_e32 v0, 16, v124
	v_lshlrev_b32_e32 v18, 16, v230
	v_fmac_f32_e32 v18, v21, v0
	v_cvt_pk_bf16_f32 v0, v18, s0
	global_store_short v[74:75], v0, off offset:96
	v_lshlrev_b32_e32 v0, 16, v231
	s_waitcnt vmcnt(62)
	v_lshlrev_b32_e32 v18, 16, v127
	v_fmac_f32_e32 v18, v14, v0
	v_cvt_pk_bf16_f32 v0, v18, s0
	global_store_short v[72:73], v0, off
	v_lshlrev_b32_e32 v0, 16, v232
	v_lshlrev_b32_e32 v14, 16, v234
	v_fmac_f32_e32 v14, v10, v0
	v_cvt_pk_bf16_f32 v0, v14, s0
	global_store_short v[72:73], v0, off offset:32
	v_lshlrev_b32_e32 v0, 16, v233
	v_lshlrev_b32_e32 v10, 16, v235
	v_fmac_f32_e32 v10, v6, v0
	v_cvt_pk_bf16_f32 v0, v10, s0
	global_store_short v[72:73], v0, off offset:64
	v_lshlrev_b32_e32 v0, 16, v126
	v_lshlrev_b32_e32 v6, 16, v236
	v_fmac_f32_e32 v6, v2, v0
	v_cvt_pk_bf16_f32 v0, v6, s0
	global_store_short v[72:73], v0, off offset:96
	v_lshlrev_b32_e32 v0, 16, v237
	v_lshlrev_b32_e32 v2, 16, v129
	v_fmac_f32_e32 v2, v15, v0
	v_cvt_pk_bf16_f32 v0, v2, s0
	global_store_short v[70:71], v0, off
	v_lshlrev_b32_e32 v0, 16, v238
	v_lshlrev_b32_e32 v2, 16, v240
	v_fmac_f32_e32 v2, v11, v0
	v_cvt_pk_bf16_f32 v0, v2, s0
	global_store_short v[70:71], v0, off offset:32
	v_lshlrev_b32_e32 v0, 16, v239
	v_lshlrev_b32_e32 v2, 16, v241
	v_fmac_f32_e32 v2, v7, v0
	v_cvt_pk_bf16_f32 v0, v2, s0
	global_store_short v[70:71], v0, off offset:64
	v_lshlrev_b32_e32 v0, 16, v128
	v_lshlrev_b32_e32 v2, 16, v242
	v_fmac_f32_e32 v2, v3, v0
	v_cvt_pk_bf16_f32 v0, v2, s0
	global_store_short v[70:71], v0, off offset:96
	v_lshlrev_b32_e32 v0, 16, v243
	s_waitcnt vmcnt(62)
	v_lshlrev_b32_e32 v2, 16, v131
	v_fmac_f32_e32 v2, v16, v0
	v_cvt_pk_bf16_f32 v0, v2, s0
	global_store_short v[68:69], v0, off
	v_lshlrev_b32_e32 v0, 16, v244
	v_lshlrev_b32_e32 v2, 16, v246
	v_fmac_f32_e32 v2, v12, v0
	v_cvt_pk_bf16_f32 v0, v2, s0
	global_store_short v[68:69], v0, off offset:32
	v_lshlrev_b32_e32 v0, 16, v245
	v_lshlrev_b32_e32 v2, 16, v247
	v_fmac_f32_e32 v2, v8, v0
	v_cvt_pk_bf16_f32 v0, v2, s0
	global_store_short v[68:69], v0, off offset:64
	v_lshlrev_b32_e32 v0, 16, v130
	v_lshlrev_b32_e32 v2, 16, v248
	v_fmac_f32_e32 v2, v4, v0
	v_cvt_pk_bf16_f32 v0, v2, s0
	global_store_short v[68:69], v0, off offset:96
	v_lshlrev_b32_e32 v0, 16, v249
	s_waitcnt vmcnt(62)
	v_lshlrev_b32_e32 v2, 16, v99
	v_fmac_f32_e32 v2, v17, v0
	v_cvt_pk_bf16_f32 v0, v2, s0
	global_store_short v[66:67], v0, off
	v_lshlrev_b32_e32 v0, 16, v250
	v_lshlrev_b32_e32 v2, 16, v252
	v_fmac_f32_e32 v2, v13, v0
	v_cvt_pk_bf16_f32 v0, v2, s0
	global_store_short v[66:67], v0, off offset:32
	v_lshlrev_b32_e32 v0, 16, v251
	s_waitcnt vmcnt(62)
	v_lshlrev_b32_e32 v2, 16, v253
	v_fmac_f32_e32 v2, v9, v0
	v_cvt_pk_bf16_f32 v0, v2, s0
	global_store_short v[66:67], v0, off offset:64
	v_lshlrev_b32_e32 v0, 16, v98
	v_lshlrev_b32_e32 v2, 16, v201
	v_fmac_f32_e32 v2, v5, v0
	v_cvt_pk_bf16_f32 v0, v2, s0
	v_readfirstlane_b32 s0, v198
	global_store_short v[66:67], v0, off offset:96
	s_add_i32 s14, s0, s14
	s_cmpk_lt_i32 s14, 0x820
	s_cbranch_scc1 .LBB0_1309
	v_mov_b32_e32 v201, 0x2723000

; template <int EPI, bool AF32>
; DEV void gemm_tile(const void* Ap, int lda, const u16* Bt, int ldb, int K, int m0, int n0, const Epi& ea, char* smem) {
;     ...
;   auto gload = [&](int kt) {
;     const int k0 = kt << 6;
; #pragma unroll
;     for (int i = 0; i < 4; i++) {
;       const int c = tid + i * 256, row = c >> 3, kc = c & 7;
;       if (AF32) {
;         const float* pa = (const float*)Ap + (size_t)(m0 + row) * lda + k0 + kc * 8;
;         rfa[2 * i] = *(const f32x4*)pa;
;         rfa[2 * i + 1] = *(const f32x4*)(pa + 4);
;       } else {
;         ra[i] = *(const u32x4*)((const u16*)Ap + (size_t)(m0 + row) * lda + k0 + kc * 8);
;       }
;       rb[i] = *(const u32x4*)(Bt + (size_t)(n0 + row) * ldb + k0 + kc * 8);
;     }
;   };
;   auto swrite = [&](int buf) {
; #pragma unroll
;     for (int i = 0; i < 4; i++) {
;       const int c = tid + i * 256, row = c >> 3, kc = c & 7;
;       u32x4 va;
;       if (AF32) {
;         va = (u32x4){pack2(rfa[2 * i][0], rfa[2 * i][1]), pack2(rfa[2 * i][2], rfa[2 * i][3]),
;                      pack2(rfa[2 * i + 1][0], rfa[2 * i + 1][1]), pack2(rfa[2 * i + 1][2], rfa[2 * i + 1][3])};
;       } else {
;         va = ra[i];
;       }
;       *(u32x4*)(sA + buf * 9216 + row * 72 + kc * 8) = va;
;       *(u32x4*)(sB + buf * 9216 + row * 72 + kc * 8) = rb[i];
;     }
;   };
;   gload(0);
;   swrite(0);
;   if (nk > 1) gload(1);
;   __syncthreads();
.LBB0_1352:
	s_ashr_i32 s10, s12, 31
	s_lshr_b32 s10, s10, 24
	s_add_i32 s10, s12, s10
	s_ashr_i32 s11, s10, 8
	s_and_b32 s10, s10, 0xffffff00
	s_lshl_b32 s14, s11, 5
	s_sub_i32 s13, s12, s10
	s_sub_i32 s10, 0x104, s14
	s_min_u32 s15, s10, 32
	v_cvt_f32_ubyte0_e32 v2, s15
	v_cvt_f32_i32_e32 v0, s13
	v_rcp_iflag_f32_e32 v3, v2
	s_ashr_i32 s10, s13, 30
	s_or_b32 s16, s10, 1
	s_waitcnt vmcnt(12)
	v_mov_b32_e32 v114, v157
	v_mul_f32_e32 v3, v0, v3
	v_trunc_f32_e32 v3, v3
	v_fma_f32 v0, -v3, v2, v0
	v_cvt_i32_f32_e32 v3, v3
	v_cmp_ge_f32_e64 s[10:11], |v0|, v2
	s_and_b64 s[10:11], s[10:11], exec
	s_cselect_b32 s10, s16, 0
	v_readfirstlane_b32 s11, v3
	s_add_i32 s10, s11, s10
	s_sext_i32_i16 s11, s10
	s_mul_i32 s10, s10, s15
	s_sub_i32 s10, s13, s10
	s_sext_i32_i16 s10, s10
	s_add_i32 s14, s14, s10
	s_lshl_b32 s14, s14, 7
	s_lshl_b32 s13, s11, 7
	v_ashrrev_i32_e32 v8, 3, v114
	v_add_u32_e32 v2, s14, v8
	v_ashrrev_i32_e32 v3, 31, v2
	v_lshlrev_b32_e32 v0, 3, v114
	v_add_u32_e32 v4, 0x100, v114
	v_lshlrev_b64 v[58:59], 11, v[2:3]
	v_and_b32_e32 v0, 56, v0
	v_ashrrev_i32_e32 v9, 3, v4
	v_lshl_add_u64 v[2:3], s[0:1], 0, v[58:59]
	v_lshlrev_b32_e32 v0, 1, v0
	v_add_u32_e32 v4, s14, v9
	v_add_u32_e32 v6, 0x200, v114
	v_lshl_add_u64 v[14:15], v[2:3], 0, v[0:1]
	v_add_u32_e32 v2, s13, v8
	v_ashrrev_i32_e32 v5, 31, v4
	v_ashrrev_i32_e32 v10, 3, v6
	v_ashrrev_i32_e32 v3, 31, v2
	v_lshlrev_b64 v[62:63], 11, v[4:5]
	v_add_u32_e32 v6, s14, v10
	v_lshlrev_b64 v[60:61], 11, v[2:3]
	v_lshl_add_u64 v[4:5], s[0:1], 0, v[62:63]
	v_ashrrev_i32_e32 v7, 31, v6
	v_lshl_add_u64 v[2:3], s[4:5], 0, v[60:61]
	v_lshl_add_u64 v[16:17], v[4:5], 0, v[0:1]
	v_add_u32_e32 v4, s13, v9
	v_lshlrev_b64 v[66:67], 11, v[6:7]
	v_lshl_add_u64 v[2:3], v[2:3], 0, v[0:1]
	v_ashrrev_i32_e32 v5, 31, v4
	v_lshl_add_u64 v[6:7], s[0:1], 0, v[66:67]
	global_load_dwordx4 v[30:33], v[2:3], off
	v_lshlrev_b64 v[64:65], 11, v[4:5]
	v_lshl_add_u64 v[68:69], v[6:7], 0, v[0:1]
	v_add_u32_e32 v6, s13, v10
	global_load_dwordx4 v[26:29], v[14:15], off
	global_load_dwordx4 v[34:37], v[16:17], off
	v_lshl_add_u64 v[4:5], s[4:5], 0, v[64:65]
	v_ashrrev_i32_e32 v7, 31, v6
	v_lshl_add_u64 v[4:5], v[4:5], 0, v[0:1]
	v_lshlrev_b64 v[70:71], 11, v[6:7]
	global_load_dwordx4 v[38:41], v[4:5], off
	v_lshl_add_u64 v[6:7], s[4:5], 0, v[70:71]
	global_load_dwordx4 v[42:45], v[68:69], off
	v_lshl_add_u64 v[18:19], v[6:7], 0, v[0:1]
	global_load_dwordx4 v[46:49], v[18:19], off
	v_add_u32_e32 v6, 0x300, v114
	v_ashrrev_i32_e32 v80, 3, v6
	v_add_u32_e32 v6, s14, v80
	v_ashrrev_i32_e32 v7, 31, v6
	v_lshlrev_b64 v[72:73], 11, v[6:7]
	v_lshl_add_u64 v[6:7], s[0:1], 0, v[72:73]
	v_lshl_add_u64 v[74:75], v[6:7], 0, v[0:1]
	v_add_u32_e32 v6, s13, v80
	v_ashrrev_i32_e32 v7, 31, v6
	v_lshlrev_b64 v[76:77], 11, v[6:7]
	v_lshl_add_u64 v[6:7], s[4:5], 0, v[76:77]
	v_lshl_add_u64 v[78:79], v[6:7], 0, v[0:1]
	global_load_dwordx4 v[50:53], v[74:75], off
	global_load_dwordx4 v[54:57], v[78:79], off
	s_waitcnt vmcnt(19)
	v_mul_lo_u32 v118, v8, s71
	v_mul_lo_u32 v119, v9, s71
	s_waitcnt vmcnt(18)
	v_mul_lo_u32 v123, v10, s71
	global_load_dwordx4 v[6:9], v[2:3], off offset:128
	global_load_dwordx4 v[10:13], v[4:5], off offset:128
	s_nop 0
	global_load_dwordx4 v[2:5], v[18:19], off offset:128
	global_load_dwordx4 v[22:25], v[14:15], off offset:128
	s_nop 0
	global_load_dwordx4 v[18:21], v[16:17], off offset:128
	s_nop 0
	global_load_dwordx4 v[14:17], v[68:69], off offset:128
	v_bfe_u32 v161, v157, 3, 4
	v_add_u32_e32 v161, 4, v161
	v_lshlrev_b32_e32 v161, 1, v161
	v_and_b32_e32 v161, 16, v161
	v_xor_b32_e32 v129, v0, v161
	v_lshl_add_u32 v122, v118, 1, v129
	v_lshl_add_u32 v121, v119, 1, v129
	v_lshl_add_u32 v120, v123, 1, v129
	v_and_b32_e32 v115, 15, v114
	s_waitcnt vmcnt(23)
	v_mul_lo_u32 v126, v80, s71
	v_bfe_u32 v116, v114, 4, 2
	v_lshl_add_u32 v124, v126, 1, v129
	s_mov_b32 s15, 0
	v_lshlrev_b32_e32 v125, 4, v116
	v_and_b32_e32 v161, 15, v157
	v_add_u32_e32 v161, 4, v161
	v_lshlrev_b32_e32 v161, 1, v161
	v_and_b32_e32 v161, 16, v161
	v_xor_b32_e32 v125, v125, v161
	s_mov_b64 s[10:11], 0
	s_waitcnt vmcnt(13)
	ds_write_b128 v122, v[30:33] offset:36864
	s_waitcnt vmcnt(12)
	ds_write_b128 v122, v[26:29]
	s_waitcnt vmcnt(11)
	ds_write_b128 v121, v[34:37]
	s_waitcnt vmcnt(10)
	ds_write_b128 v121, v[38:41] offset:36864
	s_waitcnt vmcnt(9)
	ds_write_b128 v120, v[42:45]
	s_waitcnt vmcnt(8)
	ds_write_b128 v120, v[46:49] offset:36864
	global_load_dwordx4 v[26:29], v[74:75], off offset:128
	global_load_dwordx4 v[30:33], v[78:79], off offset:128
	v_ashrrev_i32_e32 v34, 1, v114
	v_and_b32_e32 v117, 0xffffffc0, v34
	v_or_b32_e32 v34, v117, v115
	v_mul_lo_u32 v128, v34, s71
	v_lshlrev_b32_e32 v34, 4, v114
	v_and_b32_e32 v34, 0x70, v34
	v_and_b32_e32 v35, 0x4f, v114
	v_or_b32_e32 v76, v76, v34
	v_or_b32_e32 v72, v72, v34
	v_or_b32_e32 v70, v70, v34
	v_or_b32_e32 v66, v66, v34
	v_or_b32_e32 v64, v64, v34
	v_or_b32_e32 v62, v62, v34
	v_or_b32_e32 v60, v60, v34
	v_or_b32_e32 v58, v58, v34
	v_mov_b32_e32 v34, 0
	s_waitcnt vmcnt(9)
	ds_write_b128 v124, v[50:53]
	s_waitcnt vmcnt(8)
; DEV f32x4 mfma16(bf16x8 a, bf16x8 b, f32x4 c) { return __builtin_amdgcn_mfma_f32_16x16x32_bf16(a, b, c, 0, 0, 0); }
; template <int EPI, bool AF32>
; DEV void gemm_tile(const void* Ap, int lda, const u16* Bt, int ldb, int K, int m0, int n0, const Epi& ea, char* smem) {
;     ...
;   gload(0);
;   swrite(0);
;   if (nk > 1) gload(1);
;   __syncthreads();
;   for (int kt = 0; kt < nk; kt++) {
;     const int buf = kt & 1;
;     if (kt + 1 < nk) swrite(buf ^ 1);
;     if (kt + 2 < nk) gload(kt + 2);
; #pragma unroll
;     for (int ks = 0; ks < 2; ks++) {
;       bf16x8 a[4], b[4];
; #pragma unroll
;       for (int m = 0; m < 4; m++) a[m] = *(const bf16x8*)(sA + buf * 9216 + (wr * 64 + m * 16 + fr) * 72 + ks * 32 + fq * 8);
; #pragma unroll
;       for (int n = 0; n < 4; n++) b[n] = *(const bf16x8*)(sB + buf * 9216 + (wc * 64 + n * 16 + fr) * 72 + ks * 32 + fq * 8);
;       __builtin_amdgcn_s_setprio(1);
; #pragma unroll
;       for (int m = 0; m < 4; m++)
; #pragma unroll
;         for (int n = 0; n < 4; n++) acc[m][n] = mfma16(a[m], b[n], acc[m][n]);
;       __builtin_amdgcn_s_setprio(0);
;     }
;     __syncthreads();
	ds_write_b128 v124, v[54:57] offset:36864
	v_mul_u32_u24_e32 v127, 0x48, v35
	v_lshl_add_u64 v[98:99], s[6:7], 0, v[76:77]
	v_lshl_add_u64 v[100:101], s[8:9], 0, v[72:73]
	v_lshl_add_u64 v[102:103], s[6:7], 0, v[70:71]
	v_lshl_add_u64 v[104:105], s[8:9], 0, v[66:67]
	v_lshl_add_u64 v[106:107], s[6:7], 0, v[64:65]
	v_lshl_add_u64 v[108:109], s[8:9], 0, v[62:63]
	v_lshl_add_u64 v[110:111], s[6:7], 0, v[60:61]
	v_lshl_add_u64 v[112:113], s[8:9], 0, v[58:59]
	v_mov_b32_e32 v35, v34
	v_mov_b32_e32 v36, v34
	v_mov_b32_e32 v37, v34
	v_mov_b32_e32 v38, v34
	v_mov_b32_e32 v39, v34
	v_mov_b32_e32 v40, v34
	v_mov_b32_e32 v41, v34
	v_mov_b32_e32 v42, v34
	v_mov_b32_e32 v43, v34
	v_mov_b32_e32 v44, v34
	v_mov_b32_e32 v45, v34
	v_mov_b32_e32 v46, v34
	v_mov_b32_e32 v47, v34
	v_mov_b32_e32 v48, v34
	v_mov_b32_e32 v49, v34
	v_mov_b32_e32 v50, v34
	v_mov_b32_e32 v51, v34
	v_mov_b32_e32 v52, v34
	v_mov_b32_e32 v53, v34
	v_mov_b32_e32 v54, v34
	v_mov_b32_e32 v55, v34
	v_mov_b32_e32 v56, v34
	v_mov_b32_e32 v57, v34
	v_mov_b32_e32 v58, v34
	v_mov_b32_e32 v59, v34
	v_mov_b32_e32 v60, v34
	v_mov_b32_e32 v61, v34
	v_mov_b32_e32 v62, v34
	v_mov_b32_e32 v63, v34
	v_mov_b32_e32 v64, v34
	v_mov_b32_e32 v65, v34
	v_mov_b32_e32 v66, v34
	v_mov_b32_e32 v67, v34
	v_mov_b32_e32 v68, v34
	v_mov_b32_e32 v69, v34
	v_mov_b32_e32 v70, v34
	v_mov_b32_e32 v71, v34
	v_mov_b32_e32 v72, v34
	v_mov_b32_e32 v73, v34
	v_mov_b32_e32 v74, v34
	v_mov_b32_e32 v75, v34
	v_mov_b32_e32 v76, v34
	v_mov_b32_e32 v77, v34
	v_mov_b32_e32 v78, v34
	v_mov_b32_e32 v79, v34
	v_mov_b32_e32 v80, v34
	v_mov_b32_e32 v81, v34
	v_mov_b32_e32 v82, v34
	v_mov_b32_e32 v83, v34
	v_mov_b32_e32 v84, v34
	v_mov_b32_e32 v85, v34
	v_mov_b32_e32 v86, v34
	v_mov_b32_e32 v87, v34
	v_mov_b32_e32 v88, v34
	v_mov_b32_e32 v89, v34
	v_mov_b32_e32 v90, v34
	v_mov_b32_e32 v91, v34
	v_mov_b32_e32 v92, v34
	v_mov_b32_e32 v93, v34
	v_mov_b32_e32 v94, v34
	v_mov_b32_e32 v95, v34
	v_mov_b32_e32 v96, v34
	v_mov_b32_e32 v97, v34
	s_waitcnt lgkmcnt(0)
	s_barrier
	v_lshl_add_u32 v161, v128, 1, v125
	v_lshl_add_u32 v129, v127, 1, v125
	s_mov_b32 s15, 0
	s_mov_b64 s[10:11], 0x100
	ds_read_b128 v[130:133], v161
	ds_read_b128 v[134:137], v161 offset:2304
	ds_read_b128 v[138:141], v161 offset:4608
	ds_read_b128 v[142:145], v161 offset:6912
	ds_read_b128 v[146:149], v129 offset:36864
	ds_read_b128 v[150:153], v129 offset:39168
	ds_read_b128 v[162:165], v129 offset:41472
	ds_read_b128 v[166:169], v129 offset:43776
.Lgk5_loop:
	s_waitcnt lgkmcnt(0)
	ds_read_b128 v[222:225], v161 offset:64
	ds_read_b128 v[226:229], v161 offset:2368
	ds_read_b128 v[230:233], v161 offset:4672
	ds_read_b128 v[234:237], v161 offset:6976
	ds_read_b128 v[238:241], v129 offset:36928
	ds_read_b128 v[242:245], v129 offset:39232
	ds_read_b128 v[246:249], v129 offset:41536
	ds_read_b128 v[250:253], v129 offset:43840
	v_mfma_f32_16x16x32_bf16 v[34:37], v[130:133], v[146:149], v[34:37]
	v_mfma_f32_16x16x32_bf16 v[38:41], v[130:133], v[150:153], v[38:41]
	v_mfma_f32_16x16x32_bf16 v[42:45], v[130:133], v[162:165], v[42:45]
	v_mfma_f32_16x16x32_bf16 v[46:49], v[130:133], v[166:169], v[46:49]
	s_waitcnt vmcnt(0)
	ds_write_b128 v122, v[22:25] offset:18432
	ds_write_b128 v122, v[6:9] offset:55296
	v_mfma_f32_16x16x32_bf16 v[50:53], v[134:137], v[146:149], v[50:53]
	ds_write_b128 v121, v[18:21] offset:18432
	ds_write_b128 v121, v[10:13] offset:55296
	v_mfma_f32_16x16x32_bf16 v[54:57], v[134:137], v[150:153], v[54:57]
	ds_write_b128 v120, v[14:17] offset:18432
	ds_write_b128 v120, v[2:5] offset:55296
	v_mfma_f32_16x16x32_bf16 v[58:61], v[134:137], v[162:165], v[58:61]
	ds_write_b128 v124, v[26:29] offset:18432
	ds_write_b128 v124, v[30:33] offset:55296
	v_mfma_f32_16x16x32_bf16 v[62:65], v[134:137], v[166:169], v[62:65]
	global_load_dwordx4 v[22:25], v[112:113], off
	v_mfma_f32_16x16x32_bf16 v[66:69], v[138:141], v[146:149], v[66:69]
	global_load_dwordx4 v[6:9], v[110:111], off
	v_mfma_f32_16x16x32_bf16 v[70:73], v[138:141], v[150:153], v[70:73]
	global_load_dwordx4 v[18:21], v[108:109], off
	v_mfma_f32_16x16x32_bf16 v[74:77], v[138:141], v[162:165], v[74:77]
	global_load_dwordx4 v[10:13], v[106:107], off
	v_mfma_f32_16x16x32_bf16 v[78:81], v[138:141], v[166:169], v[78:81]
	global_load_dwordx4 v[14:17], v[104:105], off
	v_mfma_f32_16x16x32_bf16 v[82:85], v[142:145], v[146:149], v[82:85]
	global_load_dwordx4 v[2:5], v[102:103], off
	v_mfma_f32_16x16x32_bf16 v[86:89], v[142:145], v[150:153], v[86:89]
	global_load_dwordx4 v[26:29], v[100:101], off
	v_mfma_f32_16x16x32_bf16 v[90:93], v[142:145], v[162:165], v[90:93]
	global_load_dwordx4 v[30:33], v[98:99], off
	v_mfma_f32_16x16x32_bf16 v[94:97], v[142:145], v[166:169], v[94:97]
	s_waitcnt lgkmcnt(0)
	s_barrier
; DEV f32x4 mfma16(bf16x8 a, bf16x8 b, f32x4 c) { return __builtin_amdgcn_mfma_f32_16x16x32_bf16(a, b, c, 0, 0, 0); }
; template <int EPI, bool AF32>
; DEV void gemm_tile(const void* Ap, int lda, const u16* Bt, int ldb, int K, int m0, int n0, const Epi& ea, char* smem) {
;     ...
;   for (int kt = 0; kt < nk; kt++) {
;     const int buf = kt & 1;
;     if (kt + 1 < nk) swrite(buf ^ 1);
;     if (kt + 2 < nk) gload(kt + 2);
; #pragma unroll
;     for (int ks = 0; ks < 2; ks++) {
;       bf16x8 a[4], b[4];
; #pragma unroll
;       for (int m = 0; m < 4; m++) a[m] = *(const bf16x8*)(sA + buf * 9216 + (wr * 64 + m * 16 + fr) * 72 + ks * 32 + fq * 8);
; #pragma unroll
;       for (int n = 0; n < 4; n++) b[n] = *(const bf16x8*)(sB + buf * 9216 + (wc * 64 + n * 16 + fr) * 72 + ks * 32 + fq * 8);
;       __builtin_amdgcn_s_setprio(1);
; #pragma unroll
;       for (int m = 0; m < 4; m++)
; #pragma unroll
;         for (int n = 0; n < 4; n++) acc[m][n] = mfma16(a[m], b[n], acc[m][n]);
;       __builtin_amdgcn_s_setprio(0);
;     }
;     __syncthreads();
	ds_read_b128 v[130:133], v161 offset:18432
	v_mfma_f32_16x16x32_bf16 v[34:37], v[222:225], v[238:241], v[34:37]
	ds_read_b128 v[134:137], v161 offset:20736
	v_mfma_f32_16x16x32_bf16 v[38:41], v[222:225], v[242:245], v[38:41]
	ds_read_b128 v[138:141], v161 offset:23040
	v_mfma_f32_16x16x32_bf16 v[42:45], v[222:225], v[246:249], v[42:45]
	ds_read_b128 v[142:145], v161 offset:25344
	v_mfma_f32_16x16x32_bf16 v[46:49], v[222:225], v[250:253], v[46:49]
	ds_read_b128 v[146:149], v129 offset:55296
	v_mfma_f32_16x16x32_bf16 v[50:53], v[226:229], v[238:241], v[50:53]
	ds_read_b128 v[150:153], v129 offset:57600
	v_mfma_f32_16x16x32_bf16 v[54:57], v[226:229], v[242:245], v[54:57]
	ds_read_b128 v[162:165], v129 offset:59904
	v_mfma_f32_16x16x32_bf16 v[58:61], v[226:229], v[246:249], v[58:61]
	ds_read_b128 v[166:169], v129 offset:62208
	v_mfma_f32_16x16x32_bf16 v[62:65], v[226:229], v[250:253], v[62:65]
	v_mfma_f32_16x16x32_bf16 v[66:69], v[230:233], v[238:241], v[66:69]
	v_mfma_f32_16x16x32_bf16 v[70:73], v[230:233], v[242:245], v[70:73]
	v_mfma_f32_16x16x32_bf16 v[74:77], v[230:233], v[246:249], v[74:77]
	v_mfma_f32_16x16x32_bf16 v[78:81], v[230:233], v[250:253], v[78:81]
	v_mfma_f32_16x16x32_bf16 v[82:85], v[234:237], v[238:241], v[82:85]
	v_mfma_f32_16x16x32_bf16 v[86:89], v[234:237], v[242:245], v[86:89]
	v_mfma_f32_16x16x32_bf16 v[90:93], v[234:237], v[246:249], v[90:93]
	v_mfma_f32_16x16x32_bf16 v[94:97], v[234:237], v[250:253], v[94:97]
	s_waitcnt lgkmcnt(0)
	ds_read_b128 v[222:225], v161 offset:18496
	ds_read_b128 v[226:229], v161 offset:20800
	ds_read_b128 v[230:233], v161 offset:23104
	ds_read_b128 v[234:237], v161 offset:25408
	ds_read_b128 v[238:241], v129 offset:55360
	ds_read_b128 v[242:245], v129 offset:57664
	ds_read_b128 v[246:249], v129 offset:59968
	ds_read_b128 v[250:253], v129 offset:62272
	v_mfma_f32_16x16x32_bf16 v[34:37], v[130:133], v[146:149], v[34:37]
	v_mfma_f32_16x16x32_bf16 v[38:41], v[130:133], v[150:153], v[38:41]
	v_mfma_f32_16x16x32_bf16 v[42:45], v[130:133], v[162:165], v[42:45]
	v_mfma_f32_16x16x32_bf16 v[46:49], v[130:133], v[166:169], v[46:49]
	s_waitcnt vmcnt(0)
	ds_write_b128 v122, v[22:25]
	ds_write_b128 v122, v[6:9] offset:36864
	v_mfma_f32_16x16x32_bf16 v[50:53], v[134:137], v[146:149], v[50:53]
	ds_write_b128 v121, v[18:21]
	ds_write_b128 v121, v[10:13] offset:36864
	v_mfma_f32_16x16x32_bf16 v[54:57], v[134:137], v[150:153], v[54:57]
	ds_write_b128 v120, v[14:17]
	ds_write_b128 v120, v[2:5] offset:36864
	v_mfma_f32_16x16x32_bf16 v[58:61], v[134:137], v[162:165], v[58:61]
	ds_write_b128 v124, v[26:29]
	ds_write_b128 v124, v[30:33] offset:36864
	v_mfma_f32_16x16x32_bf16 v[62:65], v[134:137], v[166:169], v[62:65]
	global_load_dwordx4 v[22:25], v[112:113], off offset:128
	v_mfma_f32_16x16x32_bf16 v[66:69], v[138:141], v[146:149], v[66:69]
	global_load_dwordx4 v[6:9], v[110:111], off offset:128
	v_mfma_f32_16x16x32_bf16 v[70:73], v[138:141], v[150:153], v[70:73]
	global_load_dwordx4 v[18:21], v[108:109], off offset:128
	v_mfma_f32_16x16x32_bf16 v[74:77], v[138:141], v[162:165], v[74:77]
	global_load_dwordx4 v[10:13], v[106:107], off offset:128
	v_mfma_f32_16x16x32_bf16 v[78:81], v[138:141], v[166:169], v[78:81]
	global_load_dwordx4 v[14:17], v[104:105], off offset:128
	v_mfma_f32_16x16x32_bf16 v[82:85], v[142:145], v[146:149], v[82:85]
	global_load_dwordx4 v[2:5], v[102:103], off offset:128
	v_mfma_f32_16x16x32_bf16 v[86:89], v[142:145], v[150:153], v[86:89]
	global_load_dwordx4 v[26:29], v[100:101], off offset:128
	v_mfma_f32_16x16x32_bf16 v[90:93], v[142:145], v[162:165], v[90:93]
	global_load_dwordx4 v[30:33], v[98:99], off offset:128
	v_mfma_f32_16x16x32_bf16 v[94:97], v[142:145], v[166:169], v[94:97]
	s_waitcnt lgkmcnt(0)
	s_barrier
	ds_read_b128 v[130:133], v161
	v_mfma_f32_16x16x32_bf16 v[34:37], v[222:225], v[238:241], v[34:37]
	ds_read_b128 v[134:137], v161 offset:2304
	v_mfma_f32_16x16x32_bf16 v[38:41], v[222:225], v[242:245], v[38:41]
	ds_read_b128 v[138:141], v161 offset:4608
	v_mfma_f32_16x16x32_bf16 v[42:45], v[222:225], v[246:249], v[42:45]
	ds_read_b128 v[142:145], v161 offset:6912
	v_mfma_f32_16x16x32_bf16 v[46:49], v[222:225], v[250:253], v[46:49]
	ds_read_b128 v[146:149], v129 offset:36864
	v_mfma_f32_16x16x32_bf16 v[50:53], v[226:229], v[238:241], v[50:53]
	ds_read_b128 v[150:153], v129 offset:39168
	v_mfma_f32_16x16x32_bf16 v[54:57], v[226:229], v[242:245], v[54:57]
	ds_read_b128 v[162:165], v129 offset:41472
	v_mfma_f32_16x16x32_bf16 v[58:61], v[226:229], v[246:249], v[58:61]
	ds_read_b128 v[166:169], v129 offset:43776
	v_mfma_f32_16x16x32_bf16 v[62:65], v[226:229], v[250:253], v[62:65]
	v_mfma_f32_16x16x32_bf16 v[66:69], v[230:233], v[238:241], v[66:69]
	v_lshl_add_u64 v[112:113], v[112:113], 0, s[10:11]
	v_mfma_f32_16x16x32_bf16 v[70:73], v[230:233], v[242:245], v[70:73]
	v_lshl_add_u64 v[110:111], v[110:111], 0, s[10:11]
	v_mfma_f32_16x16x32_bf16 v[74:77], v[230:233], v[246:249], v[74:77]
	v_lshl_add_u64 v[108:109], v[108:109], 0, s[10:11]
	v_mfma_f32_16x16x32_bf16 v[78:81], v[230:233], v[250:253], v[78:81]
	v_lshl_add_u64 v[106:107], v[106:107], 0, s[10:11]
	v_mfma_f32_16x16x32_bf16 v[82:85], v[234:237], v[238:241], v[82:85]
	v_lshl_add_u64 v[104:105], v[104:105], 0, s[10:11]
	v_mfma_f32_16x16x32_bf16 v[86:89], v[234:237], v[242:245], v[86:89]
	v_lshl_add_u64 v[102:103], v[102:103], 0, s[10:11]
	v_mfma_f32_16x16x32_bf16 v[90:93], v[234:237], v[246:249], v[90:93]
	v_lshl_add_u64 v[100:101], v[100:101], 0, s[10:11]
	v_mfma_f32_16x16x32_bf16 v[94:97], v[234:237], v[250:253], v[94:97]
	v_lshl_add_u64 v[98:99], v[98:99], 0, s[10:11]
	s_add_i32 s15, s15, 1
	s_cmp_lg_u32 s15, 7
	s_cbranch_scc1 .Lgk5_loop
; DEV f32x4 mfma16(bf16x8 a, bf16x8 b, f32x4 c) { return __builtin_amdgcn_mfma_f32_16x16x32_bf16(a, b, c, 0, 0, 0); }
; template <int EPI, bool AF32>
; DEV void gemm_tile(const void* Ap, int lda, const u16* Bt, int ldb, int K, int m0, int n0, const Epi& ea, char* smem) {
;     ...
;   for (int kt = 0; kt < nk; kt++) {
;     const int buf = kt & 1;
;     if (kt + 1 < nk) swrite(buf ^ 1);
;     if (kt + 2 < nk) gload(kt + 2);
; #pragma unroll
;     for (int ks = 0; ks < 2; ks++) {
;       bf16x8 a[4], b[4];
; #pragma unroll
;       for (int m = 0; m < 4; m++) a[m] = *(const bf16x8*)(sA + buf * 9216 + (wr * 64 + m * 16 + fr) * 72 + ks * 32 + fq * 8);
; #pragma unroll
;       for (int n = 0; n < 4; n++) b[n] = *(const bf16x8*)(sB + buf * 9216 + (wc * 64 + n * 16 + fr) * 72 + ks * 32 + fq * 8);
;       __builtin_amdgcn_s_setprio(1);
; #pragma unroll
;       for (int m = 0; m < 4; m++)
; #pragma unroll
;         for (int n = 0; n < 4; n++) acc[m][n] = mfma16(a[m], b[n], acc[m][n]);
;       __builtin_amdgcn_s_setprio(0);
;     }
;     __syncthreads();
	s_waitcnt vmcnt(7)
	ds_write_b128 v122, v[22:25] offset:18432
	s_waitcnt vmcnt(6)
	ds_write_b128 v122, v[6:9] offset:55296
	s_waitcnt vmcnt(5)
	ds_write_b128 v121, v[18:21] offset:18432
	s_waitcnt vmcnt(4)
	ds_write_b128 v121, v[10:13] offset:55296
	s_waitcnt vmcnt(3)
	ds_write_b128 v120, v[14:17] offset:18432
	s_waitcnt vmcnt(2)
	ds_write_b128 v120, v[2:5] offset:55296
	s_waitcnt vmcnt(1)
	ds_write_b128 v124, v[26:29] offset:18432
	s_waitcnt vmcnt(0)
	ds_write_b128 v124, v[30:33] offset:55296
	v_lshl_add_u32 v0, v128, 1, v125
	v_lshl_add_u32 v106, v127, 1, v125
	ds_read_b128 v[2:5], v0
	ds_read_b128 v[6:9], v0 offset:2304
	ds_read_b128 v[10:13], v0 offset:4608
	ds_read_b128 v[14:17], v0 offset:6912
	ds_read_b128 v[18:21], v106 offset:36864
	ds_read_b128 v[22:25], v106 offset:39168
	ds_read_b128 v[26:29], v106 offset:41472
	ds_read_b128 v[30:33], v106 offset:43776
	s_setprio 1
	s_waitcnt lgkmcnt(3)
	v_mfma_f32_16x16x32_bf16 v[34:37], v[2:5], v[18:21], v[34:37]
	s_waitcnt lgkmcnt(2)
	v_mfma_f32_16x16x32_bf16 v[38:41], v[2:5], v[22:25], v[38:41]
	s_waitcnt lgkmcnt(1)
	v_mfma_f32_16x16x32_bf16 v[42:45], v[2:5], v[26:29], v[42:45]
	s_waitcnt lgkmcnt(0)
	v_mfma_f32_16x16x32_bf16 v[2:5], v[2:5], v[30:33], v[46:49]
	v_mfma_f32_16x16x32_bf16 v[46:49], v[6:9], v[18:21], v[50:53]
	v_mfma_f32_16x16x32_bf16 v[50:53], v[6:9], v[22:25], v[54:57]
	v_mfma_f32_16x16x32_bf16 v[54:57], v[6:9], v[26:29], v[58:61]
	v_mfma_f32_16x16x32_bf16 v[6:9], v[6:9], v[30:33], v[62:65]
	v_mfma_f32_16x16x32_bf16 v[58:61], v[10:13], v[18:21], v[66:69]
	v_mfma_f32_16x16x32_bf16 v[62:65], v[10:13], v[22:25], v[70:73]
	v_mfma_f32_16x16x32_bf16 v[66:69], v[10:13], v[26:29], v[74:77]
	v_mfma_f32_16x16x32_bf16 v[10:13], v[10:13], v[30:33], v[78:81]
	v_mfma_f32_16x16x32_bf16 v[18:21], v[14:17], v[18:21], v[82:85]
	v_mfma_f32_16x16x32_bf16 v[22:25], v[14:17], v[22:25], v[86:89]
	v_mfma_f32_16x16x32_bf16 v[26:29], v[14:17], v[26:29], v[90:93]
	v_mfma_f32_16x16x32_bf16 v[14:17], v[14:17], v[30:33], v[94:97]
	s_setprio 0
	ds_read_b128 v[30:33], v0 offset:64
	ds_read_b128 v[70:73], v0 offset:2368
	ds_read_b128 v[74:77], v0 offset:4672
	ds_read_b128 v[78:81], v0 offset:6976
	ds_read_b128 v[82:85], v106 offset:36928
	ds_read_b128 v[86:89], v106 offset:39232
	ds_read_b128 v[90:93], v106 offset:41536
	ds_read_b128 v[94:97], v106 offset:43840
	s_setprio 1
	s_waitcnt lgkmcnt(3)
	v_mfma_f32_16x16x32_bf16 v[34:37], v[30:33], v[82:85], v[34:37]
	s_waitcnt lgkmcnt(2)
	v_mfma_f32_16x16x32_bf16 v[38:41], v[30:33], v[86:89], v[38:41]
	s_waitcnt lgkmcnt(1)
	v_mfma_f32_16x16x32_bf16 v[42:45], v[30:33], v[90:93], v[42:45]
	s_waitcnt lgkmcnt(0)
	v_mfma_f32_16x16x32_bf16 v[2:5], v[30:33], v[94:97], v[2:5]
	v_mfma_f32_16x16x32_bf16 v[30:33], v[70:73], v[82:85], v[46:49]
	v_mfma_f32_16x16x32_bf16 v[46:49], v[70:73], v[86:89], v[50:53]
	v_mfma_f32_16x16x32_bf16 v[50:53], v[70:73], v[90:93], v[54:57]
	v_mfma_f32_16x16x32_bf16 v[6:9], v[70:73], v[94:97], v[6:9]
	v_mfma_f32_16x16x32_bf16 v[54:57], v[74:77], v[82:85], v[58:61]
	v_mfma_f32_16x16x32_bf16 v[58:61], v[74:77], v[86:89], v[62:65]
	v_mfma_f32_16x16x32_bf16 v[62:65], v[74:77], v[90:93], v[66:69]
	v_mfma_f32_16x16x32_bf16 v[10:13], v[74:77], v[94:97], v[10:13]
	v_mfma_f32_16x16x32_bf16 v[18:21], v[78:81], v[82:85], v[18:21]
	v_mfma_f32_16x16x32_bf16 v[22:25], v[78:81], v[86:89], v[22:25]
	v_mfma_f32_16x16x32_bf16 v[26:29], v[78:81], v[90:93], v[26:29]
	v_mfma_f32_16x16x32_bf16 v[14:17], v[78:81], v[94:97], v[14:17]
	s_setprio 0
	s_barrier
	ds_read_b128 v[66:69], v0 offset:18432
	ds_read_b128 v[70:73], v0 offset:20736
	ds_read_b128 v[74:77], v0 offset:23040
	ds_read_b128 v[78:81], v0 offset:25344
	ds_read_b128 v[82:85], v106 offset:55296
	ds_read_b128 v[86:89], v106 offset:57600
	ds_read_b128 v[90:93], v106 offset:59904
	ds_read_b128 v[94:97], v106 offset:62208
	v_and_b32_e32 v114, 64, v114
	s_setprio 1
	s_waitcnt lgkmcnt(3)
	v_mfma_f32_16x16x32_bf16 v[34:37], v[66:69], v[82:85], v[34:37]
	s_waitcnt lgkmcnt(2)
	v_mfma_f32_16x16x32_bf16 v[38:41], v[66:69], v[86:89], v[38:41]
	s_waitcnt lgkmcnt(1)
	v_mfma_f32_16x16x32_bf16 v[42:45], v[66:69], v[90:93], v[42:45]
	s_waitcnt lgkmcnt(0)
	v_mfma_f32_16x16x32_bf16 v[2:5], v[66:69], v[94:97], v[2:5]
	v_mfma_f32_16x16x32_bf16 v[30:33], v[70:73], v[82:85], v[30:33]
	v_mfma_f32_16x16x32_bf16 v[66:69], v[70:73], v[86:89], v[46:49]
	v_mfma_f32_16x16x32_bf16 v[50:53], v[70:73], v[90:93], v[50:53]
	v_mfma_f32_16x16x32_bf16 v[6:9], v[70:73], v[94:97], v[6:9]
	v_mfma_f32_16x16x32_bf16 v[54:57], v[74:77], v[82:85], v[54:57]
	v_mfma_f32_16x16x32_bf16 v[58:61], v[74:77], v[86:89], v[58:61]
	v_mfma_f32_16x16x32_bf16 v[62:65], v[74:77], v[90:93], v[62:65]
	v_mfma_f32_16x16x32_bf16 v[10:13], v[74:77], v[94:97], v[10:13]
	v_mfma_f32_16x16x32_bf16 v[70:73], v[78:81], v[82:85], v[18:21]
	v_mfma_f32_16x16x32_bf16 v[74:77], v[78:81], v[86:89], v[22:25]
	v_mfma_f32_16x16x32_bf16 v[82:85], v[78:81], v[90:93], v[26:29]
	v_mfma_f32_16x16x32_bf16 v[78:81], v[78:81], v[94:97], v[14:17]
	s_setprio 0
	s_nop 1
	ds_read_b128 v[14:17], v0 offset:18496
	ds_read_b128 v[18:21], v0 offset:20800
	ds_read_b128 v[86:89], v0 offset:23104
	ds_read_b128 v[90:93], v0 offset:25408
	ds_read_b128 v[94:97], v106 offset:55360
	ds_read_b128 v[98:101], v106 offset:57664
	ds_read_b128 v[102:105], v106 offset:59968
	ds_read_b128 v[106:109], v106 offset:62272
	s_setprio 1
	s_waitcnt lgkmcnt(3)
	v_mfma_f32_16x16x32_bf16 v[110:113], v[14:17], v[94:97], v[34:37]
	s_waitcnt lgkmcnt(2)
	v_mfma_f32_16x16x32_bf16 v[118:121], v[14:17], v[98:101], v[38:41]
	s_waitcnt lgkmcnt(1)
	v_mfma_f32_16x16x32_bf16 v[122:125], v[14:17], v[102:105], v[42:45]
	s_waitcnt lgkmcnt(0)
; DEV f32x4 mfma16(bf16x8 a, bf16x8 b, f32x4 c) { return __builtin_amdgcn_mfma_f32_16x16x32_bf16(a, b, c, 0, 0, 0); }
; template <int EPI, bool AF32>
; DEV void gemm_tile(const void* Ap, int lda, const u16* Bt, int ldb, int K, int m0, int n0, const Epi& ea, char* smem) {
;     ...
;   for (int kt = 0; kt < nk; kt++) {
;     const int buf = kt & 1;
;     if (kt + 1 < nk) swrite(buf ^ 1);
;     if (kt + 2 < nk) gload(kt + 2);
; #pragma unroll
;     for (int ks = 0; ks < 2; ks++) {
;       bf16x8 a[4], b[4];
; #pragma unroll
;       for (int m = 0; m < 4; m++) a[m] = *(const bf16x8*)(sA + buf * 9216 + (wr * 64 + m * 16 + fr) * 72 + ks * 32 + fq * 8);
; #pragma unroll
;       for (int n = 0; n < 4; n++) b[n] = *(const bf16x8*)(sB + buf * 9216 + (wc * 64 + n * 16 + fr) * 72 + ks * 32 + fq * 8);
;       __builtin_amdgcn_s_setprio(1);
; #pragma unroll
;       for (int m = 0; m < 4; m++)
; #pragma unroll
;         for (int n = 0; n < 4; n++) acc[m][n] = mfma16(a[m], b[n], acc[m][n]);
;       __builtin_amdgcn_s_setprio(0);
;     }
;     __syncthreads();
;     ...
;   if (EPI == EP_RESB) {
;     const int rbase = m0 + wr * 64 + fq * 4, cbase = cb + fr;
;     float* C = (float*)ea.p0;
;     const u16* R = (const u16*)ea.p1;
;     u16 rv[4][4][4];
; #pragma unroll
;     for (int m = 0; m < 4; m++)
; #pragma unroll
;       for (int j = 0; j < 4; j++)
; #pragma unroll
;         for (int n = 0; n < 4; n++) rv[m][j][n] = R[(size_t)(rbase + m * 16 + j) * 1024 + cbase + n * 16];
;     __builtin_amdgcn_sched_barrier(0);
	v_mfma_f32_16x16x32_bf16 v[126:129], v[14:17], v[106:109], v[2:5]
	v_mfma_f32_16x16x32_bf16 v[46:49], v[18:21], v[94:97], v[30:33]
	v_mfma_f32_16x16x32_bf16 v[42:45], v[18:21], v[98:101], v[66:69]
	v_mfma_f32_16x16x32_bf16 v[38:41], v[18:21], v[102:105], v[50:53]
	v_mfma_f32_16x16x32_bf16 v[34:37], v[18:21], v[106:109], v[6:9]
	v_mfma_f32_16x16x32_bf16 v[30:33], v[86:89], v[94:97], v[54:57]
	v_mfma_f32_16x16x32_bf16 v[26:29], v[86:89], v[98:101], v[58:61]
	v_mfma_f32_16x16x32_bf16 v[22:25], v[86:89], v[102:105], v[62:65]
	v_mfma_f32_16x16x32_bf16 v[18:21], v[86:89], v[106:109], v[10:13]
	v_mfma_f32_16x16x32_bf16 v[14:17], v[90:93], v[94:97], v[70:73]
	v_mfma_f32_16x16x32_bf16 v[10:13], v[90:93], v[98:101], v[74:77]
	v_mfma_f32_16x16x32_bf16 v[6:9], v[90:93], v[102:105], v[82:85]
	v_mfma_f32_16x16x32_bf16 v[2:5], v[90:93], v[106:109], v[78:81]
	s_setprio 0
	v_add_u32_e32 v0, s14, v117
	v_lshl_or_b32 v60, v116, 2, v0
	v_or3_b32 v62, v114, s13, v115
	v_ashrrev_i32_e32 v63, 31, v62
	v_ashrrev_i32_e32 v61, 31, v60
	v_or_b32_e32 v68, 1, v60
	v_lshl_add_u64 v[64:65], v[62:63], 1, s[60:61]
	v_lshlrev_b64 v[50:51], 11, v[60:61]
	v_ashrrev_i32_e32 v69, 31, v68
	v_or_b32_e32 v72, 2, v60
	v_lshl_add_u64 v[66:67], v[64:65], 0, v[50:51]
	v_lshlrev_b64 v[50:51], 11, v[68:69]
	v_ashrrev_i32_e32 v73, 31, v72
	v_or_b32_e32 v76, 3, v60
	v_lshl_add_u64 v[70:71], v[64:65], 0, v[50:51]
	v_lshlrev_b64 v[50:51], 11, v[72:73]
	v_ashrrev_i32_e32 v77, 31, v76
	v_or_b32_e32 v80, 16, v60
	v_lshl_add_u64 v[74:75], v[64:65], 0, v[50:51]
	v_lshlrev_b64 v[50:51], 11, v[76:77]
	v_ashrrev_i32_e32 v81, 31, v80
	v_or_b32_e32 v84, 17, v60
	v_lshl_add_u64 v[78:79], v[64:65], 0, v[50:51]
	v_lshlrev_b64 v[50:51], 11, v[80:81]
	v_ashrrev_i32_e32 v85, 31, v84
	v_or_b32_e32 v88, 18, v60
	v_lshl_add_u64 v[82:83], v[64:65], 0, v[50:51]
	v_lshlrev_b64 v[50:51], 11, v[84:85]
	v_ashrrev_i32_e32 v89, 31, v88
	v_or_b32_e32 v92, 19, v60
	v_lshl_add_u64 v[86:87], v[64:65], 0, v[50:51]
	v_lshlrev_b64 v[50:51], 11, v[88:89]
	v_ashrrev_i32_e32 v93, 31, v92
	v_or_b32_e32 v96, 32, v60
	v_lshl_add_u64 v[90:91], v[64:65], 0, v[50:51]
	v_lshlrev_b64 v[50:51], 11, v[92:93]
	v_ashrrev_i32_e32 v97, 31, v96
	v_or_b32_e32 v100, 33, v60
	v_lshl_add_u64 v[94:95], v[64:65], 0, v[50:51]
	v_lshlrev_b64 v[50:51], 11, v[96:97]
	v_ashrrev_i32_e32 v101, 31, v100
	v_or_b32_e32 v104, 34, v60
	v_lshl_add_u64 v[98:99], v[64:65], 0, v[50:51]
	v_lshlrev_b64 v[50:51], 11, v[100:101]
	v_ashrrev_i32_e32 v105, 31, v104
	v_or_b32_e32 v58, 35, v60
	v_lshl_add_u64 v[102:103], v[64:65], 0, v[50:51]
	v_lshlrev_b64 v[50:51], 11, v[104:105]
	v_ashrrev_i32_e32 v59, 31, v58
	v_or_b32_e32 v56, 48, v60
	v_lshl_add_u64 v[106:107], v[64:65], 0, v[50:51]
	v_lshlrev_b64 v[50:51], 11, v[58:59]
	v_ashrrev_i32_e32 v57, 31, v56
	v_or_b32_e32 v54, 49, v60
	v_lshl_add_u64 v[108:109], v[64:65], 0, v[50:51]
	v_lshlrev_b64 v[50:51], 11, v[56:57]
	v_ashrrev_i32_e32 v55, 31, v54
	v_or_b32_e32 v52, 50, v60
	v_lshl_add_u64 v[114:115], v[64:65], 0, v[50:51]
	v_lshlrev_b64 v[50:51], 11, v[54:55]
	v_ashrrev_i32_e32 v53, 31, v52
	v_lshl_add_u64 v[116:117], v[64:65], 0, v[50:51]
	v_lshlrev_b64 v[50:51], 11, v[52:53]
	v_lshl_add_u64 v[130:131], v[64:65], 0, v[50:51]
	v_or_b32_e32 v50, 51, v60
	v_ashrrev_i32_e32 v51, 31, v50
	v_lshlrev_b64 v[132:133], 11, v[50:51]
	v_lshl_add_u64 v[64:65], v[64:65], 0, v[132:133]
	s_barrier
	global_load_ushort v0, v[66:67], off
	global_load_ushort v132, v[66:67], off offset:32
	global_load_ushort v133, v[66:67], off offset:64
	s_nop 0
	global_load_ushort v66, v[66:67], off offset:96
	s_nop 0
	global_load_ushort v67, v[70:71], off
	global_load_ushort v134, v[70:71], off offset:32
	global_load_ushort v135, v[70:71], off offset:64
	s_nop 0
	global_load_ushort v70, v[70:71], off offset:96
	s_nop 0
	global_load_ushort v71, v[74:75], off
	global_load_ushort v136, v[74:75], off offset:32
	global_load_ushort v137, v[74:75], off offset:64
	s_nop 0
	global_load_ushort v74, v[74:75], off offset:96
	s_nop 0
	global_load_ushort v75, v[78:79], off
	global_load_ushort v138, v[78:79], off offset:32
	global_load_ushort v139, v[78:79], off offset:64
	s_nop 0
	global_load_ushort v78, v[78:79], off offset:96
	s_nop 0
	global_load_ushort v79, v[82:83], off
	global_load_ushort v140, v[82:83], off offset:32
	global_load_ushort v141, v[82:83], off offset:64
	s_nop 0
	global_load_ushort v82, v[82:83], off offset:96
	s_nop 0
	global_load_ushort v83, v[86:87], off
	global_load_ushort v142, v[86:87], off offset:32
	global_load_ushort v143, v[86:87], off offset:64
	s_nop 0
	global_load_ushort v86, v[86:87], off offset:96
	s_nop 0
	global_load_ushort v87, v[90:91], off
	global_load_ushort v144, v[90:91], off offset:32
	global_load_ushort v145, v[90:91], off offset:64
	s_nop 0
	global_load_ushort v90, v[90:91], off offset:96
	s_nop 0
	global_load_ushort v91, v[94:95], off
	global_load_ushort v146, v[94:95], off offset:32
	global_load_ushort v147, v[94:95], off offset:64
	s_nop 0
	global_load_ushort v94, v[94:95], off offset:96
	s_nop 0
	global_load_ushort v95, v[98:99], off
	global_load_ushort v148, v[98:99], off offset:32
	global_load_ushort v149, v[98:99], off offset:64
	s_nop 0
	global_load_ushort v98, v[98:99], off offset:96
	s_nop 0
	global_load_ushort v99, v[102:103], off
	global_load_ushort v150, v[102:103], off offset:32
	global_load_ushort v151, v[102:103], off offset:64
	s_nop 0
	global_load_ushort v102, v[102:103], off offset:96
	s_nop 0
	global_load_ushort v103, v[106:107], off
	global_load_ushort v152, v[106:107], off offset:32
	global_load_ushort v153, v[106:107], off offset:64
	s_nop 0
	global_load_ushort v106, v[106:107], off offset:96
	s_nop 0
	global_load_ushort v107, v[108:109], off
	global_load_ushort v161, v[108:109], off offset:32
	global_load_ushort v162, v[108:109], off offset:64
	s_nop 0
	global_load_ushort v108, v[108:109], off offset:96
	s_nop 0
	global_load_ushort v109, v[114:115], off
	global_load_ushort v163, v[114:115], off offset:32
	global_load_ushort v164, v[114:115], off offset:64
	s_nop 0
	global_load_ushort v114, v[114:115], off offset:96
	s_nop 0
	global_load_ushort v115, v[116:117], off
	global_load_ushort v165, v[116:117], off offset:32
	global_load_ushort v166, v[116:117], off offset:64
	s_nop 0
	global_load_ushort v116, v[116:117], off offset:96
	s_nop 0
	global_load_ushort v117, v[130:131], off
	global_load_ushort v167, v[130:131], off offset:32
	global_load_ushort v168, v[130:131], off offset:64
	s_nop 0
	global_load_ushort v130, v[130:131], off offset:96
	s_nop 0
	global_load_ushort v131, v[64:65], off
	global_load_ushort v169, v[64:65], off offset:32
	global_load_ushort v170, v[64:65], off offset:64
	s_nop 0
	global_load_ushort v64, v[64:65], off offset:96
	v_lshl_add_u64 v[62:63], v[62:63], 2, s[2:3]
	v_lshlrev_b64 v[60:61], 12, v[60:61]
	s_waitcnt vmcnt(62)
; DEV float bf2f(u16 h) { return __uint_as_float(((unsigned)h) << 16); }
; template <int EPI, bool AF32>
; DEV void gemm_tile(const void* Ap, int lda, const u16* Bt, int ldb, int K, int m0, int n0, const Epi& ea, char* smem) {
;     ...
; #pragma unroll
;     for (int m = 0; m < 4; m++)
; #pragma unroll
;       for (int j = 0; j < 4; j++)
; #pragma unroll
;         for (int n = 0; n < 4; n++)
;           C[(size_t)(rbase + m * 16 + j) * 1024 + cbase + n * 16] = ALPHA_ * bf2f(rv[m][j][n]) + acc[m][n][j];
;     return;
	v_lshlrev_b32_e32 v0, 16, v0
	v_lshl_add_u64 v[60:61], v[62:63], 0, v[60:61]
	v_fmamk_f32 v0, v0, 0x3fb504f3, v110
	global_store_dword v[60:61], v0, off
	v_lshlrev_b32_e32 v0, 16, v132
	v_fmamk_f32 v0, v0, 0x3fb504f3, v118
	global_store_dword v[60:61], v0, off offset:64
	s_waitcnt vmcnt(62)
	v_lshlrev_b32_e32 v0, 16, v133
	v_fmamk_f32 v0, v0, 0x3fb504f3, v122
	global_store_dword v[60:61], v0, off offset:128
	v_lshlrev_b32_e32 v0, 16, v66
	v_fmamk_f32 v0, v0, 0x3fb504f3, v126
	global_store_dword v[60:61], v0, off offset:192
	v_lshlrev_b64 v[60:61], 12, v[68:69]
	s_waitcnt vmcnt(62)
	v_lshlrev_b32_e32 v0, 16, v67
	v_lshl_add_u64 v[60:61], v[62:63], 0, v[60:61]
	v_fmamk_f32 v0, v0, 0x3fb504f3, v111
	global_store_dword v[60:61], v0, off
	v_lshlrev_b32_e32 v0, 16, v134
	v_fmamk_f32 v0, v0, 0x3fb504f3, v119
	global_store_dword v[60:61], v0, off offset:64
	s_waitcnt vmcnt(62)
	v_lshlrev_b32_e32 v0, 16, v135
	v_fmamk_f32 v0, v0, 0x3fb504f3, v123
	global_store_dword v[60:61], v0, off offset:128
	v_lshlrev_b32_e32 v0, 16, v70
	v_fmamk_f32 v0, v0, 0x3fb504f3, v127
	global_store_dword v[60:61], v0, off offset:192
	v_lshlrev_b64 v[60:61], 12, v[72:73]
	s_waitcnt vmcnt(62)
	v_lshlrev_b32_e32 v0, 16, v71
	v_lshl_add_u64 v[60:61], v[62:63], 0, v[60:61]
	v_fmamk_f32 v0, v0, 0x3fb504f3, v112
	global_store_dword v[60:61], v0, off
	v_lshlrev_b32_e32 v0, 16, v136
	v_fmamk_f32 v0, v0, 0x3fb504f3, v120
	global_store_dword v[60:61], v0, off offset:64
	s_waitcnt vmcnt(62)
	v_lshlrev_b32_e32 v0, 16, v137
	v_fmamk_f32 v0, v0, 0x3fb504f3, v124
	global_store_dword v[60:61], v0, off offset:128
	v_lshlrev_b32_e32 v0, 16, v74
	v_fmamk_f32 v0, v0, 0x3fb504f3, v128
	global_store_dword v[60:61], v0, off offset:192
	s_waitcnt vmcnt(62)
	v_lshlrev_b32_e32 v0, 16, v75
	v_fmac_f32_e32 v113, 0x3fb504f3, v0
	v_lshlrev_b32_e32 v0, 16, v138
	v_fmac_f32_e32 v121, 0x3fb504f3, v0
	s_waitcnt vmcnt(61)
	v_lshlrev_b32_e32 v0, 16, v139
	v_lshlrev_b64 v[60:61], 12, v[76:77]
	v_fmac_f32_e32 v125, 0x3fb504f3, v0
	s_waitcnt vmcnt(60)
	v_lshlrev_b32_e32 v0, 16, v78
	v_lshl_add_u64 v[60:61], v[62:63], 0, v[60:61]
	v_fmac_f32_e32 v129, 0x3fb504f3, v0
	global_store_dword v[60:61], v113, off
	global_store_dword v[60:61], v121, off offset:64
	global_store_dword v[60:61], v125, off offset:128
	global_store_dword v[60:61], v129, off offset:192
	v_lshlrev_b64 v[60:61], 12, v[80:81]
	s_waitcnt vmcnt(62)
	v_lshlrev_b32_e32 v0, 16, v79
	v_lshl_add_u64 v[60:61], v[62:63], 0, v[60:61]
	v_fmamk_f32 v0, v0, 0x3fb504f3, v46
	global_store_dword v[60:61], v0, off
	v_lshlrev_b32_e32 v0, 16, v140
	v_fmamk_f32 v0, v0, 0x3fb504f3, v42
	global_store_dword v[60:61], v0, off offset:64
	s_waitcnt vmcnt(62)
	v_lshlrev_b32_e32 v0, 16, v141
	v_fmamk_f32 v0, v0, 0x3fb504f3, v38
	global_store_dword v[60:61], v0, off offset:128
	v_lshlrev_b32_e32 v0, 16, v82
	v_fmamk_f32 v0, v0, 0x3fb504f3, v34
	global_store_dword v[60:61], v0, off offset:192
	v_lshlrev_b64 v[60:61], 12, v[84:85]
	s_waitcnt vmcnt(62)
	v_lshlrev_b32_e32 v0, 16, v83
	v_lshl_add_u64 v[60:61], v[62:63], 0, v[60:61]
	v_fmamk_f32 v0, v0, 0x3fb504f3, v47
	global_store_dword v[60:61], v0, off
	v_lshlrev_b32_e32 v0, 16, v142
	v_fmamk_f32 v0, v0, 0x3fb504f3, v43
	global_store_dword v[60:61], v0, off offset:64
	s_waitcnt vmcnt(62)
	v_lshlrev_b32_e32 v0, 16, v143
	v_fmamk_f32 v0, v0, 0x3fb504f3, v39
	global_store_dword v[60:61], v0, off offset:128
	v_lshlrev_b32_e32 v0, 16, v86
	v_fmamk_f32 v0, v0, 0x3fb504f3, v35
	global_store_dword v[60:61], v0, off offset:192
	v_lshlrev_b64 v[34:35], 12, v[88:89]
	s_waitcnt vmcnt(62)
	v_lshlrev_b32_e32 v0, 16, v87
	v_lshl_add_u64 v[34:35], v[62:63], 0, v[34:35]
	v_fmamk_f32 v0, v0, 0x3fb504f3, v48
	global_store_dword v[34:35], v0, off
	v_lshlrev_b32_e32 v0, 16, v144
	v_fmamk_f32 v0, v0, 0x3fb504f3, v44
	global_store_dword v[34:35], v0, off offset:64
	s_waitcnt vmcnt(62)
	v_lshlrev_b32_e32 v0, 16, v145
	v_fmamk_f32 v0, v0, 0x3fb504f3, v40
	global_store_dword v[34:35], v0, off offset:128
	v_lshlrev_b32_e32 v0, 16, v90
	v_fmamk_f32 v0, v0, 0x3fb504f3, v36
	global_store_dword v[34:35], v0, off offset:192
	s_waitcnt vmcnt(62)
	v_lshlrev_b32_e32 v0, 16, v91
	v_fmac_f32_e32 v49, 0x3fb504f3, v0
	v_lshlrev_b32_e32 v0, 16, v146
	v_fmac_f32_e32 v45, 0x3fb504f3, v0
	s_waitcnt vmcnt(61)
	v_lshlrev_b32_e32 v0, 16, v147
	v_lshlrev_b64 v[34:35], 12, v[92:93]
	v_fmac_f32_e32 v41, 0x3fb504f3, v0
	s_waitcnt vmcnt(60)
	v_lshlrev_b32_e32 v0, 16, v94
	v_lshl_add_u64 v[34:35], v[62:63], 0, v[34:35]
	v_fmac_f32_e32 v37, 0x3fb504f3, v0
	global_store_dword v[34:35], v49, off
	global_store_dword v[34:35], v45, off offset:64
	global_store_dword v[34:35], v41, off offset:128
	global_store_dword v[34:35], v37, off offset:192
	v_lshlrev_b64 v[34:35], 12, v[96:97]
	s_waitcnt vmcnt(62)
; DEV int bidx() { int b = __builtin_amdgcn_readfirstlane(blockIdx.x); asm volatile("" : "+s"(b)); return b; }
; DEV int gdim() { int g = __builtin_amdgcn_readfirstlane(gridDim.x); asm volatile("" : "+s"(g)); return g; }
; DEV float bf2f(u16 h) { return __uint_as_float(((unsigned)h) << 16); }
; template <int EPI, bool AF32>
; DEV void gemm_tile(const void* Ap, int lda, const u16* Bt, int ldb, int K, int m0, int n0, const Epi& ea, char* smem) {
;     ...
; #pragma unroll
;     for (int m = 0; m < 4; m++)
; #pragma unroll
;       for (int j = 0; j < 4; j++)
; #pragma unroll
;         for (int n = 0; n < 4; n++)
;           C[(size_t)(rbase + m * 16 + j) * 1024 + cbase + n * 16] = ALPHA_ * bf2f(rv[m][j][n]) + acc[m][n][j];
;     return;
; template <int EPI, bool AF32>
; DEV void gemm_phase(const void* A, int lda, const u16* Bt, int ldb, int M, int N, int K, const Epi& ea, char* smem) {
;     ...
;   for (int tile = bidx(); tile < ntm * ntn; tile += gdim()) {
	v_lshlrev_b32_e32 v0, 16, v95
	v_lshl_add_u64 v[34:35], v[62:63], 0, v[34:35]
	v_fmamk_f32 v0, v0, 0x3fb504f3, v30
	global_store_dword v[34:35], v0, off
	v_lshlrev_b32_e32 v0, 16, v148
	v_fmamk_f32 v0, v0, 0x3fb504f3, v26
	global_store_dword v[34:35], v0, off offset:64
	s_waitcnt vmcnt(62)
	v_lshlrev_b32_e32 v0, 16, v149
	v_fmamk_f32 v0, v0, 0x3fb504f3, v22
	global_store_dword v[34:35], v0, off offset:128
	v_lshlrev_b32_e32 v0, 16, v98
	v_fmamk_f32 v0, v0, 0x3fb504f3, v18
	global_store_dword v[34:35], v0, off offset:192
	v_lshlrev_b64 v[34:35], 12, v[100:101]
	s_waitcnt vmcnt(62)
	v_lshlrev_b32_e32 v0, 16, v99
	v_lshl_add_u64 v[34:35], v[62:63], 0, v[34:35]
	v_fmamk_f32 v0, v0, 0x3fb504f3, v31
	global_store_dword v[34:35], v0, off
	v_lshlrev_b32_e32 v0, 16, v150
	v_fmamk_f32 v0, v0, 0x3fb504f3, v27
	global_store_dword v[34:35], v0, off offset:64
	s_waitcnt vmcnt(62)
	v_lshlrev_b32_e32 v0, 16, v151
	v_fmamk_f32 v0, v0, 0x3fb504f3, v23
	global_store_dword v[34:35], v0, off offset:128
	v_lshlrev_b32_e32 v0, 16, v102
	v_fmamk_f32 v0, v0, 0x3fb504f3, v19
	global_store_dword v[34:35], v0, off offset:192
	v_lshlrev_b64 v[18:19], 12, v[104:105]
	s_waitcnt vmcnt(62)
	v_lshlrev_b32_e32 v0, 16, v103
	v_lshl_add_u64 v[18:19], v[62:63], 0, v[18:19]
	v_fmamk_f32 v0, v0, 0x3fb504f3, v32
	global_store_dword v[18:19], v0, off
	v_lshlrev_b32_e32 v0, 16, v152
	v_fmamk_f32 v0, v0, 0x3fb504f3, v28
	global_store_dword v[18:19], v0, off offset:64
	s_waitcnt vmcnt(62)
	v_lshlrev_b32_e32 v0, 16, v153
	v_fmamk_f32 v0, v0, 0x3fb504f3, v24
	global_store_dword v[18:19], v0, off offset:128
	v_lshlrev_b32_e32 v0, 16, v106
	v_fmamk_f32 v0, v0, 0x3fb504f3, v20
	global_store_dword v[18:19], v0, off offset:192
	s_waitcnt vmcnt(62)
	v_lshlrev_b32_e32 v0, 16, v107
	v_fmac_f32_e32 v33, 0x3fb504f3, v0
	v_lshlrev_b32_e32 v0, 16, v161
	v_fmac_f32_e32 v29, 0x3fb504f3, v0
	s_waitcnt vmcnt(61)
	v_lshlrev_b32_e32 v0, 16, v162
	v_lshlrev_b64 v[18:19], 12, v[58:59]
	v_fmac_f32_e32 v25, 0x3fb504f3, v0
	s_waitcnt vmcnt(60)
	v_lshlrev_b32_e32 v0, 16, v108
	v_lshl_add_u64 v[18:19], v[62:63], 0, v[18:19]
	v_fmac_f32_e32 v21, 0x3fb504f3, v0
	global_store_dword v[18:19], v33, off
	global_store_dword v[18:19], v29, off offset:64
	global_store_dword v[18:19], v25, off offset:128
	global_store_dword v[18:19], v21, off offset:192
	v_lshlrev_b64 v[18:19], 12, v[56:57]
	s_waitcnt vmcnt(62)
	v_lshlrev_b32_e32 v0, 16, v109
	v_lshl_add_u64 v[18:19], v[62:63], 0, v[18:19]
	v_fmamk_f32 v0, v0, 0x3fb504f3, v14
	global_store_dword v[18:19], v0, off
	v_lshlrev_b32_e32 v0, 16, v163
	v_fmamk_f32 v0, v0, 0x3fb504f3, v10
	global_store_dword v[18:19], v0, off offset:64
	s_waitcnt vmcnt(62)
	v_lshlrev_b32_e32 v0, 16, v164
	v_fmamk_f32 v0, v0, 0x3fb504f3, v6
	global_store_dword v[18:19], v0, off offset:128
	v_lshlrev_b32_e32 v0, 16, v114
	v_fmamk_f32 v0, v0, 0x3fb504f3, v2
	global_store_dword v[18:19], v0, off offset:192
	v_lshlrev_b64 v[18:19], 12, v[54:55]
	s_waitcnt vmcnt(62)
	v_lshlrev_b32_e32 v0, 16, v115
	v_lshl_add_u64 v[18:19], v[62:63], 0, v[18:19]
	v_fmamk_f32 v0, v0, 0x3fb504f3, v15
	global_store_dword v[18:19], v0, off
	v_lshlrev_b32_e32 v0, 16, v165
	v_fmamk_f32 v0, v0, 0x3fb504f3, v11
	global_store_dword v[18:19], v0, off offset:64
	s_waitcnt vmcnt(62)
	v_lshlrev_b32_e32 v0, 16, v166
	v_fmamk_f32 v0, v0, 0x3fb504f3, v7
	global_store_dword v[18:19], v0, off offset:128
	v_lshlrev_b32_e32 v0, 16, v116
	v_fmamk_f32 v0, v0, 0x3fb504f3, v3
	global_store_dword v[18:19], v0, off offset:192
	v_lshlrev_b64 v[2:3], 12, v[52:53]
	s_waitcnt vmcnt(62)
	v_lshlrev_b32_e32 v0, 16, v117
	v_lshl_add_u64 v[2:3], v[62:63], 0, v[2:3]
	v_fmamk_f32 v0, v0, 0x3fb504f3, v16
	global_store_dword v[2:3], v0, off
	v_lshlrev_b32_e32 v0, 16, v167
	v_fmamk_f32 v0, v0, 0x3fb504f3, v12
	global_store_dword v[2:3], v0, off offset:64
	s_waitcnt vmcnt(62)
	v_lshlrev_b32_e32 v0, 16, v168
	v_fmamk_f32 v0, v0, 0x3fb504f3, v8
	global_store_dword v[2:3], v0, off offset:128
	v_lshlrev_b32_e32 v0, 16, v130
	v_fmamk_f32 v0, v0, 0x3fb504f3, v4
	global_store_dword v[2:3], v0, off offset:192
	s_waitcnt vmcnt(62)
	v_lshlrev_b32_e32 v0, 16, v131
	v_fmac_f32_e32 v17, 0x3fb504f3, v0
	v_lshlrev_b32_e32 v0, 16, v169
	v_fmac_f32_e32 v13, 0x3fb504f3, v0
	s_waitcnt vmcnt(61)
	v_lshlrev_b32_e32 v0, 16, v170
	v_lshlrev_b64 v[2:3], 12, v[50:51]
	v_fmac_f32_e32 v9, 0x3fb504f3, v0
	s_waitcnt vmcnt(60)
	v_lshlrev_b32_e32 v0, 16, v64
	v_lshl_add_u64 v[2:3], v[62:63], 0, v[2:3]
	v_fmac_f32_e32 v5, 0x3fb504f3, v0
	v_readfirstlane_b32 s10, v198
	global_store_dword v[2:3], v17, off
	global_store_dword v[2:3], v13, off offset:64
	global_store_dword v[2:3], v9, off offset:128
	global_store_dword v[2:3], v5, off offset:192
	s_add_i32 s12, s10, s12
	s_cmpk_lt_i32 s12, 0x820
	s_cbranch_scc1 .LBB0_1352

; template <int EPI, bool AF32>
; DEV void gemm_tile(const void* Ap, int lda, const u16* Bt, int ldb, int K, int m0, int n0, const Epi& ea, char* smem) {
;     ...
;   auto gload = [&](int kt) {
;     const int k0 = kt << 6;
; #pragma unroll
;     for (int i = 0; i < 4; i++) {
;       const int c = tid + i * 256, row = c >> 3, kc = c & 7;
;       if (AF32) {
;         const float* pa = (const float*)Ap + (size_t)(m0 + row) * lda + k0 + kc * 8;
;         rfa[2 * i] = *(const f32x4*)pa;
;         rfa[2 * i + 1] = *(const f32x4*)(pa + 4);
;       } else {
;         ra[i] = *(const u32x4*)((const u16*)Ap + (size_t)(m0 + row) * lda + k0 + kc * 8);
;       }
;       rb[i] = *(const u32x4*)(Bt + (size_t)(n0 + row) * ldb + k0 + kc * 8);
;     }
;   };
;   auto swrite = [&](int buf) {
; #pragma unroll
;     for (int i = 0; i < 4; i++) {
;       const int c = tid + i * 256, row = c >> 3, kc = c & 7;
;       u32x4 va;
;       if (AF32) {
;         va = (u32x4){pack2(rfa[2 * i][0], rfa[2 * i][1]), pack2(rfa[2 * i][2], rfa[2 * i][3]),
;                      pack2(rfa[2 * i + 1][0], rfa[2 * i + 1][1]), pack2(rfa[2 * i + 1][2], rfa[2 * i + 1][3])};
;       } else {
;         va = ra[i];
;       }
;       *(u32x4*)(sA + buf * 9216 + row * 72 + kc * 8) = va;
;       *(u32x4*)(sB + buf * 9216 + row * 72 + kc * 8) = rb[i];
;     }
;   };
;   gload(0);
;   swrite(0);
;   if (nk > 1) gload(1);
;   __syncthreads();
.LBB0_1436:
	s_mul_hi_i32 s0, s12, 0x2e8ba2e9
	s_lshr_b32 s1, s0, 31
	s_ashr_i32 s0, s0, 8
	s_add_i32 s0, s0, s1
	s_lshl_b32 s14, s0, 5
	s_mul_i32 s1, s0, 0x580
	s_sub_i32 s0, 0x104, s14
	s_min_u32 s15, s0, 32
	s_sub_i32 s13, s12, s1
	v_cvt_f32_ubyte0_e32 v2, s15
	v_cvt_f32_i32_e32 v0, s13
	v_rcp_iflag_f32_e32 v3, v2
	s_ashr_i32 s0, s13, 30
	s_or_b32 s16, s0, 1
	s_waitcnt vmcnt(12)
	v_mov_b32_e32 v114, v157
	v_mul_f32_e32 v3, v0, v3
	v_trunc_f32_e32 v3, v3
	v_fma_f32 v0, -v3, v2, v0
	v_cvt_i32_f32_e32 v3, v3
	v_cmp_ge_f32_e64 s[0:1], |v0|, v2
	s_and_b64 s[0:1], s[0:1], exec
	s_cselect_b32 s0, s16, 0
	v_readfirstlane_b32 s1, v3
	s_add_i32 s0, s1, s0
	s_sext_i32_i16 s1, s0
	s_mul_i32 s0, s0, s15
	s_sub_i32 s0, s13, s0
	s_sext_i32_i16 s0, s0
	s_add_i32 s14, s14, s0
	s_lshl_b32 s13, s14, 7
	s_lshl_b32 s14, s1, 7
	v_ashrrev_i32_e32 v8, 3, v114
	v_add_u32_e32 v2, s13, v8
	v_ashrrev_i32_e32 v3, 31, v2
	v_lshlrev_b32_e32 v0, 3, v114
	v_add_u32_e32 v4, 0x100, v114
	v_lshlrev_b64 v[58:59], 11, v[2:3]
	v_and_b32_e32 v0, 56, v0
	v_ashrrev_i32_e32 v9, 3, v4
	v_lshl_add_u64 v[2:3], s[4:5], 0, v[58:59]
	v_lshlrev_b32_e32 v0, 1, v0
	v_add_u32_e32 v4, s13, v9
	v_add_u32_e32 v6, 0x200, v114
	v_lshl_add_u64 v[14:15], v[2:3], 0, v[0:1]
	v_add_u32_e32 v2, s14, v8
	v_ashrrev_i32_e32 v5, 31, v4
	v_ashrrev_i32_e32 v10, 3, v6
	v_ashrrev_i32_e32 v3, 31, v2
	v_lshlrev_b64 v[62:63], 11, v[4:5]
	v_add_u32_e32 v6, s13, v10
	v_lshlrev_b64 v[60:61], 11, v[2:3]
	v_lshl_add_u64 v[4:5], s[4:5], 0, v[62:63]
	v_ashrrev_i32_e32 v7, 31, v6
	v_lshl_add_u64 v[2:3], s[6:7], 0, v[60:61]
	v_lshl_add_u64 v[16:17], v[4:5], 0, v[0:1]
	v_add_u32_e32 v4, s14, v9
	v_lshlrev_b64 v[66:67], 11, v[6:7]
	v_lshl_add_u64 v[2:3], v[2:3], 0, v[0:1]
	v_ashrrev_i32_e32 v5, 31, v4
	v_lshl_add_u64 v[6:7], s[4:5], 0, v[66:67]
	global_load_dwordx4 v[30:33], v[2:3], off
	v_lshlrev_b64 v[64:65], 11, v[4:5]
	v_lshl_add_u64 v[68:69], v[6:7], 0, v[0:1]
	v_add_u32_e32 v6, s14, v10
	global_load_dwordx4 v[26:29], v[14:15], off
	global_load_dwordx4 v[34:37], v[16:17], off
	v_lshl_add_u64 v[4:5], s[6:7], 0, v[64:65]
	v_ashrrev_i32_e32 v7, 31, v6
	v_lshl_add_u64 v[4:5], v[4:5], 0, v[0:1]
	v_lshlrev_b64 v[70:71], 11, v[6:7]
	global_load_dwordx4 v[38:41], v[4:5], off
	v_lshl_add_u64 v[6:7], s[6:7], 0, v[70:71]
	global_load_dwordx4 v[42:45], v[68:69], off
	v_lshl_add_u64 v[18:19], v[6:7], 0, v[0:1]
	global_load_dwordx4 v[46:49], v[18:19], off
	v_add_u32_e32 v6, 0x300, v114
	v_ashrrev_i32_e32 v80, 3, v6
	v_add_u32_e32 v6, s13, v80
	v_ashrrev_i32_e32 v7, 31, v6
	v_lshlrev_b64 v[72:73], 11, v[6:7]
	v_lshl_add_u64 v[6:7], s[4:5], 0, v[72:73]
	v_lshl_add_u64 v[74:75], v[6:7], 0, v[0:1]
	v_add_u32_e32 v6, s14, v80
	v_ashrrev_i32_e32 v7, 31, v6
	v_lshlrev_b64 v[76:77], 11, v[6:7]
	v_lshl_add_u64 v[6:7], s[6:7], 0, v[76:77]
	v_lshl_add_u64 v[78:79], v[6:7], 0, v[0:1]
	global_load_dwordx4 v[50:53], v[74:75], off
	global_load_dwordx4 v[54:57], v[78:79], off
	s_waitcnt vmcnt(19)
	v_mul_lo_u32 v118, v8, s71
	v_mul_lo_u32 v119, v9, s71
	s_waitcnt vmcnt(18)
	v_mul_lo_u32 v123, v10, s71
	global_load_dwordx4 v[6:9], v[2:3], off offset:128
	global_load_dwordx4 v[10:13], v[4:5], off offset:128
	s_nop 0
	global_load_dwordx4 v[2:5], v[18:19], off offset:128
	global_load_dwordx4 v[22:25], v[14:15], off offset:128
	s_nop 0
	global_load_dwordx4 v[18:21], v[16:17], off offset:128
	s_nop 0
	global_load_dwordx4 v[14:17], v[68:69], off offset:128
	v_bfe_u32 v161, v157, 3, 4
	v_add_u32_e32 v161, 4, v161
	v_lshlrev_b32_e32 v161, 1, v161
	v_and_b32_e32 v161, 16, v161
	v_xor_b32_e32 v129, v0, v161
	v_lshl_add_u32 v122, v118, 1, v129
	v_lshl_add_u32 v121, v119, 1, v129
	v_lshl_add_u32 v120, v123, 1, v129
	v_and_b32_e32 v115, 15, v114
	s_waitcnt vmcnt(23)
	v_mul_lo_u32 v126, v80, s71
	v_bfe_u32 v116, v114, 4, 2
	v_lshl_add_u32 v124, v126, 1, v129
	s_mov_b32 s15, 0
	v_lshlrev_b32_e32 v125, 4, v116
	v_and_b32_e32 v161, 15, v157
	v_add_u32_e32 v161, 4, v161
	v_lshlrev_b32_e32 v161, 1, v161
	v_and_b32_e32 v161, 16, v161
	v_xor_b32_e32 v125, v125, v161
	s_mov_b64 s[0:1], 0
	s_waitcnt vmcnt(13)
	ds_write_b128 v122, v[30:33] offset:36864
	s_waitcnt vmcnt(12)
	ds_write_b128 v122, v[26:29]
	s_waitcnt vmcnt(11)
	ds_write_b128 v121, v[34:37]
	s_waitcnt vmcnt(10)
	ds_write_b128 v121, v[38:41] offset:36864
	s_waitcnt vmcnt(9)
	ds_write_b128 v120, v[42:45]
	s_waitcnt vmcnt(8)
	ds_write_b128 v120, v[46:49] offset:36864
	global_load_dwordx4 v[26:29], v[74:75], off offset:128
	global_load_dwordx4 v[30:33], v[78:79], off offset:128
	v_ashrrev_i32_e32 v34, 1, v114
	v_and_b32_e32 v117, 0xffffffc0, v34
	v_or_b32_e32 v34, v117, v115
	v_mul_lo_u32 v128, v34, s71
	v_lshlrev_b32_e32 v34, 4, v114
	v_and_b32_e32 v34, 0x70, v34
	v_and_b32_e32 v35, 0x4f, v114
	v_or_b32_e32 v76, v76, v34
	v_or_b32_e32 v72, v72, v34
	v_or_b32_e32 v70, v70, v34
	v_or_b32_e32 v66, v66, v34
	v_or_b32_e32 v64, v64, v34
	v_or_b32_e32 v62, v62, v34
	v_or_b32_e32 v60, v60, v34
	v_or_b32_e32 v58, v58, v34
	v_mov_b32_e32 v34, 0
	s_waitcnt vmcnt(9)
	ds_write_b128 v124, v[50:53]
	s_waitcnt vmcnt(8)
	ds_write_b128 v124, v[54:57] offset:36864
	v_mul_u32_u24_e32 v127, 0x48, v35
	v_lshl_add_u64 v[98:99], s[8:9], 0, v[76:77]
	v_lshl_add_u64 v[100:101], s[10:11], 0, v[72:73]
	v_lshl_add_u64 v[102:103], s[8:9], 0, v[70:71]
	v_lshl_add_u64 v[104:105], s[10:11], 0, v[66:67]
	v_lshl_add_u64 v[106:107], s[8:9], 0, v[64:65]
	v_lshl_add_u64 v[108:109], s[10:11], 0, v[62:63]
	v_lshl_add_u64 v[110:111], s[8:9], 0, v[60:61]
	v_lshl_add_u64 v[112:113], s[10:11], 0, v[58:59]
	v_mov_b32_e32 v35, v34
	v_mov_b32_e32 v36, v34
	v_mov_b32_e32 v37, v34
	v_mov_b32_e32 v38, v34
	v_mov_b32_e32 v39, v34
	v_mov_b32_e32 v40, v34
	v_mov_b32_e32 v41, v34
	v_mov_b32_e32 v42, v34
	v_mov_b32_e32 v43, v34
	v_mov_b32_e32 v44, v34
	v_mov_b32_e32 v45, v34
	v_mov_b32_e32 v46, v34
	v_mov_b32_e32 v47, v34
	v_mov_b32_e32 v48, v34
	v_mov_b32_e32 v49, v34
	v_mov_b32_e32 v50, v34
	v_mov_b32_e32 v51, v34
	v_mov_b32_e32 v52, v34
	v_mov_b32_e32 v53, v34
	v_mov_b32_e32 v54, v34
	v_mov_b32_e32 v55, v34
	v_mov_b32_e32 v56, v34
	v_mov_b32_e32 v57, v34
	v_mov_b32_e32 v58, v34
	v_mov_b32_e32 v59, v34
	v_mov_b32_e32 v60, v34
	v_mov_b32_e32 v61, v34
	v_mov_b32_e32 v62, v34
	v_mov_b32_e32 v63, v34
	v_mov_b32_e32 v64, v34
	v_mov_b32_e32 v65, v34
	v_mov_b32_e32 v66, v34
	v_mov_b32_e32 v67, v34
	v_mov_b32_e32 v68, v34
	v_mov_b32_e32 v69, v34
	v_mov_b32_e32 v70, v34
	v_mov_b32_e32 v71, v34
	v_mov_b32_e32 v72, v34
	v_mov_b32_e32 v73, v34
	v_mov_b32_e32 v74, v34
	v_mov_b32_e32 v75, v34
	v_mov_b32_e32 v76, v34
	v_mov_b32_e32 v77, v34
	v_mov_b32_e32 v78, v34
	v_mov_b32_e32 v79, v34
	v_mov_b32_e32 v80, v34
	v_mov_b32_e32 v81, v34
	v_mov_b32_e32 v82, v34
	v_mov_b32_e32 v83, v34
	v_mov_b32_e32 v84, v34
	v_mov_b32_e32 v85, v34
	v_mov_b32_e32 v86, v34
	v_mov_b32_e32 v87, v34
	v_mov_b32_e32 v88, v34
	v_mov_b32_e32 v89, v34
	v_mov_b32_e32 v90, v34
	v_mov_b32_e32 v91, v34
	v_mov_b32_e32 v92, v34
	v_mov_b32_e32 v93, v34
	v_mov_b32_e32 v94, v34
	v_mov_b32_e32 v95, v34
	v_mov_b32_e32 v96, v34
	v_mov_b32_e32 v97, v34
	s_waitcnt lgkmcnt(0)
	s_barrier
; DEV f32x4 mfma16(bf16x8 a, bf16x8 b, f32x4 c) { return __builtin_amdgcn_mfma_f32_16x16x32_bf16(a, b, c, 0, 0, 0); }
; template <int EPI, bool AF32>
; DEV void gemm_tile(const void* Ap, int lda, const u16* Bt, int ldb, int K, int m0, int n0, const Epi& ea, char* smem) {
;     ...
;   for (int kt = 0; kt < nk; kt++) {
;     const int buf = kt & 1;
;     if (kt + 1 < nk) swrite(buf ^ 1);
;     if (kt + 2 < nk) gload(kt + 2);
; #pragma unroll
;     for (int ks = 0; ks < 2; ks++) {
;       bf16x8 a[4], b[4];
; #pragma unroll
;       for (int m = 0; m < 4; m++) a[m] = *(const bf16x8*)(sA + buf * 9216 + (wr * 64 + m * 16 + fr) * 72 + ks * 32 + fq * 8);
; #pragma unroll
;       for (int n = 0; n < 4; n++) b[n] = *(const bf16x8*)(sB + buf * 9216 + (wc * 64 + n * 16 + fr) * 72 + ks * 32 + fq * 8);
;       __builtin_amdgcn_s_setprio(1);
; #pragma unroll
;       for (int m = 0; m < 4; m++)
; #pragma unroll
;         for (int n = 0; n < 4; n++) acc[m][n] = mfma16(a[m], b[n], acc[m][n]);
;       __builtin_amdgcn_s_setprio(0);
;     }
;     __syncthreads();
	v_lshl_add_u32 v161, v128, 1, v125
	v_lshl_add_u32 v129, v127, 1, v125
	s_mov_b32 s15, 0
	s_mov_b64 s[0:1], 0x100
	ds_read_b128 v[130:133], v161
	ds_read_b128 v[134:137], v161 offset:2304
	ds_read_b128 v[138:141], v161 offset:4608
	ds_read_b128 v[142:145], v161 offset:6912
	ds_read_b128 v[146:149], v129 offset:36864
	ds_read_b128 v[150:153], v129 offset:39168
	ds_read_b128 v[162:165], v129 offset:41472
	ds_read_b128 v[166:169], v129 offset:43776
.Lgk6_loop:
	s_waitcnt lgkmcnt(0)
	ds_read_b128 v[222:225], v161 offset:64
	ds_read_b128 v[226:229], v161 offset:2368
	ds_read_b128 v[230:233], v161 offset:4672
	ds_read_b128 v[234:237], v161 offset:6976
	ds_read_b128 v[238:241], v129 offset:36928
	ds_read_b128 v[242:245], v129 offset:39232
	ds_read_b128 v[246:249], v129 offset:41536
	ds_read_b128 v[250:253], v129 offset:43840
	v_mfma_f32_16x16x32_bf16 v[94:97], v[130:133], v[146:149], v[94:97]
	v_mfma_f32_16x16x32_bf16 v[90:93], v[130:133], v[150:153], v[90:93]
	v_mfma_f32_16x16x32_bf16 v[86:89], v[130:133], v[162:165], v[86:89]
	v_mfma_f32_16x16x32_bf16 v[82:85], v[130:133], v[166:169], v[82:85]
	s_waitcnt vmcnt(0)
	ds_write_b128 v122, v[22:25] offset:18432
	ds_write_b128 v122, v[6:9] offset:55296
	v_mfma_f32_16x16x32_bf16 v[78:81], v[134:137], v[146:149], v[78:81]
	ds_write_b128 v121, v[18:21] offset:18432
	ds_write_b128 v121, v[10:13] offset:55296
	v_mfma_f32_16x16x32_bf16 v[74:77], v[134:137], v[150:153], v[74:77]
	ds_write_b128 v120, v[14:17] offset:18432
	ds_write_b128 v120, v[2:5] offset:55296
	v_mfma_f32_16x16x32_bf16 v[70:73], v[134:137], v[162:165], v[70:73]
	ds_write_b128 v124, v[26:29] offset:18432
	ds_write_b128 v124, v[30:33] offset:55296
	v_mfma_f32_16x16x32_bf16 v[66:69], v[134:137], v[166:169], v[66:69]
	global_load_dwordx4 v[22:25], v[112:113], off
	v_mfma_f32_16x16x32_bf16 v[62:65], v[138:141], v[146:149], v[62:65]
	global_load_dwordx4 v[6:9], v[110:111], off
	v_mfma_f32_16x16x32_bf16 v[58:61], v[138:141], v[150:153], v[58:61]
	global_load_dwordx4 v[18:21], v[108:109], off
	v_mfma_f32_16x16x32_bf16 v[54:57], v[138:141], v[162:165], v[54:57]
	global_load_dwordx4 v[10:13], v[106:107], off
	v_mfma_f32_16x16x32_bf16 v[50:53], v[138:141], v[166:169], v[50:53]
	global_load_dwordx4 v[14:17], v[104:105], off
	v_mfma_f32_16x16x32_bf16 v[46:49], v[142:145], v[146:149], v[46:49]
	global_load_dwordx4 v[2:5], v[102:103], off
	v_mfma_f32_16x16x32_bf16 v[42:45], v[142:145], v[150:153], v[42:45]
	global_load_dwordx4 v[26:29], v[100:101], off
	v_mfma_f32_16x16x32_bf16 v[38:41], v[142:145], v[162:165], v[38:41]
	global_load_dwordx4 v[30:33], v[98:99], off
	v_mfma_f32_16x16x32_bf16 v[34:37], v[142:145], v[166:169], v[34:37]
	s_waitcnt lgkmcnt(0)
	s_barrier
	ds_read_b128 v[130:133], v161 offset:18432
	v_mfma_f32_16x16x32_bf16 v[94:97], v[222:225], v[238:241], v[94:97]
	ds_read_b128 v[134:137], v161 offset:20736
	v_mfma_f32_16x16x32_bf16 v[90:93], v[222:225], v[242:245], v[90:93]
	ds_read_b128 v[138:141], v161 offset:23040
	v_mfma_f32_16x16x32_bf16 v[86:89], v[222:225], v[246:249], v[86:89]
	ds_read_b128 v[142:145], v161 offset:25344
	v_mfma_f32_16x16x32_bf16 v[82:85], v[222:225], v[250:253], v[82:85]
	ds_read_b128 v[146:149], v129 offset:55296
	v_mfma_f32_16x16x32_bf16 v[78:81], v[226:229], v[238:241], v[78:81]
	ds_read_b128 v[150:153], v129 offset:57600
	v_mfma_f32_16x16x32_bf16 v[74:77], v[226:229], v[242:245], v[74:77]
	ds_read_b128 v[162:165], v129 offset:59904
	v_mfma_f32_16x16x32_bf16 v[70:73], v[226:229], v[246:249], v[70:73]
	ds_read_b128 v[166:169], v129 offset:62208
	v_mfma_f32_16x16x32_bf16 v[66:69], v[226:229], v[250:253], v[66:69]
	v_mfma_f32_16x16x32_bf16 v[62:65], v[230:233], v[238:241], v[62:65]
	v_mfma_f32_16x16x32_bf16 v[58:61], v[230:233], v[242:245], v[58:61]
	v_mfma_f32_16x16x32_bf16 v[54:57], v[230:233], v[246:249], v[54:57]
	v_mfma_f32_16x16x32_bf16 v[50:53], v[230:233], v[250:253], v[50:53]
	v_mfma_f32_16x16x32_bf16 v[46:49], v[234:237], v[238:241], v[46:49]
	v_mfma_f32_16x16x32_bf16 v[42:45], v[234:237], v[242:245], v[42:45]
	v_mfma_f32_16x16x32_bf16 v[38:41], v[234:237], v[246:249], v[38:41]
	v_mfma_f32_16x16x32_bf16 v[34:37], v[234:237], v[250:253], v[34:37]
	s_waitcnt lgkmcnt(0)
	ds_read_b128 v[222:225], v161 offset:18496
	ds_read_b128 v[226:229], v161 offset:20800
	ds_read_b128 v[230:233], v161 offset:23104
	ds_read_b128 v[234:237], v161 offset:25408
	ds_read_b128 v[238:241], v129 offset:55360
	ds_read_b128 v[242:245], v129 offset:57664
	ds_read_b128 v[246:249], v129 offset:59968
	ds_read_b128 v[250:253], v129 offset:62272
	v_mfma_f32_16x16x32_bf16 v[94:97], v[130:133], v[146:149], v[94:97]
	v_mfma_f32_16x16x32_bf16 v[90:93], v[130:133], v[150:153], v[90:93]
	v_mfma_f32_16x16x32_bf16 v[86:89], v[130:133], v[162:165], v[86:89]
	v_mfma_f32_16x16x32_bf16 v[82:85], v[130:133], v[166:169], v[82:85]
	s_waitcnt vmcnt(0)
	ds_write_b128 v122, v[22:25]
	ds_write_b128 v122, v[6:9] offset:36864
	v_mfma_f32_16x16x32_bf16 v[78:81], v[134:137], v[146:149], v[78:81]
	ds_write_b128 v121, v[18:21]
	ds_write_b128 v121, v[10:13] offset:36864
	v_mfma_f32_16x16x32_bf16 v[74:77], v[134:137], v[150:153], v[74:77]
	ds_write_b128 v120, v[14:17]
	ds_write_b128 v120, v[2:5] offset:36864
	v_mfma_f32_16x16x32_bf16 v[70:73], v[134:137], v[162:165], v[70:73]
	ds_write_b128 v124, v[26:29]
	ds_write_b128 v124, v[30:33] offset:36864
	v_mfma_f32_16x16x32_bf16 v[66:69], v[134:137], v[166:169], v[66:69]
	global_load_dwordx4 v[22:25], v[112:113], off offset:128
	v_mfma_f32_16x16x32_bf16 v[62:65], v[138:141], v[146:149], v[62:65]
	global_load_dwordx4 v[6:9], v[110:111], off offset:128
	v_mfma_f32_16x16x32_bf16 v[58:61], v[138:141], v[150:153], v[58:61]
	global_load_dwordx4 v[18:21], v[108:109], off offset:128
	v_mfma_f32_16x16x32_bf16 v[54:57], v[138:141], v[162:165], v[54:57]
	global_load_dwordx4 v[10:13], v[106:107], off offset:128
	v_mfma_f32_16x16x32_bf16 v[50:53], v[138:141], v[166:169], v[50:53]
	global_load_dwordx4 v[14:17], v[104:105], off offset:128
	v_mfma_f32_16x16x32_bf16 v[46:49], v[142:145], v[146:149], v[46:49]
	global_load_dwordx4 v[2:5], v[102:103], off offset:128
	v_mfma_f32_16x16x32_bf16 v[42:45], v[142:145], v[150:153], v[42:45]
	global_load_dwordx4 v[26:29], v[100:101], off offset:128
	v_mfma_f32_16x16x32_bf16 v[38:41], v[142:145], v[162:165], v[38:41]
	global_load_dwordx4 v[30:33], v[98:99], off offset:128
	v_mfma_f32_16x16x32_bf16 v[34:37], v[142:145], v[166:169], v[34:37]
	s_waitcnt lgkmcnt(0)
	s_barrier
; DEV f32x4 mfma16(bf16x8 a, bf16x8 b, f32x4 c) { return __builtin_amdgcn_mfma_f32_16x16x32_bf16(a, b, c, 0, 0, 0); }
; template <int EPI, bool AF32>
; DEV void gemm_tile(const void* Ap, int lda, const u16* Bt, int ldb, int K, int m0, int n0, const Epi& ea, char* smem) {
;     ...
;   for (int kt = 0; kt < nk; kt++) {
;     const int buf = kt & 1;
;     if (kt + 1 < nk) swrite(buf ^ 1);
;     if (kt + 2 < nk) gload(kt + 2);
; #pragma unroll
;     for (int ks = 0; ks < 2; ks++) {
;       bf16x8 a[4], b[4];
; #pragma unroll
;       for (int m = 0; m < 4; m++) a[m] = *(const bf16x8*)(sA + buf * 9216 + (wr * 64 + m * 16 + fr) * 72 + ks * 32 + fq * 8);
; #pragma unroll
;       for (int n = 0; n < 4; n++) b[n] = *(const bf16x8*)(sB + buf * 9216 + (wc * 64 + n * 16 + fr) * 72 + ks * 32 + fq * 8);
;       __builtin_amdgcn_s_setprio(1);
; #pragma unroll
;       for (int m = 0; m < 4; m++)
; #pragma unroll
;         for (int n = 0; n < 4; n++) acc[m][n] = mfma16(a[m], b[n], acc[m][n]);
;       __builtin_amdgcn_s_setprio(0);
;     }
;     __syncthreads();
	ds_read_b128 v[130:133], v161
	v_mfma_f32_16x16x32_bf16 v[94:97], v[222:225], v[238:241], v[94:97]
	ds_read_b128 v[134:137], v161 offset:2304
	v_mfma_f32_16x16x32_bf16 v[90:93], v[222:225], v[242:245], v[90:93]
	ds_read_b128 v[138:141], v161 offset:4608
	v_mfma_f32_16x16x32_bf16 v[86:89], v[222:225], v[246:249], v[86:89]
	ds_read_b128 v[142:145], v161 offset:6912
	v_mfma_f32_16x16x32_bf16 v[82:85], v[222:225], v[250:253], v[82:85]
	ds_read_b128 v[146:149], v129 offset:36864
	v_mfma_f32_16x16x32_bf16 v[78:81], v[226:229], v[238:241], v[78:81]
	ds_read_b128 v[150:153], v129 offset:39168
	v_mfma_f32_16x16x32_bf16 v[74:77], v[226:229], v[242:245], v[74:77]
	ds_read_b128 v[162:165], v129 offset:41472
	v_mfma_f32_16x16x32_bf16 v[70:73], v[226:229], v[246:249], v[70:73]
	ds_read_b128 v[166:169], v129 offset:43776
	v_mfma_f32_16x16x32_bf16 v[66:69], v[226:229], v[250:253], v[66:69]
	v_mfma_f32_16x16x32_bf16 v[62:65], v[230:233], v[238:241], v[62:65]
	v_lshl_add_u64 v[112:113], v[112:113], 0, s[0:1]
	v_mfma_f32_16x16x32_bf16 v[58:61], v[230:233], v[242:245], v[58:61]
	v_lshl_add_u64 v[110:111], v[110:111], 0, s[0:1]
	v_mfma_f32_16x16x32_bf16 v[54:57], v[230:233], v[246:249], v[54:57]
	v_lshl_add_u64 v[108:109], v[108:109], 0, s[0:1]
	v_mfma_f32_16x16x32_bf16 v[50:53], v[230:233], v[250:253], v[50:53]
	v_lshl_add_u64 v[106:107], v[106:107], 0, s[0:1]
	v_mfma_f32_16x16x32_bf16 v[46:49], v[234:237], v[238:241], v[46:49]
	v_lshl_add_u64 v[104:105], v[104:105], 0, s[0:1]
	v_mfma_f32_16x16x32_bf16 v[42:45], v[234:237], v[242:245], v[42:45]
	v_lshl_add_u64 v[102:103], v[102:103], 0, s[0:1]
	v_mfma_f32_16x16x32_bf16 v[38:41], v[234:237], v[246:249], v[38:41]
	v_lshl_add_u64 v[100:101], v[100:101], 0, s[0:1]
	v_mfma_f32_16x16x32_bf16 v[34:37], v[234:237], v[250:253], v[34:37]
	v_lshl_add_u64 v[98:99], v[98:99], 0, s[0:1]
	s_add_i32 s15, s15, 1
	s_cmp_lg_u32 s15, 7
	s_cbranch_scc1 .Lgk6_loop
	s_waitcnt vmcnt(7)
	ds_write_b128 v122, v[22:25] offset:18432
	s_waitcnt vmcnt(6)
	ds_write_b128 v122, v[6:9] offset:55296
	s_waitcnt vmcnt(5)
	ds_write_b128 v121, v[18:21] offset:18432
	s_waitcnt vmcnt(4)
	ds_write_b128 v121, v[10:13] offset:55296
	s_waitcnt vmcnt(3)
	ds_write_b128 v120, v[14:17] offset:18432
	s_waitcnt vmcnt(2)
	ds_write_b128 v120, v[2:5] offset:55296
	s_waitcnt vmcnt(1)
	ds_write_b128 v124, v[26:29] offset:18432
	s_waitcnt vmcnt(0)
	ds_write_b128 v124, v[30:33] offset:55296
	v_lshl_add_u32 v0, v128, 1, v125
	v_lshl_add_u32 v130, v127, 1, v125
	ds_read_b128 v[2:5], v0
	ds_read_b128 v[6:9], v0 offset:2304
	ds_read_b128 v[10:13], v0 offset:4608
	ds_read_b128 v[14:17], v0 offset:6912
	ds_read_b128 v[18:21], v130 offset:36864
	ds_read_b128 v[22:25], v130 offset:39168
	ds_read_b128 v[26:29], v130 offset:41472
	ds_read_b128 v[30:33], v130 offset:43776
	s_setprio 1
	s_waitcnt lgkmcnt(3)
	v_mfma_f32_16x16x32_bf16 v[94:97], v[2:5], v[18:21], v[94:97]
	s_waitcnt lgkmcnt(2)
	v_mfma_f32_16x16x32_bf16 v[90:93], v[2:5], v[22:25], v[90:93]
	s_waitcnt lgkmcnt(1)
	v_mfma_f32_16x16x32_bf16 v[86:89], v[2:5], v[26:29], v[86:89]
	s_waitcnt lgkmcnt(0)
	v_mfma_f32_16x16x32_bf16 v[2:5], v[2:5], v[30:33], v[82:85]
	v_mfma_f32_16x16x32_bf16 v[78:81], v[6:9], v[18:21], v[78:81]
	v_mfma_f32_16x16x32_bf16 v[74:77], v[6:9], v[22:25], v[74:77]
	v_mfma_f32_16x16x32_bf16 v[70:73], v[6:9], v[26:29], v[70:73]
	v_mfma_f32_16x16x32_bf16 v[6:9], v[6:9], v[30:33], v[66:69]
	v_mfma_f32_16x16x32_bf16 v[62:65], v[10:13], v[18:21], v[62:65]
	v_mfma_f32_16x16x32_bf16 v[58:61], v[10:13], v[22:25], v[58:61]
	v_mfma_f32_16x16x32_bf16 v[54:57], v[10:13], v[26:29], v[54:57]
	v_mfma_f32_16x16x32_bf16 v[10:13], v[10:13], v[30:33], v[50:53]
	v_mfma_f32_16x16x32_bf16 v[18:21], v[14:17], v[18:21], v[46:49]
	v_mfma_f32_16x16x32_bf16 v[22:25], v[14:17], v[22:25], v[42:45]
	v_mfma_f32_16x16x32_bf16 v[26:29], v[14:17], v[26:29], v[38:41]
	v_mfma_f32_16x16x32_bf16 v[14:17], v[14:17], v[30:33], v[34:37]
	s_setprio 0
	ds_read_b128 v[30:33], v0 offset:64
	s_nop 0
	ds_read_b128 v[34:37], v0 offset:2368
	ds_read_b128 v[38:41], v0 offset:4672
	ds_read_b128 v[42:45], v0 offset:6976
	ds_read_b128 v[46:49], v130 offset:36928
	ds_read_b128 v[50:53], v130 offset:39232
	ds_read_b128 v[66:69], v130 offset:41536
	ds_read_b128 v[82:85], v130 offset:43840
	s_setprio 1
	s_waitcnt lgkmcnt(3)
	v_mfma_f32_16x16x32_bf16 v[94:97], v[30:33], v[46:49], v[94:97]
	s_waitcnt lgkmcnt(2)
	v_mfma_f32_16x16x32_bf16 v[90:93], v[30:33], v[50:53], v[90:93]
	s_waitcnt lgkmcnt(1)
	v_mfma_f32_16x16x32_bf16 v[86:89], v[30:33], v[66:69], v[86:89]
	s_waitcnt lgkmcnt(0)
	v_mfma_f32_16x16x32_bf16 v[2:5], v[30:33], v[82:85], v[2:5]
	v_mfma_f32_16x16x32_bf16 v[30:33], v[34:37], v[46:49], v[78:81]
	v_mfma_f32_16x16x32_bf16 v[74:77], v[34:37], v[50:53], v[74:77]
	v_mfma_f32_16x16x32_bf16 v[70:73], v[34:37], v[66:69], v[70:73]
	v_mfma_f32_16x16x32_bf16 v[6:9], v[34:37], v[82:85], v[6:9]
	v_mfma_f32_16x16x32_bf16 v[34:37], v[38:41], v[46:49], v[62:65]
	v_mfma_f32_16x16x32_bf16 v[58:61], v[38:41], v[50:53], v[58:61]
	v_mfma_f32_16x16x32_bf16 v[54:57], v[38:41], v[66:69], v[54:57]
	v_mfma_f32_16x16x32_bf16 v[10:13], v[38:41], v[82:85], v[10:13]
	v_mfma_f32_16x16x32_bf16 v[18:21], v[42:45], v[46:49], v[18:21]
	v_mfma_f32_16x16x32_bf16 v[22:25], v[42:45], v[50:53], v[22:25]
	v_mfma_f32_16x16x32_bf16 v[26:29], v[42:45], v[66:69], v[26:29]
	v_mfma_f32_16x16x32_bf16 v[14:17], v[42:45], v[82:85], v[14:17]
	s_setprio 0
	s_barrier
; DEV float siluf(float x) { return x * __builtin_amdgcn_rcpf(1.f + __expf(-x)); }
; DEV f32x4 mfma16(bf16x8 a, bf16x8 b, f32x4 c) { return __builtin_amdgcn_mfma_f32_16x16x32_bf16(a, b, c, 0, 0, 0); }
; template <int EPI, bool AF32>
; DEV void gemm_tile(const void* Ap, int lda, const u16* Bt, int ldb, int K, int m0, int n0, const Epi& ea, char* smem) {
;     ...
;   for (int kt = 0; kt < nk; kt++) {
;     const int buf = kt & 1;
;     if (kt + 1 < nk) swrite(buf ^ 1);
;     if (kt + 2 < nk) gload(kt + 2);
; #pragma unroll
;     for (int ks = 0; ks < 2; ks++) {
;       bf16x8 a[4], b[4];
; #pragma unroll
;       for (int m = 0; m < 4; m++) a[m] = *(const bf16x8*)(sA + buf * 9216 + (wr * 64 + m * 16 + fr) * 72 + ks * 32 + fq * 8);
; #pragma unroll
;       for (int n = 0; n < 4; n++) b[n] = *(const bf16x8*)(sB + buf * 9216 + (wc * 64 + n * 16 + fr) * 72 + ks * 32 + fq * 8);
;       __builtin_amdgcn_s_setprio(1);
; #pragma unroll
;       for (int m = 0; m < 4; m++)
; #pragma unroll
;         for (int n = 0; n < 4; n++) acc[m][n] = mfma16(a[m], b[n], acc[m][n]);
;       __builtin_amdgcn_s_setprio(0);
;     }
;     __syncthreads();
;     ...
;       } else if (EPI == EP_SWIGLU) {
;         u16* C = (u16*)ea.p0;
;         const int jb = (cb >> 6) * 32;
; #pragma unroll
;         for (int n = 0; n < 2; n++)
;           __builtin_nontemporal_store(f2bf(siluf(acc[m][n][j]) * acc[m][n + 2][j]), &C[(size_t)row * 2816 + jb + n * 16 + fr]);
	ds_read_b128 v[38:41], v0 offset:18432
	ds_read_b128 v[42:45], v0 offset:20736
	ds_read_b128 v[46:49], v0 offset:23040
	ds_read_b128 v[50:53], v0 offset:25344
	ds_read_b128 v[62:65], v130 offset:55296
	ds_read_b128 v[66:69], v130 offset:57600
	ds_read_b128 v[78:81], v130 offset:59904
	ds_read_b128 v[82:85], v130 offset:62208
	s_setprio 1
	s_waitcnt lgkmcnt(3)
	v_mfma_f32_16x16x32_bf16 v[94:97], v[38:41], v[62:65], v[94:97]
	s_waitcnt lgkmcnt(2)
	v_mfma_f32_16x16x32_bf16 v[90:93], v[38:41], v[66:69], v[90:93]
	s_waitcnt lgkmcnt(1)
	v_mfma_f32_16x16x32_bf16 v[86:89], v[38:41], v[78:81], v[86:89]
	s_waitcnt lgkmcnt(0)
	v_mfma_f32_16x16x32_bf16 v[2:5], v[38:41], v[82:85], v[2:5]
	v_mfma_f32_16x16x32_bf16 v[30:33], v[42:45], v[62:65], v[30:33]
	v_mfma_f32_16x16x32_bf16 v[38:41], v[42:45], v[66:69], v[74:77]
	v_mfma_f32_16x16x32_bf16 v[70:73], v[42:45], v[78:81], v[70:73]
	v_mfma_f32_16x16x32_bf16 v[6:9], v[42:45], v[82:85], v[6:9]
	v_mfma_f32_16x16x32_bf16 v[74:77], v[46:49], v[62:65], v[34:37]
	v_mfma_f32_16x16x32_bf16 v[98:101], v[46:49], v[66:69], v[58:61]
	v_mfma_f32_16x16x32_bf16 v[102:105], v[46:49], v[78:81], v[54:57]
	v_mfma_f32_16x16x32_bf16 v[10:13], v[46:49], v[82:85], v[10:13]
	v_mfma_f32_16x16x32_bf16 v[106:109], v[50:53], v[62:65], v[18:21]
	v_mfma_f32_16x16x32_bf16 v[66:69], v[50:53], v[66:69], v[22:25]
	v_mfma_f32_16x16x32_bf16 v[78:81], v[50:53], v[78:81], v[26:29]
	v_mfma_f32_16x16x32_bf16 v[82:85], v[50:53], v[82:85], v[14:17]
	s_setprio 0
	s_nop 1
	ds_read_b128 v[14:17], v0 offset:18496
	ds_read_b128 v[18:21], v0 offset:20800
	ds_read_b128 v[22:25], v0 offset:23104
	ds_read_b128 v[110:113], v0 offset:25408
	ds_read_b128 v[118:121], v130 offset:55360
	ds_read_b128 v[122:125], v130 offset:57664
	ds_read_b128 v[126:129], v130 offset:59968
	ds_read_b128 v[130:133], v130 offset:62272
	s_setprio 1
	s_waitcnt lgkmcnt(3)
	v_mfma_f32_16x16x32_bf16 v[58:61], v[14:17], v[118:121], v[94:97]
	s_waitcnt lgkmcnt(2)
	v_mfma_f32_16x16x32_bf16 v[50:53], v[14:17], v[122:125], v[90:93]
	s_waitcnt lgkmcnt(1)
	v_mfma_f32_16x16x32_bf16 v[62:65], v[14:17], v[126:129], v[86:89]
	s_waitcnt lgkmcnt(0)
	v_mfma_f32_16x16x32_bf16 v[54:57], v[14:17], v[130:133], v[2:5]
	v_mfma_f32_16x16x32_bf16 v[42:45], v[18:21], v[118:121], v[30:33]
	v_mfma_f32_16x16x32_bf16 v[34:37], v[18:21], v[122:125], v[38:41]
	v_mfma_f32_16x16x32_bf16 v[46:49], v[18:21], v[126:129], v[70:73]
	v_mfma_f32_16x16x32_bf16 v[38:41], v[18:21], v[130:133], v[6:9]
	v_mfma_f32_16x16x32_bf16 v[26:29], v[22:25], v[118:121], v[74:77]
	v_mfma_f32_16x16x32_bf16 v[18:21], v[22:25], v[122:125], v[98:101]
	v_mfma_f32_16x16x32_bf16 v[30:33], v[22:25], v[126:129], v[102:105]
	v_mfma_f32_16x16x32_bf16 v[22:25], v[22:25], v[130:133], v[10:13]
	v_mfma_f32_16x16x32_bf16 v[10:13], v[110:113], v[118:121], v[106:109]
	v_mfma_f32_16x16x32_bf16 v[2:5], v[110:113], v[122:125], v[66:69]
	v_mfma_f32_16x16x32_bf16 v[14:17], v[110:113], v[126:129], v[78:81]
	v_mfma_f32_16x16x32_bf16 v[6:9], v[110:113], v[130:133], v[82:85]
	s_setprio 0
	v_and_or_b32 v0, v114, 64, s14
	v_add_u32_e32 v66, s13, v117
	v_lshl_or_b32 v68, v116, 2, v66
	v_ashrrev_i32_e32 v66, 1, v0
	v_ashrrev_i32_e32 v67, 31, v66
	v_lshl_add_u64 v[66:67], v[66:67], 1, s[2:3]
	v_lshlrev_b32_e32 v0, 1, v115
	v_lshl_add_u64 v[66:67], v[66:67], 0, v[0:1]
	v_mul_f32_e32 v0, 0xbfb8aa3b, v58
	v_exp_f32_e32 v0, v0
	v_mad_i64_i32 v[70:71], s[0:1], v68, s54, v[66:67]
	v_add_f32_e32 v0, 1.0, v0
	v_rcp_f32_e32 v0, v0
	s_barrier
	v_mul_f32_e32 v0, v58, v0
	v_mul_f32_e32 v0, v62, v0
	v_cvt_pk_bf16_f32 v0, v0, s0
	global_store_short v[70:71], v0, off nt
	v_mul_f32_e32 v0, 0xbfb8aa3b, v50
	v_exp_f32_e32 v0, v0
	s_nop 0
	v_add_f32_e32 v0, 1.0, v0
	v_rcp_f32_e32 v0, v0
	s_nop 0
	v_mul_f32_e32 v0, v50, v0
	v_mul_f32_e32 v0, v54, v0
	v_cvt_pk_bf16_f32 v0, v0, s0
	global_store_short v[70:71], v0, off offset:32 nt
	v_or_b32_e32 v0, 1, v68
	v_mad_i64_i32 v[70:71], s[0:1], v0, s54, v[66:67]
	v_mul_f32_e32 v0, 0xbfb8aa3b, v59
	v_exp_f32_e32 v0, v0
	s_nop 0
	v_add_f32_e32 v0, 1.0, v0
	v_rcp_f32_e32 v0, v0
	s_nop 0
	v_mul_f32_e32 v0, v59, v0
	v_mul_f32_e32 v0, v63, v0
	v_cvt_pk_bf16_f32 v0, v0, s0
	global_store_short v[70:71], v0, off nt
	v_mul_f32_e32 v0, 0xbfb8aa3b, v51
	v_exp_f32_e32 v0, v0
	s_nop 0
	v_add_f32_e32 v0, 1.0, v0
	v_rcp_f32_e32 v0, v0
	s_nop 0
	v_mul_f32_e32 v0, v51, v0
	v_mul_f32_e32 v0, v55, v0
	v_cvt_pk_bf16_f32 v0, v0, s0
	global_store_short v[70:71], v0, off offset:32 nt
	v_or_b32_e32 v0, 2, v68
	v_mad_i64_i32 v[50:51], s[0:1], v0, s54, v[66:67]
	v_mul_f32_e32 v0, 0xbfb8aa3b, v60
	v_exp_f32_e32 v0, v0
	s_nop 0
	v_add_f32_e32 v0, 1.0, v0
	v_rcp_f32_e32 v0, v0
	s_nop 0
	v_mul_f32_e32 v0, v60, v0
	v_mul_f32_e32 v0, v64, v0
	v_cvt_pk_bf16_f32 v0, v0, s0
	global_store_short v[50:51], v0, off nt
	v_mul_f32_e32 v0, 0xbfb8aa3b, v52
	v_exp_f32_e32 v0, v0
	s_nop 0
	v_add_f32_e32 v0, 1.0, v0
	v_rcp_f32_e32 v0, v0
	s_nop 0
	v_mul_f32_e32 v0, v52, v0
	v_mul_f32_e32 v0, v56, v0
	v_cvt_pk_bf16_f32 v0, v0, s0
	global_store_short v[50:51], v0, off offset:32 nt
	v_or_b32_e32 v0, 3, v68
	v_mad_i64_i32 v[50:51], s[0:1], v0, s54, v[66:67]
	v_mul_f32_e32 v0, 0xbfb8aa3b, v61
	v_exp_f32_e32 v0, v0
	s_nop 0
	v_add_f32_e32 v0, 1.0, v0
	v_rcp_f32_e32 v0, v0
	s_nop 0
	v_mul_f32_e32 v0, v61, v0
	v_mul_f32_e32 v0, v65, v0
	v_cvt_pk_bf16_f32 v0, v0, s0
	global_store_short v[50:51], v0, off nt
	v_mul_f32_e32 v0, 0xbfb8aa3b, v53
	v_exp_f32_e32 v0, v0
	s_nop 0
	v_add_f32_e32 v0, 1.0, v0
	v_rcp_f32_e32 v0, v0
	s_nop 0
	v_mul_f32_e32 v0, v53, v0
	v_mul_f32_e32 v0, v57, v0
	v_cvt_pk_bf16_f32 v0, v0, s0
	global_store_short v[50:51], v0, off offset:32 nt
	v_or_b32_e32 v0, 16, v68
; DEV float siluf(float x) { return x * __builtin_amdgcn_rcpf(1.f + __expf(-x)); }
; template <int EPI, bool AF32>
; DEV void gemm_tile(const void* Ap, int lda, const u16* Bt, int ldb, int K, int m0, int n0, const Epi& ea, char* smem) {
;     ...
;       } else if (EPI == EP_SWIGLU) {
;         u16* C = (u16*)ea.p0;
;         const int jb = (cb >> 6) * 32;
; #pragma unroll
;         for (int n = 0; n < 2; n++)
;           __builtin_nontemporal_store(f2bf(siluf(acc[m][n][j]) * acc[m][n + 2][j]), &C[(size_t)row * 2816 + jb + n * 16 + fr]);
	v_mad_i64_i32 v[50:51], s[0:1], v0, s54, v[66:67]
	v_mul_f32_e32 v0, 0xbfb8aa3b, v42
	v_exp_f32_e32 v0, v0
	s_nop 0
	v_add_f32_e32 v0, 1.0, v0
	v_rcp_f32_e32 v0, v0
	s_nop 0
	v_mul_f32_e32 v0, v42, v0
	v_mul_f32_e32 v0, v46, v0
	v_cvt_pk_bf16_f32 v0, v0, s0
	global_store_short v[50:51], v0, off nt
	v_mul_f32_e32 v0, 0xbfb8aa3b, v34
	v_exp_f32_e32 v0, v0
	s_nop 0
	v_add_f32_e32 v0, 1.0, v0
	v_rcp_f32_e32 v0, v0
	s_nop 0
	v_mul_f32_e32 v0, v34, v0
	v_mul_f32_e32 v0, v38, v0
	v_cvt_pk_bf16_f32 v0, v0, s0
	global_store_short v[50:51], v0, off offset:32 nt
	v_or_b32_e32 v0, 17, v68
	v_mad_i64_i32 v[50:51], s[0:1], v0, s54, v[66:67]
	v_mul_f32_e32 v0, 0xbfb8aa3b, v43
	v_exp_f32_e32 v0, v0
	s_nop 0
	v_add_f32_e32 v0, 1.0, v0
	v_rcp_f32_e32 v0, v0
	s_nop 0
	v_mul_f32_e32 v0, v43, v0
	v_mul_f32_e32 v0, v47, v0
	v_cvt_pk_bf16_f32 v0, v0, s0
	global_store_short v[50:51], v0, off nt
	v_mul_f32_e32 v0, 0xbfb8aa3b, v35
	v_exp_f32_e32 v0, v0
	s_nop 0
	v_add_f32_e32 v0, 1.0, v0
	v_rcp_f32_e32 v0, v0
	s_nop 0
	v_mul_f32_e32 v0, v35, v0
	v_mul_f32_e32 v0, v39, v0
	v_cvt_pk_bf16_f32 v0, v0, s0
	global_store_short v[50:51], v0, off offset:32 nt
	v_or_b32_e32 v0, 18, v68
	v_mad_i64_i32 v[34:35], s[0:1], v0, s54, v[66:67]
	v_mul_f32_e32 v0, 0xbfb8aa3b, v44
	v_exp_f32_e32 v0, v0
	s_nop 0
	v_add_f32_e32 v0, 1.0, v0
	v_rcp_f32_e32 v0, v0
	s_nop 0
	v_mul_f32_e32 v0, v44, v0
	v_mul_f32_e32 v0, v48, v0
	v_cvt_pk_bf16_f32 v0, v0, s0
	global_store_short v[34:35], v0, off nt
	v_mul_f32_e32 v0, 0xbfb8aa3b, v36
	v_exp_f32_e32 v0, v0
	s_nop 0
	v_add_f32_e32 v0, 1.0, v0
	v_rcp_f32_e32 v0, v0
	s_nop 0
	v_mul_f32_e32 v0, v36, v0
	v_mul_f32_e32 v0, v40, v0
	v_cvt_pk_bf16_f32 v0, v0, s0
	global_store_short v[34:35], v0, off offset:32 nt
	v_or_b32_e32 v0, 19, v68
	v_mad_i64_i32 v[34:35], s[0:1], v0, s54, v[66:67]
	v_mul_f32_e32 v0, 0xbfb8aa3b, v45
	v_exp_f32_e32 v0, v0
	s_nop 0
	v_add_f32_e32 v0, 1.0, v0
	v_rcp_f32_e32 v0, v0
	s_nop 0
	v_mul_f32_e32 v0, v45, v0
	v_mul_f32_e32 v0, v49, v0
	v_cvt_pk_bf16_f32 v0, v0, s0
	global_store_short v[34:35], v0, off nt
	v_mul_f32_e32 v0, 0xbfb8aa3b, v37
	v_exp_f32_e32 v0, v0
	s_nop 0
	v_add_f32_e32 v0, 1.0, v0
	v_rcp_f32_e32 v0, v0
	s_nop 0
	v_mul_f32_e32 v0, v37, v0
	v_mul_f32_e32 v0, v41, v0
	v_cvt_pk_bf16_f32 v0, v0, s0
	global_store_short v[34:35], v0, off offset:32 nt
	v_or_b32_e32 v0, 32, v68
	v_mad_i64_i32 v[34:35], s[0:1], v0, s54, v[66:67]
	v_mul_f32_e32 v0, 0xbfb8aa3b, v26
	v_exp_f32_e32 v0, v0
	s_nop 0
	v_add_f32_e32 v0, 1.0, v0
	v_rcp_f32_e32 v0, v0
	s_nop 0
	v_mul_f32_e32 v0, v26, v0
	v_mul_f32_e32 v0, v30, v0
	v_cvt_pk_bf16_f32 v0, v0, s0
	global_store_short v[34:35], v0, off nt
	v_mul_f32_e32 v0, 0xbfb8aa3b, v18
	v_exp_f32_e32 v0, v0
	s_nop 0
	v_add_f32_e32 v0, 1.0, v0
	v_rcp_f32_e32 v0, v0
	s_nop 0
	v_mul_f32_e32 v0, v18, v0
	v_mul_f32_e32 v0, v22, v0
	v_cvt_pk_bf16_f32 v0, v0, s0
	global_store_short v[34:35], v0, off offset:32 nt
	v_or_b32_e32 v0, 33, v68
	v_mad_i64_i32 v[34:35], s[0:1], v0, s54, v[66:67]
	v_mul_f32_e32 v0, 0xbfb8aa3b, v27
	v_exp_f32_e32 v0, v0
	s_nop 0
	v_add_f32_e32 v0, 1.0, v0
	v_rcp_f32_e32 v0, v0
	s_nop 0
	v_mul_f32_e32 v0, v27, v0
	v_mul_f32_e32 v0, v31, v0
	v_cvt_pk_bf16_f32 v0, v0, s0
	global_store_short v[34:35], v0, off nt
	v_mul_f32_e32 v0, 0xbfb8aa3b, v19
	v_exp_f32_e32 v0, v0
	s_nop 0
	v_add_f32_e32 v0, 1.0, v0
	v_rcp_f32_e32 v0, v0
	s_nop 0
	v_mul_f32_e32 v0, v19, v0
	v_mul_f32_e32 v0, v23, v0
	v_cvt_pk_bf16_f32 v0, v0, s0
	global_store_short v[34:35], v0, off offset:32 nt
	v_or_b32_e32 v0, 34, v68
	v_mad_i64_i32 v[18:19], s[0:1], v0, s54, v[66:67]
; DEV int bidx() { int b = __builtin_amdgcn_readfirstlane(blockIdx.x); asm volatile("" : "+s"(b)); return b; }
; DEV int gdim() { int g = __builtin_amdgcn_readfirstlane(gridDim.x); asm volatile("" : "+s"(g)); return g; }
; DEV float siluf(float x) { return x * __builtin_amdgcn_rcpf(1.f + __expf(-x)); }
; template <int EPI, bool AF32>
; DEV void gemm_tile(const void* Ap, int lda, const u16* Bt, int ldb, int K, int m0, int n0, const Epi& ea, char* smem) {
;     ...
;       } else if (EPI == EP_SWIGLU) {
;         u16* C = (u16*)ea.p0;
;         const int jb = (cb >> 6) * 32;
; #pragma unroll
;         for (int n = 0; n < 2; n++)
;           __builtin_nontemporal_store(f2bf(siluf(acc[m][n][j]) * acc[m][n + 2][j]), &C[(size_t)row * 2816 + jb + n * 16 + fr]);
; template <int EPI, bool AF32>
; DEV void gemm_phase(const void* A, int lda, const u16* Bt, int ldb, int M, int N, int K, const Epi& ea, char* smem) {
;     ...
;   for (int tile = bidx(); tile < ntm * ntn; tile += gdim()) {
	v_mul_f32_e32 v0, 0xbfb8aa3b, v28
	v_exp_f32_e32 v0, v0
	s_nop 0
	v_add_f32_e32 v0, 1.0, v0
	v_rcp_f32_e32 v0, v0
	s_nop 0
	v_mul_f32_e32 v0, v28, v0
	v_mul_f32_e32 v0, v32, v0
	v_cvt_pk_bf16_f32 v0, v0, s0
	global_store_short v[18:19], v0, off nt
	v_mul_f32_e32 v0, 0xbfb8aa3b, v20
	v_exp_f32_e32 v0, v0
	s_nop 0
	v_add_f32_e32 v0, 1.0, v0
	v_rcp_f32_e32 v0, v0
	s_nop 0
	v_mul_f32_e32 v0, v20, v0
	v_mul_f32_e32 v0, v24, v0
	v_cvt_pk_bf16_f32 v0, v0, s0
	global_store_short v[18:19], v0, off offset:32 nt
	v_or_b32_e32 v0, 35, v68
	v_mad_i64_i32 v[18:19], s[0:1], v0, s54, v[66:67]
	v_mul_f32_e32 v0, 0xbfb8aa3b, v29
	v_exp_f32_e32 v0, v0
	s_nop 0
	v_add_f32_e32 v0, 1.0, v0
	v_rcp_f32_e32 v0, v0
	s_nop 0
	v_mul_f32_e32 v0, v29, v0
	v_mul_f32_e32 v0, v33, v0
	v_cvt_pk_bf16_f32 v0, v0, s0
	global_store_short v[18:19], v0, off nt
	v_mul_f32_e32 v0, 0xbfb8aa3b, v21
	v_exp_f32_e32 v0, v0
	s_nop 0
	v_add_f32_e32 v0, 1.0, v0
	v_rcp_f32_e32 v0, v0
	s_nop 0
	v_mul_f32_e32 v0, v21, v0
	v_mul_f32_e32 v0, v25, v0
	v_cvt_pk_bf16_f32 v0, v0, s0
	global_store_short v[18:19], v0, off offset:32 nt
	v_or_b32_e32 v0, 48, v68
	v_mad_i64_i32 v[18:19], s[0:1], v0, s54, v[66:67]
	v_mul_f32_e32 v0, 0xbfb8aa3b, v10
	v_exp_f32_e32 v0, v0
	s_nop 0
	v_add_f32_e32 v0, 1.0, v0
	v_rcp_f32_e32 v0, v0
	s_nop 0
	v_mul_f32_e32 v0, v10, v0
	v_mul_f32_e32 v0, v14, v0
	v_cvt_pk_bf16_f32 v0, v0, s0
	global_store_short v[18:19], v0, off nt
	v_mul_f32_e32 v0, 0xbfb8aa3b, v2
	v_exp_f32_e32 v0, v0
	s_nop 0
	v_add_f32_e32 v0, 1.0, v0
	v_rcp_f32_e32 v0, v0
	s_nop 0
	v_mul_f32_e32 v0, v2, v0
	v_mul_f32_e32 v0, v6, v0
	v_cvt_pk_bf16_f32 v0, v0, s0
	global_store_short v[18:19], v0, off offset:32 nt
	v_or_b32_e32 v0, 49, v68
	v_mad_i64_i32 v[18:19], s[0:1], v0, s54, v[66:67]
	v_mul_f32_e32 v0, 0xbfb8aa3b, v11
	v_exp_f32_e32 v0, v0
	s_nop 0
	v_add_f32_e32 v0, 1.0, v0
	v_rcp_f32_e32 v0, v0
	s_nop 0
	v_mul_f32_e32 v0, v11, v0
	v_mul_f32_e32 v0, v15, v0
	v_cvt_pk_bf16_f32 v0, v0, s0
	global_store_short v[18:19], v0, off nt
	v_mul_f32_e32 v0, 0xbfb8aa3b, v3
	v_exp_f32_e32 v0, v0
	s_nop 0
	v_add_f32_e32 v0, 1.0, v0
	v_rcp_f32_e32 v0, v0
	s_nop 0
	v_mul_f32_e32 v0, v3, v0
	v_mul_f32_e32 v0, v7, v0
	v_cvt_pk_bf16_f32 v0, v0, s0
	global_store_short v[18:19], v0, off offset:32 nt
	v_or_b32_e32 v0, 50, v68
	v_mad_i64_i32 v[2:3], s[0:1], v0, s54, v[66:67]
	v_mul_f32_e32 v0, 0xbfb8aa3b, v12
	v_exp_f32_e32 v0, v0
	s_nop 0
	v_add_f32_e32 v0, 1.0, v0
	v_rcp_f32_e32 v0, v0
	s_nop 0
	v_mul_f32_e32 v0, v12, v0
	v_mul_f32_e32 v0, v16, v0
	v_cvt_pk_bf16_f32 v0, v0, s0
	global_store_short v[2:3], v0, off nt
	v_mul_f32_e32 v0, 0xbfb8aa3b, v4
	v_exp_f32_e32 v0, v0
	s_nop 0
	v_add_f32_e32 v0, 1.0, v0
	v_rcp_f32_e32 v0, v0
	s_nop 0
	v_mul_f32_e32 v0, v4, v0
	v_mul_f32_e32 v0, v8, v0
	v_cvt_pk_bf16_f32 v0, v0, s0
	global_store_short v[2:3], v0, off offset:32 nt
	v_or_b32_e32 v0, 51, v68
	v_mad_i64_i32 v[2:3], s[0:1], v0, s54, v[66:67]
	v_mul_f32_e32 v0, 0xbfb8aa3b, v13
	v_exp_f32_e32 v0, v0
	s_nop 0
	v_add_f32_e32 v0, 1.0, v0
	v_rcp_f32_e32 v0, v0
	s_nop 0
	v_mul_f32_e32 v0, v13, v0
	v_mul_f32_e32 v0, v17, v0
	v_cvt_pk_bf16_f32 v0, v0, s0
	global_store_short v[2:3], v0, off nt
	v_mul_f32_e32 v0, 0xbfb8aa3b, v5
	v_exp_f32_e32 v0, v0
	s_nop 0
	v_add_f32_e32 v0, 1.0, v0
	v_rcp_f32_e32 v0, v0
	s_nop 0
	v_mul_f32_e32 v0, v5, v0
	v_mul_f32_e32 v0, v9, v0
	v_cvt_pk_bf16_f32 v0, v0, s0
	v_readfirstlane_b32 s0, v198
	global_store_short v[2:3], v0, off offset:32 nt
	s_add_i32 s12, s0, s12
	s_cmpk_lt_i32 s12, 0x2cb0
	s_cbranch_scc1 .LBB0_1436

; template <int EPI, bool AF32>
; DEV void gemm_tile(const void* Ap, int lda, const u16* Bt, int ldb, int K, int m0, int n0, const Epi& ea, char* smem) {
;     ...
;   auto gload = [&](int kt) {
;     const int k0 = kt << 6;
; #pragma unroll
;     for (int i = 0; i < 4; i++) {
;       const int c = tid + i * 256, row = c >> 3, kc = c & 7;
;       if (AF32) {
;         const float* pa = (const float*)Ap + (size_t)(m0 + row) * lda + k0 + kc * 8;
;         rfa[2 * i] = *(const f32x4*)pa;
;         rfa[2 * i + 1] = *(const f32x4*)(pa + 4);
;       } else {
;         ra[i] = *(const u32x4*)((const u16*)Ap + (size_t)(m0 + row) * lda + k0 + kc * 8);
;       }
;       rb[i] = *(const u32x4*)(Bt + (size_t)(n0 + row) * ldb + k0 + kc * 8);
;     }
;   };
;   auto swrite = [&](int buf) {
; #pragma unroll
;     for (int i = 0; i < 4; i++) {
;       const int c = tid + i * 256, row = c >> 3, kc = c & 7;
;       u32x4 va;
;       if (AF32) {
;         va = (u32x4){pack2(rfa[2 * i][0], rfa[2 * i][1]), pack2(rfa[2 * i][2], rfa[2 * i][3]),
;                      pack2(rfa[2 * i + 1][0], rfa[2 * i + 1][1]), pack2(rfa[2 * i + 1][2], rfa[2 * i + 1][3])};
;       } else {
;         va = ra[i];
;       }
;       *(u32x4*)(sA + buf * 9216 + row * 72 + kc * 8) = va;
;       *(u32x4*)(sB + buf * 9216 + row * 72 + kc * 8) = rb[i];
;     }
;   };
;   gload(0);
;   swrite(0);
;   if (nk > 1) gload(1);
;   __syncthreads();
.LBB0_1478:
	s_ashr_i32 s0, s14, 31
	s_lshr_b32 s0, s0, 24
	s_add_i32 s0, s14, s0
	s_ashr_i32 s1, s0, 8
	s_and_b32 s0, s0, 0xffffff00
	s_lshl_b32 s16, s1, 5
	s_sub_i32 s15, s14, s0
	s_sub_i32 s0, 0x104, s16
	s_min_u32 s17, s0, 32
	v_cvt_f32_ubyte0_e32 v2, s17
	v_cvt_f32_i32_e32 v0, s15
	v_rcp_iflag_f32_e32 v3, v2
	s_ashr_i32 s0, s15, 30
	s_or_b32 s18, s0, 1
	s_waitcnt vmcnt(12)
	v_mov_b32_e32 v116, v157
	v_mul_f32_e32 v3, v0, v3
	v_trunc_f32_e32 v3, v3
	v_fma_f32 v0, -v3, v2, v0
	v_cvt_i32_f32_e32 v3, v3
	v_cmp_ge_f32_e64 s[0:1], |v0|, v2
	s_and_b64 s[0:1], s[0:1], exec
	s_cselect_b32 s0, s18, 0
	v_readfirstlane_b32 s1, v3
	s_add_i32 s0, s1, s0
	s_sext_i32_i16 s1, s0
	s_mul_i32 s0, s0, s17
	s_sub_i32 s0, s15, s0
	s_sext_i32_i16 s0, s0
	s_add_i32 s16, s16, s0
	s_lshl_b32 s16, s16, 7
	v_mov_b64_e32 v[2:3], s[6:7]
	v_ashrrev_i32_e32 v54, 3, v116
	v_lshlrev_b32_e32 v0, 3, v116
	v_add_u32_e32 v62, s16, v54
	v_and_b32_e32 v0, 56, v0
	s_lshl_b32 s15, s1, 7
	v_mad_i64_i32 v[4:5], s[0:1], v62, s54, v[2:3]
	v_lshlrev_b32_e32 v0, 1, v0
	v_add_u32_e32 v18, 0x100, v116
	v_add_u32_e32 v26, 0x200, v116
	v_lshl_add_u64 v[6:7], v[4:5], 0, v[0:1]
	v_add_u32_e32 v55, s15, v54
	v_mov_b64_e32 v[4:5], s[8:9]
	v_ashrrev_i32_e32 v70, 3, v18
	v_ashrrev_i32_e32 v71, 3, v26
	v_mad_i64_i32 v[8:9], s[0:1], v55, s54, v[4:5]
	v_add_u32_e32 v64, s16, v70
	v_add_u32_e32 v56, s15, v70
	v_add_u32_e32 v66, s16, v71
	v_add_u32_e32 v58, s15, v71
	v_lshl_add_u64 v[8:9], v[8:9], 0, v[0:1]
	v_mad_i64_i32 v[18:19], s[0:1], v64, s54, v[2:3]
	v_mad_i64_i32 v[22:23], s[0:1], v56, s54, v[4:5]
	v_mad_i64_i32 v[26:27], s[0:1], v66, s54, v[2:3]
	v_mad_i64_i32 v[30:31], s[0:1], v58, s54, v[4:5]
	global_load_dwordx4 v[14:17], v[8:9], off
	v_lshl_add_u64 v[42:43], v[18:19], 0, v[0:1]
	v_lshl_add_u64 v[44:45], v[22:23], 0, v[0:1]
	v_lshl_add_u64 v[46:47], v[26:27], 0, v[0:1]
	v_lshl_add_u64 v[48:49], v[30:31], 0, v[0:1]
	global_load_dwordx4 v[10:13], v[6:7], off
	global_load_dwordx4 v[18:21], v[42:43], off
	global_load_dwordx4 v[22:25], v[44:45], off
	global_load_dwordx4 v[26:29], v[46:47], off
	global_load_dwordx4 v[30:33], v[48:49], off
	v_add_u32_e32 v34, 0x300, v116
	v_ashrrev_i32_e32 v72, 3, v34
	v_add_u32_e32 v68, s16, v72
	v_mad_i64_i32 v[2:3], s[0:1], v68, s54, v[2:3]
	v_lshl_add_u64 v[50:51], v[2:3], 0, v[0:1]
	global_load_dwordx4 v[34:37], v[50:51], off
	v_add_u32_e32 v60, s15, v72
	v_mad_i64_i32 v[2:3], s[0:1], v60, s54, v[4:5]
	s_waitcnt vmcnt(18)
	v_mul_lo_u32 v119, v54, s71
	v_lshl_add_u64 v[52:53], v[2:3], 0, v[0:1]
	v_bfe_u32 v161, v157, 3, 4
	v_add_u32_e32 v161, 4, v161
	v_lshlrev_b32_e32 v161, 1, v161
	v_and_b32_e32 v161, 16, v161
	v_xor_b32_e32 v129, v0, v161
	v_lshl_add_u32 v118, v119, 1, v129
	v_mul_lo_u32 v121, v70, s71
	s_waitcnt vmcnt(17)
	v_mul_lo_u32 v124, v71, s71
	global_load_dwordx4 v[38:41], v[52:53], off
	global_load_dwordx4 v[2:5], v[8:9], off offset:128
	v_lshl_add_u32 v120, v121, 1, v129
	global_load_dwordx4 v[6:9], v[6:7], off offset:128
	v_lshl_add_u32 v122, v124, 1, v129
	s_waitcnt vmcnt(19)
	v_mul_lo_u32 v126, v72, s71
	v_lshl_add_u32 v123, v126, 1, v129
	v_and_b32_e32 v114, 15, v116
	v_mad_i64_i32 v[54:55], s[0:1], v55, s54, 0
	v_mad_i64_i32 v[56:57], s[0:1], v56, s54, 0
	v_mad_i64_i32 v[58:59], s[0:1], v58, s54, 0
	v_mad_i64_i32 v[60:61], s[0:1], v60, s54, 0
	v_mad_i64_i32 v[62:63], s[0:1], v62, s54, 0
	v_mad_i64_i32 v[64:65], s[0:1], v64, s54, 0
	v_mad_i64_i32 v[66:67], s[0:1], v66, s54, 0
	v_mad_i64_i32 v[68:69], s[0:1], v68, s54, 0
	s_waitcnt vmcnt(9)
	ds_write_b128 v118, v[14:17] offset:36864
	s_waitcnt vmcnt(8)
	ds_write_b128 v118, v[10:13]
	global_load_dwordx4 v[10:13], v[42:43], off offset:128
	s_waitcnt vmcnt(8)
	ds_write_b128 v120, v[18:21]
	global_load_dwordx4 v[14:17], v[44:45], off offset:128
	s_waitcnt vmcnt(8)
	ds_write_b128 v120, v[22:25] offset:36864
	global_load_dwordx4 v[18:21], v[46:47], off offset:128
	s_waitcnt vmcnt(8)
	ds_write_b128 v122, v[26:29]
	global_load_dwordx4 v[22:25], v[48:49], off offset:128
	s_waitcnt vmcnt(8)
	ds_write_b128 v122, v[30:33] offset:36864
	global_load_dwordx4 v[26:29], v[50:51], off offset:128
	global_load_dwordx4 v[30:33], v[52:53], off offset:128
	v_bfe_u32 v115, v116, 4, 2
	s_waitcnt vmcnt(9)
	ds_write_b128 v123, v[34:37]
	v_ashrrev_i32_e32 v34, 1, v116
	v_and_b32_e32 v117, 0xffffffc0, v34
	v_or_b32_e32 v34, v117, v114
	v_mul_lo_u32 v128, v34, s71
	v_lshlrev_b32_e32 v34, 4, v116
	v_and_b32_e32 v34, 0x70, v34
	v_and_b32_e32 v35, 0x4f, v116
	v_or_b32_e32 v60, v60, v34
	v_or_b32_e32 v68, v68, v34
	v_or_b32_e32 v58, v58, v34
	v_or_b32_e32 v66, v66, v34
	v_or_b32_e32 v56, v56, v34
	v_or_b32_e32 v64, v64, v34
	v_or_b32_e32 v54, v54, v34
	v_or_b32_e32 v62, v62, v34
	v_mov_b32_e32 v34, 0
	s_mov_b32 s17, 0
	s_waitcnt vmcnt(8)
	ds_write_b128 v123, v[38:41] offset:36864
	v_lshlrev_b32_e32 v125, 4, v115
	v_and_b32_e32 v161, 15, v157
	v_add_u32_e32 v161, 4, v161
	v_lshlrev_b32_e32 v161, 1, v161
	v_and_b32_e32 v161, 16, v161
	v_xor_b32_e32 v125, v125, v161
	v_mul_u32_u24_e32 v127, 0x48, v35
	v_lshl_add_u64 v[98:99], s[10:11], 0, v[60:61]
	v_lshl_add_u64 v[100:101], s[12:13], 0, v[68:69]
	v_lshl_add_u64 v[102:103], s[10:11], 0, v[58:59]
	v_lshl_add_u64 v[104:105], s[12:13], 0, v[66:67]
	v_lshl_add_u64 v[106:107], s[10:11], 0, v[56:57]
	v_lshl_add_u64 v[108:109], s[12:13], 0, v[64:65]
	v_lshl_add_u64 v[110:111], s[10:11], 0, v[54:55]
	v_lshl_add_u64 v[112:113], s[12:13], 0, v[62:63]
	s_mov_b64 s[0:1], 0
	v_mov_b32_e32 v35, v34
	v_mov_b32_e32 v36, v34
	v_mov_b32_e32 v37, v34
	v_mov_b32_e32 v38, v34
	v_mov_b32_e32 v39, v34
	v_mov_b32_e32 v40, v34
	v_mov_b32_e32 v41, v34
	v_mov_b32_e32 v42, v34
	v_mov_b32_e32 v43, v34
	v_mov_b32_e32 v44, v34
	v_mov_b32_e32 v45, v34
	v_mov_b32_e32 v46, v34
	v_mov_b32_e32 v47, v34
	v_mov_b32_e32 v48, v34
	v_mov_b32_e32 v49, v34
	v_mov_b32_e32 v50, v34
	v_mov_b32_e32 v51, v34
	v_mov_b32_e32 v52, v34
	v_mov_b32_e32 v53, v34
	v_mov_b32_e32 v54, v34
	v_mov_b32_e32 v55, v34
	v_mov_b32_e32 v56, v34
	v_mov_b32_e32 v57, v34
	v_mov_b32_e32 v58, v34
	v_mov_b32_e32 v59, v34
	v_mov_b32_e32 v60, v34
	v_mov_b32_e32 v61, v34
	v_mov_b32_e32 v62, v34
	v_mov_b32_e32 v63, v34
	v_mov_b32_e32 v64, v34
	v_mov_b32_e32 v65, v34
	v_mov_b32_e32 v66, v34
	v_mov_b32_e32 v67, v34
	v_mov_b32_e32 v68, v34
	v_mov_b32_e32 v69, v34
	v_mov_b32_e32 v70, v34
	v_mov_b32_e32 v71, v34
	v_mov_b32_e32 v72, v34
	v_mov_b32_e32 v73, v34
	v_mov_b32_e32 v74, v34
	v_mov_b32_e32 v75, v34
	v_mov_b32_e32 v76, v34
	v_mov_b32_e32 v77, v34
	v_mov_b32_e32 v78, v34
	v_mov_b32_e32 v79, v34
	v_mov_b32_e32 v80, v34
	v_mov_b32_e32 v81, v34
	v_mov_b32_e32 v82, v34
	v_mov_b32_e32 v83, v34
	v_mov_b32_e32 v84, v34
	v_mov_b32_e32 v85, v34
	v_mov_b32_e32 v86, v34
	v_mov_b32_e32 v87, v34
	v_mov_b32_e32 v88, v34
	v_mov_b32_e32 v89, v34
	v_mov_b32_e32 v90, v34
	v_mov_b32_e32 v91, v34
	v_mov_b32_e32 v92, v34
	v_mov_b32_e32 v93, v34
	v_mov_b32_e32 v94, v34
	v_mov_b32_e32 v95, v34
	v_mov_b32_e32 v96, v34
	v_mov_b32_e32 v97, v34
	s_waitcnt lgkmcnt(0)
	s_barrier
; DEV f32x4 mfma16(bf16x8 a, bf16x8 b, f32x4 c) { return __builtin_amdgcn_mfma_f32_16x16x32_bf16(a, b, c, 0, 0, 0); }
; template <int EPI, bool AF32>
; DEV void gemm_tile(const void* Ap, int lda, const u16* Bt, int ldb, int K, int m0, int n0, const Epi& ea, char* smem) {
;     ...
;   for (int kt = 0; kt < nk; kt++) {
;     const int buf = kt & 1;
;     if (kt + 1 < nk) swrite(buf ^ 1);
;     if (kt + 2 < nk) gload(kt + 2);
; #pragma unroll
;     for (int ks = 0; ks < 2; ks++) {
;       bf16x8 a[4], b[4];
; #pragma unroll
;       for (int m = 0; m < 4; m++) a[m] = *(const bf16x8*)(sA + buf * 9216 + (wr * 64 + m * 16 + fr) * 72 + ks * 32 + fq * 8);
; #pragma unroll
;       for (int n = 0; n < 4; n++) b[n] = *(const bf16x8*)(sB + buf * 9216 + (wc * 64 + n * 16 + fr) * 72 + ks * 32 + fq * 8);
;       __builtin_amdgcn_s_setprio(1);
; #pragma unroll
;       for (int m = 0; m < 4; m++)
; #pragma unroll
;         for (int n = 0; n < 4; n++) acc[m][n] = mfma16(a[m], b[n], acc[m][n]);
;       __builtin_amdgcn_s_setprio(0);
;     }
;     __syncthreads();
	v_lshl_add_u32 v161, v128, 1, v125
	v_lshl_add_u32 v129, v127, 1, v125
	s_mov_b32 s17, 0
	s_mov_b64 s[0:1], 0x100
	ds_read_b128 v[130:133], v161
	ds_read_b128 v[134:137], v161 offset:2304
	ds_read_b128 v[138:141], v161 offset:4608
	ds_read_b128 v[142:145], v161 offset:6912
	ds_read_b128 v[146:149], v129 offset:36864
	ds_read_b128 v[150:153], v129 offset:39168
	ds_read_b128 v[162:165], v129 offset:41472
	ds_read_b128 v[166:169], v129 offset:43776
.Lgk7_loop:
	s_waitcnt lgkmcnt(0)
	ds_read_b128 v[222:225], v161 offset:64
	ds_read_b128 v[226:229], v161 offset:2368
	ds_read_b128 v[230:233], v161 offset:4672
	ds_read_b128 v[234:237], v161 offset:6976
	ds_read_b128 v[238:241], v129 offset:36928
	ds_read_b128 v[242:245], v129 offset:39232
	ds_read_b128 v[246:249], v129 offset:41536
	ds_read_b128 v[250:253], v129 offset:43840
	v_mfma_f32_16x16x32_bf16 v[34:37], v[130:133], v[146:149], v[34:37]
	v_mfma_f32_16x16x32_bf16 v[38:41], v[130:133], v[150:153], v[38:41]
	v_mfma_f32_16x16x32_bf16 v[42:45], v[130:133], v[162:165], v[42:45]
	v_mfma_f32_16x16x32_bf16 v[46:49], v[130:133], v[166:169], v[46:49]
	s_waitcnt vmcnt(0)
	ds_write_b128 v118, v[6:9] offset:18432
	ds_write_b128 v118, v[2:5] offset:55296
	v_mfma_f32_16x16x32_bf16 v[50:53], v[134:137], v[146:149], v[50:53]
	ds_write_b128 v120, v[10:13] offset:18432
	ds_write_b128 v120, v[14:17] offset:55296
	v_mfma_f32_16x16x32_bf16 v[54:57], v[134:137], v[150:153], v[54:57]
	ds_write_b128 v122, v[18:21] offset:18432
	ds_write_b128 v122, v[22:25] offset:55296
	v_mfma_f32_16x16x32_bf16 v[58:61], v[134:137], v[162:165], v[58:61]
	ds_write_b128 v123, v[26:29] offset:18432
	ds_write_b128 v123, v[30:33] offset:55296
	v_mfma_f32_16x16x32_bf16 v[62:65], v[134:137], v[166:169], v[62:65]
	global_load_dwordx4 v[6:9], v[112:113], off
	v_mfma_f32_16x16x32_bf16 v[66:69], v[138:141], v[146:149], v[66:69]
	global_load_dwordx4 v[2:5], v[110:111], off
	v_mfma_f32_16x16x32_bf16 v[70:73], v[138:141], v[150:153], v[70:73]
	global_load_dwordx4 v[10:13], v[108:109], off
	v_mfma_f32_16x16x32_bf16 v[74:77], v[138:141], v[162:165], v[74:77]
	global_load_dwordx4 v[14:17], v[106:107], off
	v_mfma_f32_16x16x32_bf16 v[78:81], v[138:141], v[166:169], v[78:81]
	global_load_dwordx4 v[18:21], v[104:105], off
	v_mfma_f32_16x16x32_bf16 v[82:85], v[142:145], v[146:149], v[82:85]
	global_load_dwordx4 v[22:25], v[102:103], off
	v_mfma_f32_16x16x32_bf16 v[86:89], v[142:145], v[150:153], v[86:89]
	global_load_dwordx4 v[26:29], v[100:101], off
	v_mfma_f32_16x16x32_bf16 v[90:93], v[142:145], v[162:165], v[90:93]
	global_load_dwordx4 v[30:33], v[98:99], off
	v_mfma_f32_16x16x32_bf16 v[94:97], v[142:145], v[166:169], v[94:97]
	s_waitcnt lgkmcnt(0)
	s_barrier
	ds_read_b128 v[130:133], v161 offset:18432
	v_mfma_f32_16x16x32_bf16 v[34:37], v[222:225], v[238:241], v[34:37]
	ds_read_b128 v[134:137], v161 offset:20736
	v_mfma_f32_16x16x32_bf16 v[38:41], v[222:225], v[242:245], v[38:41]
	ds_read_b128 v[138:141], v161 offset:23040
	v_mfma_f32_16x16x32_bf16 v[42:45], v[222:225], v[246:249], v[42:45]
	ds_read_b128 v[142:145], v161 offset:25344
	v_mfma_f32_16x16x32_bf16 v[46:49], v[222:225], v[250:253], v[46:49]
	ds_read_b128 v[146:149], v129 offset:55296
	v_mfma_f32_16x16x32_bf16 v[50:53], v[226:229], v[238:241], v[50:53]
	ds_read_b128 v[150:153], v129 offset:57600
	v_mfma_f32_16x16x32_bf16 v[54:57], v[226:229], v[242:245], v[54:57]
	ds_read_b128 v[162:165], v129 offset:59904
	v_mfma_f32_16x16x32_bf16 v[58:61], v[226:229], v[246:249], v[58:61]
	ds_read_b128 v[166:169], v129 offset:62208
	v_mfma_f32_16x16x32_bf16 v[62:65], v[226:229], v[250:253], v[62:65]
	v_mfma_f32_16x16x32_bf16 v[66:69], v[230:233], v[238:241], v[66:69]
	v_mfma_f32_16x16x32_bf16 v[70:73], v[230:233], v[242:245], v[70:73]
	v_mfma_f32_16x16x32_bf16 v[74:77], v[230:233], v[246:249], v[74:77]
	v_mfma_f32_16x16x32_bf16 v[78:81], v[230:233], v[250:253], v[78:81]
	v_mfma_f32_16x16x32_bf16 v[82:85], v[234:237], v[238:241], v[82:85]
	v_mfma_f32_16x16x32_bf16 v[86:89], v[234:237], v[242:245], v[86:89]
	v_mfma_f32_16x16x32_bf16 v[90:93], v[234:237], v[246:249], v[90:93]
	v_mfma_f32_16x16x32_bf16 v[94:97], v[234:237], v[250:253], v[94:97]
	s_waitcnt lgkmcnt(0)
	ds_read_b128 v[222:225], v161 offset:18496
	ds_read_b128 v[226:229], v161 offset:20800
	ds_read_b128 v[230:233], v161 offset:23104
	ds_read_b128 v[234:237], v161 offset:25408
	ds_read_b128 v[238:241], v129 offset:55360
	ds_read_b128 v[242:245], v129 offset:57664
	ds_read_b128 v[246:249], v129 offset:59968
	ds_read_b128 v[250:253], v129 offset:62272
	v_mfma_f32_16x16x32_bf16 v[34:37], v[130:133], v[146:149], v[34:37]
	v_mfma_f32_16x16x32_bf16 v[38:41], v[130:133], v[150:153], v[38:41]
	v_mfma_f32_16x16x32_bf16 v[42:45], v[130:133], v[162:165], v[42:45]
	v_mfma_f32_16x16x32_bf16 v[46:49], v[130:133], v[166:169], v[46:49]
	s_waitcnt vmcnt(0)
	ds_write_b128 v118, v[6:9]
	ds_write_b128 v118, v[2:5] offset:36864
	v_mfma_f32_16x16x32_bf16 v[50:53], v[134:137], v[146:149], v[50:53]
	ds_write_b128 v120, v[10:13]
	ds_write_b128 v120, v[14:17] offset:36864
	v_mfma_f32_16x16x32_bf16 v[54:57], v[134:137], v[150:153], v[54:57]
	ds_write_b128 v122, v[18:21]
	ds_write_b128 v122, v[22:25] offset:36864
	v_mfma_f32_16x16x32_bf16 v[58:61], v[134:137], v[162:165], v[58:61]
	ds_write_b128 v123, v[26:29]
	ds_write_b128 v123, v[30:33] offset:36864
	v_mfma_f32_16x16x32_bf16 v[62:65], v[134:137], v[166:169], v[62:65]
	global_load_dwordx4 v[6:9], v[112:113], off offset:128
	v_mfma_f32_16x16x32_bf16 v[66:69], v[138:141], v[146:149], v[66:69]
	global_load_dwordx4 v[2:5], v[110:111], off offset:128
	v_mfma_f32_16x16x32_bf16 v[70:73], v[138:141], v[150:153], v[70:73]
	global_load_dwordx4 v[10:13], v[108:109], off offset:128
	v_mfma_f32_16x16x32_bf16 v[74:77], v[138:141], v[162:165], v[74:77]
	global_load_dwordx4 v[14:17], v[106:107], off offset:128
	v_mfma_f32_16x16x32_bf16 v[78:81], v[138:141], v[166:169], v[78:81]
	global_load_dwordx4 v[18:21], v[104:105], off offset:128
	v_mfma_f32_16x16x32_bf16 v[82:85], v[142:145], v[146:149], v[82:85]
	global_load_dwordx4 v[22:25], v[102:103], off offset:128
	v_mfma_f32_16x16x32_bf16 v[86:89], v[142:145], v[150:153], v[86:89]
	global_load_dwordx4 v[26:29], v[100:101], off offset:128
	v_mfma_f32_16x16x32_bf16 v[90:93], v[142:145], v[162:165], v[90:93]
	global_load_dwordx4 v[30:33], v[98:99], off offset:128
	v_mfma_f32_16x16x32_bf16 v[94:97], v[142:145], v[166:169], v[94:97]
	s_waitcnt lgkmcnt(0)
	s_barrier
; DEV f32x4 mfma16(bf16x8 a, bf16x8 b, f32x4 c) { return __builtin_amdgcn_mfma_f32_16x16x32_bf16(a, b, c, 0, 0, 0); }
; template <int EPI, bool AF32>
; DEV void gemm_tile(const void* Ap, int lda, const u16* Bt, int ldb, int K, int m0, int n0, const Epi& ea, char* smem) {
;     ...
;   for (int kt = 0; kt < nk; kt++) {
;     const int buf = kt & 1;
;     if (kt + 1 < nk) swrite(buf ^ 1);
;     if (kt + 2 < nk) gload(kt + 2);
; #pragma unroll
;     for (int ks = 0; ks < 2; ks++) {
;       bf16x8 a[4], b[4];
; #pragma unroll
;       for (int m = 0; m < 4; m++) a[m] = *(const bf16x8*)(sA + buf * 9216 + (wr * 64 + m * 16 + fr) * 72 + ks * 32 + fq * 8);
; #pragma unroll
;       for (int n = 0; n < 4; n++) b[n] = *(const bf16x8*)(sB + buf * 9216 + (wc * 64 + n * 16 + fr) * 72 + ks * 32 + fq * 8);
;       __builtin_amdgcn_s_setprio(1);
; #pragma unroll
;       for (int m = 0; m < 4; m++)
; #pragma unroll
;         for (int n = 0; n < 4; n++) acc[m][n] = mfma16(a[m], b[n], acc[m][n]);
;       __builtin_amdgcn_s_setprio(0);
;     }
;     __syncthreads();
	ds_read_b128 v[130:133], v161
	v_mfma_f32_16x16x32_bf16 v[34:37], v[222:225], v[238:241], v[34:37]
	ds_read_b128 v[134:137], v161 offset:2304
	v_mfma_f32_16x16x32_bf16 v[38:41], v[222:225], v[242:245], v[38:41]
	ds_read_b128 v[138:141], v161 offset:4608
	v_mfma_f32_16x16x32_bf16 v[42:45], v[222:225], v[246:249], v[42:45]
	ds_read_b128 v[142:145], v161 offset:6912
	v_mfma_f32_16x16x32_bf16 v[46:49], v[222:225], v[250:253], v[46:49]
	ds_read_b128 v[146:149], v129 offset:36864
	v_mfma_f32_16x16x32_bf16 v[50:53], v[226:229], v[238:241], v[50:53]
	ds_read_b128 v[150:153], v129 offset:39168
	v_mfma_f32_16x16x32_bf16 v[54:57], v[226:229], v[242:245], v[54:57]
	ds_read_b128 v[162:165], v129 offset:41472
	v_mfma_f32_16x16x32_bf16 v[58:61], v[226:229], v[246:249], v[58:61]
	ds_read_b128 v[166:169], v129 offset:43776
	v_mfma_f32_16x16x32_bf16 v[62:65], v[226:229], v[250:253], v[62:65]
	v_mfma_f32_16x16x32_bf16 v[66:69], v[230:233], v[238:241], v[66:69]
	v_lshl_add_u64 v[112:113], v[112:113], 0, s[0:1]
	v_mfma_f32_16x16x32_bf16 v[70:73], v[230:233], v[242:245], v[70:73]
	v_lshl_add_u64 v[110:111], v[110:111], 0, s[0:1]
	v_mfma_f32_16x16x32_bf16 v[74:77], v[230:233], v[246:249], v[74:77]
	v_lshl_add_u64 v[108:109], v[108:109], 0, s[0:1]
	v_mfma_f32_16x16x32_bf16 v[78:81], v[230:233], v[250:253], v[78:81]
	v_lshl_add_u64 v[106:107], v[106:107], 0, s[0:1]
	v_mfma_f32_16x16x32_bf16 v[82:85], v[234:237], v[238:241], v[82:85]
	v_lshl_add_u64 v[104:105], v[104:105], 0, s[0:1]
	v_mfma_f32_16x16x32_bf16 v[86:89], v[234:237], v[242:245], v[86:89]
	v_lshl_add_u64 v[102:103], v[102:103], 0, s[0:1]
	v_mfma_f32_16x16x32_bf16 v[90:93], v[234:237], v[246:249], v[90:93]
	v_lshl_add_u64 v[100:101], v[100:101], 0, s[0:1]
	v_mfma_f32_16x16x32_bf16 v[94:97], v[234:237], v[250:253], v[94:97]
	v_lshl_add_u64 v[98:99], v[98:99], 0, s[0:1]
	s_add_i32 s17, s17, 1
	s_cmp_lg_u32 s17, 21
	s_cbranch_scc1 .Lgk7_loop
	s_waitcnt vmcnt(7)
	ds_write_b128 v118, v[6:9] offset:18432
	s_waitcnt vmcnt(6)
	ds_write_b128 v118, v[2:5] offset:55296
	s_waitcnt vmcnt(5)
	ds_write_b128 v120, v[10:13] offset:18432
	s_waitcnt vmcnt(4)
	ds_write_b128 v120, v[14:17] offset:55296
	s_waitcnt vmcnt(3)
	ds_write_b128 v122, v[18:21] offset:18432
	s_waitcnt vmcnt(2)
	ds_write_b128 v122, v[22:25] offset:55296
	s_waitcnt vmcnt(1)
	ds_write_b128 v123, v[26:29] offset:18432
	s_waitcnt vmcnt(0)
	ds_write_b128 v123, v[30:33] offset:55296
	v_lshl_add_u32 v0, v128, 1, v125
	v_lshl_add_u32 v126, v127, 1, v125
	ds_read_b128 v[2:5], v0
	ds_read_b128 v[6:9], v0 offset:2304
	ds_read_b128 v[10:13], v0 offset:4608
	ds_read_b128 v[14:17], v0 offset:6912
	ds_read_b128 v[18:21], v126 offset:36864
	ds_read_b128 v[22:25], v126 offset:39168
	ds_read_b128 v[26:29], v126 offset:41472
	ds_read_b128 v[30:33], v126 offset:43776
	s_setprio 1
	s_waitcnt lgkmcnt(3)
	v_mfma_f32_16x16x32_bf16 v[34:37], v[2:5], v[18:21], v[34:37]
	s_waitcnt lgkmcnt(2)
	v_mfma_f32_16x16x32_bf16 v[38:41], v[2:5], v[22:25], v[38:41]
	s_waitcnt lgkmcnt(1)
	v_mfma_f32_16x16x32_bf16 v[42:45], v[2:5], v[26:29], v[42:45]
	s_waitcnt lgkmcnt(0)
	v_mfma_f32_16x16x32_bf16 v[2:5], v[2:5], v[30:33], v[46:49]
	v_mfma_f32_16x16x32_bf16 v[46:49], v[6:9], v[18:21], v[50:53]
	v_mfma_f32_16x16x32_bf16 v[50:53], v[6:9], v[22:25], v[54:57]
	v_mfma_f32_16x16x32_bf16 v[54:57], v[6:9], v[26:29], v[58:61]
	v_mfma_f32_16x16x32_bf16 v[6:9], v[6:9], v[30:33], v[62:65]
	v_mfma_f32_16x16x32_bf16 v[58:61], v[10:13], v[18:21], v[66:69]
	v_mfma_f32_16x16x32_bf16 v[62:65], v[10:13], v[22:25], v[70:73]
	v_mfma_f32_16x16x32_bf16 v[66:69], v[10:13], v[26:29], v[74:77]
	v_mfma_f32_16x16x32_bf16 v[10:13], v[10:13], v[30:33], v[78:81]
	v_mfma_f32_16x16x32_bf16 v[18:21], v[14:17], v[18:21], v[82:85]
	v_mfma_f32_16x16x32_bf16 v[22:25], v[14:17], v[22:25], v[86:89]
	v_mfma_f32_16x16x32_bf16 v[26:29], v[14:17], v[26:29], v[90:93]
	v_mfma_f32_16x16x32_bf16 v[14:17], v[14:17], v[30:33], v[94:97]
	s_setprio 0
	ds_read_b128 v[30:33], v0 offset:64
	ds_read_b128 v[70:73], v0 offset:2368
	ds_read_b128 v[74:77], v0 offset:4672
	ds_read_b128 v[78:81], v0 offset:6976
	ds_read_b128 v[82:85], v126 offset:36928
	ds_read_b128 v[86:89], v126 offset:39232
	ds_read_b128 v[90:93], v126 offset:41536
	ds_read_b128 v[94:97], v126 offset:43840
	s_setprio 1
	s_waitcnt lgkmcnt(3)
	v_mfma_f32_16x16x32_bf16 v[34:37], v[30:33], v[82:85], v[34:37]
	s_waitcnt lgkmcnt(2)
	v_mfma_f32_16x16x32_bf16 v[38:41], v[30:33], v[86:89], v[38:41]
	s_waitcnt lgkmcnt(1)
	v_mfma_f32_16x16x32_bf16 v[42:45], v[30:33], v[90:93], v[42:45]
	s_waitcnt lgkmcnt(0)
	v_mfma_f32_16x16x32_bf16 v[2:5], v[30:33], v[94:97], v[2:5]
	v_mfma_f32_16x16x32_bf16 v[30:33], v[70:73], v[82:85], v[46:49]
	v_mfma_f32_16x16x32_bf16 v[46:49], v[70:73], v[86:89], v[50:53]
	v_mfma_f32_16x16x32_bf16 v[50:53], v[70:73], v[90:93], v[54:57]
	v_mfma_f32_16x16x32_bf16 v[6:9], v[70:73], v[94:97], v[6:9]
	v_mfma_f32_16x16x32_bf16 v[54:57], v[74:77], v[82:85], v[58:61]
	v_mfma_f32_16x16x32_bf16 v[58:61], v[74:77], v[86:89], v[62:65]
	v_mfma_f32_16x16x32_bf16 v[62:65], v[74:77], v[90:93], v[66:69]
	v_mfma_f32_16x16x32_bf16 v[10:13], v[74:77], v[94:97], v[10:13]
	v_mfma_f32_16x16x32_bf16 v[18:21], v[78:81], v[82:85], v[18:21]
	v_mfma_f32_16x16x32_bf16 v[22:25], v[78:81], v[86:89], v[22:25]
	v_mfma_f32_16x16x32_bf16 v[26:29], v[78:81], v[90:93], v[26:29]
	v_mfma_f32_16x16x32_bf16 v[14:17], v[78:81], v[94:97], v[14:17]
	s_setprio 0
	s_barrier
; DEV f32x4 mfma16(bf16x8 a, bf16x8 b, f32x4 c) { return __builtin_amdgcn_mfma_f32_16x16x32_bf16(a, b, c, 0, 0, 0); }
; template <int EPI, bool AF32>
; DEV void gemm_tile(const void* Ap, int lda, const u16* Bt, int ldb, int K, int m0, int n0, const Epi& ea, char* smem) {
;     ...
;   for (int kt = 0; kt < nk; kt++) {
;     const int buf = kt & 1;
;     if (kt + 1 < nk) swrite(buf ^ 1);
;     if (kt + 2 < nk) gload(kt + 2);
; #pragma unroll
;     for (int ks = 0; ks < 2; ks++) {
;       bf16x8 a[4], b[4];
; #pragma unroll
;       for (int m = 0; m < 4; m++) a[m] = *(const bf16x8*)(sA + buf * 9216 + (wr * 64 + m * 16 + fr) * 72 + ks * 32 + fq * 8);
; #pragma unroll
;       for (int n = 0; n < 4; n++) b[n] = *(const bf16x8*)(sB + buf * 9216 + (wc * 64 + n * 16 + fr) * 72 + ks * 32 + fq * 8);
;       __builtin_amdgcn_s_setprio(1);
; #pragma unroll
;       for (int m = 0; m < 4; m++)
; #pragma unroll
;         for (int n = 0; n < 4; n++) acc[m][n] = mfma16(a[m], b[n], acc[m][n]);
;       __builtin_amdgcn_s_setprio(0);
;     }
;     __syncthreads();
;     ...
;   if (EPI == EP_RES || EPI == EP_MERGE1 || EPI == EP_MERGE2) {
;     const int rbase = m0 + wr * 64 + fq * 4, cbase = cb + fr;
;     if (EPI == EP_RES) {
;       float* C = (float*)ea.p0;
;       const float* R = (const float*)ea.p1;
;       float rv[4][4][4];
; #pragma unroll
;       for (int m = 0; m < 4; m++)
; #pragma unroll
;         for (int j = 0; j < 4; j++)
; #pragma unroll
;           for (int n = 0; n < 4; n++) rv[m][j][n] = R[(size_t)(rbase + m * 16 + j) * 1024 + cbase + n * 16];
;       __builtin_amdgcn_sched_barrier(0);
	ds_read_b128 v[66:69], v0 offset:18432
	ds_read_b128 v[70:73], v0 offset:20736
	ds_read_b128 v[74:77], v0 offset:23040
	ds_read_b128 v[78:81], v0 offset:25344
	ds_read_b128 v[82:85], v126 offset:55296
	ds_read_b128 v[86:89], v126 offset:57600
	ds_read_b128 v[90:93], v126 offset:59904
	ds_read_b128 v[94:97], v126 offset:62208
	v_and_b32_e32 v116, 64, v116
	s_setprio 1
	s_waitcnt lgkmcnt(3)
	v_mfma_f32_16x16x32_bf16 v[34:37], v[66:69], v[82:85], v[34:37]
	s_waitcnt lgkmcnt(2)
	v_mfma_f32_16x16x32_bf16 v[38:41], v[66:69], v[86:89], v[38:41]
	s_waitcnt lgkmcnt(1)
	v_mfma_f32_16x16x32_bf16 v[42:45], v[66:69], v[90:93], v[42:45]
	s_waitcnt lgkmcnt(0)
	v_mfma_f32_16x16x32_bf16 v[2:5], v[66:69], v[94:97], v[2:5]
	v_mfma_f32_16x16x32_bf16 v[30:33], v[70:73], v[82:85], v[30:33]
	v_mfma_f32_16x16x32_bf16 v[66:69], v[70:73], v[86:89], v[46:49]
	v_mfma_f32_16x16x32_bf16 v[98:101], v[70:73], v[90:93], v[50:53]
	v_mfma_f32_16x16x32_bf16 v[6:9], v[70:73], v[94:97], v[6:9]
	v_mfma_f32_16x16x32_bf16 v[70:73], v[74:77], v[82:85], v[54:57]
	v_mfma_f32_16x16x32_bf16 v[102:105], v[74:77], v[86:89], v[58:61]
	v_mfma_f32_16x16x32_bf16 v[106:109], v[74:77], v[90:93], v[62:65]
	v_mfma_f32_16x16x32_bf16 v[10:13], v[74:77], v[94:97], v[10:13]
	v_mfma_f32_16x16x32_bf16 v[74:77], v[78:81], v[82:85], v[18:21]
	v_mfma_f32_16x16x32_bf16 v[82:85], v[78:81], v[86:89], v[22:25]
	v_mfma_f32_16x16x32_bf16 v[86:89], v[78:81], v[90:93], v[26:29]
	v_mfma_f32_16x16x32_bf16 v[78:81], v[78:81], v[94:97], v[14:17]
	s_setprio 0
	s_nop 1
	ds_read_b128 v[14:17], v0 offset:18496
	ds_read_b128 v[18:21], v0 offset:20800
	ds_read_b128 v[90:93], v0 offset:23104
	ds_read_b128 v[94:97], v0 offset:25408
	ds_read_b128 v[110:113], v126 offset:55360
	ds_read_b128 v[118:121], v126 offset:57664
	ds_read_b128 v[122:125], v126 offset:59968
	ds_read_b128 v[126:129], v126 offset:62272
	s_setprio 1
	s_waitcnt lgkmcnt(3)
	v_mfma_f32_16x16x32_bf16 v[62:65], v[14:17], v[110:113], v[34:37]
	s_waitcnt lgkmcnt(2)
	v_mfma_f32_16x16x32_bf16 v[58:61], v[14:17], v[118:121], v[38:41]
	s_waitcnt lgkmcnt(1)
	v_mfma_f32_16x16x32_bf16 v[54:57], v[14:17], v[122:125], v[42:45]
	s_waitcnt lgkmcnt(0)
	v_mfma_f32_16x16x32_bf16 v[50:53], v[14:17], v[126:129], v[2:5]
	v_mfma_f32_16x16x32_bf16 v[46:49], v[18:21], v[110:113], v[30:33]
	v_mfma_f32_16x16x32_bf16 v[42:45], v[18:21], v[118:121], v[66:69]
	v_mfma_f32_16x16x32_bf16 v[38:41], v[18:21], v[122:125], v[98:101]
	v_mfma_f32_16x16x32_bf16 v[34:37], v[18:21], v[126:129], v[6:9]
	v_mfma_f32_16x16x32_bf16 v[30:33], v[90:93], v[110:113], v[70:73]
	v_mfma_f32_16x16x32_bf16 v[26:29], v[90:93], v[118:121], v[102:105]
	v_mfma_f32_16x16x32_bf16 v[22:25], v[90:93], v[122:125], v[106:109]
	v_mfma_f32_16x16x32_bf16 v[18:21], v[90:93], v[126:129], v[10:13]
	v_mfma_f32_16x16x32_bf16 v[14:17], v[94:97], v[110:113], v[74:77]
	v_mfma_f32_16x16x32_bf16 v[10:13], v[94:97], v[118:121], v[82:85]
	v_mfma_f32_16x16x32_bf16 v[6:9], v[94:97], v[122:125], v[86:89]
	v_mfma_f32_16x16x32_bf16 v[2:5], v[94:97], v[126:129], v[78:81]
	s_setprio 0
	v_add_u32_e32 v0, s16, v117
	v_or3_b32 v66, v116, s15, v114
	v_lshl_or_b32 v72, v115, 2, v0
	v_ashrrev_i32_e32 v67, 31, v66
	v_lshlrev_b64 v[66:67], 2, v[66:67]
	v_ashrrev_i32_e32 v73, 31, v72
	v_lshl_add_u64 v[74:75], s[4:5], 0, v[66:67]
	v_lshlrev_b64 v[68:69], 12, v[72:73]
	v_lshl_add_u64 v[70:71], v[74:75], 0, v[68:69]
	s_barrier
	global_load_dword v0, v[70:71], off
	global_load_dword v104, v[70:71], off offset:64
	global_load_dword v105, v[70:71], off offset:128
	global_load_dword v106, v[70:71], off offset:192
	v_or_b32_e32 v70, 1, v72
	v_ashrrev_i32_e32 v71, 31, v70
	v_lshlrev_b64 v[70:71], 12, v[70:71]
	v_lshl_add_u64 v[76:77], v[74:75], 0, v[70:71]
	global_load_dword v107, v[76:77], off
	global_load_dword v108, v[76:77], off offset:64
	global_load_dword v109, v[76:77], off offset:128
	global_load_dword v110, v[76:77], off offset:192
	v_or_b32_e32 v76, 2, v72
	v_ashrrev_i32_e32 v77, 31, v76
	v_lshlrev_b64 v[76:77], 12, v[76:77]
	v_lshl_add_u64 v[78:79], v[74:75], 0, v[76:77]
	global_load_dword v111, v[78:79], off
	global_load_dword v112, v[78:79], off offset:64
	global_load_dword v113, v[78:79], off offset:128
	global_load_dword v114, v[78:79], off offset:192
	v_or_b32_e32 v78, 3, v72
	v_ashrrev_i32_e32 v79, 31, v78
	v_lshlrev_b64 v[78:79], 12, v[78:79]
	v_lshl_add_u64 v[80:81], v[74:75], 0, v[78:79]
	global_load_dword v115, v[80:81], off
	global_load_dword v116, v[80:81], off offset:64
	global_load_dword v117, v[80:81], off offset:128
	global_load_dword v118, v[80:81], off offset:192
	v_or_b32_e32 v80, 16, v72
	v_ashrrev_i32_e32 v81, 31, v80
	v_lshlrev_b64 v[80:81], 12, v[80:81]
	v_lshl_add_u64 v[82:83], v[74:75], 0, v[80:81]
	global_load_dword v119, v[82:83], off
	global_load_dword v120, v[82:83], off offset:64
	global_load_dword v121, v[82:83], off offset:128
	global_load_dword v122, v[82:83], off offset:192
	v_or_b32_e32 v82, 17, v72
	v_ashrrev_i32_e32 v83, 31, v82
	v_lshlrev_b64 v[82:83], 12, v[82:83]
	v_lshl_add_u64 v[84:85], v[74:75], 0, v[82:83]
	global_load_dword v123, v[84:85], off
	global_load_dword v124, v[84:85], off offset:64
	global_load_dword v125, v[84:85], off offset:128
	global_load_dword v126, v[84:85], off offset:192
	v_or_b32_e32 v84, 18, v72
	v_ashrrev_i32_e32 v85, 31, v84
	v_lshlrev_b64 v[84:85], 12, v[84:85]
	v_lshl_add_u64 v[86:87], v[74:75], 0, v[84:85]
	global_load_dword v127, v[86:87], off
	global_load_dword v128, v[86:87], off offset:64
	global_load_dword v129, v[86:87], off offset:128
	global_load_dword v130, v[86:87], off offset:192
	v_or_b32_e32 v86, 19, v72
	v_ashrrev_i32_e32 v87, 31, v86
	v_lshlrev_b64 v[86:87], 12, v[86:87]
; template <int EPI, bool AF32>
; DEV void gemm_tile(const void* Ap, int lda, const u16* Bt, int ldb, int K, int m0, int n0, const Epi& ea, char* smem) {
;     ...
; #pragma unroll
;       for (int m = 0; m < 4; m++)
; #pragma unroll
;         for (int j = 0; j < 4; j++)
; #pragma unroll
;           for (int n = 0; n < 4; n++) rv[m][j][n] = R[(size_t)(rbase + m * 16 + j) * 1024 + cbase + n * 16];
;       __builtin_amdgcn_sched_barrier(0);
; #pragma unroll
;       for (int m = 0; m < 4; m++)
; #pragma unroll
;         for (int j = 0; j < 4; j++)
; #pragma unroll
;           for (int n = 0; n < 4; n++)
;             C[(size_t)(rbase + m * 16 + j) * 1024 + cbase + n * 16] = ALPHA_ * rv[m][j][n] + acc[m][n][j];
	v_lshl_add_u64 v[88:89], v[74:75], 0, v[86:87]
	global_load_dword v131, v[88:89], off
	global_load_dword v132, v[88:89], off offset:64
	global_load_dword v133, v[88:89], off offset:128
	global_load_dword v134, v[88:89], off offset:192
	v_or_b32_e32 v88, 32, v72
	v_ashrrev_i32_e32 v89, 31, v88
	v_lshlrev_b64 v[88:89], 12, v[88:89]
	v_lshl_add_u64 v[90:91], v[74:75], 0, v[88:89]
	global_load_dword v135, v[90:91], off
	global_load_dword v136, v[90:91], off offset:64
	global_load_dword v137, v[90:91], off offset:128
	global_load_dword v138, v[90:91], off offset:192
	v_or_b32_e32 v90, 33, v72
	v_ashrrev_i32_e32 v91, 31, v90
	v_lshlrev_b64 v[90:91], 12, v[90:91]
	v_lshl_add_u64 v[92:93], v[74:75], 0, v[90:91]
	global_load_dword v139, v[92:93], off
	global_load_dword v140, v[92:93], off offset:64
	global_load_dword v141, v[92:93], off offset:128
	global_load_dword v142, v[92:93], off offset:192
	v_or_b32_e32 v92, 34, v72
	v_ashrrev_i32_e32 v93, 31, v92
	v_lshlrev_b64 v[92:93], 12, v[92:93]
	v_lshl_add_u64 v[94:95], v[74:75], 0, v[92:93]
	global_load_dword v143, v[94:95], off
	global_load_dword v144, v[94:95], off offset:64
	global_load_dword v145, v[94:95], off offset:128
	global_load_dword v146, v[94:95], off offset:192
	v_or_b32_e32 v94, 35, v72
	v_ashrrev_i32_e32 v95, 31, v94
	v_lshlrev_b64 v[94:95], 12, v[94:95]
	v_lshl_add_u64 v[96:97], v[74:75], 0, v[94:95]
	global_load_dword v147, v[96:97], off
	global_load_dword v148, v[96:97], off offset:64
	global_load_dword v149, v[96:97], off offset:128
	global_load_dword v150, v[96:97], off offset:192
	v_or_b32_e32 v96, 48, v72
	v_ashrrev_i32_e32 v97, 31, v96
	v_lshlrev_b64 v[96:97], 12, v[96:97]
	v_lshl_add_u64 v[98:99], v[74:75], 0, v[96:97]
	global_load_dword v151, v[98:99], off
	global_load_dword v152, v[98:99], off offset:64
	global_load_dword v153, v[98:99], off offset:128
	global_load_dword v161, v[98:99], off offset:192
	v_or_b32_e32 v98, 49, v72
	v_ashrrev_i32_e32 v99, 31, v98
	v_lshlrev_b64 v[98:99], 12, v[98:99]
	v_lshl_add_u64 v[100:101], v[74:75], 0, v[98:99]
	global_load_dword v162, v[100:101], off
	global_load_dword v163, v[100:101], off offset:64
	global_load_dword v164, v[100:101], off offset:128
	global_load_dword v165, v[100:101], off offset:192
	v_or_b32_e32 v100, 50, v72
	v_or_b32_e32 v72, 51, v72
	v_ashrrev_i32_e32 v101, 31, v100
	v_ashrrev_i32_e32 v73, 31, v72
	v_lshlrev_b64 v[100:101], 12, v[100:101]
	v_lshlrev_b64 v[72:73], 12, v[72:73]
	v_lshl_add_u64 v[102:103], v[74:75], 0, v[100:101]
	v_lshl_add_u64 v[74:75], v[74:75], 0, v[72:73]
	global_load_dword v166, v[102:103], off
	global_load_dword v167, v[102:103], off offset:64
	global_load_dword v168, v[102:103], off offset:128
	s_nop 0
	global_load_dword v102, v[102:103], off offset:192
	s_nop 0
	global_load_dword v103, v[74:75], off
	global_load_dword v169, v[74:75], off offset:64
	global_load_dword v170, v[74:75], off offset:128
	s_nop 0
	global_load_dword v74, v[74:75], off offset:192
	v_lshl_add_u64 v[66:67], s[2:3], 0, v[66:67]
	v_lshl_add_u64 v[68:69], v[66:67], 0, v[68:69]
	s_waitcnt vmcnt(62)
	v_fmamk_f32 v0, v0, 0x3fb504f3, v62
	global_store_dword v[68:69], v0, off
	v_fmamk_f32 v0, v104, 0x3fb504f3, v58
	global_store_dword v[68:69], v0, off offset:64
	s_waitcnt vmcnt(62)
	v_fmamk_f32 v0, v105, 0x3fb504f3, v54
	global_store_dword v[68:69], v0, off offset:128
	v_fmamk_f32 v0, v106, 0x3fb504f3, v50
	global_store_dword v[68:69], v0, off offset:192
	v_lshl_add_u64 v[68:69], v[66:67], 0, v[70:71]
	s_waitcnt vmcnt(62)
	v_fmamk_f32 v0, v107, 0x3fb504f3, v63
	global_store_dword v[68:69], v0, off
	v_fmamk_f32 v0, v108, 0x3fb504f3, v59
	global_store_dword v[68:69], v0, off offset:64
	s_waitcnt vmcnt(62)
	v_fmamk_f32 v0, v109, 0x3fb504f3, v55
	global_store_dword v[68:69], v0, off offset:128
	v_fmamk_f32 v0, v110, 0x3fb504f3, v51
	global_store_dword v[68:69], v0, off offset:192
	v_lshl_add_u64 v[50:51], v[66:67], 0, v[76:77]
	s_waitcnt vmcnt(62)
	v_fmamk_f32 v0, v111, 0x3fb504f3, v64
	global_store_dword v[50:51], v0, off
	v_fmamk_f32 v0, v112, 0x3fb504f3, v60
	global_store_dword v[50:51], v0, off offset:64
	s_waitcnt vmcnt(62)
	v_fmamk_f32 v0, v113, 0x3fb504f3, v56
	global_store_dword v[50:51], v0, off offset:128
	v_fmamk_f32 v0, v114, 0x3fb504f3, v52
	global_store_dword v[50:51], v0, off offset:192
	v_lshl_add_u64 v[50:51], v[66:67], 0, v[78:79]
	s_waitcnt vmcnt(62)
	v_fmac_f32_e32 v65, 0x3fb504f3, v115
	v_fmac_f32_e32 v61, 0x3fb504f3, v116
	s_waitcnt vmcnt(61)
	v_fmac_f32_e32 v57, 0x3fb504f3, v117
	s_waitcnt vmcnt(60)
	v_fmac_f32_e32 v53, 0x3fb504f3, v118
	global_store_dword v[50:51], v65, off
	global_store_dword v[50:51], v61, off offset:64
	global_store_dword v[50:51], v57, off offset:128
	global_store_dword v[50:51], v53, off offset:192
	v_lshl_add_u64 v[50:51], v[66:67], 0, v[80:81]
	s_waitcnt vmcnt(62)
	v_fmamk_f32 v0, v119, 0x3fb504f3, v46
	global_store_dword v[50:51], v0, off
	v_fmamk_f32 v0, v120, 0x3fb504f3, v42
	global_store_dword v[50:51], v0, off offset:64
	s_waitcnt vmcnt(62)
; DEV int bidx() { int b = __builtin_amdgcn_readfirstlane(blockIdx.x); asm volatile("" : "+s"(b)); return b; }
; DEV int gdim() { int g = __builtin_amdgcn_readfirstlane(gridDim.x); asm volatile("" : "+s"(g)); return g; }
; template <int EPI, bool AF32>
; DEV void gemm_tile(const void* Ap, int lda, const u16* Bt, int ldb, int K, int m0, int n0, const Epi& ea, char* smem) {
;     ...
; #pragma unroll
;       for (int m = 0; m < 4; m++)
; #pragma unroll
;         for (int j = 0; j < 4; j++)
; #pragma unroll
;           for (int n = 0; n < 4; n++)
;             C[(size_t)(rbase + m * 16 + j) * 1024 + cbase + n * 16] = ALPHA_ * rv[m][j][n] + acc[m][n][j];
; template <int EPI, bool AF32>
; DEV void gemm_phase(const void* A, int lda, const u16* Bt, int ldb, int M, int N, int K, const Epi& ea, char* smem) {
;     ...
;   for (int tile = bidx(); tile < ntm * ntn; tile += gdim()) {
;     int m, n;
;     tile_mn(tile, ntm, ntn, m, n);
;     gemm_tile<EPI, AF32>(A, lda, Bt, ldb, K, m << 7, n << 7, ea, smem);
;   }
	v_fmamk_f32 v0, v121, 0x3fb504f3, v38
	global_store_dword v[50:51], v0, off offset:128
	v_fmamk_f32 v0, v122, 0x3fb504f3, v34
	global_store_dword v[50:51], v0, off offset:192
	v_lshl_add_u64 v[50:51], v[66:67], 0, v[82:83]
	s_waitcnt vmcnt(62)
	v_fmamk_f32 v0, v123, 0x3fb504f3, v47
	global_store_dword v[50:51], v0, off
	v_fmamk_f32 v0, v124, 0x3fb504f3, v43
	global_store_dword v[50:51], v0, off offset:64
	s_waitcnt vmcnt(62)
	v_fmamk_f32 v0, v125, 0x3fb504f3, v39
	global_store_dword v[50:51], v0, off offset:128
	v_fmamk_f32 v0, v126, 0x3fb504f3, v35
	global_store_dword v[50:51], v0, off offset:192
	v_lshl_add_u64 v[34:35], v[66:67], 0, v[84:85]
	s_waitcnt vmcnt(62)
	v_fmamk_f32 v0, v127, 0x3fb504f3, v48
	global_store_dword v[34:35], v0, off
	v_fmamk_f32 v0, v128, 0x3fb504f3, v44
	global_store_dword v[34:35], v0, off offset:64
	s_waitcnt vmcnt(62)
	v_fmamk_f32 v0, v129, 0x3fb504f3, v40
	global_store_dword v[34:35], v0, off offset:128
	v_fmamk_f32 v0, v130, 0x3fb504f3, v36
	global_store_dword v[34:35], v0, off offset:192
	v_lshl_add_u64 v[34:35], v[66:67], 0, v[86:87]
	s_waitcnt vmcnt(62)
	v_fmac_f32_e32 v49, 0x3fb504f3, v131
	v_fmac_f32_e32 v45, 0x3fb504f3, v132
	s_waitcnt vmcnt(61)
	v_fmac_f32_e32 v41, 0x3fb504f3, v133
	s_waitcnt vmcnt(60)
	v_fmac_f32_e32 v37, 0x3fb504f3, v134
	global_store_dword v[34:35], v49, off
	global_store_dword v[34:35], v45, off offset:64
	global_store_dword v[34:35], v41, off offset:128
	global_store_dword v[34:35], v37, off offset:192
	v_lshl_add_u64 v[34:35], v[66:67], 0, v[88:89]
	s_waitcnt vmcnt(62)
	v_fmamk_f32 v0, v135, 0x3fb504f3, v30
	global_store_dword v[34:35], v0, off
	v_fmamk_f32 v0, v136, 0x3fb504f3, v26
	global_store_dword v[34:35], v0, off offset:64
	s_waitcnt vmcnt(62)
	v_fmamk_f32 v0, v137, 0x3fb504f3, v22
	global_store_dword v[34:35], v0, off offset:128
	v_fmamk_f32 v0, v138, 0x3fb504f3, v18
	global_store_dword v[34:35], v0, off offset:192
	v_lshl_add_u64 v[34:35], v[66:67], 0, v[90:91]
	s_waitcnt vmcnt(62)
	v_fmamk_f32 v0, v139, 0x3fb504f3, v31
	global_store_dword v[34:35], v0, off
	v_fmamk_f32 v0, v140, 0x3fb504f3, v27
	global_store_dword v[34:35], v0, off offset:64
	s_waitcnt vmcnt(62)
	v_fmamk_f32 v0, v141, 0x3fb504f3, v23
	global_store_dword v[34:35], v0, off offset:128
	v_fmamk_f32 v0, v142, 0x3fb504f3, v19
	global_store_dword v[34:35], v0, off offset:192
	v_lshl_add_u64 v[18:19], v[66:67], 0, v[92:93]
	s_waitcnt vmcnt(62)
	v_fmamk_f32 v0, v143, 0x3fb504f3, v32
	global_store_dword v[18:19], v0, off
	v_fmamk_f32 v0, v144, 0x3fb504f3, v28
	global_store_dword v[18:19], v0, off offset:64
	s_waitcnt vmcnt(62)
	v_fmamk_f32 v0, v145, 0x3fb504f3, v24
	global_store_dword v[18:19], v0, off offset:128
	v_fmamk_f32 v0, v146, 0x3fb504f3, v20
	global_store_dword v[18:19], v0, off offset:192
	v_lshl_add_u64 v[18:19], v[66:67], 0, v[94:95]
	s_waitcnt vmcnt(62)
	v_fmac_f32_e32 v33, 0x3fb504f3, v147
	v_fmac_f32_e32 v29, 0x3fb504f3, v148
	s_waitcnt vmcnt(61)
	v_fmac_f32_e32 v25, 0x3fb504f3, v149
	s_waitcnt vmcnt(60)
	v_fmac_f32_e32 v21, 0x3fb504f3, v150
	global_store_dword v[18:19], v33, off
	global_store_dword v[18:19], v29, off offset:64
	global_store_dword v[18:19], v25, off offset:128
	global_store_dword v[18:19], v21, off offset:192
	v_lshl_add_u64 v[18:19], v[66:67], 0, v[96:97]
	s_waitcnt vmcnt(62)
	v_fmamk_f32 v0, v151, 0x3fb504f3, v14
	global_store_dword v[18:19], v0, off
	v_fmamk_f32 v0, v152, 0x3fb504f3, v10
	global_store_dword v[18:19], v0, off offset:64
	s_waitcnt vmcnt(62)
	v_fmamk_f32 v0, v153, 0x3fb504f3, v6
	global_store_dword v[18:19], v0, off offset:128
	v_fmamk_f32 v0, v161, 0x3fb504f3, v2
	global_store_dword v[18:19], v0, off offset:192
	v_lshl_add_u64 v[18:19], v[66:67], 0, v[98:99]
	s_waitcnt vmcnt(62)
	v_fmamk_f32 v0, v162, 0x3fb504f3, v15
	global_store_dword v[18:19], v0, off
	v_fmamk_f32 v0, v163, 0x3fb504f3, v11
	global_store_dword v[18:19], v0, off offset:64
	s_waitcnt vmcnt(62)
	v_fmamk_f32 v0, v164, 0x3fb504f3, v7
	global_store_dword v[18:19], v0, off offset:128
	v_fmamk_f32 v0, v165, 0x3fb504f3, v3
	global_store_dword v[18:19], v0, off offset:192
	v_lshl_add_u64 v[2:3], v[66:67], 0, v[100:101]
	s_waitcnt vmcnt(62)
	v_fmamk_f32 v0, v166, 0x3fb504f3, v16
	global_store_dword v[2:3], v0, off
	v_fmamk_f32 v0, v167, 0x3fb504f3, v12
	global_store_dword v[2:3], v0, off offset:64
	s_waitcnt vmcnt(62)
	v_fmamk_f32 v0, v168, 0x3fb504f3, v8
	global_store_dword v[2:3], v0, off offset:128
	v_fmamk_f32 v0, v102, 0x3fb504f3, v4
	global_store_dword v[2:3], v0, off offset:192
	v_lshl_add_u64 v[2:3], v[66:67], 0, v[72:73]
	s_waitcnt vmcnt(62)
	v_fmac_f32_e32 v17, 0x3fb504f3, v103
	v_fmac_f32_e32 v13, 0x3fb504f3, v169
	s_waitcnt vmcnt(61)
	v_fmac_f32_e32 v9, 0x3fb504f3, v170
	s_waitcnt vmcnt(60)
	v_fmac_f32_e32 v5, 0x3fb504f3, v74
	v_readfirstlane_b32 s0, v198
	global_store_dword v[2:3], v17, off
	global_store_dword v[2:3], v13, off offset:64
	global_store_dword v[2:3], v9, off offset:128
	global_store_dword v[2:3], v5, off offset:192
	s_add_i32 s14, s0, s14
	s_cmpk_lt_i32 s14, 0x820
	s_cbranch_scc1 .LBB0_1478
